# phase 2 scattered bf16 stores: per-store address arithmetic folded into offset immediates off one kept base address per group (kdT, w, kwT, vT); 275 dead address instructions removed
# baseline (speedup 1.0000x reference)
; DI void conv32(const bf16_t* __restrict__ Pcol, int tok, int spos, const float* wl, int wstride, float* acc) {
; #pragma unroll
;   for (int hq = 0; hq < 2; ++hq) {
;     __builtin_amdgcn_sched_barrier(0);
;     uint4 v[4][2];
; #pragma unroll
;     for (int j = 0; j < 4; ++j) {
;       const bool ok = (spos - 3 + j >= 0);
;       const uint4* src = (const uint4*)(Pcol + (size_t)(tok - 3 + (ok ? j : 3)) * 4096) + 2 * hq;
; #pragma unroll
;       for (int q = 0; q < 2; ++q) {
;         v[j][q] = src[q];
;         if (!ok) v[j][q] = make_uint4(0u, 0u, 0u, 0u);
;       }
;     }
; #pragma unroll
;     for (int i = 0; i < 16; ++i) acc[16 * hq + i] = 0.f;
; #pragma unroll
;     for (int j = 0; j < 4; ++j) {
;       const float4* w4 = (const float4*)(wl + j * wstride + 16 * hq);
; #pragma unroll
;       for (int q = 0; q < 2; ++q) {
;         float f[8];
;         unpack8(v[j][q], f);
;         float4 wa = w4[2 * q], wb = w4[2 * q + 1];
;         float* a = acc + 16 * hq + 8 * q;
;         a[0] += wa.x * f[0]; a[1] += wa.y * f[1]; a[2] += wa.z * f[2]; a[3] += wa.w * f[3];
;         a[4] += wb.x * f[4]; a[5] += wb.y * f[5]; a[6] += wb.z * f[6]; a[7] += wb.w * f[7];
; DI void gdn_pre(const Params& p, int ch, char* smem) {
;     ...
;   const int t = tid >> 2, part = tid & 3;
;   const float gct = s_gc[t], bet = s_beta[t], egt = s_eg[t], gcl = s_gc[63];
;   float kk[32], vv[32];
;   {
;     float a[32];
;     conv32(P + h * 128 + part * 32, tok0 + t, c * 64 + t, s_w + part * 32, 384, a);
.LBB0_300:
	s_or_b64 exec, exec, s[8:9]
	s_mul_i32 s5, s16, 0x12000
	s_mul_hi_i32 s4, s16, 0x12000
	s_add_u32 s34, s3, s5
	v_and_b32_e32 v0, -4, v34
	s_addc_u32 s35, s44, s4
	s_waitcnt lgkmcnt(0)
	s_barrier
	ds_read2st64_b32 v[36:37], v0 offset0:201 offset1:202
	ds_read_b32 v38, v0 offset:51968
	ds_read_b32 v96, v33 offset:51964
	s_add_u32 s36, s34, 0x8000
	s_addc_u32 s37, s35, 0
	s_lshl_b32 s0, s0, 8
	v_lshlrev_b32_e32 v0, 5, v34
	v_ashrrev_i32_e32 v35, 2, v34
	s_add_u32 s4, s86, s0
	v_and_b32_e32 v100, 0x60, v0
	s_addc_u32 s5, s87, 0
	v_lshlrev_b32_e32 v32, 1, v100
	v_add_u32_e32 v8, s6, v35
	v_lshl_add_u64 v[24:25], s[4:5], 0, v[32:33]
	v_add_u32_e32 v48, s1, v35
	v_lshlrev_b32_e32 v39, 2, v100
	v_add_u32_e32 v26, -3, v8
	v_cmp_lt_i32_e64 s[6:7], 1, v48
	v_cmp_lt_i32_e64 s[8:9], 0, v48
	v_ashrrev_i32_e32 v9, 31, v8
	v_cmp_lt_i32_e64 s[10:11], 2, v48
	v_cndmask_b32_e64 v16, 3, 1, s[6:7]
	v_cndmask_b32_e64 v27, 3, 2, s[8:9]
	v_lshlrev_b64 v[0:1], 13, v[8:9]
	v_cndmask_b32_e64 v8, v8, v26, s[10:11]
	v_add_u32_e32 v16, v16, v26
	v_add_u32_e32 v26, v27, v26
	v_ashrrev_i32_e32 v9, 31, v8
	v_ashrrev_i32_e32 v17, 31, v16
	v_ashrrev_i32_e32 v27, 31, v26
	v_lshlrev_b64 v[8:9], 13, v[8:9]
	v_lshlrev_b64 v[16:17], 13, v[16:17]
	v_lshlrev_b64 v[26:27], 13, v[26:27]
	v_lshl_add_u64 v[40:41], v[24:25], 0, v[0:1]
	v_lshl_add_u64 v[46:47], v[24:25], 0, v[8:9]
	v_lshl_add_u64 v[44:45], v[24:25], 0, v[16:17]
	v_lshl_add_u64 v[42:43], v[24:25], 0, v[26:27]
	global_load_dwordx4 v[0:3], v[40:41], off
	global_load_dwordx4 v[4:7], v[40:41], off offset:16
	global_load_dwordx4 v[8:11], v[46:47], off
	global_load_dwordx4 v[12:15], v[46:47], off offset:16
	global_load_dwordx4 v[16:19], v[44:45], off
	global_load_dwordx4 v[20:23], v[44:45], off offset:16
	global_load_dwordx4 v[24:27], v[42:43], off
	global_load_dwordx4 v[28:31], v[42:43], off offset:16
	v_cmp_lt_i32_e32 vcc, -1, v48
	s_waitcnt vmcnt(7)
	s_nop 0
	v_cndmask_b32_e32 v48, 0, v3, vcc
	v_cndmask_b32_e32 v49, 0, v2, vcc
	v_cndmask_b32_e32 v50, 0, v1, vcc
	v_cndmask_b32_e32 v51, 0, v0, vcc
	s_waitcnt vmcnt(6)
	v_cndmask_b32_e32 v101, 0, v6, vcc
	v_cndmask_b32_e32 v112, 0, v5, vcc
	v_cndmask_b32_e32 v113, 0, v4, vcc
	s_waitcnt vmcnt(5)
	v_cndmask_b32_e64 v0, 0, v11, s[10:11]
	v_cndmask_b32_e64 v1, 0, v10, s[10:11]
	v_cndmask_b32_e64 v2, 0, v9, s[10:11]
	v_cndmask_b32_e64 v3, 0, v8, s[10:11]
	s_waitcnt vmcnt(4)
	v_cndmask_b32_e64 v8, 0, v15, s[10:11]
	v_cndmask_b32_e64 v5, 0, v14, s[10:11]
	v_cndmask_b32_e64 v4, 0, v13, s[10:11]
	v_cndmask_b32_e64 v6, 0, v12, s[10:11]
	s_waitcnt vmcnt(3)
	v_cndmask_b32_e64 v9, 0, v19, s[6:7]
	v_cndmask_b32_e64 v10, 0, v18, s[6:7]
	v_cndmask_b32_e64 v11, 0, v17, s[6:7]
	v_cndmask_b32_e64 v12, 0, v16, s[6:7]
	s_waitcnt vmcnt(2)
	v_cndmask_b32_e64 v13, 0, v23, s[6:7]
	v_cndmask_b32_e64 v14, 0, v22, s[6:7]
	v_cndmask_b32_e64 v15, 0, v21, s[6:7]
	v_cndmask_b32_e64 v16, 0, v20, s[6:7]
	s_waitcnt vmcnt(1)
	v_cndmask_b32_e64 v17, 0, v27, s[8:9]
	v_cndmask_b32_e64 v18, 0, v26, s[8:9]
	v_cndmask_b32_e64 v19, 0, v25, s[8:9]
	v_cndmask_b32_e64 v20, 0, v24, s[8:9]
	s_waitcnt vmcnt(0)
	v_cndmask_b32_e64 v21, 0, v31, s[8:9]
	v_cndmask_b32_e64 v22, 0, v30, s[8:9]
	v_cndmask_b32_e64 v23, 0, v29, s[8:9]
	v_cndmask_b32_e64 v24, 0, v28, s[8:9]
	v_lshlrev_b32_e32 v30, 16, v3
	v_and_b32_e32 v31, 0xffff0000, v3
	v_lshlrev_b32_e32 v68, 16, v2
	v_and_b32_e32 v69, 0xffff0000, v2
	v_lshlrev_b32_e32 v70, 16, v1
	v_and_b32_e32 v71, 0xffff0000, v1
	v_lshlrev_b32_e32 v72, 16, v0
	v_and_b32_e32 v73, 0xffff0000, v0
	v_lshlrev_b32_e32 v0, 16, v8
	v_and_b32_e32 v1, 0xffff0000, v8
	v_lshlrev_b32_e32 v60, 16, v12
	v_and_b32_e32 v61, 0xffff0000, v12
	v_lshlrev_b32_e32 v76, 16, v11
	v_and_b32_e32 v77, 0xffff0000, v11
	v_lshlrev_b32_e32 v78, 16, v10
	v_and_b32_e32 v79, 0xffff0000, v10
	v_lshlrev_b32_e32 v80, 16, v9
	v_and_b32_e32 v81, 0xffff0000, v9
	v_lshlrev_b32_e32 v82, 16, v16
	v_and_b32_e32 v83, 0xffff0000, v16
	v_lshlrev_b32_e32 v84, 16, v15
	v_and_b32_e32 v85, 0xffff0000, v15
	v_lshlrev_b32_e32 v86, 16, v14
	v_and_b32_e32 v87, 0xffff0000, v14
	v_lshlrev_b32_e32 v2, 16, v13
	v_and_b32_e32 v3, 0xffff0000, v13
	v_lshlrev_b32_e32 v64, 16, v20
	v_and_b32_e32 v65, 0xffff0000, v20
	v_lshlrev_b32_e32 v88, 16, v19
	v_and_b32_e32 v89, 0xffff0000, v19
	v_lshlrev_b32_e32 v90, 16, v18
	v_and_b32_e32 v91, 0xffff0000, v18
	v_lshlrev_b32_e32 v92, 16, v17
	v_and_b32_e32 v93, 0xffff0000, v17
	v_lshlrev_b32_e32 v94, 16, v24
	v_and_b32_e32 v95, 0xffff0000, v24
	v_lshlrev_b32_e32 v98, 16, v23
	v_and_b32_e32 v99, 0xffff0000, v23
	v_lshlrev_b32_e32 v102, 16, v22
	v_and_b32_e32 v103, 0xffff0000, v22
	v_lshlrev_b32_e32 v8, 16, v21
	v_and_b32_e32 v9, 0xffff0000, v21
	ds_read_b128 v[10:13], v39 offset:52224
	ds_read_b128 v[14:17], v39 offset:52240
	ds_read_b128 v[18:21], v39 offset:52256
	ds_read_b128 v[22:25], v39 offset:52272
	ds_read_b128 v[26:29], v39 offset:53760
	v_lshlrev_b32_e32 v104, 16, v51
	v_and_b32_e32 v105, 0xffff0000, v51
	v_lshlrev_b32_e32 v106, 16, v50
	v_and_b32_e32 v107, 0xffff0000, v50
	v_lshlrev_b32_e32 v108, 16, v49
	v_and_b32_e32 v109, 0xffff0000, v49
	v_lshlrev_b32_e32 v110, 16, v48
	v_and_b32_e32 v111, 0xffff0000, v48
	ds_read_b128 v[48:51], v39 offset:55296
	ds_read_b128 v[52:55], v39 offset:56832
	ds_read_b128 v[56:59], v39 offset:53776
	s_waitcnt lgkmcnt(7)
	v_pk_fma_f32 v[10:11], v[10:11], v[30:31], 0 op_sel_hi:[1,1,0]
	s_waitcnt lgkmcnt(4)
	v_pk_fma_f32 v[0:1], v[24:25], v[0:1], 0 op_sel_hi:[1,1,0]
	s_waitcnt lgkmcnt(3)
	v_pk_fma_f32 v[10:11], v[26:27], v[60:61], v[10:11]
	ds_read_b128 v[60:63], v39 offset:55312
	s_waitcnt lgkmcnt(3)
	v_pk_fma_f32 v[10:11], v[48:49], v[64:65], v[10:11]
	ds_read_b128 v[64:67], v39 offset:56848
	s_waitcnt lgkmcnt(3)
; DI float sigmoidf_(float x) { return __builtin_amdgcn_rcpf(1.f + __expf(-x)); }
; DI void conv32(const bf16_t* __restrict__ Pcol, int tok, int spos, const float* wl, int wstride, float* acc) {
; #pragma unroll
;   for (int hq = 0; hq < 2; ++hq) {
;     __builtin_amdgcn_sched_barrier(0);
;     uint4 v[4][2];
; #pragma unroll
;     for (int j = 0; j < 4; ++j) {
;       const bool ok = (spos - 3 + j >= 0);
;       const uint4* src = (const uint4*)(Pcol + (size_t)(tok - 3 + (ok ? j : 3)) * 4096) + 2 * hq;
; #pragma unroll
;       for (int q = 0; q < 2; ++q) {
;         v[j][q] = src[q];
;         if (!ok) v[j][q] = make_uint4(0u, 0u, 0u, 0u);
;       }
;     }
; #pragma unroll
;     for (int i = 0; i < 16; ++i) acc[16 * hq + i] = 0.f;
; #pragma unroll
;     for (int j = 0; j < 4; ++j) {
;       const float4* w4 = (const float4*)(wl + j * wstride + 16 * hq);
; #pragma unroll
;       for (int q = 0; q < 2; ++q) {
;         float f[8];
;         unpack8(v[j][q], f);
;         float4 wa = w4[2 * q], wb = w4[2 * q + 1];
;         float* a = acc + 16 * hq + 8 * q;
;         a[0] += wa.x * f[0]; a[1] += wa.y * f[1]; a[2] += wa.z * f[2]; a[3] += wa.w * f[3];
;         a[4] += wb.x * f[4]; a[5] += wb.y * f[5]; a[6] += wb.z * f[6]; a[7] += wb.w * f[7];
;       }
;     }
; #pragma unroll
;     for (int i = 0; i < 16; ++i) acc[16 * hq + i] = acc[16 * hq + i] * sigmoidf_(acc[16 * hq + i]);
;   }
	v_pk_fma_f32 v[30:31], v[52:53], v[104:105], v[10:11]
	v_pk_fma_f32 v[10:11], v[12:13], v[68:69], 0 op_sel_hi:[1,1,0]
	v_cndmask_b32_e32 v97, 0, v7, vcc
	v_pk_fma_f32 v[10:11], v[28:29], v[76:77], v[10:11]
	v_lshlrev_b32_e32 v74, 16, v6
	v_pk_fma_f32 v[10:11], v[50:51], v[88:89], v[10:11]
	v_and_b32_e32 v75, 0xffff0000, v6
	v_pk_fma_f32 v[68:69], v[54:55], v[106:107], v[10:11]
	v_pk_fma_f32 v[10:11], v[14:15], v[70:71], 0 op_sel_hi:[1,1,0]
	v_lshlrev_b32_e32 v6, 16, v4
	s_waitcnt lgkmcnt(2)
	v_pk_fma_f32 v[10:11], v[56:57], v[78:79], v[10:11]
	v_and_b32_e32 v7, 0xffff0000, v4
	s_waitcnt lgkmcnt(1)
	v_pk_fma_f32 v[10:11], v[60:61], v[90:91], v[10:11]
	v_lshlrev_b32_e32 v4, 16, v5
	s_waitcnt lgkmcnt(0)
	v_pk_fma_f32 v[60:61], v[64:65], v[108:109], v[10:11]
	v_pk_fma_f32 v[10:11], v[16:17], v[72:73], 0 op_sel_hi:[1,1,0]
	v_and_b32_e32 v5, 0xffff0000, v5
	v_pk_fma_f32 v[10:11], v[58:59], v[80:81], v[10:11]
	v_pk_fma_f32 v[4:5], v[22:23], v[4:5], 0 op_sel_hi:[1,1,0]
	v_pk_fma_f32 v[10:11], v[62:63], v[92:93], v[10:11]
	v_pk_fma_f32 v[6:7], v[20:21], v[6:7], 0 op_sel_hi:[1,1,0]
	v_pk_fma_f32 v[62:63], v[66:67], v[110:111], v[10:11]
	ds_read_b128 v[10:13], v39 offset:53792
	ds_read_b128 v[14:17], v39 offset:55328
	ds_read_b128 v[26:29], v39 offset:56864
	ds_read_b128 v[48:51], v39 offset:53808
	ds_read_b128 v[52:55], v39 offset:55344
	ds_read_b128 v[56:59], v39 offset:56880
	v_lshlrev_b32_e32 v70, 16, v101
	v_and_b32_e32 v71, 0xffff0000, v101
	s_waitcnt lgkmcnt(2)
	v_pk_fma_f32 v[0:1], v[50:51], v[2:3], v[0:1]
	v_mul_f32_e32 v2, 0xbfb8aa3b, v30
	v_mul_f32_e32 v3, 0xbfb8aa3b, v31
	v_exp_f32_e32 v2, v2
	v_exp_f32_e32 v3, v3
	v_pk_fma_f32 v[4:5], v[48:49], v[86:87], v[4:5]
	v_pk_fma_f32 v[18:19], v[18:19], v[74:75], 0 op_sel_hi:[1,1,0]
	v_pk_fma_f32 v[6:7], v[12:13], v[84:85], v[6:7]
	s_waitcnt lgkmcnt(1)
	v_pk_fma_f32 v[4:5], v[52:53], v[102:103], v[4:5]
	v_lshlrev_b32_e32 v66, 16, v112
	v_and_b32_e32 v67, 0xffff0000, v112
	v_pk_fma_f32 v[10:11], v[10:11], v[82:83], v[18:19]
	v_pk_fma_f32 v[6:7], v[16:17], v[98:99], v[6:7]
	s_waitcnt lgkmcnt(0)
	v_pk_fma_f32 v[18:19], v[56:57], v[70:71], v[4:5]
	v_mul_f32_e32 v4, 0xbfb8aa3b, v68
	v_pk_fma_f32 v[16:17], v[28:29], v[66:67], v[6:7]
	v_add_f32_e32 v2, 1.0, v2
	v_add_f32_e32 v3, 1.0, v3
	v_exp_f32_e32 v6, v4
	v_mul_f32_e32 v4, 0xbfb8aa3b, v69
	v_rcp_f32_e32 v2, v2
	v_rcp_f32_e32 v3, v3
	v_exp_f32_e32 v7, v4
	v_pk_fma_f32 v[0:1], v[54:55], v[8:9], v[0:1]
	v_lshlrev_b32_e32 v64, 16, v113
	v_pk_mul_f32 v[4:5], v[30:31], v[2:3]
	v_add_f32_e32 v2, 1.0, v6
	v_add_f32_e32 v3, 1.0, v7
	v_mul_f32_e32 v6, 0xbfb8aa3b, v60
	v_rcp_f32_e32 v2, v2
	v_rcp_f32_e32 v3, v3
	v_exp_f32_e32 v8, v6
	v_mul_f32_e32 v6, 0xbfb8aa3b, v61
	v_exp_f32_e32 v9, v6
	v_and_b32_e32 v65, 0xffff0000, v113
	v_pk_fma_f32 v[10:11], v[14:15], v[94:95], v[10:11]
	v_pk_mul_f32 v[6:7], v[68:69], v[2:3]
	v_add_f32_e32 v2, 1.0, v8
	v_mul_f32_e32 v8, 0xbfb8aa3b, v62
	v_pk_fma_f32 v[14:15], v[26:27], v[64:65], v[10:11]
	v_add_f32_e32 v3, 1.0, v9
	v_exp_f32_e32 v10, v8
	v_mul_f32_e32 v8, 0xbfb8aa3b, v63
	v_rcp_f32_e32 v2, v2
	v_rcp_f32_e32 v3, v3
	v_exp_f32_e32 v11, v8
	v_mul_f32_e32 v21, 0xbfb8aa3b, v19
	v_exp_f32_e32 v23, v21
	v_pk_mul_f32 v[8:9], v[60:61], v[2:3]
	v_add_f32_e32 v2, 1.0, v10
	v_add_f32_e32 v3, 1.0, v11
	v_mul_f32_e32 v10, 0xbfb8aa3b, v14
	v_rcp_f32_e32 v2, v2
	v_rcp_f32_e32 v3, v3
	v_exp_f32_e32 v12, v10
	v_mul_f32_e32 v10, 0xbfb8aa3b, v15
	v_exp_f32_e32 v13, v10
	v_pk_mul_f32 v[10:11], v[62:63], v[2:3]
	v_add_f32_e32 v2, 1.0, v12
	v_mul_f32_e32 v12, 0xbfb8aa3b, v16
	v_add_f32_e32 v3, 1.0, v13
	v_exp_f32_e32 v12, v12
	v_mul_f32_e32 v13, 0xbfb8aa3b, v17
	v_exp_f32_e32 v13, v13
	v_lshlrev_b32_e32 v72, 16, v97
	v_add_f32_e32 v12, 1.0, v12
	v_rcp_f32_e32 v20, v12
	v_add_f32_e32 v12, 1.0, v13
	v_mul_f32_e32 v13, 0xbfb8aa3b, v18
	v_exp_f32_e32 v13, v13
	v_and_b32_e32 v73, 0xffff0000, v97
	v_pk_fma_f32 v[0:1], v[58:59], v[72:73], v[0:1]
	v_rcp_f32_e32 v21, v12
	v_add_f32_e32 v12, 1.0, v13
	v_mul_f32_e32 v13, 0xbfb8aa3b, v0
	v_rcp_f32_e32 v22, v12
	v_add_f32_e32 v12, 1.0, v23
	v_exp_f32_e32 v13, v13
	v_mul_f32_e32 v23, 0xbfb8aa3b, v1
	v_exp_f32_e32 v25, v23
	v_rcp_f32_e32 v23, v12
	v_add_f32_e32 v12, 1.0, v13
	v_rcp_f32_e32 v24, v12
	v_add_f32_e32 v12, 1.0, v25
	v_rcp_f32_e32 v2, v2
	v_rcp_f32_e32 v3, v3
	v_rcp_f32_e32 v25, v12
	v_pk_mul_f32 v[12:13], v[14:15], v[2:3]
	v_pk_mul_f32 v[14:15], v[16:17], v[20:21]
	v_pk_mul_f32 v[16:17], v[18:19], v[22:23]
	v_pk_mul_f32 v[18:19], v[0:1], v[24:25]
	global_load_dwordx4 v[0:3], v[46:47], off offset:32
	global_load_dwordx4 v[20:23], v[46:47], off offset:48
	global_load_dwordx4 v[24:27], v[44:45], off offset:32
	global_load_dwordx4 v[28:31], v[44:45], off offset:48
	global_load_dwordx4 v[48:51], v[42:43], off offset:32
	global_load_dwordx4 v[52:55], v[42:43], off offset:48
	global_load_dwordx4 v[56:59], v[40:41], off offset:32
	global_load_dwordx4 v[60:63], v[40:41], off offset:48
	v_add_u32_e32 v142, 64, v133
	v_xor_b32_e32 v97, 2, v132
	s_waitcnt vmcnt(7)
	v_cndmask_b32_e64 v3, 0, v3, s[10:11]
	v_cndmask_b32_e64 v2, 0, v2, s[10:11]
	v_cndmask_b32_e64 v1, 0, v1, s[10:11]
	v_cndmask_b32_e64 v0, 0, v0, s[10:11]
	s_waitcnt vmcnt(6)
	v_cndmask_b32_e64 v22, 0, v22, s[10:11]
	v_cndmask_b32_e64 v64, 0, v21, s[10:11]
	s_waitcnt vmcnt(1)
	v_cndmask_b32_e32 v59, 0, v59, vcc
	v_cndmask_b32_e32 v58, 0, v58, vcc
	v_cndmask_b32_e32 v65, 0, v57, vcc
	v_cndmask_b32_e32 v66, 0, v56, vcc
	s_waitcnt vmcnt(0)
; DI float sigmoidf_(float x) { return __builtin_amdgcn_rcpf(1.f + __expf(-x)); }
; DI void conv32(const bf16_t* __restrict__ Pcol, int tok, int spos, const float* wl, int wstride, float* acc) {
;     ...
;   for (int hq = 0; hq < 2; ++hq) {
;     __builtin_amdgcn_sched_barrier(0);
;     uint4 v[4][2];
; #pragma unroll
;     for (int j = 0; j < 4; ++j) {
;       const bool ok = (spos - 3 + j >= 0);
;       const uint4* src = (const uint4*)(Pcol + (size_t)(tok - 3 + (ok ? j : 3)) * 4096) + 2 * hq;
; #pragma unroll
;       for (int q = 0; q < 2; ++q) {
;         v[j][q] = src[q];
;         if (!ok) v[j][q] = make_uint4(0u, 0u, 0u, 0u);
;       }
;     }
; #pragma unroll
;     for (int i = 0; i < 16; ++i) acc[16 * hq + i] = 0.f;
; #pragma unroll
;     for (int j = 0; j < 4; ++j) {
;       const float4* w4 = (const float4*)(wl + j * wstride + 16 * hq);
; #pragma unroll
;       for (int q = 0; q < 2; ++q) {
;         float f[8];
;         unpack8(v[j][q], f);
;         float4 wa = w4[2 * q], wb = w4[2 * q + 1];
;         float* a = acc + 16 * hq + 8 * q;
;         a[0] += wa.x * f[0]; a[1] += wa.y * f[1]; a[2] += wa.z * f[2]; a[3] += wa.w * f[3];
;         a[4] += wb.x * f[4]; a[5] += wb.y * f[5]; a[6] += wb.z * f[6]; a[7] += wb.w * f[7];
;       }
;     }
; #pragma unroll
;     for (int i = 0; i < 16; ++i) acc[16 * hq + i] = acc[16 * hq + i] * sigmoidf_(acc[16 * hq + i]);
;   }
	v_cndmask_b32_e32 v63, 0, v63, vcc
	v_cndmask_b32_e32 v62, 0, v62, vcc
	v_cndmask_b32_e32 v61, 0, v61, vcc
	v_cndmask_b32_e32 v60, 0, v60, vcc
	v_cndmask_b32_e64 v30, 0, v30, s[6:7]
	v_lshlrev_b32_e32 v94, 16, v0
	v_and_b32_e32 v95, 0xffff0000, v0
	v_lshlrev_b32_e32 v74, 16, v1
	v_and_b32_e32 v75, 0xffff0000, v1
	v_lshlrev_b32_e32 v98, 16, v2
	v_and_b32_e32 v99, 0xffff0000, v2
	v_lshlrev_b32_e32 v106, 16, v3
	v_and_b32_e32 v107, 0xffff0000, v3
	v_lshlrev_b32_e32 v76, 16, v64
	v_and_b32_e32 v77, 0xffff0000, v64
	v_lshlrev_b32_e32 v80, 16, v22
	v_and_b32_e32 v81, 0xffff0000, v22
	v_lshlrev_b32_e32 v124, 16, v66
	v_and_b32_e32 v125, 0xffff0000, v66
	v_lshlrev_b32_e32 v126, 16, v65
	v_and_b32_e32 v127, 0xffff0000, v65
	v_lshlrev_b32_e32 v128, 16, v58
	v_and_b32_e32 v129, 0xffff0000, v58
	v_lshlrev_b32_e32 v144, 16, v59
	v_and_b32_e32 v145, 0xffff0000, v59
	v_lshlrev_b32_e32 v58, 16, v60
	v_and_b32_e32 v59, 0xffff0000, v60
	v_lshlrev_b32_e32 v64, 16, v61
	v_and_b32_e32 v65, 0xffff0000, v61
	v_lshlrev_b32_e32 v130, 16, v62
	v_and_b32_e32 v131, 0xffff0000, v62
	v_lshlrev_b32_e32 v146, 16, v63
	v_and_b32_e32 v147, 0xffff0000, v63
	ds_read_b128 v[0:3], v39 offset:52336
	ds_read_b128 v[60:63], v39 offset:53872
	ds_read_b128 v[66:69], v39 offset:55408
	ds_read_b128 v[70:73], v39 offset:56944
	ds_read_b128 v[86:89], v39 offset:52288
	v_cndmask_b32_e64 v54, 0, v54, s[8:9]
	v_lshlrev_b32_e32 v82, 16, v30
	v_and_b32_e32 v83, 0xffff0000, v30
	s_waitcnt lgkmcnt(4)
	v_pk_fma_f32 v[0:1], v[0:1], v[80:81], 0 op_sel_hi:[1,1,0]
	v_lshlrev_b32_e32 v102, 16, v54
	v_and_b32_e32 v103, 0xffff0000, v54
	s_waitcnt lgkmcnt(3)
	v_pk_fma_f32 v[0:1], v[60:61], v[82:83], v[0:1]
	v_cndmask_b32_e64 v23, 0, v23, s[10:11]
	s_waitcnt lgkmcnt(2)
	v_pk_fma_f32 v[0:1], v[66:67], v[102:103], v[0:1]
	v_cndmask_b32_e64 v31, 0, v31, s[6:7]
	s_waitcnt lgkmcnt(1)
	v_pk_fma_f32 v[60:61], v[70:71], v[130:131], v[0:1]
	v_lshlrev_b32_e32 v90, 16, v23
	v_mul_f32_e32 v0, 0xbfb8aa3b, v60
	v_exp_f32_e32 v0, v0
	v_mul_f32_e32 v1, 0xbfb8aa3b, v61
	v_exp_f32_e32 v1, v1
	v_and_b32_e32 v91, 0xffff0000, v23
	v_add_f32_e32 v0, 1.0, v0
	v_cndmask_b32_e64 v55, 0, v55, s[8:9]
	v_lshlrev_b32_e32 v92, 16, v31
	v_and_b32_e32 v93, 0xffff0000, v31
	v_rcp_f32_e32 v66, v0
	v_add_f32_e32 v67, 1.0, v1
	v_pk_fma_f32 v[0:1], v[2:3], v[90:91], 0 op_sel_hi:[1,1,0]
	v_lshlrev_b32_e32 v104, 16, v55
	v_and_b32_e32 v105, 0xffff0000, v55
	v_pk_fma_f32 v[0:1], v[62:63], v[92:93], v[0:1]
	ds_read_b128 v[80:83], v39 offset:52304
	v_pk_fma_f32 v[0:1], v[68:69], v[104:105], v[0:1]
	v_xor_b32_e32 v70, 1, v132
	v_pk_fma_f32 v[62:63], v[72:73], v[146:147], v[0:1]
	v_cmp_lt_i32_e64 s[12:13], v70, v142
	v_mul_f32_e32 v0, 0xbfb8aa3b, v62
	v_exp_f32_e32 v0, v0
	v_mul_f32_e32 v1, 0xbfb8aa3b, v63
	v_exp_f32_e32 v1, v1
	v_cndmask_b32_e64 v70, v132, v70, s[12:13]
	v_add_f32_e32 v0, 1.0, v0
	v_rcp_f32_e32 v68, v0
	v_add_f32_e32 v0, 1.0, v1
	v_rcp_f32_e32 v69, v0
	ds_read_b128 v[0:3], v39 offset:52320
	v_lshlrev_b32_e32 v130, 2, v70
	ds_read_b128 v[70:73], v39 offset:53840
	ds_read_b128 v[90:93], v39 offset:55376
	ds_read_b128 v[102:105], v39 offset:56912
	v_cndmask_b32_e64 v27, 0, v27, s[6:7]
	v_cndmask_b32_e64 v51, 0, v51, s[8:9]
	v_lshlrev_b32_e32 v114, 16, v27
	v_and_b32_e32 v115, 0xffff0000, v27
	s_waitcnt lgkmcnt(4)
	v_pk_fma_f32 v[82:83], v[82:83], v[106:107], 0 op_sel_hi:[1,1,0]
	v_lshlrev_b32_e32 v122, 16, v51
	v_and_b32_e32 v123, 0xffff0000, v51
	s_waitcnt lgkmcnt(2)
	v_pk_fma_f32 v[72:73], v[72:73], v[114:115], v[82:83]
	v_cndmask_b32_e64 v26, 0, v26, s[6:7]
	s_waitcnt lgkmcnt(1)
	v_pk_fma_f32 v[72:73], v[92:93], v[122:123], v[72:73]
	v_cndmask_b32_e64 v50, 0, v50, s[8:9]
	s_waitcnt lgkmcnt(0)
	v_pk_fma_f32 v[72:73], v[104:105], v[144:145], v[72:73]
	v_lshlrev_b32_e32 v108, 16, v26
	v_mul_f32_e32 v82, 0xbfb8aa3b, v72
	v_mul_f32_e32 v83, 0xbfb8aa3b, v73
	v_and_b32_e32 v109, 0xffff0000, v26
	v_exp_f32_e32 v82, v82
	v_exp_f32_e32 v83, v83
	v_pk_fma_f32 v[80:81], v[80:81], v[98:99], 0 op_sel_hi:[1,1,0]
	v_lshlrev_b32_e32 v120, 16, v50
	v_and_b32_e32 v121, 0xffff0000, v50
	v_pk_fma_f32 v[70:71], v[70:71], v[108:109], v[80:81]
	v_cndmask_b32_e64 v25, 0, v25, s[6:7]
	v_pk_fma_f32 v[70:71], v[90:91], v[120:121], v[70:71]
	v_add_f32_e32 v82, 1.0, v82
	v_pk_fma_f32 v[98:99], v[102:103], v[128:129], v[70:71]
	ds_read_b128 v[90:93], v39 offset:53824
	ds_read_b128 v[102:105], v39 offset:55360
	ds_read_b128 v[106:109], v39 offset:56896
	v_add_f32_e32 v83, 1.0, v83
	v_mul_f32_e32 v70, 0xbfb8aa3b, v98
	v_cndmask_b32_e64 v49, 0, v49, s[8:9]
	v_lshlrev_b32_e32 v112, 16, v25
	v_and_b32_e32 v113, 0xffff0000, v25
	v_rcp_f32_e32 v82, v82
	v_rcp_f32_e32 v83, v83
	v_exp_f32_e32 v80, v70
	v_pk_fma_f32 v[74:75], v[88:89], v[74:75], 0 op_sel_hi:[1,1,0]
	v_lshlrev_b32_e32 v118, 16, v49
	v_and_b32_e32 v119, 0xffff0000, v49
	s_waitcnt lgkmcnt(2)
	v_pk_fma_f32 v[74:75], v[92:93], v[112:113], v[74:75]
	v_cmp_lt_i32_e64 s[12:13], v97, v142
	s_waitcnt lgkmcnt(1)
	v_pk_fma_f32 v[74:75], v[104:105], v[118:119], v[74:75]
	v_cndmask_b32_e64 v24, 0, v24, s[6:7]
	v_cndmask_b32_e64 v70, v132, v97, s[12:13]
	s_waitcnt lgkmcnt(0)
; DI float sigmoidf_(float x) { return __builtin_amdgcn_rcpf(1.f + __expf(-x)); }
; DI void conv32(const bf16_t* __restrict__ Pcol, int tok, int spos, const float* wl, int wstride, float* acc) {
;     ...
;     for (int i = 0; i < 16; ++i) acc[16 * hq + i] = acc[16 * hq + i] * sigmoidf_(acc[16 * hq + i]);
;   }
; DI void gdn_pre(const Params& p, int ch, char* smem) {
;     ...
;     float ss = 0.f;
; #pragma unroll
;     for (int i = 0; i < 32; ++i) ss += a[i] * a[i];
;     ss += __shfl_xor(ss, 1);
;     ss += __shfl_xor(ss, 2);
	v_pk_fma_f32 v[74:75], v[108:109], v[126:127], v[74:75]
	v_lshlrev_b32_e32 v131, 2, v70
	v_pk_mul_f32 v[70:71], v[72:73], v[82:83]
	v_add_f32_e32 v72, 1.0, v80
	v_mul_f32_e32 v80, 0xbfb8aa3b, v74
	v_exp_f32_e32 v80, v80
	v_mul_f32_e32 v81, 0xbfb8aa3b, v75
	v_exp_f32_e32 v81, v81
	v_cndmask_b32_e64 v48, 0, v48, s[8:9]
	v_add_f32_e32 v80, 1.0, v80
	v_rcp_f32_e32 v88, v80
	v_add_f32_e32 v80, 1.0, v81
	v_rcp_f32_e32 v89, v80
	v_lshlrev_b32_e32 v110, 16, v24
	v_and_b32_e32 v111, 0xffff0000, v24
	v_pk_fma_f32 v[86:87], v[86:87], v[94:95], 0 op_sel_hi:[1,1,0]
	v_lshlrev_b32_e32 v116, 16, v48
	v_and_b32_e32 v117, 0xffff0000, v48
	v_pk_fma_f32 v[86:87], v[90:91], v[110:111], v[86:87]
	v_pk_mul_f32 v[74:75], v[74:75], v[88:89]
	v_pk_fma_f32 v[86:87], v[102:103], v[116:117], v[86:87]
	v_cndmask_b32_e64 v21, 0, v20, s[10:11]
	v_pk_fma_f32 v[88:89], v[106:107], v[124:125], v[86:87]
	ds_read_b128 v[92:95], v39 offset:53856
	ds_read_b128 v[102:105], v39 offset:55392
	ds_read_b128 v[106:109], v39 offset:56928
	v_cndmask_b32_e64 v29, 0, v29, s[6:7]
	v_cndmask_b32_e64 v28, 0, v28, s[6:7]
	v_cndmask_b32_e64 v53, 0, v53, s[8:9]
	v_lshlrev_b32_e32 v20, 16, v21
	v_and_b32_e32 v21, 0xffff0000, v21
	v_lshlrev_b32_e32 v78, 16, v29
	v_and_b32_e32 v79, 0xffff0000, v29
	v_pk_fma_f32 v[2:3], v[2:3], v[76:77], 0 op_sel_hi:[1,1,0]
	v_cndmask_b32_e64 v52, 0, v52, s[8:9]
	v_lshlrev_b32_e32 v26, 16, v28
	v_and_b32_e32 v27, 0xffff0000, v28
	v_lshlrev_b32_e32 v84, 16, v53
	v_and_b32_e32 v85, 0xffff0000, v53
	s_waitcnt lgkmcnt(2)
	v_pk_fma_f32 v[2:3], v[94:95], v[78:79], v[2:3]
	v_pk_fma_f32 v[0:1], v[0:1], v[20:21], 0 op_sel_hi:[1,1,0]
	v_lshlrev_b32_e32 v56, 16, v52
	v_and_b32_e32 v57, 0xffff0000, v52
	s_waitcnt lgkmcnt(1)
	v_pk_fma_f32 v[2:3], v[104:105], v[84:85], v[2:3]
	v_pk_fma_f32 v[0:1], v[92:93], v[26:27], v[0:1]
	s_waitcnt lgkmcnt(0)
	v_pk_fma_f32 v[2:3], v[108:109], v[64:65], v[2:3]
	v_pk_fma_f32 v[0:1], v[102:103], v[56:57], v[0:1]
	v_mul_f32_e32 v86, 0xbfb8aa3b, v88
	v_mul_f32_e32 v64, 0xbfb8aa3b, v2
	v_pk_fma_f32 v[0:1], v[106:107], v[58:59], v[0:1]
	v_mul_f32_e32 v73, 0xbfb8aa3b, v99
	v_exp_f32_e32 v90, v86
	v_mul_f32_e32 v86, 0xbfb8aa3b, v89
	v_exp_f32_e32 v76, v64
	v_mul_f32_e32 v64, 0xbfb8aa3b, v3
	v_mul_f32_e32 v20, 0xbfb8aa3b, v0
	v_mul_f32_e32 v21, 0xbfb8aa3b, v1
	v_exp_f32_e32 v73, v73
	v_exp_f32_e32 v91, v86
	v_exp_f32_e32 v77, v64
	v_exp_f32_e32 v20, v20
	v_exp_f32_e32 v21, v21
	v_add_f32_e32 v73, 1.0, v73
	v_add_f32_e32 v90, 1.0, v90
	v_add_f32_e32 v91, 1.0, v91
	v_add_f32_e32 v76, 1.0, v76
	v_add_f32_e32 v77, 1.0, v77
	v_add_f32_e32 v20, 1.0, v20
	v_add_f32_e32 v21, 1.0, v21
	v_rcp_f32_e32 v67, v67
	v_rcp_f32_e32 v72, v72
	v_rcp_f32_e32 v73, v73
	v_rcp_f32_e32 v90, v90
	v_rcp_f32_e32 v91, v91
	v_rcp_f32_e32 v76, v76
	v_rcp_f32_e32 v77, v77
	v_rcp_f32_e32 v20, v20
	v_rcp_f32_e32 v21, v21
	v_pk_mul_f32 v[60:61], v[60:61], v[66:67]
	v_pk_mul_f32 v[62:63], v[62:63], v[68:69]
	v_pk_mul_f32 v[72:73], v[98:99], v[72:73]
	v_pk_mul_f32 v[64:65], v[88:89], v[90:91]
	v_pk_mul_f32 v[2:3], v[2:3], v[76:77]
	v_pk_mul_f32 v[0:1], v[0:1], v[20:21]
	v_pk_mul_f32 v[54:55], v[4:5], v[4:5]
	v_pk_mul_f32 v[52:53], v[6:7], v[6:7]
	v_pk_mul_f32 v[50:51], v[8:9], v[8:9]
	v_pk_mul_f32 v[48:49], v[10:11], v[10:11]
	v_pk_mul_f32 v[30:31], v[12:13], v[12:13]
	v_pk_mul_f32 v[28:29], v[14:15], v[14:15]
	v_pk_mul_f32 v[24:25], v[16:17], v[16:17]
	v_pk_mul_f32 v[22:23], v[18:19], v[18:19]
	v_pk_mul_f32 v[66:67], v[60:61], v[60:61]
	v_pk_mul_f32 v[68:69], v[62:63], v[62:63]
	v_pk_mul_f32 v[80:81], v[70:71], v[70:71]
	v_pk_mul_f32 v[82:83], v[72:73], v[72:73]
	v_pk_mul_f32 v[86:87], v[74:75], v[74:75]
	v_pk_mul_f32 v[26:27], v[64:65], v[64:65]
	v_pk_mul_f32 v[56:57], v[2:3], v[2:3]
	v_pk_mul_f32 v[20:21], v[0:1], v[0:1]
	v_add_f32_e32 v54, v54, v55
	v_add_f32_e32 v52, v54, v52
	v_add_f32_e32 v52, v52, v53
	v_add_f32_e32 v50, v52, v50
	v_add_f32_e32 v50, v50, v51
	v_add_f32_e32 v48, v50, v48
	v_add_f32_e32 v48, v48, v49
	v_add_f32_e32 v30, v48, v30
	v_add_f32_e32 v30, v30, v31
	v_add_f32_e32 v28, v30, v28
	v_add_f32_e32 v28, v28, v29
	v_add_f32_e32 v24, v28, v24
	v_add_f32_e32 v24, v24, v25
	v_add_f32_e32 v22, v24, v22
	v_add_f32_e32 v22, v22, v23
	v_add_f32_e32 v22, v22, v26
	v_add_f32_e32 v22, v22, v27
	v_add_f32_e32 v22, v22, v86
	v_add_f32_e32 v22, v22, v87
	v_add_f32_e32 v22, v22, v82
	v_add_f32_e32 v22, v22, v83
	v_add_f32_e32 v22, v22, v80
	v_add_f32_e32 v22, v22, v81
	v_add_f32_e32 v20, v22, v20
	v_add_f32_e32 v20, v20, v21
	v_add_f32_e32 v20, v20, v56
	v_add_f32_e32 v20, v20, v57
	v_add_f32_e32 v20, v20, v66
	v_add_f32_e32 v20, v20, v67
	v_add_f32_e32 v20, v20, v68
	v_add_f32_e32 v20, v20, v69
	ds_bpermute_b32 v21, v130, v20
	s_waitcnt lgkmcnt(0)
	v_add_f32_e32 v20, v20, v21
	ds_bpermute_b32 v21, v131, v20
	s_waitcnt lgkmcnt(0)
; DI int fragoff(int row, int k, int KS) { return (((row >> 4) * KS + (k >> 5)) << 9) + (((((k >> 3) & 3) << 4) + (row & 15)) << 3) + (k & 7); }
; DI void gdn_pre(const Params& p, int ch, char* smem) {
;     ...
;     float rn = rsqrtf(ss + 1e-6f) * 0.08838834764831845f;
; #pragma unroll
;     for (int i = 0; i < 32; ++i) a[i] *= rn;
; #pragma unroll
;     for (int q = 0; q < 4; ++q) *(uint4*)(qh + t * 136 + part * 32 + 8 * q) = pack8(a + 8 * q);
; #pragma unroll
;     for (int i = 0; i < 32; ++i) a[i] *= egt;
; #pragma unroll
;     for (int q = 0; q < 4; ++q) *(uint4*)(o_qd + fragoff(t, part * 32 + 8 * q, 4)) = pack8(a + 8 * q);
;   }
;   {
;     conv32(P + 512 + h * 128 + part * 32, tok0 + t, c * 64 + t, s_w + 128 + part * 32, 384, kk);
	v_add_f32_e32 v20, v20, v21
	v_add_f32_e32 v20, 0x358637bd, v20
	v_mul_f32_e32 v21, 0x4b800000, v20
	v_cmp_gt_f32_e64 s[12:13], s67, v20
	s_nop 1
	v_cndmask_b32_e64 v20, v20, v21, s[12:13]
	v_rsq_f32_e32 v20, v20
	s_nop 0
	v_mul_f32_e32 v21, 0x45800000, v20
	v_cndmask_b32_e64 v20, v20, v21, s[12:13]
	v_mul_f32_e32 v20, 0x3db504f3, v20
	v_pk_mul_f32 v[22:23], v[4:5], v[20:21] op_sel_hi:[1,0]
	v_pk_mul_f32 v[6:7], v[6:7], v[20:21] op_sel_hi:[1,0]
	v_pk_mul_f32 v[8:9], v[8:9], v[20:21] op_sel_hi:[1,0]
	v_pk_mul_f32 v[10:11], v[10:11], v[20:21] op_sel_hi:[1,0]
	v_pk_mul_f32 v[12:13], v[12:13], v[20:21] op_sel_hi:[1,0]
	v_pk_mul_f32 v[14:15], v[14:15], v[20:21] op_sel_hi:[1,0]
	v_pk_mul_f32 v[16:17], v[16:17], v[20:21] op_sel_hi:[1,0]
	v_pk_mul_f32 v[18:19], v[18:19], v[20:21] op_sel_hi:[1,0]
	v_pk_mul_f32 v[48:49], v[0:1], v[20:21] op_sel_hi:[1,0]
	v_pk_mul_f32 v[50:51], v[2:3], v[20:21] op_sel_hi:[1,0]
	v_mad_u64_u32 v[4:5], s[0:1], v35, s70, v[32:33]
	v_cvt_pk_bf16_f32 v0, v22, v23
	v_cvt_pk_bf16_f32 v1, v6, v7
	v_cvt_pk_bf16_f32 v2, v8, v9
	v_cvt_pk_bf16_f32 v3, v10, v11
	v_pk_mul_f32 v[24:25], v[64:65], v[20:21] op_sel_hi:[1,0]
	v_pk_mul_f32 v[26:27], v[74:75], v[20:21] op_sel_hi:[1,0]
	v_pk_mul_f32 v[28:29], v[72:73], v[20:21] op_sel_hi:[1,0]
	v_pk_mul_f32 v[30:31], v[70:71], v[20:21] op_sel_hi:[1,0]
	ds_write_b128 v4, v[0:3]
	v_cvt_pk_bf16_f32 v0, v12, v13
	v_cvt_pk_bf16_f32 v1, v14, v15
	v_cvt_pk_bf16_f32 v2, v16, v17
	v_cvt_pk_bf16_f32 v3, v18, v19
	v_lshrrev_b32_e32 v5, 2, v35
	v_and_b32_e32 v32, 3, v34
	v_pk_mul_f32 v[52:53], v[60:61], v[20:21] op_sel_hi:[1,0]
	v_pk_mul_f32 v[20:21], v[62:63], v[20:21] op_sel_hi:[1,0]
	ds_write_b128 v4, v[0:3] offset:16
	v_cvt_pk_bf16_f32 v0, v24, v25
	v_cvt_pk_bf16_f32 v1, v26, v27
	v_cvt_pk_bf16_f32 v2, v28, v29
	v_cvt_pk_bf16_f32 v3, v30, v31
	v_and_or_b32 v5, v5, s71, v32
	v_lshlrev_b32_e32 v32, 3, v35
	ds_write_b128 v4, v[0:3] offset:32
	v_cvt_pk_bf16_f32 v0, v48, v49
	v_cvt_pk_bf16_f32 v1, v50, v51
	v_cvt_pk_bf16_f32 v2, v52, v53
	v_cvt_pk_bf16_f32 v3, v20, v21
	v_and_b32_e32 v32, 0x78, v32
	ds_write_b128 v4, v[0:3] offset:48
	v_pk_mul_f32 v[0:1], v[38:39], v[22:23] op_sel_hi:[0,1]
	v_pk_mul_f32 v[22:23], v[38:39], v[26:27] op_sel_hi:[0,1]
	v_pk_mul_f32 v[26:27], v[38:39], v[30:31] op_sel_hi:[0,1]
	v_pk_mul_f32 v[30:31], v[38:39], v[50:51] op_sel_hi:[0,1]
	v_lshl_or_b32 v50, v5, 9, v32
	v_pk_mul_f32 v[2:3], v[38:39], v[6:7] op_sel_hi:[0,1]
	v_pk_mul_f32 v[6:7], v[38:39], v[8:9] op_sel_hi:[0,1]
	v_ashrrev_i32_e32 v51, 31, v50
	v_pk_mul_f32 v[8:9], v[38:39], v[10:11] op_sel_hi:[0,1]
	v_cvt_pk_bf16_f32 v0, v0, v1
	v_cvt_pk_bf16_f32 v1, v2, v3
	v_cvt_pk_bf16_f32 v2, v6, v7
	v_lshl_add_u64 v[6:7], v[50:51], 1, s[34:35]
	s_mov_b64 s[0:1], 0x4000
	v_cvt_pk_bf16_f32 v3, v8, v9
	v_lshl_add_u64 v[8:9], v[6:7], 0, s[0:1]
	v_add_co_u32_e64 v6, s[12:13], s72, v6
	v_pk_mul_f32 v[10:11], v[38:39], v[12:13] op_sel_hi:[0,1]
	v_pk_mul_f32 v[12:13], v[38:39], v[14:15] op_sel_hi:[0,1]
	v_pk_mul_f32 v[14:15], v[38:39], v[16:17] op_sel_hi:[0,1]
	v_pk_mul_f32 v[16:17], v[38:39], v[18:19] op_sel_hi:[0,1]
	v_addc_co_u32_e64 v7, s[12:13], 0, v7, s[12:13]
	v_pk_mul_f32 v[18:19], v[38:39], v[24:25] op_sel_hi:[0,1]
	v_pk_mul_f32 v[24:25], v[38:39], v[28:29] op_sel_hi:[0,1]
	global_store_dwordx4 v[6:7], v[0:3], off
	v_pk_mul_f32 v[28:29], v[38:39], v[48:49] op_sel_hi:[0,1]
	v_pk_mul_f32 v[48:49], v[38:39], v[52:53] op_sel_hi:[0,1]
	v_cvt_pk_bf16_f32 v0, v10, v11
	v_cvt_pk_bf16_f32 v1, v12, v13
	v_cvt_pk_bf16_f32 v2, v14, v15
	v_cvt_pk_bf16_f32 v3, v16, v17
	v_pk_mul_f32 v[20:21], v[38:39], v[20:21] op_sel_hi:[0,1]
	global_store_dwordx4 v[8:9], v[0:3], off offset:256
	s_nop 1
	v_cvt_pk_bf16_f32 v0, v18, v19
	v_cvt_pk_bf16_f32 v1, v22, v23
	v_cvt_pk_bf16_f32 v2, v24, v25
	v_cvt_pk_bf16_f32 v3, v26, v27
	global_store_dwordx4 v[8:9], v[0:3], off offset:512
	s_nop 1
	v_cvt_pk_bf16_f32 v0, v28, v29
	v_cvt_pk_bf16_f32 v1, v30, v31
	v_cvt_pk_bf16_f32 v2, v48, v49
	v_cvt_pk_bf16_f32 v3, v20, v21
	global_store_dwordx4 v[8:9], v[0:3], off offset:768
	global_load_dwordx4 v[0:3], v[46:47], off offset:1024
	s_nop 0
	global_load_dwordx4 v[6:9], v[46:47], off offset:1040
	global_load_dwordx4 v[10:13], v[44:45], off offset:1024
	global_load_dwordx4 v[14:17], v[44:45], off offset:1040
	global_load_dwordx4 v[18:21], v[42:43], off offset:1024
	global_load_dwordx4 v[22:25], v[42:43], off offset:1040
	global_load_dwordx4 v[26:29], v[40:41], off offset:1024
	global_load_dwordx4 v[48:51], v[40:41], off offset:1040
	s_waitcnt vmcnt(7)
	v_cndmask_b32_e64 v3, 0, v3, s[10:11]
	v_cndmask_b32_e64 v2, 0, v2, s[10:11]
	s_waitcnt vmcnt(6)
	v_cndmask_b32_e64 v30, 0, v8, s[10:11]
	v_cndmask_b32_e64 v7, 0, v7, s[10:11]
	v_cndmask_b32_e64 v6, 0, v6, s[10:11]
	s_waitcnt vmcnt(5)
	v_cndmask_b32_e64 v13, 0, v13, s[6:7]
	v_cndmask_b32_e64 v12, 0, v12, s[6:7]
	v_cndmask_b32_e64 v11, 0, v11, s[6:7]
	v_cndmask_b32_e64 v10, 0, v10, s[6:7]
	s_waitcnt vmcnt(4)
	v_cndmask_b32_e64 v17, 0, v17, s[6:7]
	v_cndmask_b32_e64 v16, 0, v16, s[6:7]
	v_cndmask_b32_e64 v15, 0, v15, s[6:7]
	v_cndmask_b32_e64 v14, 0, v14, s[6:7]
	s_waitcnt vmcnt(3)
	v_cndmask_b32_e64 v21, 0, v21, s[8:9]
	v_cndmask_b32_e64 v20, 0, v20, s[8:9]
	v_cndmask_b32_e64 v19, 0, v19, s[8:9]
	v_cndmask_b32_e64 v18, 0, v18, s[8:9]
	s_waitcnt vmcnt(2)
	v_cndmask_b32_e64 v25, 0, v25, s[8:9]
	v_cndmask_b32_e64 v24, 0, v24, s[8:9]
	v_cndmask_b32_e64 v23, 0, v23, s[8:9]
	v_cndmask_b32_e64 v22, 0, v22, s[8:9]
	s_waitcnt vmcnt(1)
; DI void conv32(const bf16_t* __restrict__ Pcol, int tok, int spos, const float* wl, int wstride, float* acc) {
;     ...
;   for (int hq = 0; hq < 2; ++hq) {
;     __builtin_amdgcn_sched_barrier(0);
;     uint4 v[4][2];
; #pragma unroll
;     for (int j = 0; j < 4; ++j) {
;       const bool ok = (spos - 3 + j >= 0);
;       const uint4* src = (const uint4*)(Pcol + (size_t)(tok - 3 + (ok ? j : 3)) * 4096) + 2 * hq;
; #pragma unroll
;       for (int q = 0; q < 2; ++q) {
;         v[j][q] = src[q];
;         if (!ok) v[j][q] = make_uint4(0u, 0u, 0u, 0u);
;       }
;     }
; #pragma unroll
;     for (int i = 0; i < 16; ++i) acc[16 * hq + i] = 0.f;
; #pragma unroll
;     for (int j = 0; j < 4; ++j) {
;       const float4* w4 = (const float4*)(wl + j * wstride + 16 * hq);
; #pragma unroll
;       for (int q = 0; q < 2; ++q) {
;         float f[8];
;         unpack8(v[j][q], f);
;         float4 wa = w4[2 * q], wb = w4[2 * q + 1];
;         float* a = acc + 16 * hq + 8 * q;
;         a[0] += wa.x * f[0]; a[1] += wa.y * f[1]; a[2] += wa.z * f[2]; a[3] += wa.w * f[3];
;         a[4] += wb.x * f[4]; a[5] += wb.y * f[5]; a[6] += wb.z * f[6]; a[7] += wb.w * f[7];
;       }
	v_cndmask_b32_e32 v29, 0, v29, vcc
	v_cndmask_b32_e32 v28, 0, v28, vcc
	v_cndmask_b32_e32 v27, 0, v27, vcc
	v_cndmask_b32_e32 v26, 0, v26, vcc
	v_cndmask_b32_e64 v5, 0, v9, s[10:11]
	v_lshlrev_b32_e32 v70, 16, v2
	v_and_b32_e32 v71, 0xffff0000, v2
	v_lshlrev_b32_e32 v72, 16, v3
	v_and_b32_e32 v73, 0xffff0000, v3
	v_lshlrev_b32_e32 v74, 16, v6
	v_and_b32_e32 v75, 0xffff0000, v6
	v_lshlrev_b32_e32 v8, 16, v7
	v_and_b32_e32 v9, 0xffff0000, v7
	v_lshlrev_b32_e32 v6, 16, v30
	v_and_b32_e32 v7, 0xffff0000, v30
	v_lshlrev_b32_e32 v60, 16, v10
	v_and_b32_e32 v61, 0xffff0000, v10
	v_lshlrev_b32_e32 v76, 16, v11
	v_and_b32_e32 v77, 0xffff0000, v11
	v_lshlrev_b32_e32 v78, 16, v12
	v_and_b32_e32 v79, 0xffff0000, v12
	v_lshlrev_b32_e32 v80, 16, v13
	v_and_b32_e32 v81, 0xffff0000, v13
	v_lshlrev_b32_e32 v82, 16, v14
	v_and_b32_e32 v83, 0xffff0000, v14
	v_lshlrev_b32_e32 v84, 16, v15
	v_and_b32_e32 v85, 0xffff0000, v15
	v_lshlrev_b32_e32 v86, 16, v16
	v_and_b32_e32 v87, 0xffff0000, v16
	v_lshlrev_b32_e32 v2, 16, v17
	v_and_b32_e32 v3, 0xffff0000, v17
	v_lshlrev_b32_e32 v64, 16, v18
	v_and_b32_e32 v65, 0xffff0000, v18
	v_lshlrev_b32_e32 v88, 16, v19
	v_and_b32_e32 v89, 0xffff0000, v19
	v_lshlrev_b32_e32 v90, 16, v20
	v_and_b32_e32 v91, 0xffff0000, v20
	v_lshlrev_b32_e32 v92, 16, v21
	v_and_b32_e32 v93, 0xffff0000, v21
	v_lshlrev_b32_e32 v94, 16, v22
	v_and_b32_e32 v95, 0xffff0000, v22
	v_lshlrev_b32_e32 v98, 16, v23
	v_and_b32_e32 v99, 0xffff0000, v23
	v_lshlrev_b32_e32 v102, 16, v24
	v_and_b32_e32 v103, 0xffff0000, v24
	v_lshlrev_b32_e32 v10, 16, v25
	v_and_b32_e32 v11, 0xffff0000, v25
	v_lshlrev_b32_e32 v104, 16, v26
	v_and_b32_e32 v105, 0xffff0000, v26
	v_lshlrev_b32_e32 v106, 16, v27
	v_and_b32_e32 v107, 0xffff0000, v27
	v_lshlrev_b32_e32 v108, 16, v28
	v_and_b32_e32 v109, 0xffff0000, v28
	v_lshlrev_b32_e32 v110, 16, v29
	v_and_b32_e32 v111, 0xffff0000, v29
	ds_read_b128 v[12:15], v39 offset:52736
	ds_read_b128 v[16:19], v39 offset:52752
	ds_read_b128 v[20:23], v39 offset:52768
	ds_read_b128 v[24:27], v39 offset:52784
	ds_read_b128 v[28:31], v39 offset:54272
	v_cndmask_b32_e64 v0, 0, v0, s[10:11]
	s_waitcnt vmcnt(0)
	v_cndmask_b32_e32 v101, 0, v49, vcc
	v_cndmask_b32_e32 v112, 0, v48, vcc
	v_lshlrev_b32_e32 v48, 16, v0
	v_and_b32_e32 v49, 0xffff0000, v0
	v_cndmask_b32_e32 v32, 0, v51, vcc
	v_cndmask_b32_e32 v97, 0, v50, vcc
	s_waitcnt lgkmcnt(4)
	v_pk_fma_f32 v[12:13], v[12:13], v[48:49], 0 op_sel_hi:[1,1,0]
	ds_read_b128 v[48:51], v39 offset:55808
	ds_read_b128 v[52:55], v39 offset:57344
	ds_read_b128 v[56:59], v39 offset:54288
	v_cndmask_b32_e64 v1, 0, v1, s[10:11]
	s_waitcnt lgkmcnt(3)
	v_pk_fma_f32 v[12:13], v[28:29], v[60:61], v[12:13]
	v_lshlrev_b32_e32 v68, 16, v1
	v_and_b32_e32 v69, 0xffff0000, v1
	s_waitcnt lgkmcnt(2)
	v_pk_fma_f32 v[12:13], v[48:49], v[64:65], v[12:13]
	ds_read_b128 v[60:63], v39 offset:55824
	ds_read_b128 v[64:67], v39 offset:57360
	s_waitcnt lgkmcnt(3)
	v_pk_fma_f32 v[104:105], v[52:53], v[104:105], v[12:13]
	v_pk_fma_f32 v[12:13], v[14:15], v[68:69], 0 op_sel_hi:[1,1,0]
	v_lshlrev_b32_e32 v0, 16, v5
	v_pk_fma_f32 v[12:13], v[30:31], v[76:77], v[12:13]
	v_and_b32_e32 v1, 0xffff0000, v5
	v_pk_fma_f32 v[12:13], v[50:51], v[88:89], v[12:13]
	v_pk_fma_f32 v[0:1], v[26:27], v[0:1], 0 op_sel_hi:[1,1,0]
	v_pk_fma_f32 v[68:69], v[54:55], v[106:107], v[12:13]
	v_pk_fma_f32 v[12:13], v[16:17], v[70:71], 0 op_sel_hi:[1,1,0]
	v_pk_fma_f32 v[6:7], v[24:25], v[6:7], 0 op_sel_hi:[1,1,0]
	s_waitcnt lgkmcnt(2)
	v_pk_fma_f32 v[12:13], v[56:57], v[78:79], v[12:13]
	v_pk_fma_f32 v[8:9], v[22:23], v[8:9], 0 op_sel_hi:[1,1,0]
	s_waitcnt lgkmcnt(1)
	v_pk_fma_f32 v[12:13], v[60:61], v[90:91], v[12:13]
	v_lshlrev_b32_e32 v70, 16, v97
	s_waitcnt lgkmcnt(0)
	v_pk_fma_f32 v[60:61], v[64:65], v[108:109], v[12:13]
	v_pk_fma_f32 v[12:13], v[18:19], v[72:73], 0 op_sel_hi:[1,1,0]
	v_and_b32_e32 v71, 0xffff0000, v97
	v_pk_fma_f32 v[12:13], v[58:59], v[80:81], v[12:13]
	v_pk_fma_f32 v[20:21], v[20:21], v[74:75], 0 op_sel_hi:[1,1,0]
	v_pk_fma_f32 v[12:13], v[62:63], v[92:93], v[12:13]
	v_mul_f32_e32 v5, 0xbfb8aa3b, v68
	v_pk_fma_f32 v[62:63], v[66:67], v[110:111], v[12:13]
	ds_read_b128 v[12:15], v39 offset:54304
	ds_read_b128 v[16:19], v39 offset:55840
	ds_read_b128 v[28:31], v39 offset:57376
	ds_read_b128 v[48:51], v39 offset:54320
	ds_read_b128 v[52:55], v39 offset:55856
	ds_read_b128 v[56:59], v39 offset:57392
	v_lshlrev_b32_e32 v66, 16, v101
	s_waitcnt lgkmcnt(5)
	v_pk_fma_f32 v[8:9], v[14:15], v[84:85], v[8:9]
	s_waitcnt lgkmcnt(2)
	v_pk_fma_f32 v[0:1], v[50:51], v[2:3], v[0:1]
	v_mul_f32_e32 v2, 0xbfb8aa3b, v104
	v_mul_f32_e32 v3, 0xbfb8aa3b, v105
	v_exp_f32_e32 v2, v2
	v_exp_f32_e32 v3, v3
	v_pk_fma_f32 v[6:7], v[48:49], v[86:87], v[6:7]
	v_and_b32_e32 v67, 0xffff0000, v101
	s_waitcnt lgkmcnt(1)
	v_pk_fma_f32 v[6:7], v[52:53], v[102:103], v[6:7]
	v_pk_fma_f32 v[12:13], v[12:13], v[82:83], v[20:21]
	v_pk_fma_f32 v[8:9], v[18:19], v[98:99], v[8:9]
	s_waitcnt lgkmcnt(0)
; DI float sigmoidf_(float x) { return __builtin_amdgcn_rcpf(1.f + __expf(-x)); }
; DI void conv32(const bf16_t* __restrict__ Pcol, int tok, int spos, const float* wl, int wstride, float* acc) {
;     ...
; #pragma unroll
;     for (int j = 0; j < 4; ++j) {
;       const bool ok = (spos - 3 + j >= 0);
;       const uint4* src = (const uint4*)(Pcol + (size_t)(tok - 3 + (ok ? j : 3)) * 4096) + 2 * hq;
; #pragma unroll
;       for (int q = 0; q < 2; ++q) {
;         v[j][q] = src[q];
;         if (!ok) v[j][q] = make_uint4(0u, 0u, 0u, 0u);
;       }
;     }
; #pragma unroll
;     for (int i = 0; i < 16; ++i) acc[16 * hq + i] = 0.f;
; #pragma unroll
;     for (int j = 0; j < 4; ++j) {
;       const float4* w4 = (const float4*)(wl + j * wstride + 16 * hq);
; #pragma unroll
;       for (int q = 0; q < 2; ++q) {
;         float f[8];
;         unpack8(v[j][q], f);
;         float4 wa = w4[2 * q], wb = w4[2 * q + 1];
;         float* a = acc + 16 * hq + 8 * q;
;         a[0] += wa.x * f[0]; a[1] += wa.y * f[1]; a[2] += wa.z * f[2]; a[3] += wa.w * f[3];
;         a[4] += wb.x * f[4]; a[5] += wb.y * f[5]; a[6] += wb.z * f[6]; a[7] += wb.w * f[7];
;       }
;     }
; #pragma unroll
;     for (int i = 0; i < 16; ++i) acc[16 * hq + i] = acc[16 * hq + i] * sigmoidf_(acc[16 * hq + i]);
	v_pk_fma_f32 v[20:21], v[56:57], v[70:71], v[6:7]
	v_add_f32_e32 v2, 1.0, v2
	v_add_f32_e32 v3, 1.0, v3
	v_mul_f32_e32 v6, 0xbfb8aa3b, v69
	v_pk_fma_f32 v[18:19], v[30:31], v[66:67], v[8:9]
	v_rcp_f32_e32 v2, v2
	v_rcp_f32_e32 v3, v3
	v_exp_f32_e32 v5, v5
	v_exp_f32_e32 v8, v6
	v_pk_fma_f32 v[0:1], v[54:55], v[10:11], v[0:1]
	v_pk_mul_f32 v[6:7], v[104:105], v[2:3]
	v_add_f32_e32 v2, 1.0, v5
	v_add_f32_e32 v3, 1.0, v8
	v_mul_f32_e32 v5, 0xbfb8aa3b, v60
	v_mul_f32_e32 v8, 0xbfb8aa3b, v61
	v_rcp_f32_e32 v2, v2
	v_rcp_f32_e32 v3, v3
	v_exp_f32_e32 v5, v5
	v_exp_f32_e32 v10, v8
	v_lshlrev_b32_e32 v64, 16, v112
	v_and_b32_e32 v65, 0xffff0000, v112
	v_pk_fma_f32 v[12:13], v[16:17], v[94:95], v[12:13]
	v_pk_mul_f32 v[8:9], v[68:69], v[2:3]
	v_add_f32_e32 v2, 1.0, v5
	v_add_f32_e32 v3, 1.0, v10
	v_mul_f32_e32 v5, 0xbfb8aa3b, v62
	v_mul_f32_e32 v10, 0xbfb8aa3b, v63
	v_pk_fma_f32 v[16:17], v[28:29], v[64:65], v[12:13]
	v_rcp_f32_e32 v2, v2
	v_rcp_f32_e32 v3, v3
	v_exp_f32_e32 v5, v5
	v_exp_f32_e32 v12, v10
	v_mul_f32_e32 v15, 0xbfb8aa3b, v21
	v_pk_mul_f32 v[10:11], v[60:61], v[2:3]
	v_add_f32_e32 v2, 1.0, v5
	v_add_f32_e32 v3, 1.0, v12
	v_mul_f32_e32 v5, 0xbfb8aa3b, v16
	v_rcp_f32_e32 v2, v2
	v_rcp_f32_e32 v3, v3
	v_exp_f32_e32 v5, v5
	v_mul_f32_e32 v12, 0xbfb8aa3b, v17
	v_exp_f32_e32 v14, v12
	v_pk_mul_f32 v[12:13], v[62:63], v[2:3]
	v_add_f32_e32 v2, 1.0, v5
	v_mul_f32_e32 v5, 0xbfb8aa3b, v18
	v_add_f32_e32 v3, 1.0, v14
	v_exp_f32_e32 v5, v5
	v_mul_f32_e32 v14, 0xbfb8aa3b, v19
	v_exp_f32_e32 v14, v14
	v_exp_f32_e32 v15, v15
	v_add_f32_e32 v5, 1.0, v5
	v_rcp_f32_e32 v22, v5
	v_add_f32_e32 v5, 1.0, v14
	v_mul_f32_e32 v14, 0xbfb8aa3b, v20
	v_exp_f32_e32 v14, v14
	v_lshlrev_b32_e32 v72, 16, v32
	v_and_b32_e32 v73, 0xffff0000, v32
	v_pk_fma_f32 v[0:1], v[58:59], v[72:73], v[0:1]
	v_rcp_f32_e32 v23, v5
	v_add_f32_e32 v5, 1.0, v14
	v_mul_f32_e32 v14, 0xbfb8aa3b, v0
	v_rcp_f32_e32 v24, v5
	v_add_f32_e32 v5, 1.0, v15
	v_exp_f32_e32 v14, v14
	v_mul_f32_e32 v15, 0xbfb8aa3b, v1
	v_exp_f32_e32 v15, v15
	v_rcp_f32_e32 v25, v5
	v_add_f32_e32 v5, 1.0, v14
	v_rcp_f32_e32 v26, v5
	v_add_f32_e32 v5, 1.0, v15
	v_rcp_f32_e32 v2, v2
	v_rcp_f32_e32 v3, v3
	v_rcp_f32_e32 v27, v5
	v_pk_mul_f32 v[14:15], v[16:17], v[2:3]
	v_pk_mul_f32 v[16:17], v[18:19], v[22:23]
	v_pk_mul_f32 v[18:19], v[20:21], v[24:25]
	v_pk_mul_f32 v[20:21], v[0:1], v[26:27]
	global_load_dwordx4 v[0:3], v[46:47], off offset:1056
	global_load_dwordx4 v[22:25], v[46:47], off offset:1072
	global_load_dwordx4 v[26:29], v[44:45], off offset:1056
	global_load_dwordx4 v[48:51], v[44:45], off offset:1072
	global_load_dwordx4 v[52:55], v[42:43], off offset:1056
	global_load_dwordx4 v[56:59], v[42:43], off offset:1072
	global_load_dwordx4 v[60:63], v[40:41], off offset:1056
	global_load_dwordx4 v[64:67], v[40:41], off offset:1072
	s_waitcnt vmcnt(7)
	v_cndmask_b32_e64 v3, 0, v3, s[10:11]
	v_cndmask_b32_e64 v2, 0, v2, s[10:11]
	v_cndmask_b32_e64 v1, 0, v1, s[10:11]
	v_cndmask_b32_e64 v0, 0, v0, s[10:11]
	s_waitcnt vmcnt(6)
	v_cndmask_b32_e64 v5, 0, v25, s[10:11]
	s_waitcnt vmcnt(5)
	v_cndmask_b32_e64 v25, 0, v29, s[6:7]
	s_waitcnt vmcnt(4)
	v_cndmask_b32_e64 v29, 0, v51, s[6:7]
	v_cndmask_b32_e64 v30, 0, v50, s[6:7]
	s_waitcnt vmcnt(3)
	v_cndmask_b32_e64 v50, 0, v53, s[8:9]
	v_cndmask_b32_e64 v51, 0, v52, s[8:9]
	s_waitcnt vmcnt(2)
	v_cndmask_b32_e64 v52, 0, v59, s[8:9]
	v_cndmask_b32_e64 v53, 0, v58, s[8:9]
	s_waitcnt vmcnt(1)
	v_cndmask_b32_e32 v58, 0, v63, vcc
	v_cndmask_b32_e32 v59, 0, v62, vcc
	v_cndmask_b32_e32 v74, 0, v61, vcc
	v_cndmask_b32_e32 v75, 0, v60, vcc
	s_waitcnt vmcnt(0)
	v_cndmask_b32_e32 v84, 0, v67, vcc
	v_cndmask_b32_e32 v85, 0, v66, vcc
	v_cndmask_b32_e32 v65, 0, v65, vcc
	v_cndmask_b32_e32 v64, 0, v64, vcc
	v_cndmask_b32_e64 v26, 0, v26, s[6:7]
	v_lshlrev_b32_e32 v82, 16, v0
	v_and_b32_e32 v83, 0xffff0000, v0
	v_lshlrev_b32_e32 v98, 16, v1
	v_and_b32_e32 v99, 0xffff0000, v1
	v_lshlrev_b32_e32 v126, 16, v2
	v_and_b32_e32 v127, 0xffff0000, v2
	v_lshlrev_b32_e32 v90, 16, v3
	v_and_b32_e32 v91, 0xffff0000, v3
	v_lshlrev_b32_e32 v150, 16, v75
	v_and_b32_e32 v151, 0xffff0000, v75
	v_lshlrev_b32_e32 v152, 16, v74
	v_and_b32_e32 v153, 0xffff0000, v74
	v_lshlrev_b32_e32 v154, 16, v59
	v_and_b32_e32 v155, 0xffff0000, v59
	v_lshlrev_b32_e32 v156, 16, v58
	v_and_b32_e32 v157, 0xffff0000, v58
	v_lshlrev_b32_e32 v80, 16, v64
	v_and_b32_e32 v81, 0xffff0000, v64
	v_lshlrev_b32_e32 v74, 16, v65
	v_and_b32_e32 v75, 0xffff0000, v65
	v_lshlrev_b32_e32 v64, 16, v85
	v_and_b32_e32 v65, 0xffff0000, v85
	v_lshlrev_b32_e32 v58, 16, v84
	v_and_b32_e32 v59, 0xffff0000, v84
	ds_read_b128 v[0:3], v39 offset:52800
	ds_read_b128 v[84:87], v39 offset:54336
	ds_read_b128 v[102:105], v39 offset:55872
	ds_read_b128 v[106:109], v39 offset:57408
	ds_read_b128 v[110:113], v39 offset:52816
	v_lshlrev_b32_e32 v118, 16, v26
	v_and_b32_e32 v119, 0xffff0000, v26
	s_waitcnt lgkmcnt(4)
	v_pk_fma_f32 v[0:1], v[0:1], v[82:83], 0 op_sel_hi:[1,1,0]
	v_lshlrev_b32_e32 v122, 16, v51
	v_and_b32_e32 v123, 0xffff0000, v51
	s_waitcnt lgkmcnt(3)
	v_pk_fma_f32 v[0:1], v[84:85], v[118:119], v[0:1]
	v_cndmask_b32_e64 v27, 0, v27, s[6:7]
	s_waitcnt lgkmcnt(2)
	v_pk_fma_f32 v[0:1], v[102:103], v[122:123], v[0:1]
	v_lshlrev_b32_e32 v128, 16, v27
	s_waitcnt lgkmcnt(1)
; DI float sigmoidf_(float x) { return __builtin_amdgcn_rcpf(1.f + __expf(-x)); }
; DI void conv32(const bf16_t* __restrict__ Pcol, int tok, int spos, const float* wl, int wstride, float* acc) {
;     ...
;     for (int j = 0; j < 4; ++j) {
;       const float4* w4 = (const float4*)(wl + j * wstride + 16 * hq);
; #pragma unroll
;       for (int q = 0; q < 2; ++q) {
;         float f[8];
;         unpack8(v[j][q], f);
;         float4 wa = w4[2 * q], wb = w4[2 * q + 1];
;         float* a = acc + 16 * hq + 8 * q;
;         a[0] += wa.x * f[0]; a[1] += wa.y * f[1]; a[2] += wa.z * f[2]; a[3] += wa.w * f[3];
;         a[4] += wb.x * f[4]; a[5] += wb.y * f[5]; a[6] += wb.z * f[6]; a[7] += wb.w * f[7];
;       }
;     }
; #pragma unroll
;     for (int i = 0; i < 16; ++i) acc[16 * hq + i] = acc[16 * hq + i] * sigmoidf_(acc[16 * hq + i]);
	v_pk_fma_f32 v[82:83], v[106:107], v[150:151], v[0:1]
	v_and_b32_e32 v129, 0xffff0000, v27
	v_mul_f32_e32 v0, 0xbfb8aa3b, v82
	v_exp_f32_e32 v0, v0
	v_mul_f32_e32 v1, 0xbfb8aa3b, v83
	v_exp_f32_e32 v1, v1
	v_lshlrev_b32_e32 v146, 16, v50
	v_add_f32_e32 v0, 1.0, v0
	v_rcp_f32_e32 v106, v0
	v_add_f32_e32 v0, 1.0, v1
	v_rcp_f32_e32 v107, v0
	v_pk_fma_f32 v[0:1], v[2:3], v[98:99], 0 op_sel_hi:[1,1,0]
	v_and_b32_e32 v147, 0xffff0000, v50
	v_pk_fma_f32 v[0:1], v[86:87], v[128:129], v[0:1]
	ds_read_b128 v[114:117], v39 offset:54352
	ds_read_b128 v[118:121], v39 offset:55888
	v_pk_fma_f32 v[0:1], v[104:105], v[146:147], v[0:1]
	v_cndmask_b32_e64 v23, 0, v23, s[10:11]
	v_pk_fma_f32 v[98:99], v[108:109], v[152:153], v[0:1]
	v_cndmask_b32_e64 v22, 0, v22, s[10:11]
	v_cndmask_b32_e64 v32, 0, v48, s[6:7]
	ds_read_b128 v[122:125], v39 offset:57424
	v_mul_f32_e32 v0, 0xbfb8aa3b, v98
	v_cndmask_b32_e64 v28, 0, v28, s[6:7]
	v_lshlrev_b32_e32 v88, 16, v22
	v_and_b32_e32 v89, 0xffff0000, v22
	v_lshlrev_b32_e32 v62, 16, v23
	v_and_b32_e32 v63, 0xffff0000, v23
	v_lshlrev_b32_e32 v22, 16, v5
	v_and_b32_e32 v23, 0xffff0000, v5
	v_lshlrev_b32_e32 v76, 16, v32
	v_and_b32_e32 v77, 0xffff0000, v32
	v_exp_f32_e32 v5, v0
	v_mul_f32_e32 v32, 0xbfb8aa3b, v99
	v_cndmask_b32_e64 v31, 0, v49, s[6:7]
	v_cndmask_b32_e64 v49, 0, v54, s[8:9]
	v_lshlrev_b32_e32 v144, 16, v28
	v_and_b32_e32 v145, 0xffff0000, v28
	v_exp_f32_e32 v32, v32
	s_waitcnt lgkmcnt(3)
	v_pk_fma_f32 v[108:109], v[110:111], v[126:127], 0 op_sel_hi:[1,1,0]
	v_lshlrev_b32_e32 v148, 16, v49
	v_and_b32_e32 v149, 0xffff0000, v49
	s_waitcnt lgkmcnt(2)
	v_pk_fma_f32 v[108:109], v[114:115], v[144:145], v[108:109]
	v_add_f32_e32 v5, 1.0, v5
	s_waitcnt lgkmcnt(1)
	v_pk_fma_f32 v[108:109], v[118:119], v[148:149], v[108:109]
	v_pk_mul_f32 v[82:83], v[82:83], v[106:107]
	s_waitcnt lgkmcnt(0)
	v_pk_fma_f32 v[108:109], v[122:123], v[154:155], v[108:109]
	v_rcp_f32_e32 v106, v5
	v_add_f32_e32 v5, 1.0, v32
	v_mul_f32_e32 v32, 0xbfb8aa3b, v108
	v_exp_f32_e32 v32, v32
	v_mul_f32_e32 v97, 0xbfb8aa3b, v109
	v_exp_f32_e32 v97, v97
	v_rcp_f32_e32 v107, v5
	v_add_f32_e32 v5, 1.0, v32
	v_cndmask_b32_e64 v48, 0, v55, s[8:9]
	v_lshlrev_b32_e32 v92, 16, v25
	v_and_b32_e32 v93, 0xffff0000, v25
	v_rcp_f32_e32 v110, v5
	v_add_f32_e32 v5, 1.0, v97
	v_pk_fma_f32 v[90:91], v[112:113], v[90:91], 0 op_sel_hi:[1,1,0]
	v_lshlrev_b32_e32 v94, 16, v48
	v_and_b32_e32 v95, 0xffff0000, v48
	v_rcp_f32_e32 v111, v5
	v_pk_fma_f32 v[90:91], v[116:117], v[92:93], v[90:91]
	ds_read_b128 v[102:105], v39 offset:52832
	ds_read_b128 v[0:3], v39 offset:52848
	v_pk_fma_f32 v[90:91], v[120:121], v[94:95], v[90:91]
	v_pk_mul_f32 v[92:93], v[108:109], v[110:111]
	v_pk_fma_f32 v[126:127], v[124:125], v[156:157], v[90:91]
	v_pk_mul_f32 v[90:91], v[98:99], v[106:107]
	v_mul_f32_e32 v5, 0xbfb8aa3b, v126
	v_exp_f32_e32 v5, v5
	ds_read_b128 v[106:109], v39 offset:54368
	ds_read_b128 v[110:113], v39 offset:55904
	ds_read_b128 v[114:117], v39 offset:57440
	v_cndmask_b32_e64 v56, 0, v56, s[8:9]
	s_waitcnt lgkmcnt(4)
	v_pk_fma_f32 v[88:89], v[102:103], v[88:89], 0 op_sel_hi:[1,1,0]
	v_lshlrev_b32_e32 v78, 16, v56
	v_and_b32_e32 v79, 0xffff0000, v56
	s_waitcnt lgkmcnt(2)
	v_pk_fma_f32 v[76:77], v[106:107], v[76:77], v[88:89]
	v_add_f32_e32 v5, 1.0, v5
	s_waitcnt lgkmcnt(1)
	v_pk_fma_f32 v[88:89], v[110:111], v[78:79], v[76:77]
	v_rcp_f32_e32 v98, v5
	v_mul_f32_e32 v5, 0xbfb8aa3b, v127
	s_waitcnt lgkmcnt(0)
	v_pk_fma_f32 v[80:81], v[114:115], v[80:81], v[88:89]
	v_exp_f32_e32 v5, v5
	v_mul_f32_e32 v32, 0xbfb8aa3b, v80
	v_exp_f32_e32 v32, v32
	v_mul_f32_e32 v88, 0xbfb8aa3b, v81
	v_exp_f32_e32 v89, v88
	v_cndmask_b32_e64 v57, 0, v57, s[8:9]
	v_lshlrev_b32_e32 v68, 16, v31
	v_and_b32_e32 v69, 0xffff0000, v31
	v_pk_fma_f32 v[62:63], v[104:105], v[62:63], 0 op_sel_hi:[1,1,0]
	v_lshlrev_b32_e32 v72, 16, v57
	v_and_b32_e32 v73, 0xffff0000, v57
	v_add_f32_e32 v5, 1.0, v5
	v_pk_fma_f32 v[62:63], v[108:109], v[68:69], v[62:63]
	v_rcp_f32_e32 v99, v5
	v_add_f32_e32 v5, 1.0, v32
	v_pk_fma_f32 v[62:63], v[112:113], v[72:73], v[62:63]
	ds_read_b128 v[118:121], v39 offset:54384
	ds_read_b128 v[122:125], v39 offset:55920
	v_rcp_f32_e32 v88, v5
	v_add_f32_e32 v5, 1.0, v89
	v_pk_fma_f32 v[62:63], v[116:117], v[74:75], v[62:63]
	v_rcp_f32_e32 v89, v5
	v_mul_f32_e32 v5, 0xbfb8aa3b, v62
	v_cndmask_b32_e64 v24, 0, v24, s[10:11]
	ds_read_b128 v[76:79], v39 offset:57456
	v_exp_f32_e32 v5, v5
	v_mul_f32_e32 v32, 0xbfb8aa3b, v63
	v_lshlrev_b32_e32 v60, 16, v24
	v_and_b32_e32 v61, 0xffff0000, v24
	v_exp_f32_e32 v32, v32
	v_lshlrev_b32_e32 v66, 16, v30
	v_and_b32_e32 v67, 0xffff0000, v30
	v_pk_fma_f32 v[0:1], v[0:1], v[60:61], 0 op_sel_hi:[1,1,0]
	v_lshlrev_b32_e32 v70, 16, v53
	v_and_b32_e32 v71, 0xffff0000, v53
	s_waitcnt lgkmcnt(2)
	v_pk_fma_f32 v[0:1], v[118:119], v[66:67], v[0:1]
	v_lshlrev_b32_e32 v54, 16, v29
	v_and_b32_e32 v55, 0xffff0000, v29
	v_add_f32_e32 v5, 1.0, v5
	s_waitcnt lgkmcnt(1)
	v_pk_fma_f32 v[0:1], v[122:123], v[70:71], v[0:1]
	v_pk_fma_f32 v[2:3], v[2:3], v[22:23], 0 op_sel_hi:[1,1,0]
	v_lshlrev_b32_e32 v56, 16, v52
	v_and_b32_e32 v57, 0xffff0000, v52
	v_rcp_f32_e32 v72, v5
	v_add_f32_e32 v5, 1.0, v32
	s_waitcnt lgkmcnt(0)
; DI bf16_t f2bf(float f) { return (bf16_t)(pk2(f, 0.f) & 0xffffu); }
; DI int fragoff(int row, int k, int KS) { return (((row >> 4) * KS + (k >> 5)) << 9) + (((((k >> 3) & 3) << 4) + (row & 15)) << 3) + (k & 7); }
; DI void gdn_pre(const Params& p, int ch, char* smem) {
;     ...
;     float ss = 0.f;
; #pragma unroll
;     for (int i = 0; i < 32; ++i) ss += kk[i] * kk[i];
;     ss += __shfl_xor(ss, 1);
;     ss += __shfl_xor(ss, 2);
;     float rn = rsqrtf(ss + 1e-6f);
; #pragma unroll
;     for (int i = 0; i < 32; ++i) kk[i] *= rn;
; #pragma unroll
;     for (int q = 0; q < 4; ++q) *(uint4*)(kh + t * 136 + part * 32 + 8 * q) = pack8(kk + 8 * q);
;     const float ek = __expf(gcl - gct);
; #pragma unroll
;     for (int i = 0; i < 32; ++i) o_kdT[fragoff(part * 32 + i, t, 2)] = f2bf(kk[i] * ek);
	v_pk_fma_f32 v[0:1], v[76:77], v[64:65], v[0:1]
	v_pk_fma_f32 v[2:3], v[120:121], v[54:55], v[2:3]
	v_rcp_f32_e32 v73, v5
	v_mul_f32_e32 v5, 0xbfb8aa3b, v0
	v_pk_fma_f32 v[2:3], v[124:125], v[56:57], v[2:3]
	v_exp_f32_e32 v5, v5
	v_mul_f32_e32 v32, 0xbfb8aa3b, v1
	v_pk_fma_f32 v[2:3], v[78:79], v[58:59], v[2:3]
	v_exp_f32_e32 v32, v32
	v_mul_f32_e32 v22, 0xbfb8aa3b, v2
	v_exp_f32_e32 v22, v22
	v_mul_f32_e32 v23, 0xbfb8aa3b, v3
	v_exp_f32_e32 v23, v23
	v_add_f32_e32 v5, 1.0, v5
	v_rcp_f32_e32 v60, v5
	v_add_f32_e32 v5, 1.0, v32
	v_rcp_f32_e32 v61, v5
	v_add_f32_e32 v5, 1.0, v22
	v_rcp_f32_e32 v22, v5
	v_add_f32_e32 v5, 1.0, v23
	v_rcp_f32_e32 v23, v5
	v_pk_mul_f32 v[88:89], v[80:81], v[88:89]
	v_pk_mul_f32 v[104:105], v[62:63], v[72:73]
	v_pk_mul_f32 v[0:1], v[0:1], v[60:61]
	v_pk_mul_f32 v[2:3], v[2:3], v[22:23]
	v_pk_mul_f32 v[52:53], v[6:7], v[6:7]
	v_pk_mul_f32 v[50:51], v[8:9], v[8:9]
	v_pk_mul_f32 v[48:49], v[10:11], v[10:11]
	v_pk_mul_f32 v[30:31], v[12:13], v[12:13]
	v_pk_mul_f32 v[28:29], v[14:15], v[14:15]
	v_pk_mul_f32 v[26:27], v[16:17], v[16:17]
	v_pk_mul_f32 v[24:25], v[18:19], v[18:19]
	v_pk_mul_f32 v[84:85], v[20:21], v[20:21]
	v_pk_mul_f32 v[86:87], v[82:83], v[82:83]
	v_pk_mul_f32 v[98:99], v[126:127], v[98:99]
	v_pk_mul_f32 v[68:69], v[88:89], v[88:89]
	v_pk_mul_f32 v[54:55], v[104:105], v[104:105]
	v_pk_mul_f32 v[56:57], v[0:1], v[0:1]
	v_pk_mul_f32 v[22:23], v[2:3], v[2:3]
	v_pk_mul_f32 v[94:95], v[90:91], v[90:91]
	v_pk_mul_f32 v[102:103], v[92:93], v[92:93]
	v_pk_mul_f32 v[106:107], v[98:99], v[98:99]
	v_add_f32_e32 v5, v52, v53
	v_add_f32_e32 v5, v5, v50
	v_add_f32_e32 v5, v5, v51
	v_add_f32_e32 v5, v5, v48
	v_add_f32_e32 v5, v5, v49
	v_add_f32_e32 v5, v5, v30
	v_add_f32_e32 v5, v5, v31
	v_add_f32_e32 v5, v5, v28
	v_add_f32_e32 v5, v5, v29
	v_add_f32_e32 v5, v5, v26
	v_add_f32_e32 v5, v5, v27
	v_add_f32_e32 v5, v5, v24
	v_add_f32_e32 v5, v5, v25
	v_add_f32_e32 v5, v5, v84
	v_add_f32_e32 v5, v5, v85
	v_add_f32_e32 v5, v5, v86
	v_add_f32_e32 v5, v5, v87
	v_add_f32_e32 v5, v5, v94
	v_add_f32_e32 v5, v5, v95
	v_add_f32_e32 v5, v5, v102
	v_add_f32_e32 v5, v5, v103
	v_add_f32_e32 v5, v5, v106
	v_add_f32_e32 v5, v5, v107
	v_add_f32_e32 v5, v5, v68
	v_add_f32_e32 v5, v5, v69
	v_add_f32_e32 v5, v5, v54
	v_add_f32_e32 v5, v5, v55
	v_add_f32_e32 v5, v5, v56
	v_add_f32_e32 v5, v5, v57
	v_add_f32_e32 v5, v5, v22
	v_add_f32_e32 v5, v5, v23
	ds_bpermute_b32 v22, v130, v5
	v_and_b32_e32 v32, 31, v34
	s_waitcnt lgkmcnt(0)
	v_add_f32_e32 v5, v5, v22
	ds_bpermute_b32 v22, v131, v5
	s_waitcnt lgkmcnt(0)
	v_add_f32_e32 v5, v5, v22
	v_add_f32_e32 v5, 0x358637bd, v5
	v_cmp_gt_f32_e64 s[12:13], s67, v5
	v_mul_f32_e32 v22, 0x4b800000, v5
	s_nop 0
	v_cndmask_b32_e64 v5, v5, v22, s[12:13]
	v_rsq_f32_e32 v5, v5
	s_nop 0
	v_mul_f32_e32 v22, 0x45800000, v5
	v_cndmask_b32_e64 v22, v5, v22, s[12:13]
	v_pk_mul_f32 v[78:79], v[6:7], v[22:23] op_sel_hi:[1,0]
	v_pk_mul_f32 v[80:81], v[8:9], v[22:23] op_sel_hi:[1,0]
	v_pk_mul_f32 v[74:75], v[10:11], v[22:23] op_sel_hi:[1,0]
	v_pk_mul_f32 v[76:77], v[12:13], v[22:23] op_sel_hi:[1,0]
	v_pk_mul_f32 v[70:71], v[14:15], v[22:23] op_sel_hi:[1,0]
	v_pk_mul_f32 v[72:73], v[16:17], v[22:23] op_sel_hi:[1,0]
	v_pk_mul_f32 v[66:67], v[18:19], v[22:23] op_sel_hi:[1,0]
	v_pk_mul_f32 v[68:69], v[20:21], v[22:23] op_sel_hi:[1,0]
	v_pk_mul_f32 v[50:51], v[0:1], v[22:23] op_sel_hi:[1,0]
	v_pk_mul_f32 v[52:53], v[2:3], v[22:23] op_sel_hi:[1,0]
	v_cvt_pk_bf16_f32 v0, v78, v79
	v_cvt_pk_bf16_f32 v1, v80, v81
	v_cvt_pk_bf16_f32 v2, v74, v75
	v_cvt_pk_bf16_f32 v3, v76, v77
	v_pk_mul_f32 v[62:63], v[82:83], v[22:23] op_sel_hi:[1,0]
	v_pk_mul_f32 v[64:65], v[90:91], v[22:23] op_sel_hi:[1,0]
	v_pk_mul_f32 v[58:59], v[92:93], v[22:23] op_sel_hi:[1,0]
	v_pk_mul_f32 v[60:61], v[98:99], v[22:23] op_sel_hi:[1,0]
	ds_write_b128 v4, v[0:3] offset:17408
	v_cvt_pk_bf16_f32 v0, v70, v71
	v_cvt_pk_bf16_f32 v1, v72, v73
	v_cvt_pk_bf16_f32 v2, v66, v67
	v_cvt_pk_bf16_f32 v3, v68, v69
	v_pk_mul_f32 v[54:55], v[88:89], v[22:23] op_sel_hi:[1,0]
	v_pk_mul_f32 v[56:57], v[104:105], v[22:23] op_sel_hi:[1,0]
	ds_write_b128 v4, v[0:3] offset:17424
	v_cvt_pk_bf16_f32 v0, v62, v63
	v_cvt_pk_bf16_f32 v1, v64, v65
	v_cvt_pk_bf16_f32 v2, v58, v59
	v_cvt_pk_bf16_f32 v3, v60, v61
	ds_write_b128 v4, v[0:3] offset:17440
	v_cvt_pk_bf16_f32 v0, v54, v55
	v_cvt_pk_bf16_f32 v1, v56, v57
	v_cvt_pk_bf16_f32 v2, v50, v51
	v_cvt_pk_bf16_f32 v3, v52, v53
	ds_write_b128 v4, v[0:3] offset:17456
	v_sub_f32_e32 v0, v96, v37
	v_mul_f32_e32 v0, 0x3fb8aa3b, v0
	v_exp_f32_e32 v2, v0
	v_lshrrev_b32_e32 v0, 5, v35
	v_lshlrev_b32_e32 v1, 4, v35
	v_and_b32_e32 v5, 12, v143
	v_and_b32_e32 v3, 0x180, v1
	v_and_b32_e32 v1, 7, v35
	v_add_u32_e32 v0, v5, v0
	v_lshl_or_b32 v5, v0, 9, v1
	v_or_b32_e32 v0, v5, v3
	v_mul_f32_e32 v4, v2, v78
	v_ashrrev_i32_e32 v1, 31, v0
	v_cvt_pk_bf16_f32 v4, v4, s0
	v_lshl_add_u64 v[0:1], v[0:1], 1, s[36:37]
	v_mov_b32_e32 v244, v0
	v_mov_b32_e32 v245, v1
	global_store_short v[0:1], v4, off
	v_mul_f32_e32 v0, v2, v79
	v_cvt_pk_bf16_f32 v4, v0, s0
	global_store_short v[244:245], v4, off offset:16
	v_mul_f32_e32 v0, v2, v80
	v_cvt_pk_bf16_f32 v4, v0, s0
	global_store_short v[244:245], v4, off offset:32
	v_mul_f32_e32 v0, v2, v81
	v_cvt_pk_bf16_f32 v4, v0, s0
	global_store_short v[244:245], v4, off offset:48
	v_mul_f32_e32 v0, v2, v74
	v_cvt_pk_bf16_f32 v4, v0, s0
	global_store_short v[244:245], v4, off offset:64
	v_mul_f32_e32 v0, v2, v75
	v_cvt_pk_bf16_f32 v4, v0, s0
	global_store_short v[244:245], v4, off offset:80
	v_mul_f32_e32 v0, v2, v76
	v_cvt_pk_bf16_f32 v4, v0, s0
	global_store_short v[244:245], v4, off offset:96
	v_mul_f32_e32 v0, v2, v77
; #define MFMA32(a, b, c) __builtin_amdgcn_mfma_f32_32x32x16_bf16((a), (b), (c), 0, 0, 0)
; DI bf16_t f2bf(float f) { return (bf16_t)(pk2(f, 0.f) & 0xffffu); }
; DI int fragoff(int row, int k, int KS) { return (((row >> 4) * KS + (k >> 5)) << 9) + (((((k >> 3) & 3) << 4) + (row & 15)) << 3) + (k & 7); }
; DI int crow32(int r, int half) { return (r & 3) + 8 * (r >> 2) + 4 * half; }
; DI void gdn_pre(const Params& p, int ch, char* smem) {
;     ...
;     for (int i = 0; i < 32; ++i) o_kdT[fragoff(part * 32 + i, t, 2)] = f2bf(kk[i] * ek);
;   }
;   __syncthreads();
;   {
;     const int ti = wave >> 1, tj = wave & 1;
;     f32x16 accA, accQ;
; #pragma unroll
;     for (int r = 0; r < 16; ++r) { accA[r] = 0.f; accQ[r] = 0.f; }
; #pragma unroll
;     for (int s = 0; s < 8; ++s) {
;       const int ko = s * 16 + (lane >> 5) * 8;
;       bf16x8 bk = *(const bf16x8*)(kh + (tj * 32 + (lane & 31)) * 136 + ko);
;       bf16x8 ak = *(const bf16x8*)(kh + (ti * 32 + (lane & 31)) * 136 + ko);
;       bf16x8 aq = *(const bf16x8*)(qh + (ti * 32 + (lane & 31)) * 136 + ko);
;       accA = MFMA32(ak, bk, accA);
;       accQ = MFMA32(aq, bk, accQ);
;     }
;     const int j = tj * 32 + (lane & 31);
;     const float gcj = s_gc[j];
; #pragma unroll
;     for (int r = 0; r < 16; ++r) {
;       const int i = ti * 32 + crow32(r, lane >> 5);
;       const float dec = (i >= j) ? __expf(s_gc[i] - gcj) : 0.f;
	v_cvt_pk_bf16_f32 v4, v0, s0
	global_store_short v[244:245], v4, off offset:112
	v_mul_f32_e32 v0, v2, v70
	v_cvt_pk_bf16_f32 v4, v0, s0
	global_store_short v[244:245], v4, off offset:128
	v_mul_f32_e32 v0, v2, v71
	v_cvt_pk_bf16_f32 v4, v0, s0
	global_store_short v[244:245], v4, off offset:144
	v_mul_f32_e32 v0, v2, v72
	v_cvt_pk_bf16_f32 v4, v0, s0
	global_store_short v[244:245], v4, off offset:160
	v_mul_f32_e32 v0, v2, v73
	v_cvt_pk_bf16_f32 v4, v0, s0
	global_store_short v[244:245], v4, off offset:176
	v_mul_f32_e32 v0, v2, v66
	v_cvt_pk_bf16_f32 v4, v0, s0
	global_store_short v[244:245], v4, off offset:192
	v_mul_f32_e32 v0, v2, v67
	v_cvt_pk_bf16_f32 v4, v0, s0
	global_store_short v[244:245], v4, off offset:208
	v_mul_f32_e32 v0, v2, v68
	v_cvt_pk_bf16_f32 v4, v0, s0
	global_store_short v[244:245], v4, off offset:224
	v_mul_f32_e32 v0, v2, v69
	v_cvt_pk_bf16_f32 v4, v0, s0
	global_store_short v[244:245], v4, off offset:240
	v_mul_f32_e32 v0, v2, v62
	v_add_u32_e32 v5, 0x400, v5
	v_cvt_pk_bf16_f32 v4, v0, s0
	global_store_short v[244:245], v4, off offset:2048
	v_mul_f32_e32 v0, v2, v63
	v_cvt_pk_bf16_f32 v3, v0, s0
	global_store_short v[244:245], v3, off offset:2064
	v_mul_f32_e32 v0, v2, v64
	v_cvt_pk_bf16_f32 v3, v0, s0
	global_store_short v[244:245], v3, off offset:2080
	v_mul_f32_e32 v0, v2, v65
	v_cvt_pk_bf16_f32 v3, v0, s0
	global_store_short v[244:245], v3, off offset:2096
	v_mul_f32_e32 v0, v2, v58
	v_cvt_pk_bf16_f32 v3, v0, s0
	global_store_short v[244:245], v3, off offset:2112
	v_mul_f32_e32 v0, v2, v59
	v_cvt_pk_bf16_f32 v3, v0, s0
	global_store_short v[244:245], v3, off offset:2128
	v_mul_f32_e32 v0, v2, v60
	v_cvt_pk_bf16_f32 v3, v0, s0
	global_store_short v[244:245], v3, off offset:2144
	v_mul_f32_e32 v0, v2, v61
	v_cvt_pk_bf16_f32 v3, v0, s0
	global_store_short v[244:245], v3, off offset:2160
	v_mul_f32_e32 v0, v2, v54
	v_cvt_pk_bf16_f32 v3, v0, s0
	global_store_short v[244:245], v3, off offset:2176
	v_mul_f32_e32 v0, v2, v55
	v_cvt_pk_bf16_f32 v3, v0, s0
	global_store_short v[244:245], v3, off offset:2192
	v_mul_f32_e32 v0, v2, v56
	v_cvt_pk_bf16_f32 v3, v0, s0
	global_store_short v[244:245], v3, off offset:2208
	v_mul_f32_e32 v0, v2, v57
	v_cvt_pk_bf16_f32 v3, v0, s0
	global_store_short v[244:245], v3, off offset:2224
	v_mul_f32_e32 v0, v2, v50
	v_cvt_pk_bf16_f32 v3, v0, s0
	global_store_short v[244:245], v3, off offset:2240
	v_mul_f32_e32 v0, v2, v51
	v_cvt_pk_bf16_f32 v3, v0, s0
	global_store_short v[244:245], v3, off offset:2256
	v_mul_f32_e32 v0, v2, v52
	v_cvt_pk_bf16_f32 v3, v0, s0
	global_store_short v[244:245], v3, off offset:2272
	v_mul_f32_e32 v0, v2, v53
	v_cvt_pk_bf16_f32 v2, v0, s0
	global_store_short v[244:245], v2, off offset:2288
	v_lshrrev_b32_e32 v1, 1, v34
	v_bfi_b32 v0, s92, v35, v34
	v_and_b32_e32 v4, 16, v1
	v_mad_u64_u32 v[90:91], s[0:1], v0, s70, v[4:5]
	s_waitcnt lgkmcnt(0)
	s_barrier
	ds_read_b128 v[0:3], v90 offset:17408
	v_bfe_u32 v37, v34, 6, 1
	v_lshl_or_b32 v48, v37, 5, v32
	v_mad_u32_u24 v49, v48, s70, v4
	ds_read_b128 v[4:7], v49 offset:17408
	s_waitcnt lgkmcnt(0)
	v_mfma_f32_32x32x16_bf16 v[16:31], v[0:3], v[4:7], 0
	ds_read_b128 v[0:3], v90
	ds_read_b128 v[82:85], v90 offset:17440
	ds_read_b128 v[86:89], v49 offset:17440
	s_waitcnt lgkmcnt(0)
	v_mfma_f32_32x32x16_bf16 v[16:31], v[82:85], v[86:89], v[16:31]
	ds_read_b128 v[82:85], v90 offset:32
	v_mfma_f32_32x32x16_bf16 v[0:15], v[0:3], v[4:7], 0
	s_waitcnt lgkmcnt(0)
	v_mfma_f32_32x32x16_bf16 v[0:15], v[82:85], v[86:89], v[0:15]
	ds_read_b128 v[82:85], v90 offset:17472
	ds_read_b128 v[86:89], v49 offset:17472
	s_waitcnt lgkmcnt(0)
	v_mfma_f32_32x32x16_bf16 v[16:31], v[82:85], v[86:89], v[16:31]
	ds_read_b128 v[82:85], v90 offset:64
	s_waitcnt lgkmcnt(0)
	v_mfma_f32_32x32x16_bf16 v[0:15], v[82:85], v[86:89], v[0:15]
	ds_read_b128 v[82:85], v90 offset:17504
	ds_read_b128 v[86:89], v49 offset:17504
	s_waitcnt lgkmcnt(0)
	v_mfma_f32_32x32x16_bf16 v[16:31], v[82:85], v[86:89], v[16:31]
	ds_read_b128 v[82:85], v90 offset:96
	s_waitcnt lgkmcnt(0)
	v_mfma_f32_32x32x16_bf16 v[0:15], v[82:85], v[86:89], v[0:15]
	ds_read_b128 v[82:85], v90 offset:17536
	ds_read_b128 v[86:89], v49 offset:17536
	s_waitcnt lgkmcnt(0)
	v_mfma_f32_32x32x16_bf16 v[16:31], v[82:85], v[86:89], v[16:31]
	ds_read_b128 v[82:85], v90 offset:128
	s_waitcnt lgkmcnt(0)
	v_mfma_f32_32x32x16_bf16 v[0:15], v[82:85], v[86:89], v[0:15]
	ds_read_b128 v[82:85], v90 offset:17568
	ds_read_b128 v[86:89], v49 offset:17568
	s_waitcnt lgkmcnt(0)
	v_mfma_f32_32x32x16_bf16 v[16:31], v[82:85], v[86:89], v[16:31]
	ds_read_b128 v[82:85], v90 offset:160
	s_waitcnt lgkmcnt(0)
	v_mfma_f32_32x32x16_bf16 v[0:15], v[82:85], v[86:89], v[0:15]
	ds_read_b128 v[82:85], v90 offset:17600
	ds_read_b128 v[86:89], v49 offset:17600
	s_waitcnt lgkmcnt(0)
	v_mfma_f32_32x32x16_bf16 v[16:31], v[82:85], v[86:89], v[16:31]
	ds_read_b128 v[82:85], v90 offset:192
	s_waitcnt lgkmcnt(0)
	v_mfma_f32_32x32x16_bf16 v[0:15], v[82:85], v[86:89], v[0:15]
	ds_read_b128 v[82:85], v90 offset:17632
	ds_read_b128 v[86:89], v49 offset:17632
	ds_read_b128 v[90:93], v90 offset:224
	v_lshlrev_b32_e32 v49, 2, v48
	s_waitcnt lgkmcnt(1)
	v_mfma_f32_32x32x16_bf16 v[16:31], v[82:85], v[86:89], v[16:31]
	ds_read_b32 v82, v49 offset:51712
	v_lshrrev_b32_e32 v83, 3, v34
	v_and_b32_e32 v85, 0xffffffe0, v35
	s_waitcnt lgkmcnt(1)
	v_mfma_f32_32x32x16_bf16 v[0:15], v[90:93], v[86:89], v[0:15]
	v_and_b32_e32 v86, 4, v83
	v_or_b32_e32 v84, v86, v85
	v_cmp_ge_i32_e64 s[12:13], v84, v48
	v_mov_b32_e32 v89, 0
	v_lshlrev_b32_e32 v83, 2, v84
	v_mov_b32_e32 v87, 0
	s_and_saveexec_b64 s[36:37], s[12:13]
	s_cbranch_execz .LBB0_302
	ds_read_b32 v87, v83 offset:51712
	s_waitcnt lgkmcnt(0)
	v_sub_f32_e32 v87, v87, v82
	v_mul_f32_e32 v87, 0x3fb8aa3b, v87
	v_exp_f32_e32 v87, v87

; DI void gdn_pre(const Params& p, int ch, char* smem) {
;     ...
; #pragma unroll
;   for (int i = 1; i < 64; ++i) {
;     f32x2 sa = {0.f, 0.f}, sb = {0.f, 0.f};
;     const f32x2* arow = (const f32x2*)(Amat + i * 64);
; #pragma unroll
;     for (int k = 0; k < (i >> 1); ++k) {
;       const f32x2 a2 = arow[k];
;       if (k & 1) sb = __builtin_elementwise_fma(a2, c2[k], sb);
;       else sa = __builtin_elementwise_fma(a2, c2[k], sa);
;     }
;     float tot = (sa[0] + sa[1]) + (sb[0] + sb[1]);
;     if (i & 1) tot += Amat[i * 64 + i - 1] * c2[(i - 1) >> 1][0];
;     c2[i >> 1][i & 1] -= tot;
;     __builtin_amdgcn_sched_barrier(0);
;   }
.LBB0_368:
	s_or_b64 exec, exec, s[8:9]
	ds_read_b32 v19, v33 offset:35072
	s_waitcnt lgkmcnt(0)
	v_fma_f32 v19, v19, v0, 0
	v_sub_f32_e32 v1, v1, v19
	ds_read_b64 v[126:127], v33 offset:35328
	s_waitcnt lgkmcnt(0)
	v_pk_fma_f32 v[126:127], v[126:127], v[0:1], 0 op_sel_hi:[1,1,0]
	s_nop 0
	v_add_f32_e32 v19, v126, v127
	v_add_f32_e32 v19, 0, v19
	v_sub_f32_e32 v6, v6, v19
	ds_read_b96 v[126:128], v33 offset:35584
	s_waitcnt lgkmcnt(0)
	v_pk_fma_f32 v[126:127], v[126:127], v[0:1], 0 op_sel_hi:[1,1,0]
	s_nop 0
	v_add_f32_e32 v19, v126, v127
	v_add_f32_e32 v19, 0, v19
	v_fmac_f32_e32 v19, v128, v6
	v_sub_f32_e32 v7, v7, v19
	ds_read_b128 v[126:129], v33 offset:35840
	s_waitcnt lgkmcnt(0)
	v_pk_fma_f32 v[126:127], v[126:127], v[0:1], 0 op_sel_hi:[1,1,0]
	v_pk_fma_f32 v[128:129], v[128:129], v[6:7], 0 op_sel_hi:[1,1,0]
	v_mov_b32_e32 v144, v126
	v_mov_b32_e32 v145, v128
	v_mov_b32_e32 v128, v127
	v_pk_add_f32 v[126:127], v[144:145], v[128:129]
	s_nop 0
	v_pk_add_f32 v[126:127], v[126:127], v[126:127] op_sel:[0,1] op_sel_hi:[1,0]
	s_nop 0
	v_pk_add_f32 v[8:9], v[8:9], v[126:127] neg_lo:[0,1] neg_hi:[0,1]
	ds_read_b128 v[126:129], v33 offset:36096
	ds_read_b32 v9, v33 offset:36112
	s_waitcnt lgkmcnt(1)
	v_pk_fma_f32 v[126:127], v[126:127], v[0:1], 0 op_sel_hi:[1,1,0]
	v_pk_fma_f32 v[128:129], v[128:129], v[6:7], 0 op_sel_hi:[1,1,0]
	v_mov_b32_e32 v144, v126
	v_mov_b32_e32 v145, v128
	v_mov_b32_e32 v128, v127
	v_pk_add_f32 v[126:127], v[144:145], v[128:129]
	s_nop 0
	v_add_f32_e32 v19, v126, v127
	s_waitcnt lgkmcnt(0)
	v_fmac_f32_e32 v19, v9, v8
	v_sub_f32_e32 v9, v124, v19
	ds_read_b128 v[124:127], v33 offset:36352
	ds_read_b64 v[128:129], v33 offset:36368
	s_waitcnt lgkmcnt(1)
	v_pk_fma_f32 v[124:125], v[124:125], v[0:1], 0 op_sel_hi:[1,1,0]
	v_pk_fma_f32 v[126:127], v[126:127], v[6:7], 0 op_sel_hi:[1,1,0]
	s_waitcnt lgkmcnt(0)
	v_pk_fma_f32 v[124:125], v[128:129], v[8:9], v[124:125]
	v_mov_b32_e32 v128, v126
	v_mov_b32_e32 v129, v124
	v_mov_b32_e32 v124, v127
	v_pk_add_f32 v[124:125], v[128:129], v[124:125]
	s_nop 0
	v_pk_add_f32 v[124:125], v[124:125], v[124:125] op_sel:[0,1] op_sel_hi:[1,0]
	s_nop 0
	v_pk_add_f32 v[10:11], v[10:11], v[124:125] neg_lo:[0,1] neg_hi:[0,1]
	ds_read_b128 v[124:127], v33 offset:36608
	ds_read_b96 v[144:146], v33 offset:36624
	s_waitcnt lgkmcnt(1)
	v_pk_fma_f32 v[124:125], v[124:125], v[0:1], 0 op_sel_hi:[1,1,0]
	v_pk_fma_f32 v[126:127], v[126:127], v[6:7], 0 op_sel_hi:[1,1,0]
	s_waitcnt lgkmcnt(0)
	v_pk_fma_f32 v[124:125], v[144:145], v[8:9], v[124:125]
	v_mov_b32_e32 v128, v126
	v_mov_b32_e32 v129, v124
	v_mov_b32_e32 v124, v127
	v_pk_add_f32 v[124:125], v[128:129], v[124:125]
	s_nop 0
	v_add_f32_e32 v11, v124, v125
	v_fmac_f32_e32 v11, v146, v10
	v_sub_f32_e32 v11, v122, v11
	ds_read_b128 v[122:125], v33 offset:36864
	ds_read_b128 v[126:129], v33 offset:36880
	s_waitcnt lgkmcnt(1)
	v_pk_fma_f32 v[122:123], v[122:123], v[0:1], 0 op_sel_hi:[1,1,0]
	v_pk_fma_f32 v[124:125], v[124:125], v[6:7], 0 op_sel_hi:[1,1,0]
	s_waitcnt lgkmcnt(0)
	v_pk_fma_f32 v[122:123], v[126:127], v[8:9], v[122:123]
	v_pk_fma_f32 v[124:125], v[128:129], v[10:11], v[124:125]
	v_mov_b32_e32 v126, v122
	v_mov_b32_e32 v127, v124
	v_mov_b32_e32 v124, v123
	v_pk_add_f32 v[122:123], v[126:127], v[124:125]
	s_nop 0
	v_pk_add_f32 v[122:123], v[122:123], v[122:123] op_sel:[0,1] op_sel_hi:[1,0]
	s_nop 0
	v_pk_add_f32 v[12:13], v[12:13], v[122:123] neg_lo:[0,1] neg_hi:[0,1]
	ds_read_b128 v[122:125], v33 offset:37120
	ds_read_b128 v[126:129], v33 offset:37136
	ds_read_b32 v13, v33 offset:37152
	s_waitcnt lgkmcnt(2)
	v_pk_fma_f32 v[122:123], v[122:123], v[0:1], 0 op_sel_hi:[1,1,0]
	v_pk_fma_f32 v[124:125], v[124:125], v[6:7], 0 op_sel_hi:[1,1,0]
	s_waitcnt lgkmcnt(1)
	v_pk_fma_f32 v[122:123], v[126:127], v[8:9], v[122:123]
	v_pk_fma_f32 v[124:125], v[128:129], v[10:11], v[124:125]
	v_mov_b32_e32 v126, v122
	v_mov_b32_e32 v127, v124
	v_mov_b32_e32 v124, v123
	v_pk_add_f32 v[122:123], v[126:127], v[124:125]
	s_nop 0
	v_add_f32_e32 v19, v122, v123
	s_waitcnt lgkmcnt(0)
	v_fmac_f32_e32 v19, v13, v12
	v_sub_f32_e32 v13, v120, v19
	ds_read_b128 v[120:123], v33 offset:37376
	ds_read_b128 v[124:127], v33 offset:37392
	ds_read_b64 v[128:129], v33 offset:37408
	s_waitcnt lgkmcnt(2)
	v_pk_fma_f32 v[120:121], v[120:121], v[0:1], 0 op_sel_hi:[1,1,0]
	v_pk_fma_f32 v[122:123], v[122:123], v[6:7], 0 op_sel_hi:[1,1,0]
	s_waitcnt lgkmcnt(1)
	v_pk_fma_f32 v[120:121], v[124:125], v[8:9], v[120:121]
	v_pk_fma_f32 v[122:123], v[126:127], v[10:11], v[122:123]
	s_waitcnt lgkmcnt(0)
	v_pk_fma_f32 v[120:121], v[128:129], v[12:13], v[120:121]
	v_mov_b32_e32 v124, v122
	v_mov_b32_e32 v125, v120
	v_mov_b32_e32 v120, v123
	v_pk_add_f32 v[120:121], v[124:125], v[120:121]
	s_nop 0
	v_pk_add_f32 v[120:121], v[120:121], v[120:121] op_sel:[0,1] op_sel_hi:[1,0]
	s_nop 0
	v_pk_add_f32 v[16:17], v[16:17], v[120:121] neg_lo:[0,1] neg_hi:[0,1]
	ds_read_b128 v[120:123], v33 offset:37632
	ds_read_b128 v[124:127], v33 offset:37648
	ds_read_b96 v[144:146], v33 offset:37664
	s_waitcnt lgkmcnt(2)
	v_pk_fma_f32 v[120:121], v[120:121], v[0:1], 0 op_sel_hi:[1,1,0]
	v_pk_fma_f32 v[122:123], v[122:123], v[6:7], 0 op_sel_hi:[1,1,0]
	s_waitcnt lgkmcnt(1)
	v_pk_fma_f32 v[120:121], v[124:125], v[8:9], v[120:121]
	v_pk_fma_f32 v[122:123], v[126:127], v[10:11], v[122:123]
	s_waitcnt lgkmcnt(0)
	v_pk_fma_f32 v[120:121], v[144:145], v[12:13], v[120:121]
	v_mov_b32_e32 v124, v122
	v_mov_b32_e32 v125, v120
	v_mov_b32_e32 v120, v123
	v_pk_add_f32 v[120:121], v[124:125], v[120:121]
	s_nop 0
	v_add_f32_e32 v17, v120, v121
	v_fmac_f32_e32 v17, v146, v16
	v_sub_f32_e32 v17, v118, v17
	ds_read_b128 v[118:121], v33 offset:37888
	ds_read_b128 v[122:125], v33 offset:37904
	ds_read_b128 v[126:129], v33 offset:37920
	s_waitcnt lgkmcnt(2)
; DI void gdn_pre(const Params& p, int ch, char* smem) {
;     ...
; #pragma unroll
;   for (int i = 1; i < 64; ++i) {
;     f32x2 sa = {0.f, 0.f}, sb = {0.f, 0.f};
;     const f32x2* arow = (const f32x2*)(Amat + i * 64);
; #pragma unroll
;     for (int k = 0; k < (i >> 1); ++k) {
;       const f32x2 a2 = arow[k];
;       if (k & 1) sb = __builtin_elementwise_fma(a2, c2[k], sb);
;       else sa = __builtin_elementwise_fma(a2, c2[k], sa);
;     }
;     float tot = (sa[0] + sa[1]) + (sb[0] + sb[1]);
;     if (i & 1) tot += Amat[i * 64 + i - 1] * c2[(i - 1) >> 1][0];
;     c2[i >> 1][i & 1] -= tot;
;     __builtin_amdgcn_sched_barrier(0);
;   }
	v_pk_fma_f32 v[118:119], v[118:119], v[0:1], 0 op_sel_hi:[1,1,0]
	v_pk_fma_f32 v[120:121], v[120:121], v[6:7], 0 op_sel_hi:[1,1,0]
	s_waitcnt lgkmcnt(1)
	v_pk_fma_f32 v[118:119], v[122:123], v[8:9], v[118:119]
	v_pk_fma_f32 v[120:121], v[124:125], v[10:11], v[120:121]
	s_waitcnt lgkmcnt(0)
	v_pk_fma_f32 v[118:119], v[126:127], v[12:13], v[118:119]
	v_pk_fma_f32 v[120:121], v[128:129], v[16:17], v[120:121]
	v_mov_b32_e32 v122, v118
	v_mov_b32_e32 v123, v120
	v_mov_b32_e32 v120, v119
	v_pk_add_f32 v[118:119], v[122:123], v[120:121]
	s_nop 0
	v_pk_add_f32 v[118:119], v[118:119], v[118:119] op_sel:[0,1] op_sel_hi:[1,0]
	s_nop 0
	v_pk_add_f32 v[20:21], v[20:21], v[118:119] neg_lo:[0,1] neg_hi:[0,1]
	ds_read_b128 v[118:121], v33 offset:38144
	ds_read_b128 v[122:125], v33 offset:38160
	ds_read_b128 v[126:129], v33 offset:38176
	ds_read_b32 v19, v33 offset:38192
	s_waitcnt lgkmcnt(3)
	v_pk_fma_f32 v[118:119], v[118:119], v[0:1], 0 op_sel_hi:[1,1,0]
	v_pk_fma_f32 v[120:121], v[120:121], v[6:7], 0 op_sel_hi:[1,1,0]
	s_waitcnt lgkmcnt(2)
	v_pk_fma_f32 v[118:119], v[122:123], v[8:9], v[118:119]
	v_pk_fma_f32 v[120:121], v[124:125], v[10:11], v[120:121]
	s_waitcnt lgkmcnt(1)
	v_pk_fma_f32 v[118:119], v[126:127], v[12:13], v[118:119]
	v_pk_fma_f32 v[120:121], v[128:129], v[16:17], v[120:121]
	v_mov_b32_e32 v122, v118
	v_mov_b32_e32 v123, v120
	v_mov_b32_e32 v120, v119
	v_pk_add_f32 v[118:119], v[122:123], v[120:121]
	s_nop 0
	v_add_f32_e32 v21, v118, v119
	s_waitcnt lgkmcnt(0)
	v_fmac_f32_e32 v21, v20, v19
	v_sub_f32_e32 v21, v116, v21
	ds_read_b128 v[116:119], v33 offset:38400
	ds_read_b128 v[120:123], v33 offset:38416
	ds_read_b128 v[124:127], v33 offset:38432
	ds_read_b64 v[128:129], v33 offset:38448
	s_waitcnt lgkmcnt(3)
	v_pk_fma_f32 v[116:117], v[116:117], v[0:1], 0 op_sel_hi:[1,1,0]
	v_pk_fma_f32 v[118:119], v[118:119], v[6:7], 0 op_sel_hi:[1,1,0]
	s_waitcnt lgkmcnt(2)
	v_pk_fma_f32 v[116:117], v[120:121], v[8:9], v[116:117]
	v_pk_fma_f32 v[118:119], v[122:123], v[10:11], v[118:119]
	s_waitcnt lgkmcnt(1)
	v_pk_fma_f32 v[116:117], v[124:125], v[12:13], v[116:117]
	v_pk_fma_f32 v[118:119], v[126:127], v[16:17], v[118:119]
	s_waitcnt lgkmcnt(0)
	v_pk_fma_f32 v[116:117], v[128:129], v[20:21], v[116:117]
	v_mov_b32_e32 v120, v118
	v_mov_b32_e32 v121, v116
	v_mov_b32_e32 v116, v119
	v_pk_add_f32 v[116:117], v[120:121], v[116:117]
	s_nop 0
	v_pk_add_f32 v[116:117], v[116:117], v[116:117] op_sel:[0,1] op_sel_hi:[1,0]
	s_nop 0
	v_pk_add_f32 v[22:23], v[22:23], v[116:117] neg_lo:[0,1] neg_hi:[0,1]
	ds_read_b128 v[116:119], v33 offset:38656
	ds_read_b128 v[120:123], v33 offset:38672
	ds_read_b128 v[124:127], v33 offset:38688
	ds_read_b96 v[144:146], v33 offset:38704
	s_waitcnt lgkmcnt(3)
	v_pk_fma_f32 v[116:117], v[116:117], v[0:1], 0 op_sel_hi:[1,1,0]
	v_pk_fma_f32 v[118:119], v[118:119], v[6:7], 0 op_sel_hi:[1,1,0]
	s_waitcnt lgkmcnt(2)
	v_pk_fma_f32 v[116:117], v[120:121], v[8:9], v[116:117]
	v_pk_fma_f32 v[118:119], v[122:123], v[10:11], v[118:119]
	s_waitcnt lgkmcnt(1)
	v_pk_fma_f32 v[116:117], v[124:125], v[12:13], v[116:117]
	v_pk_fma_f32 v[118:119], v[126:127], v[16:17], v[118:119]
	s_waitcnt lgkmcnt(0)
	v_pk_fma_f32 v[116:117], v[144:145], v[20:21], v[116:117]
	v_mov_b32_e32 v120, v118
	v_mov_b32_e32 v121, v116
	v_mov_b32_e32 v116, v119
	v_pk_add_f32 v[116:117], v[120:121], v[116:117]
	s_nop 0
	v_add_f32_e32 v19, v116, v117
	v_fmac_f32_e32 v19, v22, v146
	v_sub_f32_e32 v23, v114, v19
	ds_read_b128 v[114:117], v33 offset:38912
	ds_read_b128 v[118:121], v33 offset:38928
	ds_read_b128 v[122:125], v33 offset:38944
	ds_read_b128 v[126:129], v33 offset:38960
	s_waitcnt lgkmcnt(3)
	v_pk_fma_f32 v[114:115], v[114:115], v[0:1], 0 op_sel_hi:[1,1,0]
	v_pk_fma_f32 v[116:117], v[116:117], v[6:7], 0 op_sel_hi:[1,1,0]
	s_waitcnt lgkmcnt(2)
	v_pk_fma_f32 v[114:115], v[118:119], v[8:9], v[114:115]
	v_pk_fma_f32 v[116:117], v[120:121], v[10:11], v[116:117]
	s_waitcnt lgkmcnt(1)
	v_pk_fma_f32 v[114:115], v[122:123], v[12:13], v[114:115]
	v_pk_fma_f32 v[116:117], v[124:125], v[16:17], v[116:117]
	s_waitcnt lgkmcnt(0)
	v_pk_fma_f32 v[114:115], v[126:127], v[20:21], v[114:115]
	v_pk_fma_f32 v[116:117], v[128:129], v[22:23], v[116:117]
	v_mov_b32_e32 v118, v114
	v_mov_b32_e32 v119, v116
	v_mov_b32_e32 v116, v115
	v_pk_add_f32 v[114:115], v[118:119], v[116:117]
	s_nop 0
	v_pk_add_f32 v[114:115], v[114:115], v[114:115] op_sel:[0,1] op_sel_hi:[1,0]
	s_nop 0
	v_pk_add_f32 v[24:25], v[24:25], v[114:115] neg_lo:[0,1] neg_hi:[0,1]
	ds_read_b128 v[114:117], v33 offset:39168
	ds_read_b128 v[118:121], v33 offset:39184
	ds_read_b128 v[122:125], v33 offset:39200
	ds_read_b128 v[126:129], v33 offset:39216
	ds_read_b32 v19, v33 offset:39232
	s_waitcnt lgkmcnt(4)
	v_pk_fma_f32 v[114:115], v[114:115], v[0:1], 0 op_sel_hi:[1,1,0]
	v_pk_fma_f32 v[116:117], v[116:117], v[6:7], 0 op_sel_hi:[1,1,0]
	s_waitcnt lgkmcnt(3)
	v_pk_fma_f32 v[114:115], v[118:119], v[8:9], v[114:115]
	v_pk_fma_f32 v[116:117], v[120:121], v[10:11], v[116:117]
	s_waitcnt lgkmcnt(2)
	v_pk_fma_f32 v[114:115], v[122:123], v[12:13], v[114:115]
	v_pk_fma_f32 v[116:117], v[124:125], v[16:17], v[116:117]
	s_waitcnt lgkmcnt(1)
	v_pk_fma_f32 v[114:115], v[126:127], v[20:21], v[114:115]
	v_pk_fma_f32 v[116:117], v[128:129], v[22:23], v[116:117]
	v_mov_b32_e32 v118, v114
	v_mov_b32_e32 v119, v116
	v_mov_b32_e32 v116, v115
	v_pk_add_f32 v[114:115], v[118:119], v[116:117]
	s_nop 0
	v_add_f32_e32 v25, v114, v115
	s_waitcnt lgkmcnt(0)
	v_fmac_f32_e32 v25, v24, v19
	v_sub_f32_e32 v25, v112, v25
	ds_read_b128 v[112:115], v33 offset:39424
	ds_read_b128 v[116:119], v33 offset:39440
	ds_read_b128 v[120:123], v33 offset:39456
	ds_read_b128 v[124:127], v33 offset:39472
	s_waitcnt lgkmcnt(3)
; DI void gdn_pre(const Params& p, int ch, char* smem) {
;     ...
; #pragma unroll
;   for (int i = 1; i < 64; ++i) {
;     f32x2 sa = {0.f, 0.f}, sb = {0.f, 0.f};
;     const f32x2* arow = (const f32x2*)(Amat + i * 64);
; #pragma unroll
;     for (int k = 0; k < (i >> 1); ++k) {
;       const f32x2 a2 = arow[k];
;       if (k & 1) sb = __builtin_elementwise_fma(a2, c2[k], sb);
;       else sa = __builtin_elementwise_fma(a2, c2[k], sa);
;     }
;     float tot = (sa[0] + sa[1]) + (sb[0] + sb[1]);
;     if (i & 1) tot += Amat[i * 64 + i - 1] * c2[(i - 1) >> 1][0];
;     c2[i >> 1][i & 1] -= tot;
;     __builtin_amdgcn_sched_barrier(0);
;   }
	v_pk_fma_f32 v[112:113], v[112:113], v[0:1], 0 op_sel_hi:[1,1,0]
	s_waitcnt lgkmcnt(2)
	v_pk_fma_f32 v[112:113], v[116:117], v[8:9], v[112:113]
	ds_read_b64 v[116:117], v33 offset:39488
	v_pk_fma_f32 v[114:115], v[114:115], v[6:7], 0 op_sel_hi:[1,1,0]
	s_waitcnt lgkmcnt(2)
	v_pk_fma_f32 v[112:113], v[120:121], v[12:13], v[112:113]
	v_pk_fma_f32 v[114:115], v[118:119], v[10:11], v[114:115]
	s_waitcnt lgkmcnt(1)
	v_pk_fma_f32 v[112:113], v[124:125], v[20:21], v[112:113]
	v_pk_fma_f32 v[114:115], v[122:123], v[16:17], v[114:115]
	s_waitcnt lgkmcnt(0)
	v_pk_fma_f32 v[112:113], v[116:117], v[24:25], v[112:113]
	v_pk_fma_f32 v[114:115], v[126:127], v[22:23], v[114:115]
	v_mov_b32_e32 v117, v112
	v_mov_b32_e32 v116, v114
	v_mov_b32_e32 v112, v115
	v_pk_add_f32 v[112:113], v[116:117], v[112:113]
	s_nop 0
	v_pk_add_f32 v[112:113], v[112:113], v[112:113] op_sel:[0,1] op_sel_hi:[1,0]
	s_nop 0
	v_pk_add_f32 v[26:27], v[26:27], v[112:113] neg_lo:[0,1] neg_hi:[0,1]
	ds_read_b128 v[112:115], v33 offset:39680
	ds_read_b128 v[116:119], v33 offset:39696
	ds_read_b128 v[120:123], v33 offset:39712
	ds_read_b128 v[124:127], v33 offset:39728
	s_waitcnt lgkmcnt(3)
	v_pk_fma_f32 v[112:113], v[112:113], v[0:1], 0 op_sel_hi:[1,1,0]
	v_pk_fma_f32 v[114:115], v[114:115], v[6:7], 0 op_sel_hi:[1,1,0]
	s_waitcnt lgkmcnt(2)
	v_pk_fma_f32 v[116:117], v[116:117], v[8:9], v[112:113]
	v_pk_fma_f32 v[118:119], v[118:119], v[10:11], v[114:115]
	ds_read_b96 v[112:114], v33 offset:39744
	s_waitcnt lgkmcnt(2)
	v_pk_fma_f32 v[116:117], v[120:121], v[12:13], v[116:117]
	v_pk_fma_f32 v[118:119], v[122:123], v[16:17], v[118:119]
	s_waitcnt lgkmcnt(1)
	v_pk_fma_f32 v[116:117], v[124:125], v[20:21], v[116:117]
	v_pk_fma_f32 v[118:119], v[126:127], v[22:23], v[118:119]
	s_waitcnt lgkmcnt(0)
	v_pk_fma_f32 v[112:113], v[112:113], v[24:25], v[116:117]
	v_mov_b32_e32 v116, v118
	v_mov_b32_e32 v117, v112
	v_mov_b32_e32 v112, v119
	v_pk_add_f32 v[112:113], v[116:117], v[112:113]
	s_nop 0
	v_add_f32_e32 v19, v112, v113
	v_fmac_f32_e32 v19, v26, v114
	v_sub_f32_e32 v27, v36, v19
	ds_read_b128 v[112:115], v33 offset:39936
	ds_read_b128 v[116:119], v33 offset:39952
	ds_read_b128 v[120:123], v33 offset:39968
	ds_read_b128 v[124:127], v33 offset:39984
	s_waitcnt lgkmcnt(3)
	v_pk_fma_f32 v[36:37], v[112:113], v[0:1], 0 op_sel_hi:[1,1,0]
	v_pk_fma_f32 v[112:113], v[114:115], v[6:7], 0 op_sel_hi:[1,1,0]
	s_waitcnt lgkmcnt(2)
	v_pk_fma_f32 v[36:37], v[116:117], v[8:9], v[36:37]
	v_pk_fma_f32 v[116:117], v[118:119], v[10:11], v[112:113]
	ds_read_b128 v[112:115], v33 offset:40000
	s_waitcnt lgkmcnt(2)
	v_pk_fma_f32 v[36:37], v[120:121], v[12:13], v[36:37]
	v_pk_fma_f32 v[116:117], v[122:123], v[16:17], v[116:117]
	s_waitcnt lgkmcnt(1)
	v_pk_fma_f32 v[36:37], v[124:125], v[20:21], v[36:37]
	v_pk_fma_f32 v[116:117], v[126:127], v[22:23], v[116:117]
	s_waitcnt lgkmcnt(0)
	v_pk_fma_f32 v[36:37], v[112:113], v[24:25], v[36:37]
	v_pk_fma_f32 v[112:113], v[114:115], v[26:27], v[116:117]
	v_mov_b32_e32 v114, v36
	v_mov_b32_e32 v115, v112
	v_mov_b32_e32 v112, v37
	v_pk_add_f32 v[36:37], v[114:115], v[112:113]
	s_nop 0
	v_pk_add_f32 v[36:37], v[36:37], v[36:37] op_sel:[0,1] op_sel_hi:[1,0]
	s_nop 0
	v_pk_add_f32 v[36:37], v[108:109], v[36:37] neg_lo:[0,1] neg_hi:[0,1]
	ds_read_b128 v[112:115], v33 offset:40192
	ds_read_b128 v[116:119], v33 offset:40208
	ds_read_b128 v[120:123], v33 offset:40224
	ds_read_b128 v[124:127], v33 offset:40240
	ds_read_b32 v19, v33 offset:40272
	s_waitcnt lgkmcnt(4)
	v_pk_fma_f32 v[108:109], v[112:113], v[0:1], 0 op_sel_hi:[1,1,0]
	v_pk_fma_f32 v[112:113], v[114:115], v[6:7], 0 op_sel_hi:[1,1,0]
	s_waitcnt lgkmcnt(3)
	v_pk_fma_f32 v[108:109], v[116:117], v[8:9], v[108:109]
	v_pk_fma_f32 v[116:117], v[118:119], v[10:11], v[112:113]
	ds_read_b128 v[112:115], v33 offset:40256
	s_waitcnt lgkmcnt(3)
	v_pk_fma_f32 v[108:109], v[120:121], v[12:13], v[108:109]
	v_pk_fma_f32 v[116:117], v[122:123], v[16:17], v[116:117]
	s_waitcnt lgkmcnt(2)
	v_pk_fma_f32 v[108:109], v[124:125], v[20:21], v[108:109]
	v_pk_fma_f32 v[116:117], v[126:127], v[22:23], v[116:117]
	s_waitcnt lgkmcnt(0)
	v_pk_fma_f32 v[108:109], v[112:113], v[24:25], v[108:109]
	v_pk_fma_f32 v[112:113], v[114:115], v[26:27], v[116:117]
	v_mov_b32_e32 v114, v108
	v_mov_b32_e32 v115, v112
	v_mov_b32_e32 v112, v109
	v_pk_add_f32 v[108:109], v[114:115], v[112:113]
	s_nop 0
	v_add_f32_e32 v31, v108, v109
	v_fmac_f32_e32 v31, v36, v19
	v_sub_f32_e32 v37, v38, v31
	ds_read_b128 v[112:115], v33 offset:40448
	ds_read_b128 v[116:119], v33 offset:40464
	ds_read_b128 v[120:123], v33 offset:40480
	ds_read_b128 v[124:127], v33 offset:40496
	s_waitcnt lgkmcnt(3)
	v_pk_fma_f32 v[38:39], v[112:113], v[0:1], 0 op_sel_hi:[1,1,0]
	v_pk_fma_f32 v[108:109], v[114:115], v[6:7], 0 op_sel_hi:[1,1,0]
	ds_read_b128 v[112:115], v33 offset:40512
	s_waitcnt lgkmcnt(3)
	v_pk_fma_f32 v[38:39], v[116:117], v[8:9], v[38:39]
	ds_read_b64 v[116:117], v33 offset:40528
	v_pk_fma_f32 v[108:109], v[118:119], v[10:11], v[108:109]
	s_waitcnt lgkmcnt(3)
	v_pk_fma_f32 v[38:39], v[120:121], v[12:13], v[38:39]
	v_pk_fma_f32 v[108:109], v[122:123], v[16:17], v[108:109]
	s_waitcnt lgkmcnt(2)
	v_pk_fma_f32 v[38:39], v[124:125], v[20:21], v[38:39]
	v_pk_fma_f32 v[108:109], v[126:127], v[22:23], v[108:109]
	s_waitcnt lgkmcnt(1)
	v_pk_fma_f32 v[38:39], v[112:113], v[24:25], v[38:39]
	v_pk_fma_f32 v[108:109], v[114:115], v[26:27], v[108:109]
	s_waitcnt lgkmcnt(0)
; DI void gdn_pre(const Params& p, int ch, char* smem) {
;     ...
; #pragma unroll
;   for (int i = 1; i < 64; ++i) {
;     f32x2 sa = {0.f, 0.f}, sb = {0.f, 0.f};
;     const f32x2* arow = (const f32x2*)(Amat + i * 64);
; #pragma unroll
;     for (int k = 0; k < (i >> 1); ++k) {
;       const f32x2 a2 = arow[k];
;       if (k & 1) sb = __builtin_elementwise_fma(a2, c2[k], sb);
;       else sa = __builtin_elementwise_fma(a2, c2[k], sa);
;     }
;     float tot = (sa[0] + sa[1]) + (sb[0] + sb[1]);
;     if (i & 1) tot += Amat[i * 64 + i - 1] * c2[(i - 1) >> 1][0];
;     c2[i >> 1][i & 1] -= tot;
;     __builtin_amdgcn_sched_barrier(0);
;   }
	v_pk_fma_f32 v[38:39], v[116:117], v[36:37], v[38:39]
	v_mov_b32_e32 v112, v108
	v_mov_b32_e32 v113, v38
	v_mov_b32_e32 v38, v109
	v_pk_add_f32 v[38:39], v[112:113], v[38:39]
	s_nop 0
	v_pk_add_f32 v[38:39], v[38:39], v[38:39] op_sel:[0,1] op_sel_hi:[1,0]
	s_nop 0
	v_pk_add_f32 v[38:39], v[106:107], v[38:39] neg_lo:[0,1] neg_hi:[0,1]
	ds_read_b128 v[106:109], v33 offset:40704
	ds_read_b128 v[112:115], v33 offset:40720
	ds_read_b128 v[116:119], v33 offset:40736
	ds_read_b128 v[120:123], v33 offset:40752
	s_waitcnt lgkmcnt(3)
	v_pk_fma_f32 v[106:107], v[106:107], v[0:1], 0 op_sel_hi:[1,1,0]
	v_pk_fma_f32 v[108:109], v[108:109], v[6:7], 0 op_sel_hi:[1,1,0]
	s_waitcnt lgkmcnt(2)
	v_pk_fma_f32 v[106:107], v[112:113], v[8:9], v[106:107]
	v_pk_fma_f32 v[112:113], v[114:115], v[10:11], v[108:109]
	s_waitcnt lgkmcnt(1)
	v_pk_fma_f32 v[116:117], v[116:117], v[12:13], v[106:107]
	ds_read_b128 v[106:109], v33 offset:40768
	v_pk_fma_f32 v[118:119], v[118:119], v[16:17], v[112:113]
	ds_read_b96 v[112:114], v33 offset:40784
	s_waitcnt lgkmcnt(2)
	v_pk_fma_f32 v[116:117], v[120:121], v[20:21], v[116:117]
	v_pk_fma_f32 v[118:119], v[122:123], v[22:23], v[118:119]
	s_waitcnt lgkmcnt(1)
	v_pk_fma_f32 v[106:107], v[106:107], v[24:25], v[116:117]
	v_pk_fma_f32 v[108:109], v[108:109], v[26:27], v[118:119]
	s_waitcnt lgkmcnt(0)
	v_pk_fma_f32 v[106:107], v[112:113], v[36:37], v[106:107]
	v_mov_b32_e32 v112, v108
	v_mov_b32_e32 v113, v106
	v_mov_b32_e32 v106, v109
	v_pk_add_f32 v[106:107], v[112:113], v[106:107]
	s_nop 0
	v_add_f32_e32 v19, v106, v107
	v_fmac_f32_e32 v19, v38, v114
	v_sub_f32_e32 v39, v110, v19
	ds_read_b128 v[106:109], v33 offset:40960
	ds_read_b128 v[110:113], v33 offset:40976
	ds_read_b128 v[114:117], v33 offset:40992
	ds_read_b128 v[118:121], v33 offset:41008
	s_waitcnt lgkmcnt(3)
	v_pk_fma_f32 v[106:107], v[106:107], v[0:1], 0 op_sel_hi:[1,1,0]
	v_pk_fma_f32 v[108:109], v[108:109], v[6:7], 0 op_sel_hi:[1,1,0]
	s_waitcnt lgkmcnt(2)
	v_pk_fma_f32 v[106:107], v[110:111], v[8:9], v[106:107]
	v_pk_fma_f32 v[110:111], v[112:113], v[10:11], v[108:109]
	s_waitcnt lgkmcnt(1)
	v_pk_fma_f32 v[114:115], v[114:115], v[12:13], v[106:107]
	ds_read_b128 v[106:109], v33 offset:41024
	v_pk_fma_f32 v[116:117], v[116:117], v[16:17], v[110:111]
	ds_read_b128 v[110:113], v33 offset:41040
	s_waitcnt lgkmcnt(2)
	v_pk_fma_f32 v[114:115], v[118:119], v[20:21], v[114:115]
	v_pk_fma_f32 v[116:117], v[120:121], v[22:23], v[116:117]
	s_waitcnt lgkmcnt(1)
	v_pk_fma_f32 v[106:107], v[106:107], v[24:25], v[114:115]
	v_pk_fma_f32 v[108:109], v[108:109], v[26:27], v[116:117]
	s_waitcnt lgkmcnt(0)
	v_pk_fma_f32 v[106:107], v[110:111], v[36:37], v[106:107]
	v_pk_fma_f32 v[108:109], v[112:113], v[38:39], v[108:109]
	v_mov_b32_e32 v110, v106
	v_mov_b32_e32 v111, v108
	v_mov_b32_e32 v108, v107
	v_pk_add_f32 v[106:107], v[110:111], v[108:109]
	s_nop 0
	v_pk_add_f32 v[106:107], v[106:107], v[106:107] op_sel:[0,1] op_sel_hi:[1,0]
	s_nop 0
	v_pk_add_f32 v[42:43], v[42:43], v[106:107] neg_lo:[0,1] neg_hi:[0,1]
	ds_read_b128 v[106:109], v33 offset:41216
	ds_read_b128 v[110:113], v33 offset:41232
	ds_read_b128 v[114:117], v33 offset:41248
	ds_read_b128 v[118:121], v33 offset:41264
	ds_read_b32 v19, v33 offset:41312
	s_waitcnt lgkmcnt(4)
	v_pk_fma_f32 v[106:107], v[106:107], v[0:1], 0 op_sel_hi:[1,1,0]
	v_pk_fma_f32 v[108:109], v[108:109], v[6:7], 0 op_sel_hi:[1,1,0]
	s_waitcnt lgkmcnt(3)
	v_pk_fma_f32 v[106:107], v[110:111], v[8:9], v[106:107]
	v_pk_fma_f32 v[110:111], v[112:113], v[10:11], v[108:109]
	s_waitcnt lgkmcnt(2)
	v_pk_fma_f32 v[114:115], v[114:115], v[12:13], v[106:107]
	ds_read_b128 v[106:109], v33 offset:41280
	v_pk_fma_f32 v[116:117], v[116:117], v[16:17], v[110:111]
	ds_read_b128 v[110:113], v33 offset:41296
	s_waitcnt lgkmcnt(3)
	v_pk_fma_f32 v[114:115], v[118:119], v[20:21], v[114:115]
	v_pk_fma_f32 v[116:117], v[120:121], v[22:23], v[116:117]
	s_waitcnt lgkmcnt(1)
	v_pk_fma_f32 v[106:107], v[106:107], v[24:25], v[114:115]
	v_pk_fma_f32 v[108:109], v[108:109], v[26:27], v[116:117]
	s_waitcnt lgkmcnt(0)
	v_pk_fma_f32 v[106:107], v[110:111], v[36:37], v[106:107]
	v_pk_fma_f32 v[108:109], v[112:113], v[38:39], v[108:109]
	v_mov_b32_e32 v110, v106
	v_mov_b32_e32 v111, v108
	v_mov_b32_e32 v108, v107
	v_pk_add_f32 v[106:107], v[110:111], v[108:109]
	s_nop 0
	v_add_f32_e32 v31, v106, v107
	v_fmac_f32_e32 v31, v42, v19
	v_sub_f32_e32 v43, v80, v31
	ds_read_b128 v[106:109], v33 offset:41472
	ds_read_b128 v[110:113], v33 offset:41488
	ds_read_b128 v[114:117], v33 offset:41504
	ds_read_b128 v[118:121], v33 offset:41520
	s_waitcnt lgkmcnt(3)
	v_pk_fma_f32 v[80:81], v[106:107], v[0:1], 0 op_sel_hi:[1,1,0]
	v_pk_fma_f32 v[106:107], v[108:109], v[6:7], 0 op_sel_hi:[1,1,0]
	s_waitcnt lgkmcnt(2)
	v_pk_fma_f32 v[80:81], v[110:111], v[8:9], v[80:81]
	v_pk_fma_f32 v[106:107], v[112:113], v[10:11], v[106:107]
	s_waitcnt lgkmcnt(1)
	v_pk_fma_f32 v[80:81], v[114:115], v[12:13], v[80:81]
	v_pk_fma_f32 v[114:115], v[116:117], v[16:17], v[106:107]
	ds_read_b128 v[106:109], v33 offset:41536
	ds_read_b128 v[110:113], v33 offset:41552
	ds_read_b64 v[116:117], v33 offset:41568
	s_waitcnt lgkmcnt(3)
	v_pk_fma_f32 v[80:81], v[118:119], v[20:21], v[80:81]
	v_pk_fma_f32 v[114:115], v[120:121], v[22:23], v[114:115]
	s_waitcnt lgkmcnt(2)
	v_pk_fma_f32 v[80:81], v[106:107], v[24:25], v[80:81]
	v_pk_fma_f32 v[106:107], v[108:109], v[26:27], v[114:115]
	s_waitcnt lgkmcnt(1)
	v_pk_fma_f32 v[80:81], v[110:111], v[36:37], v[80:81]
	v_pk_fma_f32 v[106:107], v[112:113], v[38:39], v[106:107]
	s_waitcnt lgkmcnt(0)
; DI void gdn_pre(const Params& p, int ch, char* smem) {
;     ...
; #pragma unroll
;   for (int i = 1; i < 64; ++i) {
;     f32x2 sa = {0.f, 0.f}, sb = {0.f, 0.f};
;     const f32x2* arow = (const f32x2*)(Amat + i * 64);
; #pragma unroll
;     for (int k = 0; k < (i >> 1); ++k) {
;       const f32x2 a2 = arow[k];
;       if (k & 1) sb = __builtin_elementwise_fma(a2, c2[k], sb);
;       else sa = __builtin_elementwise_fma(a2, c2[k], sa);
;     }
;     float tot = (sa[0] + sa[1]) + (sb[0] + sb[1]);
;     if (i & 1) tot += Amat[i * 64 + i - 1] * c2[(i - 1) >> 1][0];
;     c2[i >> 1][i & 1] -= tot;
;     __builtin_amdgcn_sched_barrier(0);
;   }
	v_pk_fma_f32 v[80:81], v[116:117], v[42:43], v[80:81]
	v_mov_b32_e32 v108, v106
	v_mov_b32_e32 v109, v80
	v_mov_b32_e32 v80, v107
	v_pk_add_f32 v[80:81], v[108:109], v[80:81]
	s_nop 0
	v_pk_add_f32 v[80:81], v[80:81], v[80:81] op_sel:[0,1] op_sel_hi:[1,0]
	s_nop 0
	v_pk_add_f32 v[46:47], v[46:47], v[80:81] neg_lo:[0,1] neg_hi:[0,1]
	ds_read_b128 v[106:109], v33 offset:41728
	ds_read_b128 v[110:113], v33 offset:41744
	ds_read_b128 v[114:117], v33 offset:41760
	ds_read_b128 v[118:121], v33 offset:41776
	s_waitcnt lgkmcnt(3)
	v_pk_fma_f32 v[80:81], v[106:107], v[0:1], 0 op_sel_hi:[1,1,0]
	v_pk_fma_f32 v[106:107], v[108:109], v[6:7], 0 op_sel_hi:[1,1,0]
	s_waitcnt lgkmcnt(2)
	v_pk_fma_f32 v[80:81], v[110:111], v[8:9], v[80:81]
	v_pk_fma_f32 v[106:107], v[112:113], v[10:11], v[106:107]
	s_waitcnt lgkmcnt(1)
	v_pk_fma_f32 v[80:81], v[114:115], v[12:13], v[80:81]
	v_pk_fma_f32 v[114:115], v[116:117], v[16:17], v[106:107]
	ds_read_b128 v[106:109], v33 offset:41792
	ds_read_b128 v[110:113], v33 offset:41808
	s_waitcnt lgkmcnt(2)
	v_pk_fma_f32 v[80:81], v[118:119], v[20:21], v[80:81]
	v_pk_fma_f32 v[118:119], v[120:121], v[22:23], v[114:115]
	ds_read_b96 v[114:116], v33 offset:41824
	s_waitcnt lgkmcnt(2)
	v_pk_fma_f32 v[80:81], v[106:107], v[24:25], v[80:81]
	v_pk_fma_f32 v[106:107], v[108:109], v[26:27], v[118:119]
	s_waitcnt lgkmcnt(1)
	v_pk_fma_f32 v[80:81], v[110:111], v[36:37], v[80:81]
	v_pk_fma_f32 v[106:107], v[112:113], v[38:39], v[106:107]
	s_waitcnt lgkmcnt(0)
	v_pk_fma_f32 v[80:81], v[114:115], v[42:43], v[80:81]
	v_mov_b32_e32 v108, v106
	v_mov_b32_e32 v109, v80
	v_mov_b32_e32 v80, v107
	v_pk_add_f32 v[80:81], v[108:109], v[80:81]
	s_nop 0
	v_add_f32_e32 v19, v80, v81
	v_fmac_f32_e32 v19, v46, v116
	v_sub_f32_e32 v47, v50, v19
	ds_read_b128 v[106:109], v33 offset:41984
	ds_read_b128 v[110:113], v33 offset:42000
	ds_read_b128 v[114:117], v33 offset:42016
	ds_read_b128 v[118:121], v33 offset:42032
	s_waitcnt lgkmcnt(3)
	v_pk_fma_f32 v[50:51], v[106:107], v[0:1], 0 op_sel_hi:[1,1,0]
	v_pk_fma_f32 v[80:81], v[108:109], v[6:7], 0 op_sel_hi:[1,1,0]
	ds_read_b128 v[106:109], v33 offset:42048
	s_waitcnt lgkmcnt(3)
	v_pk_fma_f32 v[50:51], v[110:111], v[8:9], v[50:51]
	v_pk_fma_f32 v[80:81], v[112:113], v[10:11], v[80:81]
	ds_read_b128 v[110:113], v33 offset:42064
	s_waitcnt lgkmcnt(3)
	v_pk_fma_f32 v[50:51], v[114:115], v[12:13], v[50:51]
	v_pk_fma_f32 v[80:81], v[116:117], v[16:17], v[80:81]
	ds_read_b128 v[114:117], v33 offset:42080
	s_waitcnt lgkmcnt(3)
	v_pk_fma_f32 v[50:51], v[118:119], v[20:21], v[50:51]
	v_pk_fma_f32 v[80:81], v[120:121], v[22:23], v[80:81]
	s_waitcnt lgkmcnt(2)
	v_pk_fma_f32 v[50:51], v[106:107], v[24:25], v[50:51]
	v_pk_fma_f32 v[80:81], v[108:109], v[26:27], v[80:81]
	s_waitcnt lgkmcnt(1)
	v_pk_fma_f32 v[50:51], v[110:111], v[36:37], v[50:51]
	v_pk_fma_f32 v[80:81], v[112:113], v[38:39], v[80:81]
	s_waitcnt lgkmcnt(0)
	v_pk_fma_f32 v[50:51], v[114:115], v[42:43], v[50:51]
	v_pk_fma_f32 v[80:81], v[116:117], v[46:47], v[80:81]
	v_mov_b32_e32 v106, v50
	v_mov_b32_e32 v107, v80
	v_mov_b32_e32 v80, v51
	v_pk_add_f32 v[50:51], v[106:107], v[80:81]
	s_nop 0
	v_pk_add_f32 v[50:51], v[50:51], v[50:51] op_sel:[0,1] op_sel_hi:[1,0]
	s_nop 0
	v_pk_add_f32 v[50:51], v[104:105], v[50:51] neg_lo:[0,1] neg_hi:[0,1]
	ds_read_b128 v[104:107], v33 offset:42240
	ds_read_b128 v[108:111], v33 offset:42256
	ds_read_b128 v[112:115], v33 offset:42272
	ds_read_b128 v[116:119], v33 offset:42288
	ds_read_b32 v19, v33 offset:42352
	s_waitcnt lgkmcnt(4)
	v_pk_fma_f32 v[80:81], v[104:105], v[0:1], 0 op_sel_hi:[1,1,0]
	v_pk_fma_f32 v[104:105], v[106:107], v[6:7], 0 op_sel_hi:[1,1,0]
	s_waitcnt lgkmcnt(3)
	v_pk_fma_f32 v[80:81], v[108:109], v[8:9], v[80:81]
	v_pk_fma_f32 v[108:109], v[110:111], v[10:11], v[104:105]
	ds_read_b128 v[104:107], v33 offset:42304
	s_waitcnt lgkmcnt(3)
	v_pk_fma_f32 v[80:81], v[112:113], v[12:13], v[80:81]
	v_pk_fma_f32 v[112:113], v[114:115], v[16:17], v[108:109]
	ds_read_b128 v[108:111], v33 offset:42320
	s_waitcnt lgkmcnt(3)
	v_pk_fma_f32 v[80:81], v[116:117], v[20:21], v[80:81]
	v_pk_fma_f32 v[116:117], v[118:119], v[22:23], v[112:113]
	ds_read_b128 v[112:115], v33 offset:42336
	s_waitcnt lgkmcnt(2)
	v_pk_fma_f32 v[80:81], v[104:105], v[24:25], v[80:81]
	v_pk_fma_f32 v[104:105], v[106:107], v[26:27], v[116:117]
	s_waitcnt lgkmcnt(1)
	v_pk_fma_f32 v[80:81], v[108:109], v[36:37], v[80:81]
	v_pk_fma_f32 v[104:105], v[110:111], v[38:39], v[104:105]
	s_waitcnt lgkmcnt(0)
	v_pk_fma_f32 v[80:81], v[112:113], v[42:43], v[80:81]
	v_pk_fma_f32 v[104:105], v[114:115], v[46:47], v[104:105]
	v_mov_b32_e32 v106, v80
	v_mov_b32_e32 v107, v104
	v_mov_b32_e32 v104, v81
	v_pk_add_f32 v[80:81], v[106:107], v[104:105]
	s_nop 0
	v_add_f32_e32 v31, v80, v81
	v_fmac_f32_e32 v31, v50, v19
	v_sub_f32_e32 v51, v54, v31
	ds_read_b128 v[104:107], v33 offset:42496
	ds_read_b128 v[108:111], v33 offset:42512
	ds_read_b128 v[112:115], v33 offset:42528
	ds_read_b128 v[116:119], v33 offset:42544
	s_waitcnt lgkmcnt(3)
	v_pk_fma_f32 v[54:55], v[104:105], v[0:1], 0 op_sel_hi:[1,1,0]
	v_pk_fma_f32 v[80:81], v[106:107], v[6:7], 0 op_sel_hi:[1,1,0]
	ds_read_b128 v[104:107], v33 offset:42560
	s_waitcnt lgkmcnt(3)
	v_pk_fma_f32 v[54:55], v[108:109], v[8:9], v[54:55]
	v_pk_fma_f32 v[80:81], v[110:111], v[10:11], v[80:81]
	s_waitcnt lgkmcnt(2)
	v_pk_fma_f32 v[54:55], v[112:113], v[12:13], v[54:55]
	ds_read_b128 v[108:111], v33 offset:42576
	v_pk_fma_f32 v[80:81], v[114:115], v[16:17], v[80:81]
	s_waitcnt lgkmcnt(2)
	v_pk_fma_f32 v[54:55], v[116:117], v[20:21], v[54:55]
	ds_read_b128 v[112:115], v33 offset:42592
	s_waitcnt lgkmcnt(2)
; DI void gdn_pre(const Params& p, int ch, char* smem) {
;     ...
; #pragma unroll
;   for (int i = 1; i < 64; ++i) {
;     f32x2 sa = {0.f, 0.f}, sb = {0.f, 0.f};
;     const f32x2* arow = (const f32x2*)(Amat + i * 64);
; #pragma unroll
;     for (int k = 0; k < (i >> 1); ++k) {
;       const f32x2 a2 = arow[k];
;       if (k & 1) sb = __builtin_elementwise_fma(a2, c2[k], sb);
;       else sa = __builtin_elementwise_fma(a2, c2[k], sa);
;     }
;     float tot = (sa[0] + sa[1]) + (sb[0] + sb[1]);
;     if (i & 1) tot += Amat[i * 64 + i - 1] * c2[(i - 1) >> 1][0];
;     c2[i >> 1][i & 1] -= tot;
;     __builtin_amdgcn_sched_barrier(0);
;   }
	v_pk_fma_f32 v[54:55], v[104:105], v[24:25], v[54:55]
	ds_read_b64 v[104:105], v33 offset:42608
	v_pk_fma_f32 v[80:81], v[118:119], v[22:23], v[80:81]
	s_waitcnt lgkmcnt(2)
	v_pk_fma_f32 v[54:55], v[108:109], v[36:37], v[54:55]
	v_pk_fma_f32 v[80:81], v[106:107], v[26:27], v[80:81]
	s_waitcnt lgkmcnt(1)
	v_pk_fma_f32 v[54:55], v[112:113], v[42:43], v[54:55]
	v_pk_fma_f32 v[80:81], v[110:111], v[38:39], v[80:81]
	s_waitcnt lgkmcnt(0)
	v_pk_fma_f32 v[54:55], v[104:105], v[50:51], v[54:55]
	v_pk_fma_f32 v[80:81], v[114:115], v[46:47], v[80:81]
	v_mov_b32_e32 v105, v54
	v_mov_b32_e32 v104, v80
	v_mov_b32_e32 v54, v81
	v_pk_add_f32 v[54:55], v[104:105], v[54:55]
	s_nop 0
	v_pk_add_f32 v[54:55], v[54:55], v[54:55] op_sel:[0,1] op_sel_hi:[1,0]
	s_nop 0
	v_pk_add_f32 v[54:55], v[102:103], v[54:55] neg_lo:[0,1] neg_hi:[0,1]
	ds_read_b128 v[102:105], v33 offset:42752
	ds_read_b128 v[106:109], v33 offset:42768
	ds_read_b128 v[110:113], v33 offset:42784
	ds_read_b128 v[114:117], v33 offset:42800
	s_waitcnt lgkmcnt(3)
	v_pk_fma_f32 v[80:81], v[102:103], v[0:1], 0 op_sel_hi:[1,1,0]
	v_pk_fma_f32 v[102:103], v[104:105], v[6:7], 0 op_sel_hi:[1,1,0]
	s_waitcnt lgkmcnt(2)
	v_pk_fma_f32 v[80:81], v[106:107], v[8:9], v[80:81]
	v_pk_fma_f32 v[106:107], v[108:109], v[10:11], v[102:103]
	ds_read_b128 v[102:105], v33 offset:42816
	s_waitcnt lgkmcnt(2)
	v_pk_fma_f32 v[80:81], v[110:111], v[12:13], v[80:81]
	v_pk_fma_f32 v[106:107], v[112:113], v[16:17], v[106:107]
	s_waitcnt lgkmcnt(1)
	v_pk_fma_f32 v[80:81], v[114:115], v[20:21], v[80:81]
	v_pk_fma_f32 v[114:115], v[116:117], v[22:23], v[106:107]
	ds_read_b128 v[106:109], v33 offset:42832
	ds_read_b128 v[110:113], v33 offset:42848
	s_waitcnt lgkmcnt(2)
	v_pk_fma_f32 v[80:81], v[102:103], v[24:25], v[80:81]
	v_pk_fma_f32 v[114:115], v[104:105], v[26:27], v[114:115]
	ds_read_b96 v[102:104], v33 offset:42864
	s_waitcnt lgkmcnt(2)
	v_pk_fma_f32 v[80:81], v[106:107], v[36:37], v[80:81]
	v_pk_fma_f32 v[106:107], v[108:109], v[38:39], v[114:115]
	s_waitcnt lgkmcnt(1)
	v_pk_fma_f32 v[80:81], v[110:111], v[42:43], v[80:81]
	v_pk_fma_f32 v[106:107], v[112:113], v[46:47], v[106:107]
	s_waitcnt lgkmcnt(0)
	v_pk_fma_f32 v[80:81], v[102:103], v[50:51], v[80:81]
	v_mov_b32_e32 v102, v106
	v_mov_b32_e32 v103, v80
	v_mov_b32_e32 v80, v107
	v_pk_add_f32 v[80:81], v[102:103], v[80:81]
	s_nop 0
	v_add_f32_e32 v19, v80, v81
	v_fmac_f32_e32 v19, v54, v104
	v_sub_f32_e32 v55, v56, v19
	ds_read_b128 v[102:105], v33 offset:43008
	ds_read_b128 v[106:109], v33 offset:43024
	ds_read_b128 v[110:113], v33 offset:43040
	ds_read_b128 v[114:117], v33 offset:43056
	s_waitcnt lgkmcnt(3)
	v_pk_fma_f32 v[56:57], v[102:103], v[0:1], 0 op_sel_hi:[1,1,0]
	v_pk_fma_f32 v[80:81], v[104:105], v[6:7], 0 op_sel_hi:[1,1,0]
	ds_read_b128 v[102:105], v33 offset:43072
	s_waitcnt lgkmcnt(3)
	v_pk_fma_f32 v[56:57], v[106:107], v[8:9], v[56:57]
	v_pk_fma_f32 v[80:81], v[108:109], v[10:11], v[80:81]
	s_waitcnt lgkmcnt(2)
	v_pk_fma_f32 v[56:57], v[110:111], v[12:13], v[56:57]
	v_pk_fma_f32 v[80:81], v[112:113], v[16:17], v[80:81]
	ds_read_b128 v[106:109], v33 offset:43088
	s_waitcnt lgkmcnt(2)
	v_pk_fma_f32 v[56:57], v[114:115], v[20:21], v[56:57]
	v_pk_fma_f32 v[80:81], v[116:117], v[22:23], v[80:81]
	ds_read_b128 v[110:113], v33 offset:43104
	s_waitcnt lgkmcnt(2)
	v_pk_fma_f32 v[56:57], v[102:103], v[24:25], v[56:57]
	v_pk_fma_f32 v[80:81], v[104:105], v[26:27], v[80:81]
	ds_read_b128 v[102:105], v33 offset:43120
	s_waitcnt lgkmcnt(2)
	v_pk_fma_f32 v[56:57], v[106:107], v[36:37], v[56:57]
	v_pk_fma_f32 v[80:81], v[108:109], v[38:39], v[80:81]
	s_waitcnt lgkmcnt(1)
	v_pk_fma_f32 v[56:57], v[110:111], v[42:43], v[56:57]
	v_pk_fma_f32 v[80:81], v[112:113], v[46:47], v[80:81]
	s_waitcnt lgkmcnt(0)
	v_pk_fma_f32 v[56:57], v[102:103], v[50:51], v[56:57]
	v_pk_fma_f32 v[80:81], v[104:105], v[54:55], v[80:81]
	v_mov_b32_e32 v102, v56
	v_mov_b32_e32 v103, v80
	v_mov_b32_e32 v80, v57
	v_pk_add_f32 v[56:57], v[102:103], v[80:81]
	s_nop 0
	v_pk_add_f32 v[56:57], v[56:57], v[56:57] op_sel:[0,1] op_sel_hi:[1,0]
	s_nop 0
	v_pk_add_f32 v[56:57], v[100:101], v[56:57] neg_lo:[0,1] neg_hi:[0,1]
	ds_read_b128 v[100:103], v33 offset:43264
	ds_read_b128 v[104:107], v33 offset:43280
	ds_read_b128 v[108:111], v33 offset:43296
	ds_read_b128 v[112:115], v33 offset:43312
	ds_read_b32 v19, v33 offset:43392
	s_waitcnt lgkmcnt(4)
	v_pk_fma_f32 v[80:81], v[100:101], v[0:1], 0 op_sel_hi:[1,1,0]
	v_pk_fma_f32 v[100:101], v[102:103], v[6:7], 0 op_sel_hi:[1,1,0]
	s_waitcnt lgkmcnt(3)
	v_pk_fma_f32 v[80:81], v[104:105], v[8:9], v[80:81]
	v_pk_fma_f32 v[104:105], v[106:107], v[10:11], v[100:101]
	ds_read_b128 v[100:103], v33 offset:43328
	s_waitcnt lgkmcnt(3)
	v_pk_fma_f32 v[80:81], v[108:109], v[12:13], v[80:81]
	v_pk_fma_f32 v[104:105], v[110:111], v[16:17], v[104:105]
	s_waitcnt lgkmcnt(2)
	v_pk_fma_f32 v[80:81], v[112:113], v[20:21], v[80:81]
	v_pk_fma_f32 v[112:113], v[114:115], v[22:23], v[104:105]
	ds_read_b128 v[104:107], v33 offset:43344
	ds_read_b128 v[108:111], v33 offset:43360
	s_waitcnt lgkmcnt(2)
	v_pk_fma_f32 v[80:81], v[100:101], v[24:25], v[80:81]
	v_pk_fma_f32 v[112:113], v[102:103], v[26:27], v[112:113]
	ds_read_b128 v[100:103], v33 offset:43376
	s_waitcnt lgkmcnt(2)
	v_pk_fma_f32 v[80:81], v[104:105], v[36:37], v[80:81]
	v_pk_fma_f32 v[104:105], v[106:107], v[38:39], v[112:113]
	s_waitcnt lgkmcnt(1)
	v_pk_fma_f32 v[80:81], v[108:109], v[42:43], v[80:81]
	v_pk_fma_f32 v[104:105], v[110:111], v[46:47], v[104:105]
	s_waitcnt lgkmcnt(0)
; DI void gdn_pre(const Params& p, int ch, char* smem) {
;     ...
; #pragma unroll
;   for (int i = 1; i < 64; ++i) {
;     f32x2 sa = {0.f, 0.f}, sb = {0.f, 0.f};
;     const f32x2* arow = (const f32x2*)(Amat + i * 64);
; #pragma unroll
;     for (int k = 0; k < (i >> 1); ++k) {
;       const f32x2 a2 = arow[k];
;       if (k & 1) sb = __builtin_elementwise_fma(a2, c2[k], sb);
;       else sa = __builtin_elementwise_fma(a2, c2[k], sa);
;     }
;     float tot = (sa[0] + sa[1]) + (sb[0] + sb[1]);
;     if (i & 1) tot += Amat[i * 64 + i - 1] * c2[(i - 1) >> 1][0];
;     c2[i >> 1][i & 1] -= tot;
;     __builtin_amdgcn_sched_barrier(0);
;   }
	v_pk_fma_f32 v[80:81], v[100:101], v[50:51], v[80:81]
	v_pk_fma_f32 v[100:101], v[102:103], v[54:55], v[104:105]
	v_mov_b32_e32 v102, v80
	v_mov_b32_e32 v103, v100
	v_mov_b32_e32 v100, v81
	v_pk_add_f32 v[80:81], v[102:103], v[100:101]
	s_nop 0
	v_add_f32_e32 v31, v80, v81
	v_fmac_f32_e32 v31, v56, v19
	v_sub_f32_e32 v57, v60, v31
	ds_read_b128 v[100:103], v33 offset:43520
	ds_read_b128 v[104:107], v33 offset:43536
	ds_read_b128 v[108:111], v33 offset:43552
	ds_read_b128 v[112:115], v33 offset:43568
	s_waitcnt lgkmcnt(3)
	v_pk_fma_f32 v[60:61], v[100:101], v[0:1], 0 op_sel_hi:[1,1,0]
	v_pk_fma_f32 v[80:81], v[102:103], v[6:7], 0 op_sel_hi:[1,1,0]
	ds_read_b128 v[100:103], v33 offset:43584
	s_waitcnt lgkmcnt(3)
	v_pk_fma_f32 v[60:61], v[104:105], v[8:9], v[60:61]
	v_pk_fma_f32 v[80:81], v[106:107], v[10:11], v[80:81]
	ds_read_b128 v[104:107], v33 offset:43600
	s_waitcnt lgkmcnt(3)
	v_pk_fma_f32 v[60:61], v[108:109], v[12:13], v[60:61]
	v_pk_fma_f32 v[80:81], v[110:111], v[16:17], v[80:81]
	s_waitcnt lgkmcnt(2)
	v_pk_fma_f32 v[60:61], v[112:113], v[20:21], v[60:61]
	v_pk_fma_f32 v[80:81], v[114:115], v[22:23], v[80:81]
	s_waitcnt lgkmcnt(1)
	v_pk_fma_f32 v[60:61], v[100:101], v[24:25], v[60:61]
	v_pk_fma_f32 v[80:81], v[102:103], v[26:27], v[80:81]
	ds_read_b128 v[100:103], v33 offset:43616
	ds_read_b128 v[108:111], v33 offset:43632
	s_waitcnt lgkmcnt(2)
	v_pk_fma_f32 v[60:61], v[104:105], v[36:37], v[60:61]
	ds_read_b64 v[104:105], v33 offset:43648
	v_pk_fma_f32 v[80:81], v[106:107], v[38:39], v[80:81]
	s_waitcnt lgkmcnt(2)
	v_pk_fma_f32 v[60:61], v[100:101], v[42:43], v[60:61]
	v_pk_fma_f32 v[80:81], v[102:103], v[46:47], v[80:81]
	s_waitcnt lgkmcnt(1)
	v_pk_fma_f32 v[60:61], v[108:109], v[50:51], v[60:61]
	v_pk_fma_f32 v[80:81], v[110:111], v[54:55], v[80:81]
	s_waitcnt lgkmcnt(0)
	v_pk_fma_f32 v[60:61], v[104:105], v[56:57], v[60:61]
	v_mov_b32_e32 v100, v80
	v_mov_b32_e32 v101, v60
	v_mov_b32_e32 v60, v81
	v_pk_add_f32 v[60:61], v[100:101], v[60:61]
	s_nop 0
	v_pk_add_f32 v[60:61], v[60:61], v[60:61] op_sel:[0,1] op_sel_hi:[1,0]
	s_nop 0
	v_pk_add_f32 v[60:61], v[98:99], v[60:61] neg_lo:[0,1] neg_hi:[0,1]
	ds_read_b128 v[98:101], v33 offset:43776
	ds_read_b128 v[102:105], v33 offset:43792
	ds_read_b128 v[106:109], v33 offset:43808
	ds_read_b128 v[110:113], v33 offset:43824
	s_waitcnt lgkmcnt(3)
	v_pk_fma_f32 v[80:81], v[98:99], v[0:1], 0 op_sel_hi:[1,1,0]
	v_pk_fma_f32 v[98:99], v[100:101], v[6:7], 0 op_sel_hi:[1,1,0]
	s_waitcnt lgkmcnt(2)
	v_pk_fma_f32 v[80:81], v[102:103], v[8:9], v[80:81]
	v_pk_fma_f32 v[102:103], v[104:105], v[10:11], v[98:99]
	ds_read_b128 v[98:101], v33 offset:43840
	s_waitcnt lgkmcnt(2)
	v_pk_fma_f32 v[80:81], v[106:107], v[12:13], v[80:81]
	v_pk_fma_f32 v[106:107], v[108:109], v[16:17], v[102:103]
	ds_read_b128 v[102:105], v33 offset:43856
	s_waitcnt lgkmcnt(2)
	v_pk_fma_f32 v[80:81], v[110:111], v[20:21], v[80:81]
	v_pk_fma_f32 v[106:107], v[112:113], v[22:23], v[106:107]
	s_waitcnt lgkmcnt(1)
	v_pk_fma_f32 v[80:81], v[98:99], v[24:25], v[80:81]
	v_pk_fma_f32 v[110:111], v[100:101], v[26:27], v[106:107]
	ds_read_b128 v[98:101], v33 offset:43872
	ds_read_b128 v[106:109], v33 offset:43888
	s_waitcnt lgkmcnt(2)
	v_pk_fma_f32 v[80:81], v[102:103], v[36:37], v[80:81]
	v_pk_fma_f32 v[110:111], v[104:105], v[38:39], v[110:111]
	ds_read_b96 v[102:104], v33 offset:43904
	s_waitcnt lgkmcnt(2)
	v_pk_fma_f32 v[80:81], v[98:99], v[42:43], v[80:81]
	v_pk_fma_f32 v[98:99], v[100:101], v[46:47], v[110:111]
	s_waitcnt lgkmcnt(1)
	v_pk_fma_f32 v[80:81], v[106:107], v[50:51], v[80:81]
	v_pk_fma_f32 v[98:99], v[108:109], v[54:55], v[98:99]
	s_waitcnt lgkmcnt(0)
	v_pk_fma_f32 v[80:81], v[102:103], v[56:57], v[80:81]
	v_mov_b32_e32 v100, v98
	v_mov_b32_e32 v101, v80
	v_mov_b32_e32 v80, v99
	v_pk_add_f32 v[80:81], v[100:101], v[80:81]
	s_nop 0
	v_add_f32_e32 v19, v80, v81
	v_fmac_f32_e32 v19, v60, v104
	v_sub_f32_e32 v61, v64, v19
	ds_read_b128 v[98:101], v33 offset:44032
	ds_read_b128 v[102:105], v33 offset:44048
	ds_read_b128 v[106:109], v33 offset:44064
	ds_read_b128 v[110:113], v33 offset:44080
	s_waitcnt lgkmcnt(3)
	v_pk_fma_f32 v[64:65], v[98:99], v[0:1], 0 op_sel_hi:[1,1,0]
	v_pk_fma_f32 v[80:81], v[100:101], v[6:7], 0 op_sel_hi:[1,1,0]
	ds_read_b128 v[98:101], v33 offset:44096
	s_waitcnt lgkmcnt(3)
	v_pk_fma_f32 v[64:65], v[102:103], v[8:9], v[64:65]
	v_pk_fma_f32 v[80:81], v[104:105], v[10:11], v[80:81]
	ds_read_b128 v[102:105], v33 offset:44112
	s_waitcnt lgkmcnt(3)
	v_pk_fma_f32 v[64:65], v[106:107], v[12:13], v[64:65]
	v_pk_fma_f32 v[80:81], v[108:109], v[16:17], v[80:81]
	s_waitcnt lgkmcnt(2)
	v_pk_fma_f32 v[64:65], v[110:111], v[20:21], v[64:65]
	v_pk_fma_f32 v[80:81], v[112:113], v[22:23], v[80:81]
	s_waitcnt lgkmcnt(1)
	v_pk_fma_f32 v[64:65], v[98:99], v[24:25], v[64:65]
	v_pk_fma_f32 v[80:81], v[100:101], v[26:27], v[80:81]
	ds_read_b128 v[98:101], v33 offset:44128
	ds_read_b128 v[106:109], v33 offset:44144
	s_waitcnt lgkmcnt(2)
	v_pk_fma_f32 v[64:65], v[102:103], v[36:37], v[64:65]
	v_pk_fma_f32 v[80:81], v[104:105], v[38:39], v[80:81]
	ds_read_b128 v[102:105], v33 offset:44160
	s_waitcnt lgkmcnt(2)
	v_pk_fma_f32 v[64:65], v[98:99], v[42:43], v[64:65]
	v_pk_fma_f32 v[80:81], v[100:101], v[46:47], v[80:81]
	s_waitcnt lgkmcnt(1)
	v_pk_fma_f32 v[64:65], v[106:107], v[50:51], v[64:65]
	v_pk_fma_f32 v[80:81], v[108:109], v[54:55], v[80:81]
	s_waitcnt lgkmcnt(0)
; DI void gdn_pre(const Params& p, int ch, char* smem) {
;     ...
; #pragma unroll
;   for (int i = 1; i < 64; ++i) {
;     f32x2 sa = {0.f, 0.f}, sb = {0.f, 0.f};
;     const f32x2* arow = (const f32x2*)(Amat + i * 64);
; #pragma unroll
;     for (int k = 0; k < (i >> 1); ++k) {
;       const f32x2 a2 = arow[k];
;       if (k & 1) sb = __builtin_elementwise_fma(a2, c2[k], sb);
;       else sa = __builtin_elementwise_fma(a2, c2[k], sa);
;     }
;     float tot = (sa[0] + sa[1]) + (sb[0] + sb[1]);
;     if (i & 1) tot += Amat[i * 64 + i - 1] * c2[(i - 1) >> 1][0];
;     c2[i >> 1][i & 1] -= tot;
;     __builtin_amdgcn_sched_barrier(0);
;   }
	v_pk_fma_f32 v[64:65], v[102:103], v[56:57], v[64:65]
	v_pk_fma_f32 v[80:81], v[104:105], v[60:61], v[80:81]
	v_mov_b32_e32 v98, v64
	v_mov_b32_e32 v99, v80
	v_mov_b32_e32 v80, v65
	v_pk_add_f32 v[64:65], v[98:99], v[80:81]
	s_nop 0
	v_pk_add_f32 v[64:65], v[64:65], v[64:65] op_sel:[0,1] op_sel_hi:[1,0]
	s_nop 0
	v_pk_add_f32 v[64:65], v[96:97], v[64:65] neg_lo:[0,1] neg_hi:[0,1]
	ds_read_b128 v[96:99], v33 offset:44288
	ds_read_b128 v[100:103], v33 offset:44304
	ds_read_b128 v[104:107], v33 offset:44320
	ds_read_b128 v[108:111], v33 offset:44336
	ds_read_b32 v19, v33 offset:44432
	s_waitcnt lgkmcnt(4)
	v_pk_fma_f32 v[80:81], v[96:97], v[0:1], 0 op_sel_hi:[1,1,0]
	v_pk_fma_f32 v[96:97], v[98:99], v[6:7], 0 op_sel_hi:[1,1,0]
	s_waitcnt lgkmcnt(3)
	v_pk_fma_f32 v[80:81], v[100:101], v[8:9], v[80:81]
	v_pk_fma_f32 v[100:101], v[102:103], v[10:11], v[96:97]
	ds_read_b128 v[96:99], v33 offset:44352
	s_waitcnt lgkmcnt(3)
	v_pk_fma_f32 v[80:81], v[104:105], v[12:13], v[80:81]
	v_pk_fma_f32 v[104:105], v[106:107], v[16:17], v[100:101]
	ds_read_b128 v[100:103], v33 offset:44368
	s_waitcnt lgkmcnt(3)
	v_pk_fma_f32 v[80:81], v[108:109], v[20:21], v[80:81]
	v_pk_fma_f32 v[108:109], v[110:111], v[22:23], v[104:105]
	ds_read_b128 v[104:107], v33 offset:44384
	s_waitcnt lgkmcnt(2)
	v_pk_fma_f32 v[80:81], v[96:97], v[24:25], v[80:81]
	v_pk_fma_f32 v[108:109], v[98:99], v[26:27], v[108:109]
	ds_read_b128 v[96:99], v33 offset:44400
	s_waitcnt lgkmcnt(2)
	v_pk_fma_f32 v[80:81], v[100:101], v[36:37], v[80:81]
	v_pk_fma_f32 v[108:109], v[102:103], v[38:39], v[108:109]
	ds_read_b128 v[100:103], v33 offset:44416
	s_waitcnt lgkmcnt(2)
	v_pk_fma_f32 v[80:81], v[104:105], v[42:43], v[80:81]
	v_pk_fma_f32 v[104:105], v[106:107], v[46:47], v[108:109]
	s_waitcnt lgkmcnt(1)
	v_pk_fma_f32 v[80:81], v[96:97], v[50:51], v[80:81]
	v_pk_fma_f32 v[96:97], v[98:99], v[54:55], v[104:105]
	s_waitcnt lgkmcnt(0)
	v_pk_fma_f32 v[80:81], v[100:101], v[56:57], v[80:81]
	v_pk_fma_f32 v[96:97], v[102:103], v[60:61], v[96:97]
	v_mov_b32_e32 v98, v80
	v_mov_b32_e32 v99, v96
	v_mov_b32_e32 v96, v81
	v_pk_add_f32 v[80:81], v[98:99], v[96:97]
	s_nop 0
	v_add_f32_e32 v31, v80, v81
	v_fmac_f32_e32 v31, v64, v19
	v_sub_f32_e32 v65, v68, v31
	ds_read_b128 v[96:99], v33 offset:44544
	ds_read_b128 v[100:103], v33 offset:44560
	ds_read_b128 v[104:107], v33 offset:44576
	ds_read_b128 v[108:111], v33 offset:44592
	s_waitcnt lgkmcnt(3)
	v_pk_fma_f32 v[68:69], v[96:97], v[0:1], 0 op_sel_hi:[1,1,0]
	v_pk_fma_f32 v[80:81], v[98:99], v[6:7], 0 op_sel_hi:[1,1,0]
	ds_read_b128 v[96:99], v33 offset:44608
	s_waitcnt lgkmcnt(3)
	v_pk_fma_f32 v[68:69], v[100:101], v[8:9], v[68:69]
	v_pk_fma_f32 v[80:81], v[102:103], v[10:11], v[80:81]
	ds_read_b128 v[100:103], v33 offset:44624
	s_waitcnt lgkmcnt(3)
	v_pk_fma_f32 v[68:69], v[104:105], v[12:13], v[68:69]
	v_pk_fma_f32 v[80:81], v[106:107], v[16:17], v[80:81]
	ds_read_b128 v[104:107], v33 offset:44640
	s_waitcnt lgkmcnt(3)
	v_pk_fma_f32 v[68:69], v[108:109], v[20:21], v[68:69]
	v_pk_fma_f32 v[80:81], v[110:111], v[22:23], v[80:81]
	s_waitcnt lgkmcnt(2)
	v_pk_fma_f32 v[68:69], v[96:97], v[24:25], v[68:69]
	v_pk_fma_f32 v[80:81], v[98:99], v[26:27], v[80:81]
	ds_read_b128 v[96:99], v33 offset:44656
	s_waitcnt lgkmcnt(2)
	v_pk_fma_f32 v[68:69], v[100:101], v[36:37], v[68:69]
	v_pk_fma_f32 v[80:81], v[102:103], v[38:39], v[80:81]
	ds_read_b128 v[100:103], v33 offset:44672
	s_waitcnt lgkmcnt(2)
	v_pk_fma_f32 v[68:69], v[104:105], v[42:43], v[68:69]
	ds_read_b64 v[104:105], v33 offset:44688
	v_pk_fma_f32 v[80:81], v[106:107], v[46:47], v[80:81]
	s_waitcnt lgkmcnt(2)
	v_pk_fma_f32 v[68:69], v[96:97], v[50:51], v[68:69]
	v_pk_fma_f32 v[80:81], v[98:99], v[54:55], v[80:81]
	s_waitcnt lgkmcnt(1)
	v_pk_fma_f32 v[68:69], v[100:101], v[56:57], v[68:69]
	v_pk_fma_f32 v[80:81], v[102:103], v[60:61], v[80:81]
	s_waitcnt lgkmcnt(0)
	v_pk_fma_f32 v[68:69], v[104:105], v[64:65], v[68:69]
	v_mov_b32_e32 v96, v80
	v_mov_b32_e32 v97, v68
	v_mov_b32_e32 v68, v81
	v_pk_add_f32 v[68:69], v[96:97], v[68:69]
	s_nop 0
	v_pk_add_f32 v[68:69], v[68:69], v[68:69] op_sel:[0,1] op_sel_hi:[1,0]
	s_nop 0
	v_pk_add_f32 v[68:69], v[94:95], v[68:69] neg_lo:[0,1] neg_hi:[0,1]
	ds_read_b128 v[94:97], v33 offset:44800
	ds_read_b128 v[98:101], v33 offset:44816
	ds_read_b128 v[102:105], v33 offset:44832
	ds_read_b128 v[106:109], v33 offset:44848
	s_waitcnt lgkmcnt(3)
	v_pk_fma_f32 v[80:81], v[94:95], v[0:1], 0 op_sel_hi:[1,1,0]
	v_pk_fma_f32 v[94:95], v[96:97], v[6:7], 0 op_sel_hi:[1,1,0]
	s_waitcnt lgkmcnt(2)
	v_pk_fma_f32 v[80:81], v[98:99], v[8:9], v[80:81]
	v_pk_fma_f32 v[98:99], v[100:101], v[10:11], v[94:95]
	ds_read_b128 v[94:97], v33 offset:44864
	s_waitcnt lgkmcnt(2)
	v_pk_fma_f32 v[80:81], v[102:103], v[12:13], v[80:81]
	v_pk_fma_f32 v[102:103], v[104:105], v[16:17], v[98:99]
	ds_read_b128 v[98:101], v33 offset:44880
	s_waitcnt lgkmcnt(2)
	v_pk_fma_f32 v[80:81], v[106:107], v[20:21], v[80:81]
	v_pk_fma_f32 v[106:107], v[108:109], v[22:23], v[102:103]
	ds_read_b128 v[102:105], v33 offset:44896
	s_waitcnt lgkmcnt(2)
	v_pk_fma_f32 v[80:81], v[94:95], v[24:25], v[80:81]
	v_pk_fma_f32 v[94:95], v[96:97], v[26:27], v[106:107]
	s_waitcnt lgkmcnt(1)
	v_pk_fma_f32 v[80:81], v[98:99], v[36:37], v[80:81]
	v_pk_fma_f32 v[106:107], v[100:101], v[38:39], v[94:95]
	ds_read_b128 v[94:97], v33 offset:44912
	ds_read_b128 v[98:101], v33 offset:44928
	s_waitcnt lgkmcnt(2)
	v_pk_fma_f32 v[80:81], v[102:103], v[42:43], v[80:81]
	v_pk_fma_f32 v[106:107], v[104:105], v[46:47], v[106:107]
	ds_read_b96 v[102:104], v33 offset:44944
	s_waitcnt lgkmcnt(2)
; DI void gdn_pre(const Params& p, int ch, char* smem) {
;     ...
; #pragma unroll
;   for (int i = 1; i < 64; ++i) {
;     f32x2 sa = {0.f, 0.f}, sb = {0.f, 0.f};
;     const f32x2* arow = (const f32x2*)(Amat + i * 64);
; #pragma unroll
;     for (int k = 0; k < (i >> 1); ++k) {
;       const f32x2 a2 = arow[k];
;       if (k & 1) sb = __builtin_elementwise_fma(a2, c2[k], sb);
;       else sa = __builtin_elementwise_fma(a2, c2[k], sa);
;     }
;     float tot = (sa[0] + sa[1]) + (sb[0] + sb[1]);
;     if (i & 1) tot += Amat[i * 64 + i - 1] * c2[(i - 1) >> 1][0];
;     c2[i >> 1][i & 1] -= tot;
;     __builtin_amdgcn_sched_barrier(0);
;   }
	v_pk_fma_f32 v[80:81], v[94:95], v[50:51], v[80:81]
	v_pk_fma_f32 v[94:95], v[96:97], v[54:55], v[106:107]
	s_waitcnt lgkmcnt(1)
	v_pk_fma_f32 v[80:81], v[98:99], v[56:57], v[80:81]
	v_pk_fma_f32 v[94:95], v[100:101], v[60:61], v[94:95]
	s_waitcnt lgkmcnt(0)
	v_pk_fma_f32 v[80:81], v[102:103], v[64:65], v[80:81]
	v_mov_b32_e32 v96, v94
	v_mov_b32_e32 v97, v80
	v_mov_b32_e32 v80, v95
	v_pk_add_f32 v[80:81], v[96:97], v[80:81]
	s_nop 0
	v_add_f32_e32 v19, v80, v81
	v_fmac_f32_e32 v19, v68, v104
	v_sub_f32_e32 v69, v70, v19
	ds_read_b128 v[94:97], v33 offset:45056
	ds_read_b128 v[98:101], v33 offset:45072
	ds_read_b128 v[102:105], v33 offset:45088
	ds_read_b128 v[106:109], v33 offset:45104
	s_waitcnt lgkmcnt(3)
	v_pk_fma_f32 v[70:71], v[94:95], v[0:1], 0 op_sel_hi:[1,1,0]
	v_pk_fma_f32 v[80:81], v[96:97], v[6:7], 0 op_sel_hi:[1,1,0]
	ds_read_b128 v[94:97], v33 offset:45120
	s_waitcnt lgkmcnt(3)
	v_pk_fma_f32 v[70:71], v[98:99], v[8:9], v[70:71]
	v_pk_fma_f32 v[80:81], v[100:101], v[10:11], v[80:81]
	ds_read_b128 v[98:101], v33 offset:45136
	s_waitcnt lgkmcnt(3)
	v_pk_fma_f32 v[70:71], v[102:103], v[12:13], v[70:71]
	v_pk_fma_f32 v[80:81], v[104:105], v[16:17], v[80:81]
	ds_read_b128 v[102:105], v33 offset:45152
	s_waitcnt lgkmcnt(3)
	v_pk_fma_f32 v[70:71], v[106:107], v[20:21], v[70:71]
	v_pk_fma_f32 v[80:81], v[108:109], v[22:23], v[80:81]
	s_waitcnt lgkmcnt(2)
	v_pk_fma_f32 v[70:71], v[94:95], v[24:25], v[70:71]
	v_pk_fma_f32 v[80:81], v[96:97], v[26:27], v[80:81]
	ds_read_b128 v[94:97], v33 offset:45168
	s_waitcnt lgkmcnt(2)
	v_pk_fma_f32 v[70:71], v[98:99], v[36:37], v[70:71]
	v_pk_fma_f32 v[80:81], v[100:101], v[38:39], v[80:81]
	ds_read_b128 v[98:101], v33 offset:45184
	s_waitcnt lgkmcnt(2)
	v_pk_fma_f32 v[70:71], v[102:103], v[42:43], v[70:71]
	v_pk_fma_f32 v[80:81], v[104:105], v[46:47], v[80:81]
	ds_read_b128 v[102:105], v33 offset:45200
	s_waitcnt lgkmcnt(2)
	v_pk_fma_f32 v[70:71], v[94:95], v[50:51], v[70:71]
	v_pk_fma_f32 v[80:81], v[96:97], v[54:55], v[80:81]
	s_waitcnt lgkmcnt(1)
	v_pk_fma_f32 v[70:71], v[98:99], v[56:57], v[70:71]
	v_pk_fma_f32 v[80:81], v[100:101], v[60:61], v[80:81]
	s_waitcnt lgkmcnt(0)
	v_pk_fma_f32 v[70:71], v[102:103], v[64:65], v[70:71]
	v_pk_fma_f32 v[80:81], v[104:105], v[68:69], v[80:81]
	v_mov_b32_e32 v94, v70
	v_mov_b32_e32 v95, v80
	v_mov_b32_e32 v80, v71
	v_pk_add_f32 v[70:71], v[94:95], v[80:81]
	s_nop 0
	v_pk_add_f32 v[70:71], v[70:71], v[70:71] op_sel:[0,1] op_sel_hi:[1,0]
	s_nop 0
	v_pk_add_f32 v[70:71], v[92:93], v[70:71] neg_lo:[0,1] neg_hi:[0,1]
	ds_read_b128 v[92:95], v33 offset:45312
	ds_read_b128 v[96:99], v33 offset:45328
	ds_read_b128 v[100:103], v33 offset:45344
	ds_read_b128 v[104:107], v33 offset:45360
	ds_read_b32 v19, v33 offset:45472
	s_waitcnt lgkmcnt(4)
	v_pk_fma_f32 v[80:81], v[92:93], v[0:1], 0 op_sel_hi:[1,1,0]
	v_pk_fma_f32 v[92:93], v[94:95], v[6:7], 0 op_sel_hi:[1,1,0]
	s_waitcnt lgkmcnt(3)
	v_pk_fma_f32 v[80:81], v[96:97], v[8:9], v[80:81]
	v_pk_fma_f32 v[96:97], v[98:99], v[10:11], v[92:93]
	ds_read_b128 v[92:95], v33 offset:45376
	s_waitcnt lgkmcnt(3)
	v_pk_fma_f32 v[80:81], v[100:101], v[12:13], v[80:81]
	v_pk_fma_f32 v[100:101], v[102:103], v[16:17], v[96:97]
	ds_read_b128 v[96:99], v33 offset:45392
	s_waitcnt lgkmcnt(3)
	v_pk_fma_f32 v[80:81], v[104:105], v[20:21], v[80:81]
	v_pk_fma_f32 v[104:105], v[106:107], v[22:23], v[100:101]
	ds_read_b128 v[100:103], v33 offset:45408
	s_waitcnt lgkmcnt(2)
	v_pk_fma_f32 v[80:81], v[92:93], v[24:25], v[80:81]
	v_pk_fma_f32 v[92:93], v[94:95], v[26:27], v[104:105]
	s_waitcnt lgkmcnt(1)
	v_pk_fma_f32 v[80:81], v[96:97], v[36:37], v[80:81]
	v_pk_fma_f32 v[104:105], v[98:99], v[38:39], v[92:93]
	ds_read_b128 v[92:95], v33 offset:45424
	ds_read_b128 v[96:99], v33 offset:45440
	s_waitcnt lgkmcnt(2)
	v_pk_fma_f32 v[80:81], v[100:101], v[42:43], v[80:81]
	v_pk_fma_f32 v[104:105], v[102:103], v[46:47], v[104:105]
	ds_read_b128 v[100:103], v33 offset:45456
	s_waitcnt lgkmcnt(2)
	v_pk_fma_f32 v[80:81], v[92:93], v[50:51], v[80:81]
	v_pk_fma_f32 v[92:93], v[94:95], v[54:55], v[104:105]
	s_waitcnt lgkmcnt(1)
	v_pk_fma_f32 v[80:81], v[96:97], v[56:57], v[80:81]
	v_pk_fma_f32 v[92:93], v[98:99], v[60:61], v[92:93]
	s_waitcnt lgkmcnt(0)
	v_pk_fma_f32 v[80:81], v[100:101], v[64:65], v[80:81]
	v_pk_fma_f32 v[92:93], v[102:103], v[68:69], v[92:93]
	v_mov_b32_e32 v94, v80
	v_mov_b32_e32 v95, v92
	v_mov_b32_e32 v92, v81
	v_pk_add_f32 v[80:81], v[94:95], v[92:93]
	s_nop 0
	v_add_f32_e32 v31, v80, v81
	v_fmac_f32_e32 v31, v70, v19
	v_sub_f32_e32 v71, v74, v31
	ds_read_b128 v[92:95], v33 offset:45568
	ds_read_b128 v[96:99], v33 offset:45584
	ds_read_b128 v[100:103], v33 offset:45600
	ds_read_b128 v[104:107], v33 offset:45616
	s_waitcnt lgkmcnt(3)
	v_pk_fma_f32 v[74:75], v[92:93], v[0:1], 0 op_sel_hi:[1,1,0]
	v_pk_fma_f32 v[80:81], v[94:95], v[6:7], 0 op_sel_hi:[1,1,0]
	ds_read_b128 v[92:95], v33 offset:45632
	s_waitcnt lgkmcnt(3)
	v_pk_fma_f32 v[74:75], v[96:97], v[8:9], v[74:75]
	v_pk_fma_f32 v[80:81], v[98:99], v[10:11], v[80:81]
	s_waitcnt lgkmcnt(2)
	v_pk_fma_f32 v[74:75], v[100:101], v[12:13], v[74:75]
	v_pk_fma_f32 v[80:81], v[102:103], v[16:17], v[80:81]
	ds_read_b128 v[96:99], v33 offset:45648
	s_waitcnt lgkmcnt(2)
	v_pk_fma_f32 v[74:75], v[104:105], v[20:21], v[74:75]
	v_pk_fma_f32 v[80:81], v[106:107], v[22:23], v[80:81]
	ds_read_b128 v[100:103], v33 offset:45664
	s_waitcnt lgkmcnt(2)
	v_pk_fma_f32 v[74:75], v[92:93], v[24:25], v[74:75]
	v_pk_fma_f32 v[80:81], v[94:95], v[26:27], v[80:81]
	ds_read_b128 v[92:95], v33 offset:45680
	s_waitcnt lgkmcnt(2)
	v_pk_fma_f32 v[74:75], v[96:97], v[36:37], v[74:75]
	v_pk_fma_f32 v[80:81], v[98:99], v[38:39], v[80:81]
	ds_read_b128 v[96:99], v33 offset:45696
	s_waitcnt lgkmcnt(2)
; DI void gdn_pre(const Params& p, int ch, char* smem) {
;     ...
; #pragma unroll
;   for (int i = 1; i < 64; ++i) {
;     f32x2 sa = {0.f, 0.f}, sb = {0.f, 0.f};
;     const f32x2* arow = (const f32x2*)(Amat + i * 64);
; #pragma unroll
;     for (int k = 0; k < (i >> 1); ++k) {
;       const f32x2 a2 = arow[k];
;       if (k & 1) sb = __builtin_elementwise_fma(a2, c2[k], sb);
;       else sa = __builtin_elementwise_fma(a2, c2[k], sa);
;     }
;     float tot = (sa[0] + sa[1]) + (sb[0] + sb[1]);
;     if (i & 1) tot += Amat[i * 64 + i - 1] * c2[(i - 1) >> 1][0];
;     c2[i >> 1][i & 1] -= tot;
;     __builtin_amdgcn_sched_barrier(0);
;   }
	v_pk_fma_f32 v[74:75], v[100:101], v[42:43], v[74:75]
	v_pk_fma_f32 v[80:81], v[102:103], v[46:47], v[80:81]
	ds_read_b128 v[100:103], v33 offset:45712
	s_waitcnt lgkmcnt(2)
	v_pk_fma_f32 v[74:75], v[92:93], v[50:51], v[74:75]
	ds_read_b64 v[92:93], v33 offset:45728
	v_pk_fma_f32 v[80:81], v[94:95], v[54:55], v[80:81]
	s_waitcnt lgkmcnt(2)
	v_pk_fma_f32 v[74:75], v[96:97], v[56:57], v[74:75]
	v_pk_fma_f32 v[80:81], v[98:99], v[60:61], v[80:81]
	s_waitcnt lgkmcnt(1)
	v_pk_fma_f32 v[74:75], v[100:101], v[64:65], v[74:75]
	v_pk_fma_f32 v[80:81], v[102:103], v[68:69], v[80:81]
	s_waitcnt lgkmcnt(0)
	v_pk_fma_f32 v[74:75], v[92:93], v[70:71], v[74:75]
	v_mov_b32_e32 v92, v80
	v_mov_b32_e32 v93, v74
	v_mov_b32_e32 v74, v81
	v_pk_add_f32 v[74:75], v[92:93], v[74:75]
	s_nop 0
	v_pk_add_f32 v[74:75], v[74:75], v[74:75] op_sel:[0,1] op_sel_hi:[1,0]
	s_nop 0
	v_pk_add_f32 v[74:75], v[90:91], v[74:75] neg_lo:[0,1] neg_hi:[0,1]
	ds_read_b128 v[90:93], v33 offset:45824
	ds_read_b128 v[94:97], v33 offset:45840
	ds_read_b128 v[98:101], v33 offset:45856
	ds_read_b128 v[102:105], v33 offset:45872
	s_waitcnt lgkmcnt(3)
	v_pk_fma_f32 v[80:81], v[90:91], v[0:1], 0 op_sel_hi:[1,1,0]
	v_pk_fma_f32 v[90:91], v[92:93], v[6:7], 0 op_sel_hi:[1,1,0]
	s_waitcnt lgkmcnt(2)
	v_pk_fma_f32 v[80:81], v[94:95], v[8:9], v[80:81]
	v_pk_fma_f32 v[94:95], v[96:97], v[10:11], v[90:91]
	ds_read_b128 v[90:93], v33 offset:45888
	s_waitcnt lgkmcnt(2)
	v_pk_fma_f32 v[80:81], v[98:99], v[12:13], v[80:81]
	v_pk_fma_f32 v[98:99], v[100:101], v[16:17], v[94:95]
	ds_read_b128 v[94:97], v33 offset:45904
	s_waitcnt lgkmcnt(2)
	v_pk_fma_f32 v[80:81], v[102:103], v[20:21], v[80:81]
	v_pk_fma_f32 v[102:103], v[104:105], v[22:23], v[98:99]
	ds_read_b128 v[98:101], v33 offset:45920
	s_waitcnt lgkmcnt(2)
	v_pk_fma_f32 v[80:81], v[90:91], v[24:25], v[80:81]
	v_pk_fma_f32 v[102:103], v[92:93], v[26:27], v[102:103]
	ds_read_b128 v[90:93], v33 offset:45936
	s_waitcnt lgkmcnt(2)
	v_pk_fma_f32 v[80:81], v[94:95], v[36:37], v[80:81]
	v_pk_fma_f32 v[94:95], v[96:97], v[38:39], v[102:103]
	s_waitcnt lgkmcnt(1)
	v_pk_fma_f32 v[80:81], v[98:99], v[42:43], v[80:81]
	v_pk_fma_f32 v[102:103], v[100:101], v[46:47], v[94:95]
	ds_read_b128 v[94:97], v33 offset:45952
	ds_read_b128 v[98:101], v33 offset:45968
	s_waitcnt lgkmcnt(2)
	v_pk_fma_f32 v[80:81], v[90:91], v[50:51], v[80:81]
	v_pk_fma_f32 v[102:103], v[92:93], v[54:55], v[102:103]
	ds_read_b96 v[90:92], v33 offset:45984
	s_waitcnt lgkmcnt(2)
	v_pk_fma_f32 v[80:81], v[94:95], v[56:57], v[80:81]
	v_pk_fma_f32 v[94:95], v[96:97], v[60:61], v[102:103]
	s_waitcnt lgkmcnt(1)
	v_pk_fma_f32 v[80:81], v[98:99], v[64:65], v[80:81]
	v_pk_fma_f32 v[94:95], v[100:101], v[68:69], v[94:95]
	s_waitcnt lgkmcnt(0)
	v_pk_fma_f32 v[80:81], v[90:91], v[70:71], v[80:81]
	v_mov_b32_e32 v90, v94
	v_mov_b32_e32 v91, v80
	v_mov_b32_e32 v80, v95
	v_pk_add_f32 v[80:81], v[90:91], v[80:81]
	s_nop 0
	v_add_f32_e32 v19, v80, v81
	v_fmac_f32_e32 v19, v74, v92
	v_sub_f32_e32 v75, v78, v19
	ds_read_b128 v[78:81], v33 offset:46080
	ds_read_b128 v[90:93], v33 offset:46096
	ds_read_b128 v[94:97], v33 offset:46112
	ds_read_b128 v[98:101], v33 offset:46128
	s_waitcnt lgkmcnt(3)
	v_pk_fma_f32 v[78:79], v[78:79], v[0:1], 0 op_sel_hi:[1,1,0]
	v_pk_fma_f32 v[80:81], v[80:81], v[6:7], 0 op_sel_hi:[1,1,0]
	s_waitcnt lgkmcnt(2)
	v_pk_fma_f32 v[78:79], v[90:91], v[8:9], v[78:79]
	v_pk_fma_f32 v[90:91], v[92:93], v[10:11], v[80:81]
	s_waitcnt lgkmcnt(1)
	v_pk_fma_f32 v[92:93], v[94:95], v[12:13], v[78:79]
	ds_read_b128 v[78:81], v33 offset:46144
	v_pk_fma_f32 v[94:95], v[96:97], v[16:17], v[90:91]
	s_waitcnt lgkmcnt(1)
	v_pk_fma_f32 v[96:97], v[98:99], v[20:21], v[92:93]
	ds_read_b128 v[90:93], v33 offset:46160
	v_pk_fma_f32 v[98:99], v[100:101], v[22:23], v[94:95]
	s_waitcnt lgkmcnt(1)
	v_pk_fma_f32 v[78:79], v[78:79], v[24:25], v[96:97]
	ds_read_b128 v[94:97], v33 offset:46176
	v_pk_fma_f32 v[98:99], v[80:81], v[26:27], v[98:99]
	s_waitcnt lgkmcnt(1)
	v_pk_fma_f32 v[90:91], v[90:91], v[36:37], v[78:79]
	ds_read_b128 v[78:81], v33 offset:46192
	v_pk_fma_f32 v[92:93], v[92:93], v[38:39], v[98:99]
	s_waitcnt lgkmcnt(1)
	v_pk_fma_f32 v[94:95], v[94:95], v[42:43], v[90:91]
	v_pk_fma_f32 v[98:99], v[96:97], v[46:47], v[92:93]
	ds_read_b128 v[90:93], v33 offset:46208
	s_waitcnt lgkmcnt(1)
	v_pk_fma_f32 v[100:101], v[78:79], v[50:51], v[94:95]
	ds_read_b128 v[94:97], v33 offset:46224
	v_pk_fma_f32 v[98:99], v[80:81], v[54:55], v[98:99]
	ds_read_b128 v[78:81], v33 offset:46240
	s_waitcnt lgkmcnt(2)
	v_pk_fma_f32 v[90:91], v[90:91], v[56:57], v[100:101]
	v_pk_fma_f32 v[92:93], v[92:93], v[60:61], v[98:99]
	s_waitcnt lgkmcnt(1)
	v_pk_fma_f32 v[90:91], v[94:95], v[64:65], v[90:91]
	v_pk_fma_f32 v[92:93], v[96:97], v[68:69], v[92:93]
	s_waitcnt lgkmcnt(0)
	v_pk_fma_f32 v[78:79], v[78:79], v[70:71], v[90:91]
	v_pk_fma_f32 v[80:81], v[80:81], v[74:75], v[92:93]
	v_mov_b32_e32 v90, v78
	v_mov_b32_e32 v91, v80
	v_mov_b32_e32 v80, v79
	v_pk_add_f32 v[78:79], v[90:91], v[80:81]
	s_nop 0
	v_pk_add_f32 v[78:79], v[78:79], v[78:79] op_sel:[0,1] op_sel_hi:[1,0]
	s_nop 0
	v_pk_add_f32 v[78:79], v[88:89], v[78:79] neg_lo:[0,1] neg_hi:[0,1]
	ds_read_b128 v[88:91], v33 offset:46336
	ds_read_b128 v[92:95], v33 offset:46352
	ds_read_b128 v[96:99], v33 offset:46368
	ds_read_b128 v[100:103], v33 offset:46384
	ds_read_b32 v19, v33 offset:46512
	s_waitcnt lgkmcnt(4)
	v_pk_fma_f32 v[80:81], v[88:89], v[0:1], 0 op_sel_hi:[1,1,0]
	v_pk_fma_f32 v[88:89], v[90:91], v[6:7], 0 op_sel_hi:[1,1,0]
	s_waitcnt lgkmcnt(3)
	v_pk_fma_f32 v[80:81], v[92:93], v[8:9], v[80:81]
	v_pk_fma_f32 v[92:93], v[94:95], v[10:11], v[88:89]
	ds_read_b128 v[88:91], v33 offset:46400
	s_waitcnt lgkmcnt(3)
; DI void gdn_pre(const Params& p, int ch, char* smem) {
;     ...
; #pragma unroll
;   for (int i = 1; i < 64; ++i) {
;     f32x2 sa = {0.f, 0.f}, sb = {0.f, 0.f};
;     const f32x2* arow = (const f32x2*)(Amat + i * 64);
; #pragma unroll
;     for (int k = 0; k < (i >> 1); ++k) {
;       const f32x2 a2 = arow[k];
;       if (k & 1) sb = __builtin_elementwise_fma(a2, c2[k], sb);
;       else sa = __builtin_elementwise_fma(a2, c2[k], sa);
;     }
;     float tot = (sa[0] + sa[1]) + (sb[0] + sb[1]);
;     if (i & 1) tot += Amat[i * 64 + i - 1] * c2[(i - 1) >> 1][0];
;     c2[i >> 1][i & 1] -= tot;
;     __builtin_amdgcn_sched_barrier(0);
;   }
	v_pk_fma_f32 v[80:81], v[96:97], v[12:13], v[80:81]
	v_pk_fma_f32 v[96:97], v[98:99], v[16:17], v[92:93]
	ds_read_b128 v[92:95], v33 offset:46416
	s_waitcnt lgkmcnt(3)
	v_pk_fma_f32 v[80:81], v[100:101], v[20:21], v[80:81]
	v_pk_fma_f32 v[100:101], v[102:103], v[22:23], v[96:97]
	ds_read_b128 v[96:99], v33 offset:46432
	s_waitcnt lgkmcnt(2)
	v_pk_fma_f32 v[80:81], v[88:89], v[24:25], v[80:81]
	v_pk_fma_f32 v[100:101], v[90:91], v[26:27], v[100:101]
	ds_read_b128 v[88:91], v33 offset:46448
	s_waitcnt lgkmcnt(2)
	v_pk_fma_f32 v[80:81], v[92:93], v[36:37], v[80:81]
	v_pk_fma_f32 v[100:101], v[94:95], v[38:39], v[100:101]
	ds_read_b128 v[92:95], v33 offset:46464
	s_waitcnt lgkmcnt(2)
	v_pk_fma_f32 v[80:81], v[96:97], v[42:43], v[80:81]
	v_pk_fma_f32 v[100:101], v[98:99], v[46:47], v[100:101]
	ds_read_b128 v[96:99], v33 offset:46480
	s_waitcnt lgkmcnt(2)
	v_pk_fma_f32 v[80:81], v[88:89], v[50:51], v[80:81]
	v_pk_fma_f32 v[100:101], v[90:91], v[54:55], v[100:101]
	ds_read_b128 v[88:91], v33 offset:46496
	s_waitcnt lgkmcnt(2)
	v_pk_fma_f32 v[80:81], v[92:93], v[56:57], v[80:81]
	v_pk_fma_f32 v[92:93], v[94:95], v[60:61], v[100:101]
	s_waitcnt lgkmcnt(1)
	v_pk_fma_f32 v[80:81], v[96:97], v[64:65], v[80:81]
	v_pk_fma_f32 v[92:93], v[98:99], v[68:69], v[92:93]
	s_waitcnt lgkmcnt(0)
	v_pk_fma_f32 v[80:81], v[88:89], v[70:71], v[80:81]
	v_pk_fma_f32 v[88:89], v[90:91], v[74:75], v[92:93]
	v_mov_b32_e32 v90, v80
	v_mov_b32_e32 v91, v88
	v_mov_b32_e32 v88, v81
	v_pk_add_f32 v[80:81], v[90:91], v[88:89]
	s_nop 0
	v_add_f32_e32 v31, v80, v81
	v_fmac_f32_e32 v31, v78, v19
	v_sub_f32_e32 v79, v76, v31
	ds_read_b128 v[88:91], v33 offset:46592
	ds_read_b128 v[92:95], v33 offset:46608
	ds_read_b128 v[96:99], v33 offset:46624
	ds_read_b128 v[100:103], v33 offset:46640
	s_waitcnt lgkmcnt(3)
	v_pk_fma_f32 v[76:77], v[88:89], v[0:1], 0 op_sel_hi:[1,1,0]
	v_pk_fma_f32 v[80:81], v[90:91], v[6:7], 0 op_sel_hi:[1,1,0]
	ds_read_b128 v[88:91], v33 offset:46656
	s_waitcnt lgkmcnt(3)
	v_pk_fma_f32 v[76:77], v[92:93], v[8:9], v[76:77]
	v_pk_fma_f32 v[80:81], v[94:95], v[10:11], v[80:81]
	ds_read_b128 v[92:95], v33 offset:46672
	s_waitcnt lgkmcnt(3)
	v_pk_fma_f32 v[76:77], v[96:97], v[12:13], v[76:77]
	v_pk_fma_f32 v[80:81], v[98:99], v[16:17], v[80:81]
	s_waitcnt lgkmcnt(2)
	v_pk_fma_f32 v[76:77], v[100:101], v[20:21], v[76:77]
	v_pk_fma_f32 v[80:81], v[102:103], v[22:23], v[80:81]
	ds_read_b128 v[96:99], v33 offset:46688
	s_waitcnt lgkmcnt(2)
	v_pk_fma_f32 v[76:77], v[88:89], v[24:25], v[76:77]
	v_pk_fma_f32 v[80:81], v[90:91], v[26:27], v[80:81]
	ds_read_b128 v[88:91], v33 offset:46704
	s_waitcnt lgkmcnt(2)
	v_pk_fma_f32 v[76:77], v[92:93], v[36:37], v[76:77]
	v_pk_fma_f32 v[80:81], v[94:95], v[38:39], v[80:81]
	ds_read_b128 v[92:95], v33 offset:46720
	s_waitcnt lgkmcnt(2)
	v_pk_fma_f32 v[76:77], v[96:97], v[42:43], v[76:77]
	v_pk_fma_f32 v[80:81], v[98:99], v[46:47], v[80:81]
	s_waitcnt lgkmcnt(1)
	v_pk_fma_f32 v[76:77], v[88:89], v[50:51], v[76:77]
	v_pk_fma_f32 v[80:81], v[90:91], v[54:55], v[80:81]
	ds_read_b128 v[88:91], v33 offset:46736
	ds_read_b128 v[96:99], v33 offset:46752
	s_waitcnt lgkmcnt(2)
	v_pk_fma_f32 v[76:77], v[92:93], v[56:57], v[76:77]
	ds_read_b64 v[92:93], v33 offset:46768
	v_pk_fma_f32 v[80:81], v[94:95], v[60:61], v[80:81]
	s_waitcnt lgkmcnt(2)
	v_pk_fma_f32 v[76:77], v[88:89], v[64:65], v[76:77]
	v_pk_fma_f32 v[80:81], v[90:91], v[68:69], v[80:81]
	s_waitcnt lgkmcnt(1)
	v_pk_fma_f32 v[76:77], v[96:97], v[70:71], v[76:77]
	v_pk_fma_f32 v[80:81], v[98:99], v[74:75], v[80:81]
	s_waitcnt lgkmcnt(0)
	v_pk_fma_f32 v[76:77], v[92:93], v[78:79], v[76:77]
	v_mov_b32_e32 v88, v80
	v_mov_b32_e32 v89, v76
	v_mov_b32_e32 v76, v81
	v_pk_add_f32 v[76:77], v[88:89], v[76:77]
	s_nop 0
	v_pk_add_f32 v[76:77], v[76:77], v[76:77] op_sel:[0,1] op_sel_hi:[1,0]
	s_nop 0
	v_pk_add_f32 v[76:77], v[86:87], v[76:77] neg_lo:[0,1] neg_hi:[0,1]
	ds_read_b128 v[86:89], v33 offset:46848
	ds_read_b128 v[90:93], v33 offset:46864
	ds_read_b128 v[94:97], v33 offset:46880
	ds_read_b128 v[98:101], v33 offset:46896
	s_waitcnt lgkmcnt(3)
	v_pk_fma_f32 v[80:81], v[86:87], v[0:1], 0 op_sel_hi:[1,1,0]
	v_pk_fma_f32 v[86:87], v[88:89], v[6:7], 0 op_sel_hi:[1,1,0]
	s_waitcnt lgkmcnt(2)
	v_pk_fma_f32 v[80:81], v[90:91], v[8:9], v[80:81]
	v_pk_fma_f32 v[90:91], v[92:93], v[10:11], v[86:87]
	ds_read_b128 v[86:89], v33 offset:46912
	s_waitcnt lgkmcnt(2)
	v_pk_fma_f32 v[80:81], v[94:95], v[12:13], v[80:81]
	v_pk_fma_f32 v[94:95], v[96:97], v[16:17], v[90:91]
	ds_read_b128 v[90:93], v33 offset:46928
	s_waitcnt lgkmcnt(2)
	v_pk_fma_f32 v[80:81], v[98:99], v[20:21], v[80:81]
	v_pk_fma_f32 v[98:99], v[100:101], v[22:23], v[94:95]
	ds_read_b128 v[94:97], v33 offset:46944
	s_waitcnt lgkmcnt(2)
	v_pk_fma_f32 v[80:81], v[86:87], v[24:25], v[80:81]
	v_pk_fma_f32 v[98:99], v[88:89], v[26:27], v[98:99]
	ds_read_b128 v[86:89], v33 offset:46960
	s_waitcnt lgkmcnt(2)
	v_pk_fma_f32 v[80:81], v[90:91], v[36:37], v[80:81]
	v_pk_fma_f32 v[98:99], v[92:93], v[38:39], v[98:99]
	ds_read_b128 v[90:93], v33 offset:46976
	s_waitcnt lgkmcnt(2)
	v_pk_fma_f32 v[80:81], v[94:95], v[42:43], v[80:81]
	v_pk_fma_f32 v[94:95], v[96:97], v[46:47], v[98:99]
	s_waitcnt lgkmcnt(1)
	v_pk_fma_f32 v[80:81], v[86:87], v[50:51], v[80:81]
	v_pk_fma_f32 v[98:99], v[88:89], v[54:55], v[94:95]
	ds_read_b128 v[86:89], v33 offset:46992
	ds_read_b128 v[94:97], v33 offset:47008
	s_waitcnt lgkmcnt(2)
	v_pk_fma_f32 v[80:81], v[90:91], v[56:57], v[80:81]
	v_pk_fma_f32 v[98:99], v[92:93], v[60:61], v[98:99]
	ds_read_b96 v[90:92], v33 offset:47024
	s_waitcnt lgkmcnt(2)
	v_pk_fma_f32 v[80:81], v[86:87], v[64:65], v[80:81]
	v_pk_fma_f32 v[86:87], v[88:89], v[68:69], v[98:99]
	s_waitcnt lgkmcnt(1)
; DI void gdn_pre(const Params& p, int ch, char* smem) {
;     ...
; #pragma unroll
;   for (int i = 1; i < 64; ++i) {
;     f32x2 sa = {0.f, 0.f}, sb = {0.f, 0.f};
;     const f32x2* arow = (const f32x2*)(Amat + i * 64);
; #pragma unroll
;     for (int k = 0; k < (i >> 1); ++k) {
;       const f32x2 a2 = arow[k];
;       if (k & 1) sb = __builtin_elementwise_fma(a2, c2[k], sb);
;       else sa = __builtin_elementwise_fma(a2, c2[k], sa);
;     }
;     float tot = (sa[0] + sa[1]) + (sb[0] + sb[1]);
;     if (i & 1) tot += Amat[i * 64 + i - 1] * c2[(i - 1) >> 1][0];
;     c2[i >> 1][i & 1] -= tot;
;     __builtin_amdgcn_sched_barrier(0);
;   }
	v_pk_fma_f32 v[80:81], v[94:95], v[70:71], v[80:81]
	v_pk_fma_f32 v[86:87], v[96:97], v[74:75], v[86:87]
	s_waitcnt lgkmcnt(0)
	v_pk_fma_f32 v[80:81], v[90:91], v[78:79], v[80:81]
	v_mov_b32_e32 v88, v86
	v_mov_b32_e32 v89, v80
	v_mov_b32_e32 v80, v87
	v_pk_add_f32 v[80:81], v[88:89], v[80:81]
	s_nop 0
	v_add_f32_e32 v19, v80, v81
	v_fmac_f32_e32 v19, v76, v92
	v_sub_f32_e32 v77, v72, v19
	ds_read_b128 v[86:89], v33 offset:47104
	ds_read_b128 v[90:93], v33 offset:47120
	ds_read_b128 v[94:97], v33 offset:47136
	ds_read_b128 v[98:101], v33 offset:47152
	s_waitcnt lgkmcnt(3)
	v_pk_fma_f32 v[72:73], v[86:87], v[0:1], 0 op_sel_hi:[1,1,0]
	v_pk_fma_f32 v[80:81], v[88:89], v[6:7], 0 op_sel_hi:[1,1,0]
	ds_read_b128 v[86:89], v33 offset:47168
	s_waitcnt lgkmcnt(3)
	v_pk_fma_f32 v[72:73], v[90:91], v[8:9], v[72:73]
	v_pk_fma_f32 v[80:81], v[92:93], v[10:11], v[80:81]
	ds_read_b128 v[90:93], v33 offset:47184
	s_waitcnt lgkmcnt(3)
	v_pk_fma_f32 v[72:73], v[94:95], v[12:13], v[72:73]
	v_pk_fma_f32 v[80:81], v[96:97], v[16:17], v[80:81]
	s_waitcnt lgkmcnt(2)
	v_pk_fma_f32 v[72:73], v[98:99], v[20:21], v[72:73]
	v_pk_fma_f32 v[80:81], v[100:101], v[22:23], v[80:81]
	ds_read_b128 v[94:97], v33 offset:47200
	s_waitcnt lgkmcnt(2)
	v_pk_fma_f32 v[72:73], v[86:87], v[24:25], v[72:73]
	v_pk_fma_f32 v[80:81], v[88:89], v[26:27], v[80:81]
	ds_read_b128 v[86:89], v33 offset:47216
	s_waitcnt lgkmcnt(2)
	v_pk_fma_f32 v[72:73], v[90:91], v[36:37], v[72:73]
	v_pk_fma_f32 v[80:81], v[92:93], v[38:39], v[80:81]
	ds_read_b128 v[90:93], v33 offset:47232
	s_waitcnt lgkmcnt(2)
	v_pk_fma_f32 v[72:73], v[94:95], v[42:43], v[72:73]
	v_pk_fma_f32 v[80:81], v[96:97], v[46:47], v[80:81]
	s_waitcnt lgkmcnt(1)
	v_pk_fma_f32 v[72:73], v[86:87], v[50:51], v[72:73]
	v_pk_fma_f32 v[80:81], v[88:89], v[54:55], v[80:81]
	ds_read_b128 v[86:89], v33 offset:47248
	ds_read_b128 v[94:97], v33 offset:47264
	s_waitcnt lgkmcnt(2)
	v_pk_fma_f32 v[72:73], v[90:91], v[56:57], v[72:73]
	v_pk_fma_f32 v[80:81], v[92:93], v[60:61], v[80:81]
	ds_read_b128 v[90:93], v33 offset:47280
	s_waitcnt lgkmcnt(2)
	v_pk_fma_f32 v[72:73], v[86:87], v[64:65], v[72:73]
	v_pk_fma_f32 v[80:81], v[88:89], v[68:69], v[80:81]
	s_waitcnt lgkmcnt(1)
	v_pk_fma_f32 v[72:73], v[94:95], v[70:71], v[72:73]
	v_pk_fma_f32 v[80:81], v[96:97], v[74:75], v[80:81]
	s_waitcnt lgkmcnt(0)
	v_pk_fma_f32 v[72:73], v[90:91], v[78:79], v[72:73]
	v_pk_fma_f32 v[80:81], v[92:93], v[76:77], v[80:81]
	v_mov_b32_e32 v86, v72
	v_mov_b32_e32 v87, v80
	v_mov_b32_e32 v80, v73
	v_pk_add_f32 v[72:73], v[86:87], v[80:81]
	s_nop 0
	v_pk_add_f32 v[72:73], v[72:73], v[72:73] op_sel:[0,1] op_sel_hi:[1,0]
	s_nop 0
	v_pk_add_f32 v[72:73], v[84:85], v[72:73] neg_lo:[0,1] neg_hi:[0,1]
	ds_read_b128 v[84:87], v33 offset:47360
	ds_read_b128 v[88:91], v33 offset:47376
	ds_read_b128 v[92:95], v33 offset:47392
	ds_read_b128 v[96:99], v33 offset:47408
	ds_read_b32 v19, v33 offset:47552
	s_waitcnt lgkmcnt(4)
	v_pk_fma_f32 v[80:81], v[84:85], v[0:1], 0 op_sel_hi:[1,1,0]
	v_pk_fma_f32 v[84:85], v[86:87], v[6:7], 0 op_sel_hi:[1,1,0]
	s_waitcnt lgkmcnt(3)
	v_pk_fma_f32 v[80:81], v[88:89], v[8:9], v[80:81]
	v_pk_fma_f32 v[88:89], v[90:91], v[10:11], v[84:85]
	ds_read_b128 v[84:87], v33 offset:47424
	s_waitcnt lgkmcnt(3)
	v_pk_fma_f32 v[80:81], v[92:93], v[12:13], v[80:81]
	v_pk_fma_f32 v[92:93], v[94:95], v[16:17], v[88:89]
	ds_read_b128 v[88:91], v33 offset:47440
	s_waitcnt lgkmcnt(3)
	v_pk_fma_f32 v[80:81], v[96:97], v[20:21], v[80:81]
	v_pk_fma_f32 v[96:97], v[98:99], v[22:23], v[92:93]
	ds_read_b128 v[92:95], v33 offset:47456
	s_waitcnt lgkmcnt(2)
	v_pk_fma_f32 v[80:81], v[84:85], v[24:25], v[80:81]
	v_pk_fma_f32 v[96:97], v[86:87], v[26:27], v[96:97]
	ds_read_b128 v[84:87], v33 offset:47472
	s_waitcnt lgkmcnt(2)
	v_pk_fma_f32 v[80:81], v[88:89], v[36:37], v[80:81]
	v_pk_fma_f32 v[96:97], v[90:91], v[38:39], v[96:97]
	ds_read_b128 v[88:91], v33 offset:47488
	s_waitcnt lgkmcnt(2)
	v_pk_fma_f32 v[80:81], v[92:93], v[42:43], v[80:81]
	v_pk_fma_f32 v[92:93], v[94:95], v[46:47], v[96:97]
	s_waitcnt lgkmcnt(1)
	v_pk_fma_f32 v[80:81], v[84:85], v[50:51], v[80:81]
	v_pk_fma_f32 v[96:97], v[86:87], v[54:55], v[92:93]
	ds_read_b128 v[84:87], v33 offset:47504
	ds_read_b128 v[92:95], v33 offset:47520
	s_waitcnt lgkmcnt(2)
	v_pk_fma_f32 v[80:81], v[88:89], v[56:57], v[80:81]
	v_pk_fma_f32 v[96:97], v[90:91], v[60:61], v[96:97]
	ds_read_b128 v[88:91], v33 offset:47536
	s_waitcnt lgkmcnt(2)
	v_pk_fma_f32 v[80:81], v[84:85], v[64:65], v[80:81]
	v_pk_fma_f32 v[84:85], v[86:87], v[68:69], v[96:97]
	s_waitcnt lgkmcnt(1)
	v_pk_fma_f32 v[80:81], v[92:93], v[70:71], v[80:81]
	v_pk_fma_f32 v[84:85], v[94:95], v[74:75], v[84:85]
	s_waitcnt lgkmcnt(0)
	v_pk_fma_f32 v[80:81], v[88:89], v[78:79], v[80:81]
	v_pk_fma_f32 v[84:85], v[90:91], v[76:77], v[84:85]
	v_mov_b32_e32 v86, v80
	v_mov_b32_e32 v87, v84
	v_mov_b32_e32 v84, v81
	v_pk_add_f32 v[80:81], v[86:87], v[84:85]
	s_nop 0
	v_add_f32_e32 v31, v80, v81
	v_fmac_f32_e32 v31, v72, v19
	v_sub_f32_e32 v73, v66, v31
	ds_read_b128 v[84:87], v33 offset:47616
	ds_read_b128 v[88:91], v33 offset:47632
	ds_read_b128 v[92:95], v33 offset:47648
	ds_read_b128 v[96:99], v33 offset:47664
	s_waitcnt lgkmcnt(3)
	v_pk_fma_f32 v[66:67], v[84:85], v[0:1], 0 op_sel_hi:[1,1,0]
	v_pk_fma_f32 v[80:81], v[86:87], v[6:7], 0 op_sel_hi:[1,1,0]
	ds_read_b128 v[84:87], v33 offset:47680
	s_waitcnt lgkmcnt(3)
	v_pk_fma_f32 v[66:67], v[88:89], v[8:9], v[66:67]
	v_pk_fma_f32 v[80:81], v[90:91], v[10:11], v[80:81]
	ds_read_b128 v[88:91], v33 offset:47696
	s_waitcnt lgkmcnt(3)
	v_pk_fma_f32 v[66:67], v[92:93], v[12:13], v[66:67]
	v_pk_fma_f32 v[80:81], v[94:95], v[16:17], v[80:81]
	ds_read_b128 v[92:95], v33 offset:47712
	s_waitcnt lgkmcnt(3)
; DI void gdn_pre(const Params& p, int ch, char* smem) {
;     ...
; #pragma unroll
;   for (int i = 1; i < 64; ++i) {
;     f32x2 sa = {0.f, 0.f}, sb = {0.f, 0.f};
;     const f32x2* arow = (const f32x2*)(Amat + i * 64);
; #pragma unroll
;     for (int k = 0; k < (i >> 1); ++k) {
;       const f32x2 a2 = arow[k];
;       if (k & 1) sb = __builtin_elementwise_fma(a2, c2[k], sb);
;       else sa = __builtin_elementwise_fma(a2, c2[k], sa);
;     }
;     float tot = (sa[0] + sa[1]) + (sb[0] + sb[1]);
;     if (i & 1) tot += Amat[i * 64 + i - 1] * c2[(i - 1) >> 1][0];
;     c2[i >> 1][i & 1] -= tot;
;     __builtin_amdgcn_sched_barrier(0);
;   }
	v_pk_fma_f32 v[66:67], v[96:97], v[20:21], v[66:67]
	v_pk_fma_f32 v[80:81], v[98:99], v[22:23], v[80:81]
	s_waitcnt lgkmcnt(2)
	v_pk_fma_f32 v[66:67], v[84:85], v[24:25], v[66:67]
	v_pk_fma_f32 v[80:81], v[86:87], v[26:27], v[80:81]
	ds_read_b128 v[84:87], v33 offset:47728
	s_waitcnt lgkmcnt(2)
	v_pk_fma_f32 v[66:67], v[88:89], v[36:37], v[66:67]
	v_pk_fma_f32 v[80:81], v[90:91], v[38:39], v[80:81]
	ds_read_b128 v[88:91], v33 offset:47744
	s_waitcnt lgkmcnt(2)
	v_pk_fma_f32 v[66:67], v[92:93], v[42:43], v[66:67]
	v_pk_fma_f32 v[80:81], v[94:95], v[46:47], v[80:81]
	ds_read_b128 v[92:95], v33 offset:47760
	s_waitcnt lgkmcnt(2)
	v_pk_fma_f32 v[66:67], v[84:85], v[50:51], v[66:67]
	v_pk_fma_f32 v[80:81], v[86:87], v[54:55], v[80:81]
	ds_read_b128 v[84:87], v33 offset:47776
	s_waitcnt lgkmcnt(2)
	v_pk_fma_f32 v[66:67], v[88:89], v[56:57], v[66:67]
	v_pk_fma_f32 v[80:81], v[90:91], v[60:61], v[80:81]
	ds_read_b128 v[88:91], v33 offset:47792
	s_waitcnt lgkmcnt(2)
	v_pk_fma_f32 v[66:67], v[92:93], v[64:65], v[66:67]
	ds_read_b64 v[92:93], v33 offset:47808
	v_pk_fma_f32 v[80:81], v[94:95], v[68:69], v[80:81]
	s_waitcnt lgkmcnt(2)
	v_pk_fma_f32 v[66:67], v[84:85], v[70:71], v[66:67]
	v_pk_fma_f32 v[80:81], v[86:87], v[74:75], v[80:81]
	s_waitcnt lgkmcnt(1)
	v_pk_fma_f32 v[66:67], v[88:89], v[78:79], v[66:67]
	v_pk_fma_f32 v[80:81], v[90:91], v[76:77], v[80:81]
	s_waitcnt lgkmcnt(0)
	v_pk_fma_f32 v[66:67], v[92:93], v[72:73], v[66:67]
	v_mov_b32_e32 v84, v80
	v_mov_b32_e32 v85, v66
	v_mov_b32_e32 v66, v81
	v_pk_add_f32 v[66:67], v[84:85], v[66:67]
	s_nop 0
	v_pk_add_f32 v[66:67], v[66:67], v[66:67] op_sel:[0,1] op_sel_hi:[1,0]
	s_nop 0
	v_pk_add_f32 v[66:67], v[82:83], v[66:67] neg_lo:[0,1] neg_hi:[0,1]
	ds_read_b128 v[80:83], v33 offset:47872
	ds_read_b128 v[84:87], v33 offset:47888
	ds_read_b128 v[88:91], v33 offset:47904
	ds_read_b128 v[92:95], v33 offset:47920
	s_waitcnt lgkmcnt(3)
	v_pk_fma_f32 v[80:81], v[80:81], v[0:1], 0 op_sel_hi:[1,1,0]
	v_pk_fma_f32 v[82:83], v[82:83], v[6:7], 0 op_sel_hi:[1,1,0]
	s_waitcnt lgkmcnt(2)
	v_pk_fma_f32 v[80:81], v[84:85], v[8:9], v[80:81]
	v_pk_fma_f32 v[84:85], v[86:87], v[10:11], v[82:83]
	s_waitcnt lgkmcnt(1)
	v_pk_fma_f32 v[86:87], v[88:89], v[12:13], v[80:81]
	ds_read_b128 v[80:83], v33 offset:47936
	v_pk_fma_f32 v[88:89], v[90:91], v[16:17], v[84:85]
	s_waitcnt lgkmcnt(1)
	v_pk_fma_f32 v[90:91], v[92:93], v[20:21], v[86:87]
	ds_read_b128 v[84:87], v33 offset:47952
	v_pk_fma_f32 v[92:93], v[94:95], v[22:23], v[88:89]
	s_waitcnt lgkmcnt(1)
	v_pk_fma_f32 v[80:81], v[80:81], v[24:25], v[90:91]
	ds_read_b128 v[88:91], v33 offset:47968
	v_pk_fma_f32 v[92:93], v[82:83], v[26:27], v[92:93]
	s_waitcnt lgkmcnt(1)
	v_pk_fma_f32 v[84:85], v[84:85], v[36:37], v[80:81]
	ds_read_b128 v[80:83], v33 offset:47984
	v_pk_fma_f32 v[92:93], v[86:87], v[38:39], v[92:93]
	s_waitcnt lgkmcnt(1)
	v_pk_fma_f32 v[88:89], v[88:89], v[42:43], v[84:85]
	ds_read_b128 v[84:87], v33 offset:48000
	v_pk_fma_f32 v[92:93], v[90:91], v[46:47], v[92:93]
	s_waitcnt lgkmcnt(1)
	v_pk_fma_f32 v[80:81], v[80:81], v[50:51], v[88:89]
	ds_read_b128 v[88:91], v33 offset:48016
	v_pk_fma_f32 v[82:83], v[82:83], v[54:55], v[92:93]
	s_waitcnt lgkmcnt(1)
	v_pk_fma_f32 v[84:85], v[84:85], v[56:57], v[80:81]
	v_pk_fma_f32 v[92:93], v[86:87], v[60:61], v[82:83]
	ds_read_b128 v[80:83], v33 offset:48032
	s_waitcnt lgkmcnt(1)
	v_pk_fma_f32 v[94:95], v[88:89], v[64:65], v[84:85]
	ds_read_b128 v[84:87], v33 offset:48048
	v_pk_fma_f32 v[92:93], v[90:91], v[68:69], v[92:93]
	ds_read_b96 v[88:90], v33 offset:48064
	s_waitcnt lgkmcnt(2)
	v_pk_fma_f32 v[80:81], v[80:81], v[70:71], v[94:95]
	v_pk_fma_f32 v[82:83], v[82:83], v[74:75], v[92:93]
	s_waitcnt lgkmcnt(1)
	v_pk_fma_f32 v[80:81], v[84:85], v[78:79], v[80:81]
	v_pk_fma_f32 v[82:83], v[86:87], v[76:77], v[82:83]
	s_waitcnt lgkmcnt(0)
	v_pk_fma_f32 v[80:81], v[88:89], v[72:73], v[80:81]
	v_mov_b32_e32 v84, v82
	v_mov_b32_e32 v85, v80
	v_mov_b32_e32 v80, v83
	v_pk_add_f32 v[80:81], v[84:85], v[80:81]
	s_nop 0
	v_add_f32_e32 v19, v80, v81
	v_fmac_f32_e32 v19, v66, v90
	v_sub_f32_e32 v67, v62, v19
	ds_read_b128 v[80:83], v33 offset:48128
	ds_read_b128 v[84:87], v33 offset:48144
	ds_read_b128 v[88:91], v33 offset:48160
	ds_read_b128 v[92:95], v33 offset:48176
	s_waitcnt lgkmcnt(3)
	v_pk_fma_f32 v[62:63], v[80:81], v[0:1], 0 op_sel_hi:[1,1,0]
	v_pk_fma_f32 v[80:81], v[82:83], v[6:7], 0 op_sel_hi:[1,1,0]
	s_waitcnt lgkmcnt(2)
	v_pk_fma_f32 v[62:63], v[84:85], v[8:9], v[62:63]
	v_pk_fma_f32 v[84:85], v[86:87], v[10:11], v[80:81]
	ds_read_b128 v[80:83], v33 offset:48192
	s_waitcnt lgkmcnt(2)
	v_pk_fma_f32 v[62:63], v[88:89], v[12:13], v[62:63]
	v_pk_fma_f32 v[88:89], v[90:91], v[16:17], v[84:85]
	ds_read_b128 v[84:87], v33 offset:48208
	s_waitcnt lgkmcnt(2)
	v_pk_fma_f32 v[62:63], v[92:93], v[20:21], v[62:63]
	v_pk_fma_f32 v[92:93], v[94:95], v[22:23], v[88:89]
	ds_read_b128 v[88:91], v33 offset:48224
	s_waitcnt lgkmcnt(2)
	v_pk_fma_f32 v[62:63], v[80:81], v[24:25], v[62:63]
	v_pk_fma_f32 v[92:93], v[82:83], v[26:27], v[92:93]
	ds_read_b128 v[80:83], v33 offset:48240
	s_waitcnt lgkmcnt(2)
	v_pk_fma_f32 v[62:63], v[84:85], v[36:37], v[62:63]
	v_pk_fma_f32 v[92:93], v[86:87], v[38:39], v[92:93]
	ds_read_b128 v[84:87], v33 offset:48256
	s_waitcnt lgkmcnt(2)
	v_pk_fma_f32 v[62:63], v[88:89], v[42:43], v[62:63]
	v_pk_fma_f32 v[92:93], v[90:91], v[46:47], v[92:93]
	ds_read_b128 v[88:91], v33 offset:48272
	s_waitcnt lgkmcnt(2)
	v_pk_fma_f32 v[62:63], v[80:81], v[50:51], v[62:63]
	v_pk_fma_f32 v[80:81], v[82:83], v[54:55], v[92:93]
	s_waitcnt lgkmcnt(1)
; DI void gdn_pre(const Params& p, int ch, char* smem) {
;     ...
; #pragma unroll
;   for (int i = 1; i < 64; ++i) {
;     f32x2 sa = {0.f, 0.f}, sb = {0.f, 0.f};
;     const f32x2* arow = (const f32x2*)(Amat + i * 64);
; #pragma unroll
;     for (int k = 0; k < (i >> 1); ++k) {
;       const f32x2 a2 = arow[k];
;       if (k & 1) sb = __builtin_elementwise_fma(a2, c2[k], sb);
;       else sa = __builtin_elementwise_fma(a2, c2[k], sa);
;     }
;     float tot = (sa[0] + sa[1]) + (sb[0] + sb[1]);
;     if (i & 1) tot += Amat[i * 64 + i - 1] * c2[(i - 1) >> 1][0];
;     c2[i >> 1][i & 1] -= tot;
;     __builtin_amdgcn_sched_barrier(0);
;   }
	v_pk_fma_f32 v[62:63], v[84:85], v[56:57], v[62:63]
	v_pk_fma_f32 v[92:93], v[86:87], v[60:61], v[80:81]
	ds_read_b128 v[80:83], v33 offset:48288
	ds_read_b128 v[84:87], v33 offset:48304
	s_waitcnt lgkmcnt(2)
	v_pk_fma_f32 v[62:63], v[88:89], v[64:65], v[62:63]
	v_pk_fma_f32 v[92:93], v[90:91], v[68:69], v[92:93]
	ds_read_b128 v[88:91], v33 offset:48320
	s_waitcnt lgkmcnt(2)
	v_pk_fma_f32 v[62:63], v[80:81], v[70:71], v[62:63]
	v_pk_fma_f32 v[80:81], v[82:83], v[74:75], v[92:93]
	s_waitcnt lgkmcnt(1)
	v_pk_fma_f32 v[62:63], v[84:85], v[78:79], v[62:63]
	v_pk_fma_f32 v[80:81], v[86:87], v[76:77], v[80:81]
	s_waitcnt lgkmcnt(0)
	v_pk_fma_f32 v[62:63], v[88:89], v[72:73], v[62:63]
	v_pk_fma_f32 v[80:81], v[90:91], v[66:67], v[80:81]
	v_mov_b32_e32 v82, v62
	v_mov_b32_e32 v83, v80
	v_mov_b32_e32 v80, v63
	v_pk_add_f32 v[62:63], v[82:83], v[80:81]
	s_nop 0
	v_pk_add_f32 v[62:63], v[62:63], v[62:63] op_sel:[0,1] op_sel_hi:[1,0]
	s_nop 0
	v_pk_add_f32 v[48:49], v[48:49], v[62:63] neg_lo:[0,1] neg_hi:[0,1]
	ds_read_b128 v[80:83], v33 offset:48384
	ds_read_b128 v[84:87], v33 offset:48400
	ds_read_b128 v[88:91], v33 offset:48416
	ds_read_b128 v[92:95], v33 offset:48432
	ds_read_b32 v19, v33 offset:48592
	s_waitcnt lgkmcnt(4)
	v_pk_fma_f32 v[62:63], v[80:81], v[0:1], 0 op_sel_hi:[1,1,0]
	v_pk_fma_f32 v[80:81], v[82:83], v[6:7], 0 op_sel_hi:[1,1,0]
	s_waitcnt lgkmcnt(3)
	v_pk_fma_f32 v[62:63], v[84:85], v[8:9], v[62:63]
	v_pk_fma_f32 v[84:85], v[86:87], v[10:11], v[80:81]
	ds_read_b128 v[80:83], v33 offset:48448
	s_waitcnt lgkmcnt(3)
	v_pk_fma_f32 v[62:63], v[88:89], v[12:13], v[62:63]
	v_pk_fma_f32 v[88:89], v[90:91], v[16:17], v[84:85]
	ds_read_b128 v[84:87], v33 offset:48464
	s_waitcnt lgkmcnt(3)
	v_pk_fma_f32 v[62:63], v[92:93], v[20:21], v[62:63]
	v_pk_fma_f32 v[92:93], v[94:95], v[22:23], v[88:89]
	ds_read_b128 v[88:91], v33 offset:48480
	s_waitcnt lgkmcnt(2)
	v_pk_fma_f32 v[62:63], v[80:81], v[24:25], v[62:63]
	v_pk_fma_f32 v[92:93], v[82:83], v[26:27], v[92:93]
	ds_read_b128 v[80:83], v33 offset:48496
	s_waitcnt lgkmcnt(2)
	v_pk_fma_f32 v[62:63], v[84:85], v[36:37], v[62:63]
	v_pk_fma_f32 v[92:93], v[86:87], v[38:39], v[92:93]
	ds_read_b128 v[84:87], v33 offset:48512
	s_waitcnt lgkmcnt(2)
	v_pk_fma_f32 v[62:63], v[88:89], v[42:43], v[62:63]
	v_pk_fma_f32 v[92:93], v[90:91], v[46:47], v[92:93]
	ds_read_b128 v[88:91], v33 offset:48528
	s_waitcnt lgkmcnt(2)
	v_pk_fma_f32 v[62:63], v[80:81], v[50:51], v[62:63]
	v_pk_fma_f32 v[92:93], v[82:83], v[54:55], v[92:93]
	ds_read_b128 v[80:83], v33 offset:48544
	s_waitcnt lgkmcnt(2)
	v_pk_fma_f32 v[62:63], v[84:85], v[56:57], v[62:63]
	v_pk_fma_f32 v[92:93], v[86:87], v[60:61], v[92:93]
	ds_read_b128 v[84:87], v33 offset:48560
	s_waitcnt lgkmcnt(2)
	v_pk_fma_f32 v[62:63], v[88:89], v[64:65], v[62:63]
	v_pk_fma_f32 v[92:93], v[90:91], v[68:69], v[92:93]
	ds_read_b128 v[88:91], v33 offset:48576
	s_waitcnt lgkmcnt(2)
	v_pk_fma_f32 v[62:63], v[80:81], v[70:71], v[62:63]
	v_pk_fma_f32 v[80:81], v[82:83], v[74:75], v[92:93]
	s_waitcnt lgkmcnt(1)
	v_pk_fma_f32 v[62:63], v[84:85], v[78:79], v[62:63]
	v_pk_fma_f32 v[80:81], v[86:87], v[76:77], v[80:81]
	s_waitcnt lgkmcnt(0)
	v_pk_fma_f32 v[62:63], v[88:89], v[72:73], v[62:63]
	v_pk_fma_f32 v[80:81], v[90:91], v[66:67], v[80:81]
	v_mov_b32_e32 v82, v62
	v_mov_b32_e32 v83, v80
	v_mov_b32_e32 v80, v63
	v_pk_add_f32 v[62:63], v[82:83], v[80:81]
	s_nop 0
	v_add_f32_e32 v31, v62, v63
	v_fmac_f32_e32 v31, v48, v19
	v_sub_f32_e32 v49, v58, v31
	ds_read_b128 v[80:83], v33 offset:48640
	ds_read_b128 v[84:87], v33 offset:48656
	ds_read_b128 v[88:91], v33 offset:48672
	ds_read_b128 v[92:95], v33 offset:48688
	s_waitcnt lgkmcnt(3)
	v_pk_fma_f32 v[58:59], v[80:81], v[0:1], 0 op_sel_hi:[1,1,0]
	v_pk_fma_f32 v[62:63], v[82:83], v[6:7], 0 op_sel_hi:[1,1,0]
	ds_read_b128 v[80:83], v33 offset:48704
	s_waitcnt lgkmcnt(3)
	v_pk_fma_f32 v[58:59], v[84:85], v[8:9], v[58:59]
	v_pk_fma_f32 v[62:63], v[86:87], v[10:11], v[62:63]
	s_waitcnt lgkmcnt(2)
	v_pk_fma_f32 v[58:59], v[88:89], v[12:13], v[58:59]
	v_pk_fma_f32 v[62:63], v[90:91], v[16:17], v[62:63]
	ds_read_b128 v[84:87], v33 offset:48720
	s_waitcnt lgkmcnt(2)
	v_pk_fma_f32 v[58:59], v[92:93], v[20:21], v[58:59]
	v_pk_fma_f32 v[62:63], v[94:95], v[22:23], v[62:63]
	ds_read_b128 v[88:91], v33 offset:48736
	s_waitcnt lgkmcnt(2)
	v_pk_fma_f32 v[58:59], v[80:81], v[24:25], v[58:59]
	v_pk_fma_f32 v[62:63], v[82:83], v[26:27], v[62:63]
	ds_read_b128 v[80:83], v33 offset:48752
	s_waitcnt lgkmcnt(2)
	v_pk_fma_f32 v[58:59], v[84:85], v[36:37], v[58:59]
	v_pk_fma_f32 v[62:63], v[86:87], v[38:39], v[62:63]
	ds_read_b128 v[84:87], v33 offset:48768
	s_waitcnt lgkmcnt(2)
	v_pk_fma_f32 v[58:59], v[88:89], v[42:43], v[58:59]
	v_pk_fma_f32 v[62:63], v[90:91], v[46:47], v[62:63]
	ds_read_b128 v[88:91], v33 offset:48784
	s_waitcnt lgkmcnt(2)
	v_pk_fma_f32 v[58:59], v[80:81], v[50:51], v[58:59]
	v_pk_fma_f32 v[62:63], v[82:83], v[54:55], v[62:63]
	ds_read_b128 v[80:83], v33 offset:48800
	s_waitcnt lgkmcnt(2)
	v_pk_fma_f32 v[58:59], v[84:85], v[56:57], v[58:59]
	v_pk_fma_f32 v[62:63], v[86:87], v[60:61], v[62:63]
	ds_read_b128 v[84:87], v33 offset:48816
	s_waitcnt lgkmcnt(2)
	v_pk_fma_f32 v[58:59], v[88:89], v[64:65], v[58:59]
	v_pk_fma_f32 v[62:63], v[90:91], v[68:69], v[62:63]
	ds_read_b128 v[88:91], v33 offset:48832
	s_waitcnt lgkmcnt(2)
	v_pk_fma_f32 v[58:59], v[80:81], v[70:71], v[58:59]
	ds_read_b64 v[80:81], v33 offset:48848
	v_pk_fma_f32 v[62:63], v[82:83], v[74:75], v[62:63]
	s_waitcnt lgkmcnt(2)
	v_pk_fma_f32 v[58:59], v[84:85], v[78:79], v[58:59]
	v_pk_fma_f32 v[62:63], v[86:87], v[76:77], v[62:63]
	s_waitcnt lgkmcnt(1)
; DI void gdn_pre(const Params& p, int ch, char* smem) {
;     ...
; #pragma unroll
;   for (int i = 1; i < 64; ++i) {
;     f32x2 sa = {0.f, 0.f}, sb = {0.f, 0.f};
;     const f32x2* arow = (const f32x2*)(Amat + i * 64);
; #pragma unroll
;     for (int k = 0; k < (i >> 1); ++k) {
;       const f32x2 a2 = arow[k];
;       if (k & 1) sb = __builtin_elementwise_fma(a2, c2[k], sb);
;       else sa = __builtin_elementwise_fma(a2, c2[k], sa);
;     }
;     float tot = (sa[0] + sa[1]) + (sb[0] + sb[1]);
;     if (i & 1) tot += Amat[i * 64 + i - 1] * c2[(i - 1) >> 1][0];
;     c2[i >> 1][i & 1] -= tot;
;     __builtin_amdgcn_sched_barrier(0);
;   }
	v_pk_fma_f32 v[58:59], v[88:89], v[72:73], v[58:59]
	v_pk_fma_f32 v[62:63], v[90:91], v[66:67], v[62:63]
	s_waitcnt lgkmcnt(0)
	v_pk_fma_f32 v[58:59], v[80:81], v[48:49], v[58:59]
	v_mov_b32_e32 v80, v62
	v_mov_b32_e32 v81, v58
	v_mov_b32_e32 v58, v63
	v_pk_add_f32 v[58:59], v[80:81], v[58:59]
	s_nop 0
	v_pk_add_f32 v[58:59], v[58:59], v[58:59] op_sel:[0,1] op_sel_hi:[1,0]
	s_nop 0
	v_pk_add_f32 v[40:41], v[40:41], v[58:59] neg_lo:[0,1] neg_hi:[0,1]
	ds_read_b128 v[80:83], v33 offset:48896
	ds_read_b128 v[84:87], v33 offset:48912
	ds_read_b128 v[88:91], v33 offset:48928
	ds_read_b128 v[92:95], v33 offset:48944
	s_waitcnt lgkmcnt(3)
	v_pk_fma_f32 v[58:59], v[80:81], v[0:1], 0 op_sel_hi:[1,1,0]
	v_pk_fma_f32 v[62:63], v[82:83], v[6:7], 0 op_sel_hi:[1,1,0]
	ds_read_b128 v[80:83], v33 offset:48960
	s_waitcnt lgkmcnt(3)
	v_pk_fma_f32 v[58:59], v[84:85], v[8:9], v[58:59]
	v_pk_fma_f32 v[62:63], v[86:87], v[10:11], v[62:63]
	s_waitcnt lgkmcnt(2)
	v_pk_fma_f32 v[58:59], v[88:89], v[12:13], v[58:59]
	v_pk_fma_f32 v[62:63], v[90:91], v[16:17], v[62:63]
	ds_read_b128 v[84:87], v33 offset:48976
	s_waitcnt lgkmcnt(2)
	v_pk_fma_f32 v[58:59], v[92:93], v[20:21], v[58:59]
	v_pk_fma_f32 v[62:63], v[94:95], v[22:23], v[62:63]
	ds_read_b128 v[88:91], v33 offset:48992
	s_waitcnt lgkmcnt(2)
	v_pk_fma_f32 v[58:59], v[80:81], v[24:25], v[58:59]
	v_pk_fma_f32 v[62:63], v[82:83], v[26:27], v[62:63]
	ds_read_b128 v[80:83], v33 offset:49008
	s_waitcnt lgkmcnt(2)
	v_pk_fma_f32 v[58:59], v[84:85], v[36:37], v[58:59]
	v_pk_fma_f32 v[62:63], v[86:87], v[38:39], v[62:63]
	ds_read_b128 v[84:87], v33 offset:49024
	s_waitcnt lgkmcnt(2)
	v_pk_fma_f32 v[58:59], v[88:89], v[42:43], v[58:59]
	v_pk_fma_f32 v[62:63], v[90:91], v[46:47], v[62:63]
	ds_read_b128 v[88:91], v33 offset:49040
	s_waitcnt lgkmcnt(2)
	v_pk_fma_f32 v[58:59], v[80:81], v[50:51], v[58:59]
	v_pk_fma_f32 v[62:63], v[82:83], v[54:55], v[62:63]
	ds_read_b128 v[80:83], v33 offset:49056
	s_waitcnt lgkmcnt(2)
	v_pk_fma_f32 v[58:59], v[84:85], v[56:57], v[58:59]
	v_pk_fma_f32 v[62:63], v[86:87], v[60:61], v[62:63]
	ds_read_b128 v[84:87], v33 offset:49072
	s_waitcnt lgkmcnt(2)
	v_pk_fma_f32 v[58:59], v[88:89], v[64:65], v[58:59]
	v_pk_fma_f32 v[62:63], v[90:91], v[68:69], v[62:63]
	ds_read_b128 v[88:91], v33 offset:49088
	s_waitcnt lgkmcnt(2)
	v_pk_fma_f32 v[58:59], v[80:81], v[70:71], v[58:59]
	v_pk_fma_f32 v[62:63], v[82:83], v[74:75], v[62:63]
	ds_read_b96 v[80:82], v33 offset:49104
	s_waitcnt lgkmcnt(2)
	v_pk_fma_f32 v[58:59], v[84:85], v[78:79], v[58:59]
	v_pk_fma_f32 v[62:63], v[86:87], v[76:77], v[62:63]
	s_waitcnt lgkmcnt(1)
	v_pk_fma_f32 v[58:59], v[88:89], v[72:73], v[58:59]
	v_pk_fma_f32 v[62:63], v[90:91], v[66:67], v[62:63]
	s_waitcnt lgkmcnt(0)
	v_pk_fma_f32 v[58:59], v[80:81], v[48:49], v[58:59]
	v_mov_b32_e32 v80, v62
	v_mov_b32_e32 v81, v58
	v_mov_b32_e32 v58, v63
	v_pk_add_f32 v[58:59], v[80:81], v[58:59]
	s_nop 0
	v_add_f32_e32 v19, v58, v59
	v_fmac_f32_e32 v19, v40, v82
	v_sub_f32_e32 v41, v52, v19
	ds_read_b128 v[80:83], v33 offset:49152
	ds_read_b128 v[84:87], v33 offset:49168
	ds_read_b128 v[88:91], v33 offset:49184
	ds_read_b128 v[92:95], v33 offset:49200
	s_waitcnt lgkmcnt(3)
	v_pk_fma_f32 v[52:53], v[80:81], v[0:1], 0 op_sel_hi:[1,1,0]
	v_pk_fma_f32 v[58:59], v[82:83], v[6:7], 0 op_sel_hi:[1,1,0]
	ds_read_b128 v[80:83], v33 offset:49216
	s_waitcnt lgkmcnt(3)
	v_pk_fma_f32 v[52:53], v[84:85], v[8:9], v[52:53]
	v_pk_fma_f32 v[58:59], v[86:87], v[10:11], v[58:59]
	s_waitcnt lgkmcnt(2)
	v_pk_fma_f32 v[52:53], v[88:89], v[12:13], v[52:53]
	v_pk_fma_f32 v[58:59], v[90:91], v[16:17], v[58:59]
	ds_read_b128 v[84:87], v33 offset:49232
	s_waitcnt lgkmcnt(2)
	v_pk_fma_f32 v[52:53], v[92:93], v[20:21], v[52:53]
	v_pk_fma_f32 v[58:59], v[94:95], v[22:23], v[58:59]
	ds_read_b128 v[88:91], v33 offset:49248
	s_waitcnt lgkmcnt(2)
	v_pk_fma_f32 v[52:53], v[80:81], v[24:25], v[52:53]
	v_pk_fma_f32 v[58:59], v[82:83], v[26:27], v[58:59]
	ds_read_b128 v[80:83], v33 offset:49264
	s_waitcnt lgkmcnt(2)
	v_pk_fma_f32 v[52:53], v[84:85], v[36:37], v[52:53]
	v_pk_fma_f32 v[58:59], v[86:87], v[38:39], v[58:59]
	ds_read_b128 v[84:87], v33 offset:49280
	s_waitcnt lgkmcnt(2)
	v_pk_fma_f32 v[52:53], v[88:89], v[42:43], v[52:53]
	v_pk_fma_f32 v[58:59], v[90:91], v[46:47], v[58:59]
	ds_read_b128 v[88:91], v33 offset:49296
	s_waitcnt lgkmcnt(2)
	v_pk_fma_f32 v[52:53], v[80:81], v[50:51], v[52:53]
	v_pk_fma_f32 v[58:59], v[82:83], v[54:55], v[58:59]
	ds_read_b128 v[80:83], v33 offset:49312
	s_waitcnt lgkmcnt(2)
	v_pk_fma_f32 v[52:53], v[84:85], v[56:57], v[52:53]
	v_pk_fma_f32 v[58:59], v[86:87], v[60:61], v[58:59]
	ds_read_b128 v[84:87], v33 offset:49328
	s_waitcnt lgkmcnt(2)
	v_pk_fma_f32 v[52:53], v[88:89], v[64:65], v[52:53]
	v_pk_fma_f32 v[58:59], v[90:91], v[68:69], v[58:59]
	ds_read_b128 v[88:91], v33 offset:49344
	s_waitcnt lgkmcnt(2)
	v_pk_fma_f32 v[52:53], v[80:81], v[70:71], v[52:53]
	v_pk_fma_f32 v[58:59], v[82:83], v[74:75], v[58:59]
	ds_read_b128 v[80:83], v33 offset:49360
	s_waitcnt lgkmcnt(2)
	v_pk_fma_f32 v[52:53], v[84:85], v[78:79], v[52:53]
	v_pk_fma_f32 v[58:59], v[86:87], v[76:77], v[58:59]
	s_waitcnt lgkmcnt(1)
	v_pk_fma_f32 v[52:53], v[88:89], v[72:73], v[52:53]
	v_pk_fma_f32 v[58:59], v[90:91], v[66:67], v[58:59]
	s_waitcnt lgkmcnt(0)
	v_pk_fma_f32 v[52:53], v[80:81], v[48:49], v[52:53]
	v_pk_fma_f32 v[58:59], v[82:83], v[40:41], v[58:59]
	v_mov_b32_e32 v62, v52
	v_mov_b32_e32 v63, v58
	v_mov_b32_e32 v58, v53
	v_pk_add_f32 v[52:53], v[62:63], v[58:59]
	s_nop 0
	v_pk_add_f32 v[52:53], v[52:53], v[52:53] op_sel:[0,1] op_sel_hi:[1,0]
	s_nop 0
	v_pk_add_f32 v[28:29], v[28:29], v[52:53] neg_lo:[0,1] neg_hi:[0,1]
	ds_read_b128 v[80:83], v33 offset:49408
	ds_read_b128 v[84:87], v33 offset:49424
	ds_read_b128 v[88:91], v33 offset:49440
	ds_read_b128 v[92:95], v33 offset:49456
	ds_read_b32 v19, v33 offset:49632
	s_waitcnt lgkmcnt(4)
; DI void gdn_pre(const Params& p, int ch, char* smem) {
;     ...
; #pragma unroll
;   for (int i = 1; i < 64; ++i) {
;     f32x2 sa = {0.f, 0.f}, sb = {0.f, 0.f};
;     const f32x2* arow = (const f32x2*)(Amat + i * 64);
; #pragma unroll
;     for (int k = 0; k < (i >> 1); ++k) {
;       const f32x2 a2 = arow[k];
;       if (k & 1) sb = __builtin_elementwise_fma(a2, c2[k], sb);
;       else sa = __builtin_elementwise_fma(a2, c2[k], sa);
;     }
;     float tot = (sa[0] + sa[1]) + (sb[0] + sb[1]);
;     if (i & 1) tot += Amat[i * 64 + i - 1] * c2[(i - 1) >> 1][0];
;     c2[i >> 1][i & 1] -= tot;
;     __builtin_amdgcn_sched_barrier(0);
;   }
	v_pk_fma_f32 v[52:53], v[80:81], v[0:1], 0 op_sel_hi:[1,1,0]
	v_pk_fma_f32 v[58:59], v[82:83], v[6:7], 0 op_sel_hi:[1,1,0]
	ds_read_b128 v[80:83], v33 offset:49472
	s_waitcnt lgkmcnt(4)
	v_pk_fma_f32 v[52:53], v[84:85], v[8:9], v[52:53]
	v_pk_fma_f32 v[58:59], v[86:87], v[10:11], v[58:59]
	s_waitcnt lgkmcnt(3)
	v_pk_fma_f32 v[52:53], v[88:89], v[12:13], v[52:53]
	v_pk_fma_f32 v[58:59], v[90:91], v[16:17], v[58:59]
	ds_read_b128 v[84:87], v33 offset:49488
	s_waitcnt lgkmcnt(3)
	v_pk_fma_f32 v[52:53], v[92:93], v[20:21], v[52:53]
	v_pk_fma_f32 v[58:59], v[94:95], v[22:23], v[58:59]
	ds_read_b128 v[88:91], v33 offset:49504
	s_waitcnt lgkmcnt(2)
	v_pk_fma_f32 v[52:53], v[80:81], v[24:25], v[52:53]
	v_pk_fma_f32 v[58:59], v[82:83], v[26:27], v[58:59]
	ds_read_b128 v[80:83], v33 offset:49520
	s_waitcnt lgkmcnt(2)
	v_pk_fma_f32 v[52:53], v[84:85], v[36:37], v[52:53]
	v_pk_fma_f32 v[58:59], v[86:87], v[38:39], v[58:59]
	ds_read_b128 v[84:87], v33 offset:49536
	s_waitcnt lgkmcnt(2)
	v_pk_fma_f32 v[52:53], v[88:89], v[42:43], v[52:53]
	v_pk_fma_f32 v[58:59], v[90:91], v[46:47], v[58:59]
	ds_read_b128 v[88:91], v33 offset:49552
	s_waitcnt lgkmcnt(2)
	v_pk_fma_f32 v[52:53], v[80:81], v[50:51], v[52:53]
	v_pk_fma_f32 v[58:59], v[82:83], v[54:55], v[58:59]
	ds_read_b128 v[80:83], v33 offset:49568
	s_waitcnt lgkmcnt(2)
	v_pk_fma_f32 v[52:53], v[84:85], v[56:57], v[52:53]
	v_pk_fma_f32 v[58:59], v[86:87], v[60:61], v[58:59]
	ds_read_b128 v[84:87], v33 offset:49584
	s_waitcnt lgkmcnt(2)
	v_pk_fma_f32 v[52:53], v[88:89], v[64:65], v[52:53]
	v_pk_fma_f32 v[58:59], v[90:91], v[68:69], v[58:59]
	ds_read_b128 v[88:91], v33 offset:49600
	s_waitcnt lgkmcnt(2)
	v_pk_fma_f32 v[52:53], v[80:81], v[70:71], v[52:53]
	v_pk_fma_f32 v[58:59], v[82:83], v[74:75], v[58:59]
	ds_read_b128 v[80:83], v33 offset:49616
	s_waitcnt lgkmcnt(2)
	v_pk_fma_f32 v[52:53], v[84:85], v[78:79], v[52:53]
	v_pk_fma_f32 v[58:59], v[86:87], v[76:77], v[58:59]
	s_waitcnt lgkmcnt(1)
	v_pk_fma_f32 v[52:53], v[88:89], v[72:73], v[52:53]
	v_pk_fma_f32 v[58:59], v[90:91], v[66:67], v[58:59]
	s_waitcnt lgkmcnt(0)
	v_pk_fma_f32 v[52:53], v[80:81], v[48:49], v[52:53]
	v_pk_fma_f32 v[58:59], v[82:83], v[40:41], v[58:59]
	v_mov_b32_e32 v62, v52
	v_mov_b32_e32 v63, v58
	v_mov_b32_e32 v58, v53
	v_pk_add_f32 v[52:53], v[62:63], v[58:59]
	s_nop 0
	v_add_f32_e32 v29, v52, v53
	v_fmac_f32_e32 v29, v28, v19
	v_sub_f32_e32 v29, v44, v29
	ds_read_b128 v[80:83], v33 offset:49664
	ds_read_b128 v[84:87], v33 offset:49680
	ds_read_b128 v[88:91], v33 offset:49696
	ds_read_b128 v[92:95], v33 offset:49712
	ds_read_b64 v[58:59], v33 offset:49888
	s_waitcnt lgkmcnt(4)
	v_pk_fma_f32 v[44:45], v[80:81], v[0:1], 0 op_sel_hi:[1,1,0]
	v_pk_fma_f32 v[52:53], v[82:83], v[6:7], 0 op_sel_hi:[1,1,0]
	ds_read_b128 v[80:83], v33 offset:49728
	s_waitcnt lgkmcnt(4)
	v_pk_fma_f32 v[44:45], v[84:85], v[8:9], v[44:45]
	v_pk_fma_f32 v[52:53], v[86:87], v[10:11], v[52:53]
	s_waitcnt lgkmcnt(3)
	v_pk_fma_f32 v[44:45], v[88:89], v[12:13], v[44:45]
	v_pk_fma_f32 v[52:53], v[90:91], v[16:17], v[52:53]
	ds_read_b128 v[84:87], v33 offset:49744
	s_waitcnt lgkmcnt(3)
	v_pk_fma_f32 v[44:45], v[92:93], v[20:21], v[44:45]
	v_pk_fma_f32 v[52:53], v[94:95], v[22:23], v[52:53]
	ds_read_b128 v[88:91], v33 offset:49760
	s_waitcnt lgkmcnt(2)
	v_pk_fma_f32 v[44:45], v[80:81], v[24:25], v[44:45]
	v_pk_fma_f32 v[52:53], v[82:83], v[26:27], v[52:53]
	ds_read_b128 v[80:83], v33 offset:49776
	s_waitcnt lgkmcnt(2)
	v_pk_fma_f32 v[44:45], v[84:85], v[36:37], v[44:45]
	v_pk_fma_f32 v[52:53], v[86:87], v[38:39], v[52:53]
	ds_read_b128 v[84:87], v33 offset:49792
	s_waitcnt lgkmcnt(2)
	v_pk_fma_f32 v[44:45], v[88:89], v[42:43], v[44:45]
	v_pk_fma_f32 v[52:53], v[90:91], v[46:47], v[52:53]
	ds_read_b128 v[88:91], v33 offset:49808
	s_waitcnt lgkmcnt(2)
	v_pk_fma_f32 v[44:45], v[80:81], v[50:51], v[44:45]
	v_pk_fma_f32 v[52:53], v[82:83], v[54:55], v[52:53]
	ds_read_b128 v[80:83], v33 offset:49824
	s_waitcnt lgkmcnt(2)
	v_pk_fma_f32 v[44:45], v[84:85], v[56:57], v[44:45]
	v_pk_fma_f32 v[52:53], v[86:87], v[60:61], v[52:53]
	s_waitcnt lgkmcnt(1)
	v_pk_fma_f32 v[44:45], v[88:89], v[64:65], v[44:45]
	ds_read_b128 v[84:87], v33 offset:49840
	v_pk_fma_f32 v[52:53], v[90:91], v[68:69], v[52:53]
	s_waitcnt lgkmcnt(1)
	v_pk_fma_f32 v[44:45], v[80:81], v[70:71], v[44:45]
	v_pk_fma_f32 v[52:53], v[82:83], v[74:75], v[52:53]
	ds_read_b128 v[80:83], v33 offset:49856
	ds_read_b128 v[88:91], v33 offset:49872
	s_waitcnt lgkmcnt(2)
	v_pk_fma_f32 v[44:45], v[84:85], v[78:79], v[44:45]
	v_pk_fma_f32 v[52:53], v[86:87], v[76:77], v[52:53]
	s_waitcnt lgkmcnt(1)
	v_pk_fma_f32 v[44:45], v[80:81], v[72:73], v[44:45]
	v_pk_fma_f32 v[52:53], v[82:83], v[66:67], v[52:53]
	s_waitcnt lgkmcnt(0)
	v_pk_fma_f32 v[44:45], v[88:89], v[48:49], v[44:45]
	v_pk_fma_f32 v[52:53], v[90:91], v[40:41], v[52:53]
	v_pk_fma_f32 v[44:45], v[58:59], v[28:29], v[44:45]
	v_mov_b32_e32 v58, v52
	v_mov_b32_e32 v59, v44
	v_mov_b32_e32 v44, v53
	v_pk_add_f32 v[44:45], v[58:59], v[44:45]
	s_nop 0
	v_pk_add_f32 v[44:45], v[44:45], v[44:45] op_sel:[0,1] op_sel_hi:[1,0]
	s_nop 0
	v_pk_add_f32 v[14:15], v[14:15], v[44:45] neg_lo:[0,1] neg_hi:[0,1]
	ds_read_b128 v[80:83], v33 offset:49920
	ds_read_b128 v[84:87], v33 offset:49936
	ds_read_b128 v[88:91], v33 offset:49952
	ds_read_b128 v[92:95], v33 offset:49968
	s_waitcnt lgkmcnt(3)
	v_pk_fma_f32 v[44:45], v[80:81], v[0:1], 0 op_sel_hi:[1,1,0]
	v_pk_fma_f32 v[52:53], v[82:83], v[6:7], 0 op_sel_hi:[1,1,0]
	ds_read_b128 v[80:83], v33 offset:49984
	s_waitcnt lgkmcnt(3)
	v_pk_fma_f32 v[44:45], v[84:85], v[8:9], v[44:45]
	v_pk_fma_f32 v[52:53], v[86:87], v[10:11], v[52:53]
	ds_read_b128 v[84:87], v33 offset:50000
	s_waitcnt lgkmcnt(3)
; DI void gdn_pre(const Params& p, int ch, char* smem) {
;     ...
; #pragma unroll
;   for (int i = 1; i < 64; ++i) {
;     f32x2 sa = {0.f, 0.f}, sb = {0.f, 0.f};
;     const f32x2* arow = (const f32x2*)(Amat + i * 64);
; #pragma unroll
;     for (int k = 0; k < (i >> 1); ++k) {
;       const f32x2 a2 = arow[k];
;       if (k & 1) sb = __builtin_elementwise_fma(a2, c2[k], sb);
;       else sa = __builtin_elementwise_fma(a2, c2[k], sa);
;     }
;     float tot = (sa[0] + sa[1]) + (sb[0] + sb[1]);
;     if (i & 1) tot += Amat[i * 64 + i - 1] * c2[(i - 1) >> 1][0];
;     c2[i >> 1][i & 1] -= tot;
;     __builtin_amdgcn_sched_barrier(0);
;   }
	v_pk_fma_f32 v[44:45], v[88:89], v[12:13], v[44:45]
	v_pk_fma_f32 v[52:53], v[90:91], v[16:17], v[52:53]
	s_waitcnt lgkmcnt(2)
	v_pk_fma_f32 v[44:45], v[92:93], v[20:21], v[44:45]
	v_pk_fma_f32 v[52:53], v[94:95], v[22:23], v[52:53]
	ds_read_b128 v[88:91], v33 offset:50016
	s_waitcnt lgkmcnt(2)
	v_pk_fma_f32 v[44:45], v[80:81], v[24:25], v[44:45]
	v_pk_fma_f32 v[52:53], v[82:83], v[26:27], v[52:53]
	ds_read_b128 v[80:83], v33 offset:50032
	s_waitcnt lgkmcnt(2)
	v_pk_fma_f32 v[44:45], v[84:85], v[36:37], v[44:45]
	v_pk_fma_f32 v[52:53], v[86:87], v[38:39], v[52:53]
	ds_read_b128 v[84:87], v33 offset:50048
	s_waitcnt lgkmcnt(2)
	v_pk_fma_f32 v[44:45], v[88:89], v[42:43], v[44:45]
	v_pk_fma_f32 v[52:53], v[90:91], v[46:47], v[52:53]
	ds_read_b128 v[88:91], v33 offset:50064
	s_waitcnt lgkmcnt(2)
	v_pk_fma_f32 v[44:45], v[80:81], v[50:51], v[44:45]
	v_pk_fma_f32 v[52:53], v[82:83], v[54:55], v[52:53]
	ds_read_b128 v[80:83], v33 offset:50080
	s_waitcnt lgkmcnt(2)
	v_pk_fma_f32 v[44:45], v[84:85], v[56:57], v[44:45]
	v_pk_fma_f32 v[52:53], v[86:87], v[60:61], v[52:53]
	ds_read_b128 v[84:87], v33 offset:50096
	s_waitcnt lgkmcnt(2)
	v_pk_fma_f32 v[44:45], v[88:89], v[64:65], v[44:45]
	v_pk_fma_f32 v[52:53], v[90:91], v[68:69], v[52:53]
	s_waitcnt lgkmcnt(1)
	v_pk_fma_f32 v[44:45], v[80:81], v[70:71], v[44:45]
	v_pk_fma_f32 v[52:53], v[82:83], v[74:75], v[52:53]
	ds_read_b128 v[80:83], v33 offset:50112
	ds_read_b128 v[88:91], v33 offset:50128
	s_waitcnt lgkmcnt(2)
	v_pk_fma_f32 v[44:45], v[84:85], v[78:79], v[44:45]
	v_pk_fma_f32 v[52:53], v[86:87], v[76:77], v[52:53]
	ds_read_b96 v[84:86], v33 offset:50144
	s_waitcnt lgkmcnt(2)
	v_pk_fma_f32 v[44:45], v[80:81], v[72:73], v[44:45]
	v_pk_fma_f32 v[52:53], v[82:83], v[66:67], v[52:53]
	s_waitcnt lgkmcnt(1)
	v_pk_fma_f32 v[44:45], v[88:89], v[48:49], v[44:45]
	v_pk_fma_f32 v[52:53], v[90:91], v[40:41], v[52:53]
	s_waitcnt lgkmcnt(0)
	v_pk_fma_f32 v[44:45], v[84:85], v[28:29], v[44:45]
	v_mov_b32_e32 v58, v52
	v_mov_b32_e32 v59, v44
	v_mov_b32_e32 v44, v53
	v_pk_add_f32 v[44:45], v[58:59], v[44:45]
	s_nop 0
	v_add_f32_e32 v15, v44, v45
	v_fmac_f32_e32 v15, v14, v86
	v_sub_f32_e32 v15, v30, v15
	ds_read_b128 v[80:83], v33 offset:50176
	ds_read_b128 v[84:87], v33 offset:50192
	ds_read_b128 v[88:91], v33 offset:50208
	ds_read_b128 v[92:95], v33 offset:50224
	s_waitcnt lgkmcnt(3)
	v_pk_fma_f32 v[30:31], v[80:81], v[0:1], 0 op_sel_hi:[1,1,0]
	v_pk_fma_f32 v[44:45], v[82:83], v[6:7], 0 op_sel_hi:[1,1,0]
	ds_read_b128 v[80:83], v33 offset:50240
	s_waitcnt lgkmcnt(3)
	v_pk_fma_f32 v[30:31], v[84:85], v[8:9], v[30:31]
	v_pk_fma_f32 v[44:45], v[86:87], v[10:11], v[44:45]
	ds_read_b128 v[84:87], v33 offset:50256
	s_waitcnt lgkmcnt(3)
	v_pk_fma_f32 v[30:31], v[88:89], v[12:13], v[30:31]
	v_pk_fma_f32 v[44:45], v[90:91], v[16:17], v[44:45]
	s_waitcnt lgkmcnt(2)
	v_pk_fma_f32 v[30:31], v[92:93], v[20:21], v[30:31]
	v_pk_fma_f32 v[44:45], v[94:95], v[22:23], v[44:45]
	ds_read_b128 v[88:91], v33 offset:50272
	s_waitcnt lgkmcnt(2)
	v_pk_fma_f32 v[30:31], v[80:81], v[24:25], v[30:31]
	v_pk_fma_f32 v[44:45], v[82:83], v[26:27], v[44:45]
	ds_read_b128 v[80:83], v33 offset:50288
	s_waitcnt lgkmcnt(2)
	v_pk_fma_f32 v[30:31], v[84:85], v[36:37], v[30:31]
	v_pk_fma_f32 v[44:45], v[86:87], v[38:39], v[44:45]
	ds_read_b128 v[84:87], v33 offset:50304
	s_waitcnt lgkmcnt(2)
	v_pk_fma_f32 v[30:31], v[88:89], v[42:43], v[30:31]
	v_pk_fma_f32 v[44:45], v[90:91], v[46:47], v[44:45]
	ds_read_b128 v[88:91], v33 offset:50320
	s_waitcnt lgkmcnt(2)
	v_pk_fma_f32 v[30:31], v[80:81], v[50:51], v[30:31]
	v_pk_fma_f32 v[44:45], v[82:83], v[54:55], v[44:45]
	ds_read_b128 v[80:83], v33 offset:50336
	s_waitcnt lgkmcnt(2)
	v_pk_fma_f32 v[30:31], v[84:85], v[56:57], v[30:31]
	v_pk_fma_f32 v[44:45], v[86:87], v[60:61], v[44:45]
	ds_read_b128 v[84:87], v33 offset:50352
	s_waitcnt lgkmcnt(2)
	v_pk_fma_f32 v[30:31], v[88:89], v[64:65], v[30:31]
	v_pk_fma_f32 v[44:45], v[90:91], v[68:69], v[44:45]
	s_waitcnt lgkmcnt(1)
	v_pk_fma_f32 v[30:31], v[80:81], v[70:71], v[30:31]
	v_pk_fma_f32 v[44:45], v[82:83], v[74:75], v[44:45]
	ds_read_b128 v[80:83], v33 offset:50368
	ds_read_b128 v[88:91], v33 offset:50384
	s_waitcnt lgkmcnt(2)
	v_pk_fma_f32 v[30:31], v[84:85], v[78:79], v[30:31]
	v_pk_fma_f32 v[44:45], v[86:87], v[76:77], v[44:45]
	ds_read_b128 v[84:87], v33 offset:50400
	s_waitcnt lgkmcnt(2)
	v_pk_fma_f32 v[30:31], v[80:81], v[72:73], v[30:31]
	v_pk_fma_f32 v[44:45], v[82:83], v[66:67], v[44:45]
	s_waitcnt lgkmcnt(1)
	v_pk_fma_f32 v[30:31], v[88:89], v[48:49], v[30:31]
	v_pk_fma_f32 v[44:45], v[90:91], v[40:41], v[44:45]
	s_waitcnt lgkmcnt(0)
	v_pk_fma_f32 v[30:31], v[84:85], v[28:29], v[30:31]
	v_pk_fma_f32 v[44:45], v[86:87], v[14:15], v[44:45]
	v_mov_b32_e32 v52, v30
	v_mov_b32_e32 v53, v44
	v_mov_b32_e32 v44, v31
	v_pk_add_f32 v[30:31], v[52:53], v[44:45]
	s_nop 0
	v_pk_add_f32 v[30:31], v[30:31], v[30:31] op_sel:[0,1] op_sel_hi:[1,0]
	s_nop 0
	v_pk_add_f32 v[4:5], v[4:5], v[30:31] neg_lo:[0,1] neg_hi:[0,1]
	ds_read_b128 v[80:83], v33 offset:50432
	ds_read_b128 v[84:87], v33 offset:50448
	ds_read_b128 v[88:91], v33 offset:50464
	ds_read_b128 v[92:95], v33 offset:50480
	ds_read_b32 v5, v33 offset:50672
	s_waitcnt lgkmcnt(4)
	v_pk_fma_f32 v[30:31], v[80:81], v[0:1], 0 op_sel_hi:[1,1,0]
	v_pk_fma_f32 v[44:45], v[82:83], v[6:7], 0 op_sel_hi:[1,1,0]
	ds_read_b128 v[80:83], v33 offset:50496
	s_waitcnt lgkmcnt(4)
	v_pk_fma_f32 v[30:31], v[84:85], v[8:9], v[30:31]
	v_pk_fma_f32 v[44:45], v[86:87], v[10:11], v[44:45]
	ds_read_b128 v[84:87], v33 offset:50512
	s_waitcnt lgkmcnt(4)
	v_pk_fma_f32 v[30:31], v[88:89], v[12:13], v[30:31]
	v_pk_fma_f32 v[44:45], v[90:91], v[16:17], v[44:45]
	s_waitcnt lgkmcnt(3)
; DI void gdn_pre(const Params& p, int ch, char* smem) {
;     ...
; #pragma unroll
;   for (int i = 1; i < 64; ++i) {
;     f32x2 sa = {0.f, 0.f}, sb = {0.f, 0.f};
;     const f32x2* arow = (const f32x2*)(Amat + i * 64);
; #pragma unroll
;     for (int k = 0; k < (i >> 1); ++k) {
;       const f32x2 a2 = arow[k];
;       if (k & 1) sb = __builtin_elementwise_fma(a2, c2[k], sb);
;       else sa = __builtin_elementwise_fma(a2, c2[k], sa);
;     }
;     float tot = (sa[0] + sa[1]) + (sb[0] + sb[1]);
;     if (i & 1) tot += Amat[i * 64 + i - 1] * c2[(i - 1) >> 1][0];
;     c2[i >> 1][i & 1] -= tot;
;     __builtin_amdgcn_sched_barrier(0);
;   }
	v_pk_fma_f32 v[30:31], v[92:93], v[20:21], v[30:31]
	v_pk_fma_f32 v[44:45], v[94:95], v[22:23], v[44:45]
	ds_read_b128 v[88:91], v33 offset:50528
	s_waitcnt lgkmcnt(2)
	v_pk_fma_f32 v[30:31], v[80:81], v[24:25], v[30:31]
	v_pk_fma_f32 v[44:45], v[82:83], v[26:27], v[44:45]
	ds_read_b128 v[80:83], v33 offset:50544
	s_waitcnt lgkmcnt(2)
	v_pk_fma_f32 v[30:31], v[84:85], v[36:37], v[30:31]
	v_pk_fma_f32 v[44:45], v[86:87], v[38:39], v[44:45]
	ds_read_b128 v[84:87], v33 offset:50560
	s_waitcnt lgkmcnt(2)
	v_pk_fma_f32 v[30:31], v[88:89], v[42:43], v[30:31]
	v_pk_fma_f32 v[44:45], v[90:91], v[46:47], v[44:45]
	ds_read_b128 v[88:91], v33 offset:50576
	s_waitcnt lgkmcnt(2)
	v_pk_fma_f32 v[30:31], v[80:81], v[50:51], v[30:31]
	v_pk_fma_f32 v[44:45], v[82:83], v[54:55], v[44:45]
	ds_read_b128 v[80:83], v33 offset:50592
	s_waitcnt lgkmcnt(2)
	v_pk_fma_f32 v[30:31], v[84:85], v[56:57], v[30:31]
	v_pk_fma_f32 v[44:45], v[86:87], v[60:61], v[44:45]
	ds_read_b128 v[84:87], v33 offset:50608
	s_waitcnt lgkmcnt(2)
	v_pk_fma_f32 v[30:31], v[88:89], v[64:65], v[30:31]
	v_pk_fma_f32 v[44:45], v[90:91], v[68:69], v[44:45]
	ds_read_b128 v[88:91], v33 offset:50624
	s_waitcnt lgkmcnt(2)
	v_pk_fma_f32 v[30:31], v[80:81], v[70:71], v[30:31]
	v_pk_fma_f32 v[44:45], v[82:83], v[74:75], v[44:45]
	ds_read_b128 v[80:83], v33 offset:50640
	s_waitcnt lgkmcnt(2)
	v_pk_fma_f32 v[30:31], v[84:85], v[78:79], v[30:31]
	v_pk_fma_f32 v[44:45], v[86:87], v[76:77], v[44:45]
	ds_read_b128 v[84:87], v33 offset:50656
	s_waitcnt lgkmcnt(2)
	v_pk_fma_f32 v[30:31], v[88:89], v[72:73], v[30:31]
	v_pk_fma_f32 v[44:45], v[90:91], v[66:67], v[44:45]
	s_waitcnt lgkmcnt(1)
	v_pk_fma_f32 v[30:31], v[80:81], v[48:49], v[30:31]
	v_pk_fma_f32 v[44:45], v[82:83], v[40:41], v[44:45]
	s_waitcnt lgkmcnt(0)
	v_pk_fma_f32 v[30:31], v[84:85], v[28:29], v[30:31]
	v_pk_fma_f32 v[44:45], v[86:87], v[14:15], v[44:45]
	v_mov_b32_e32 v52, v30
	v_mov_b32_e32 v53, v44
	v_mov_b32_e32 v44, v31
	v_pk_add_f32 v[30:31], v[52:53], v[44:45]
	s_nop 0
	v_add_f32_e32 v19, v30, v31
	v_fmac_f32_e32 v19, v4, v5
	v_sub_f32_e32 v5, v18, v19
	ds_read_b128 v[80:83], v33 offset:50688
	ds_read_b128 v[84:87], v33 offset:50704
	ds_read_b128 v[88:91], v33 offset:50720
	ds_read_b128 v[92:95], v33 offset:50736
	ds_read_b64 v[44:45], v33 offset:50928
	s_waitcnt lgkmcnt(4)
	v_pk_fma_f32 v[18:19], v[80:81], v[0:1], 0 op_sel_hi:[1,1,0]
	v_pk_fma_f32 v[30:31], v[82:83], v[6:7], 0 op_sel_hi:[1,1,0]
	ds_read_b128 v[80:83], v33 offset:50752
	s_waitcnt lgkmcnt(4)
	v_pk_fma_f32 v[18:19], v[84:85], v[8:9], v[18:19]
	v_pk_fma_f32 v[30:31], v[86:87], v[10:11], v[30:31]
	ds_read_b128 v[84:87], v33 offset:50768
	s_waitcnt lgkmcnt(4)
	v_pk_fma_f32 v[18:19], v[88:89], v[12:13], v[18:19]
	v_pk_fma_f32 v[30:31], v[90:91], v[16:17], v[30:31]
	s_waitcnt lgkmcnt(3)
	v_pk_fma_f32 v[18:19], v[92:93], v[20:21], v[18:19]
	v_pk_fma_f32 v[30:31], v[94:95], v[22:23], v[30:31]
	ds_read_b128 v[88:91], v33 offset:50784
	s_waitcnt lgkmcnt(2)
	v_pk_fma_f32 v[18:19], v[80:81], v[24:25], v[18:19]
	v_pk_fma_f32 v[30:31], v[82:83], v[26:27], v[30:31]
	ds_read_b128 v[80:83], v33 offset:50800
	s_waitcnt lgkmcnt(2)
	v_pk_fma_f32 v[18:19], v[84:85], v[36:37], v[18:19]
	v_pk_fma_f32 v[30:31], v[86:87], v[38:39], v[30:31]
	ds_read_b128 v[84:87], v33 offset:50816
	s_waitcnt lgkmcnt(2)
	v_pk_fma_f32 v[18:19], v[88:89], v[42:43], v[18:19]
	v_pk_fma_f32 v[30:31], v[90:91], v[46:47], v[30:31]
	ds_read_b128 v[88:91], v33 offset:50832
	s_waitcnt lgkmcnt(2)
	v_pk_fma_f32 v[18:19], v[80:81], v[50:51], v[18:19]
	v_pk_fma_f32 v[30:31], v[82:83], v[54:55], v[30:31]
	ds_read_b128 v[80:83], v33 offset:50848
	s_waitcnt lgkmcnt(2)
	v_pk_fma_f32 v[18:19], v[84:85], v[56:57], v[18:19]
	v_pk_fma_f32 v[30:31], v[86:87], v[60:61], v[30:31]
	ds_read_b128 v[84:87], v33 offset:50864
	s_waitcnt lgkmcnt(2)
	v_pk_fma_f32 v[18:19], v[88:89], v[64:65], v[18:19]
	v_pk_fma_f32 v[30:31], v[90:91], v[68:69], v[30:31]
	ds_read_b128 v[88:91], v33 offset:50880
	s_waitcnt lgkmcnt(2)
	v_pk_fma_f32 v[18:19], v[80:81], v[70:71], v[18:19]
	v_pk_fma_f32 v[30:31], v[82:83], v[74:75], v[30:31]
	ds_read_b128 v[80:83], v33 offset:50896
	s_waitcnt lgkmcnt(2)
	v_pk_fma_f32 v[18:19], v[84:85], v[78:79], v[18:19]
	v_pk_fma_f32 v[30:31], v[86:87], v[76:77], v[30:31]
	ds_read_b128 v[84:87], v33 offset:50912
	s_waitcnt lgkmcnt(2)
	v_pk_fma_f32 v[18:19], v[88:89], v[72:73], v[18:19]
	v_pk_fma_f32 v[30:31], v[90:91], v[66:67], v[30:31]
	s_waitcnt lgkmcnt(1)
	v_pk_fma_f32 v[18:19], v[80:81], v[48:49], v[18:19]
	v_pk_fma_f32 v[30:31], v[82:83], v[40:41], v[30:31]
	s_waitcnt lgkmcnt(0)
	v_pk_fma_f32 v[18:19], v[84:85], v[28:29], v[18:19]
	v_pk_fma_f32 v[30:31], v[86:87], v[14:15], v[30:31]
	v_pk_fma_f32 v[18:19], v[44:45], v[4:5], v[18:19]
	v_pk_add_f32 v[30:31], v[30:31], v[30:31] op_sel:[0,1] op_sel_hi:[1,0]
	v_pk_add_f32 v[18:19], v[18:19], v[18:19] op_sel:[0,1] op_sel_hi:[1,0]
	s_nop 0
	v_pk_add_f32 v[18:19], v[30:31], v[18:19]
	s_nop 0
	v_pk_add_f32 v[18:19], v[2:3], v[18:19] neg_lo:[0,1] neg_hi:[0,1]
	ds_read_b128 v[80:83], v33 offset:50944
	ds_read_b128 v[84:87], v33 offset:50960
	ds_read_b128 v[88:91], v33 offset:50976
	ds_read_b128 v[92:95], v33 offset:50992
	s_waitcnt lgkmcnt(3)
	v_pk_fma_f32 v[30:31], v[80:81], v[0:1], 0 op_sel_hi:[1,1,0]
	v_pk_fma_f32 v[44:45], v[82:83], v[6:7], 0 op_sel_hi:[1,1,0]
	ds_read_b128 v[80:83], v33 offset:51008
	s_waitcnt lgkmcnt(3)
	v_pk_fma_f32 v[30:31], v[84:85], v[8:9], v[30:31]
	v_pk_fma_f32 v[44:45], v[86:87], v[10:11], v[44:45]
	ds_read_b128 v[84:87], v33 offset:51024
	s_waitcnt lgkmcnt(3)
	v_pk_fma_f32 v[30:31], v[88:89], v[12:13], v[30:31]
	v_pk_fma_f32 v[44:45], v[90:91], v[16:17], v[44:45]
	ds_read_b128 v[88:91], v33 offset:51040
	s_waitcnt lgkmcnt(3)
; DI void gdn_pre(const Params& p, int ch, char* smem) {
;     ...
; #pragma unroll
;   for (int i = 1; i < 64; ++i) {
;     f32x2 sa = {0.f, 0.f}, sb = {0.f, 0.f};
;     const f32x2* arow = (const f32x2*)(Amat + i * 64);
; #pragma unroll
;     for (int k = 0; k < (i >> 1); ++k) {
;       const f32x2 a2 = arow[k];
;       if (k & 1) sb = __builtin_elementwise_fma(a2, c2[k], sb);
;       else sa = __builtin_elementwise_fma(a2, c2[k], sa);
;     }
;     float tot = (sa[0] + sa[1]) + (sb[0] + sb[1]);
;     if (i & 1) tot += Amat[i * 64 + i - 1] * c2[(i - 1) >> 1][0];
;     c2[i >> 1][i & 1] -= tot;
;     __builtin_amdgcn_sched_barrier(0);
;   }
;   if (tid < 128) {
	v_pk_fma_f32 v[30:31], v[92:93], v[20:21], v[30:31]
	v_pk_fma_f32 v[44:45], v[94:95], v[22:23], v[44:45]
	s_waitcnt lgkmcnt(2)
	v_pk_fma_f32 v[30:31], v[80:81], v[24:25], v[30:31]
	v_pk_fma_f32 v[44:45], v[82:83], v[26:27], v[44:45]
	ds_read_b128 v[80:83], v33 offset:51056
	s_waitcnt lgkmcnt(2)
	v_pk_fma_f32 v[30:31], v[84:85], v[36:37], v[30:31]
	v_pk_fma_f32 v[44:45], v[86:87], v[38:39], v[44:45]
	ds_read_b128 v[84:87], v33 offset:51072
	s_waitcnt lgkmcnt(2)
	v_pk_fma_f32 v[30:31], v[88:89], v[42:43], v[30:31]
	v_pk_fma_f32 v[44:45], v[90:91], v[46:47], v[44:45]
	ds_read_b128 v[88:91], v33 offset:51088
	s_waitcnt lgkmcnt(2)
	v_pk_fma_f32 v[30:31], v[80:81], v[50:51], v[30:31]
	v_pk_fma_f32 v[44:45], v[82:83], v[54:55], v[44:45]
	ds_read_b128 v[80:83], v33 offset:51104
	s_waitcnt lgkmcnt(2)
	v_pk_fma_f32 v[30:31], v[84:85], v[56:57], v[30:31]
	v_pk_fma_f32 v[44:45], v[86:87], v[60:61], v[44:45]
	ds_read_b128 v[84:87], v33 offset:51120
	s_waitcnt lgkmcnt(2)
	v_pk_fma_f32 v[30:31], v[88:89], v[64:65], v[30:31]
	v_pk_fma_f32 v[44:45], v[90:91], v[68:69], v[44:45]
	ds_read_b128 v[88:91], v33 offset:51136
	s_waitcnt lgkmcnt(2)
	v_pk_fma_f32 v[30:31], v[80:81], v[70:71], v[30:31]
	v_pk_fma_f32 v[44:45], v[82:83], v[74:75], v[44:45]
	ds_read_b128 v[80:83], v33 offset:51152
	s_waitcnt lgkmcnt(2)
	v_pk_fma_f32 v[30:31], v[84:85], v[78:79], v[30:31]
	v_pk_fma_f32 v[44:45], v[86:87], v[76:77], v[44:45]
	ds_read_b128 v[84:87], v33 offset:51168
	s_waitcnt lgkmcnt(2)
	v_pk_fma_f32 v[30:31], v[88:89], v[72:73], v[30:31]
	v_pk_fma_f32 v[44:45], v[90:91], v[66:67], v[44:45]
	ds_read_b96 v[88:90], v33 offset:51184
	s_waitcnt lgkmcnt(2)
	v_pk_fma_f32 v[30:31], v[80:81], v[48:49], v[30:31]
	v_pk_fma_f32 v[44:45], v[82:83], v[40:41], v[44:45]
	s_waitcnt lgkmcnt(1)
	v_pk_fma_f32 v[30:31], v[84:85], v[28:29], v[30:31]
	v_pk_fma_f32 v[44:45], v[86:87], v[14:15], v[44:45]
	s_waitcnt lgkmcnt(0)
	v_pk_fma_f32 v[30:31], v[88:89], v[4:5], v[30:31]
	v_add_f32_e32 v19, v44, v45
	v_add_f32_e32 v2, v30, v31
	v_add_f32_e32 v2, v19, v2
	v_fmac_f32_e32 v2, v18, v90
	v_sub_f32_e32 v2, v3, v2
	s_and_saveexec_b64 s[0:1], vcc
	s_xor_b64 s[6:7], exec, s[0:1]
	s_cbranch_execz .LBB0_370
; DI bf16_t f2bf(float f) { return (bf16_t)(pk2(f, 0.f) & 0xffffu); }
; DI int fragoff(int row, int k, int KS) { return (((row >> 4) * KS + (k >> 5)) << 9) + (((((k >> 3) & 3) << 4) + (row & 15)) << 3) + (k & 7); }
; DI void gdn_pre(const Params& p, int ch, char* smem) {
;     ...
;   } else {
;     const int cc = tid - 128;
; #pragma unroll
;     for (int tt = 0; tt < 64; ++tt) o_w[fragoff(tt, cc, 4)] = f2bf(c2[tt >> 1][tt & 1]);
;   }
	v_lshlrev_b32_e32 v3, 4, v34
	v_cvt_pk_bf16_f32 v0, v0, s0
	s_movk_i32 s0, 0xfe00
	v_and_b32_e32 v19, 0x180, v3
	v_and_or_b32 v3, v3, s0, v32
	v_add_u32_e32 v32, 0xfffff800, v3
	v_or_b32_e32 v30, v32, v19
	v_ashrrev_i32_e32 v31, 31, v30
	v_lshl_add_u64 v[44:45], v[30:31], 1, s[34:35]
	v_mov_b32_e32 v246, v44
	v_mov_b32_e32 v247, v45
	global_store_short v[44:45], v0, off
	v_cvt_pk_bf16_f32 v35, v1, s0
	v_cvt_pk_bf16_f32 v6, v6, s0
	global_store_short v[246:247], v6, off offset:32
	v_cvt_pk_bf16_f32 v6, v7, s0
	global_store_short v[246:247], v6, off offset:48
	v_cvt_pk_bf16_f32 v6, v8, s0
	global_store_short v[246:247], v6, off offset:64
	v_cvt_pk_bf16_f32 v6, v9, s0
	global_store_short v[246:247], v6, off offset:80
	v_cvt_pk_bf16_f32 v6, v10, s0
	global_store_short v[246:247], v6, off offset:96
	v_cvt_pk_bf16_f32 v6, v11, s0
	global_store_short v[246:247], v6, off offset:112
	v_cvt_pk_bf16_f32 v6, v12, s0
	global_store_short v[246:247], v6, off offset:128
	v_cvt_pk_bf16_f32 v6, v13, s0
	global_store_short v[246:247], v6, off offset:144
	v_cvt_pk_bf16_f32 v6, v16, s0
	global_store_short v[246:247], v6, off offset:160
	v_cvt_pk_bf16_f32 v6, v17, s0
	global_store_short v[246:247], v6, off offset:176
	v_cvt_pk_bf16_f32 v6, v20, s0
	global_store_short v[246:247], v6, off offset:192
	v_cvt_pk_bf16_f32 v6, v21, s0
	global_store_short v[246:247], v6, off offset:208
	v_cvt_pk_bf16_f32 v6, v22, s0
	global_store_short v[246:247], v6, off offset:224
	v_cvt_pk_bf16_f32 v6, v23, s0
	global_store_short v[246:247], v35, off offset:16
	global_store_short v[246:247], v6, off offset:240
	v_or_b32_e32 v0, v3, v19
	v_ashrrev_i32_e32 v1, 31, v0
	v_cvt_pk_bf16_f32 v8, v24, s0
	v_lshl_add_u64 v[6:7], v[0:1], 1, s[34:35]
	v_ashrrev_i32_e32 v1, 31, v3
	global_store_short v[6:7], v8, off
	v_cvt_pk_bf16_f32 v6, v25, s0
	v_lshl_add_u64 v[0:1], v[0:1], 1, s[34:35]
	global_store_short v[0:1], v6, off offset:16
	v_cvt_pk_bf16_f32 v6, v26, s0
	global_store_short v[0:1], v6, off offset:32
	v_cvt_pk_bf16_f32 v6, v27, s0
	global_store_short v[0:1], v6, off offset:48
	v_cvt_pk_bf16_f32 v6, v36, s0
	global_store_short v[0:1], v6, off offset:64
	v_cvt_pk_bf16_f32 v6, v37, s0
	global_store_short v[0:1], v6, off offset:80
	v_cvt_pk_bf16_f32 v6, v38, s0
	global_store_short v[0:1], v6, off offset:96
	v_cvt_pk_bf16_f32 v6, v39, s0
	global_store_short v[0:1], v6, off offset:112
	v_cvt_pk_bf16_f32 v6, v42, s0
	global_store_short v[0:1], v6, off offset:128
	v_cvt_pk_bf16_f32 v6, v43, s0
	global_store_short v[0:1], v6, off offset:144
	v_cvt_pk_bf16_f32 v6, v46, s0
	global_store_short v[0:1], v6, off offset:160
	v_cvt_pk_bf16_f32 v6, v47, s0
	global_store_short v[0:1], v6, off offset:176
	v_cvt_pk_bf16_f32 v6, v50, s0
	global_store_short v[0:1], v6, off offset:192
	v_cvt_pk_bf16_f32 v6, v51, s0
	global_store_short v[0:1], v6, off offset:208
	v_cvt_pk_bf16_f32 v6, v54, s0
	global_store_short v[0:1], v6, off offset:224
	v_cvt_pk_bf16_f32 v6, v55, s0
	v_add_u32_e32 v9, 0x800, v3
	global_store_short v[0:1], v6, off offset:240
	v_or_b32_e32 v0, v9, v19
	v_ashrrev_i32_e32 v1, 31, v0
	v_cvt_pk_bf16_f32 v8, v56, s0
	v_lshl_add_u64 v[6:7], v[0:1], 1, s[34:35]
	v_ashrrev_i32_e32 v1, 31, v9
	global_store_short v[6:7], v8, off
	v_cvt_pk_bf16_f32 v6, v57, s0
	v_lshl_add_u64 v[0:1], v[0:1], 1, s[34:35]
	global_store_short v[0:1], v6, off offset:16
	v_cvt_pk_bf16_f32 v6, v60, s0
	global_store_short v[0:1], v6, off offset:32
	v_cvt_pk_bf16_f32 v6, v61, s0
	global_store_short v[0:1], v6, off offset:48
	v_cvt_pk_bf16_f32 v6, v64, s0
	global_store_short v[0:1], v6, off offset:64
	v_cvt_pk_bf16_f32 v6, v65, s0
	global_store_short v[0:1], v6, off offset:80
	v_cvt_pk_bf16_f32 v6, v68, s0
	global_store_short v[0:1], v6, off offset:96
	v_cvt_pk_bf16_f32 v6, v69, s0
	global_store_short v[0:1], v6, off offset:112
	v_cvt_pk_bf16_f32 v6, v70, s0
	global_store_short v[0:1], v6, off offset:128
	v_cvt_pk_bf16_f32 v6, v71, s0
	global_store_short v[0:1], v6, off offset:144
	v_cvt_pk_bf16_f32 v6, v74, s0
	global_store_short v[0:1], v6, off offset:160
	v_cvt_pk_bf16_f32 v6, v75, s0
	global_store_short v[0:1], v6, off offset:176
	v_cvt_pk_bf16_f32 v6, v78, s0
	global_store_short v[0:1], v6, off offset:192
	v_cvt_pk_bf16_f32 v6, v79, s0
	global_store_short v[0:1], v6, off offset:208
	v_cvt_pk_bf16_f32 v6, v76, s0
	global_store_short v[0:1], v6, off offset:224
	v_cvt_pk_bf16_f32 v6, v77, s0
	v_add_u32_e32 v3, 0x1000, v3
	global_store_short v[0:1], v6, off offset:240
	v_or_b32_e32 v0, v3, v19
	v_ashrrev_i32_e32 v1, 31, v0
	v_lshl_add_u64 v[6:7], v[0:1], 1, s[34:35]
	v_ashrrev_i32_e32 v1, 31, v3
	v_cvt_pk_bf16_f32 v8, v72, s0
	v_lshl_add_u64 v[0:1], v[0:1], 1, s[34:35]
	v_cvt_pk_bf16_f32 v3, v66, s0
	global_store_short v[6:7], v8, off
	global_store_short v[0:1], v3, off offset:32
	v_cvt_pk_bf16_f32 v3, v67, s0
	global_store_short v[0:1], v3, off offset:48
	v_cvt_pk_bf16_f32 v3, v48, s0
	global_store_short v[0:1], v3, off offset:64
	v_cvt_pk_bf16_f32 v3, v49, s0
	global_store_short v[0:1], v3, off offset:80
	v_cvt_pk_bf16_f32 v3, v40, s0
	global_store_short v[0:1], v3, off offset:96
	v_cvt_pk_bf16_f32 v3, v41, s0
	global_store_short v[0:1], v3, off offset:112
	v_cvt_pk_bf16_f32 v3, v28, s0
	global_store_short v[0:1], v3, off offset:128
	v_cvt_pk_bf16_f32 v3, v29, s0
	global_store_short v[0:1], v3, off offset:144
	v_cvt_pk_bf16_f32 v3, v14, s0
	global_store_short v[0:1], v3, off offset:160
	v_cvt_pk_bf16_f32 v3, v15, s0
	global_store_short v[0:1], v3, off offset:176
	v_cvt_pk_bf16_f32 v3, v4, s0
	global_store_short v[0:1], v3, off offset:192
	v_cvt_pk_bf16_f32 v3, v5, s0
	v_cvt_pk_bf16_f32 v6, v73, s0
	global_store_short v[0:1], v3, off offset:208
	v_cvt_pk_bf16_f32 v3, v18, s0
	v_cvt_pk_bf16_f32 v2, v2, s0
	global_store_short v[0:1], v6, off offset:16
	global_store_short v[0:1], v3, off offset:224
	global_store_short v[0:1], v2, off offset:240

; DI void conv32(const bf16_t* __restrict__ Pcol, int tok, int spos, const float* wl, int wstride, float* acc) {
; #pragma unroll
;   for (int hq = 0; hq < 2; ++hq) {
;     __builtin_amdgcn_sched_barrier(0);
;     uint4 v[4][2];
; #pragma unroll
;     for (int j = 0; j < 4; ++j) {
;       const bool ok = (spos - 3 + j >= 0);
;       const uint4* src = (const uint4*)(Pcol + (size_t)(tok - 3 + (ok ? j : 3)) * 4096) + 2 * hq;
; #pragma unroll
;       for (int q = 0; q < 2; ++q) {
;         v[j][q] = src[q];
;         if (!ok) v[j][q] = make_uint4(0u, 0u, 0u, 0u);
;       }
;     }
; DI void mlstm_pre(const Params& p, int ch, char* smem) {
;     ...
;   const int t = tid >> 2, part = tid & 3;
;   const float wgt = __expf(b_last - s_bc[t] + s_li[t] - m_new);
;   {
;     float a[32];
;     conv32(P + 2048 + h * 128 + part * 32, tok0 + t, c * 64 + t, s_w + part * 32, 256, a);
.LBB0_404:
	s_or_b64 exec, exec, s[10:11]
	s_mul_i32 s9, s44, 0xe000
	s_mul_hi_i32 s8, s44, 0xe000
	s_add_u32 s60, s84, s9
	s_waitcnt vmcnt(63) expcnt(7) lgkmcnt(15)
	s_barrier
	ds_read2st64_b32 v[2:3], v2 offset0:136 offset1:138
	s_addc_u32 s61, s85, s8
	s_add_u32 s66, s60, 0x4000
	s_addc_u32 s67, s61, 0
	s_add_u32 s64, s60, 0x8000
	s_addc_u32 s65, s61, 0
	s_waitcnt lgkmcnt(0)
	v_sub_f32_e32 v0, v0, v3
	s_lshl_b32 s34, s34, 8
	v_add_f32_e32 v0, v0, v2
	s_add_u32 s8, s3, s34
	v_sub_f32_e32 v0, v0, v1
	s_addc_u32 s9, s4, 0
	v_add_u32_e32 v8, s70, v79
	v_mul_f32_e32 v0, 0x3fb8aa3b, v0
	v_lshl_add_u64 v[16:17], s[8:9], 0, v[28:29]
	v_add_u32_e32 v9, s90, v79
	v_add_u32_e32 v18, -3, v8
	v_exp_f32_e32 v83, v0
	v_lshlrev_b32_e32 v84, 7, v81
	v_cmp_lt_i32_e64 s[10:11], 2, v9
	v_cmp_lt_i32_e64 s[12:13], 1, v9
	v_cmp_lt_i32_e64 s[14:15], 0, v9
	v_cndmask_b32_e64 v0, v8, v18, s[10:11]
	v_ashrrev_i32_e32 v1, 31, v0
	v_lshlrev_b64 v[10:11], 13, v[0:1]
	v_lshl_add_u64 v[22:23], v[16:17], 0, v[10:11]
	global_load_dwordx4 v[0:3], v[22:23], off offset:16
	global_load_dwordx4 v[4:7], v[22:23], off
	v_cmp_lt_i32_e64 s[8:9], -1, v9
	v_ashrrev_i32_e32 v9, 31, v8
	v_lshlrev_b64 v[8:9], 13, v[8:9]
	v_lshl_add_u64 v[36:37], v[16:17], 0, v[8:9]
	s_waitcnt vmcnt(1)
	v_cndmask_b32_e64 v35, 0, v0, s[10:11]
	v_cndmask_b32_e64 v0, 3, 1, s[12:13]
	v_add_u32_e32 v0, v0, v18
	v_cndmask_b32_e64 v34, 0, v1, s[10:11]
	v_ashrrev_i32_e32 v1, 31, v0
	s_waitcnt vmcnt(0)
	v_cndmask_b32_e64 v24, 0, v7, s[10:11]
	v_cndmask_b32_e64 v25, 0, v6, s[10:11]
	v_lshlrev_b64 v[6:7], 13, v[0:1]
	v_lshl_add_u64 v[20:21], v[16:17], 0, v[6:7]
	v_cndmask_b32_e64 v32, 0, v3, s[10:11]
	v_cndmask_b32_e64 v33, 0, v2, s[10:11]
	global_load_dwordx4 v[0:3], v[20:21], off offset:16
	global_load_dwordx4 v[12:15], v[20:21], off
	v_cndmask_b32_e64 v26, 0, v5, s[10:11]
	v_cndmask_b32_e64 v27, 0, v4, s[10:11]
	v_lshlrev_b32_e32 v58, 16, v26
	v_and_b32_e32 v59, 0xffff0000, v26
	v_lshlrev_b32_e32 v64, 16, v35
	v_and_b32_e32 v65, 0xffff0000, v35
	v_lshlrev_b32_e32 v86, 16, v34
	v_and_b32_e32 v87, 0xffff0000, v34
	v_lshlrev_b32_e32 v88, 16, v33
	v_and_b32_e32 v89, 0xffff0000, v33
	v_lshlrev_b32_e32 v60, 16, v25
	v_and_b32_e32 v61, 0xffff0000, v25
	v_lshlrev_b32_e32 v62, 16, v24
	v_and_b32_e32 v63, 0xffff0000, v24
	s_waitcnt vmcnt(1)
	v_cndmask_b32_e64 v45, 0, v0, s[12:13]
	v_cndmask_b32_e64 v0, 3, 2, s[14:15]
	v_add_u32_e32 v0, v0, v18
	v_cndmask_b32_e64 v44, 0, v1, s[12:13]
	v_ashrrev_i32_e32 v1, 31, v0
	v_lshlrev_b64 v[4:5], 13, v[0:1]
	v_lshl_add_u64 v[18:19], v[16:17], 0, v[4:5]
	s_waitcnt vmcnt(0)
	v_cndmask_b32_e64 v38, 0, v15, s[12:13]
	v_cndmask_b32_e64 v39, 0, v14, s[12:13]
	v_cndmask_b32_e64 v40, 0, v13, s[12:13]
	v_cndmask_b32_e64 v41, 0, v12, s[12:13]
	v_cndmask_b32_e64 v42, 0, v3, s[12:13]
	v_cndmask_b32_e64 v43, 0, v2, s[12:13]
	global_load_dwordx4 v[0:3], v[18:19], off offset:16
	global_load_dwordx4 v[12:15], v[18:19], off
	v_lshlrev_b32_e32 v16, 16, v27
	v_and_b32_e32 v17, 0xffff0000, v27
	v_lshlrev_b32_e32 v26, 16, v41
	v_and_b32_e32 v27, 0xffff0000, v41
	v_lshlrev_b32_e32 v90, 16, v40
	v_and_b32_e32 v91, 0xffff0000, v40
	v_lshlrev_b32_e32 v92, 16, v39
	v_and_b32_e32 v93, 0xffff0000, v39
	v_lshlrev_b32_e32 v94, 16, v38
	v_and_b32_e32 v95, 0xffff0000, v38
	v_lshlrev_b32_e32 v96, 16, v45
	v_and_b32_e32 v97, 0xffff0000, v45
	v_lshlrev_b32_e32 v98, 16, v44
	v_and_b32_e32 v99, 0xffff0000, v44
	v_lshlrev_b32_e32 v100, 16, v43
	v_and_b32_e32 v101, 0xffff0000, v43
	s_waitcnt vmcnt(1)
	v_cndmask_b32_e64 v50, 0, v3, s[14:15]
	s_waitcnt vmcnt(0)
	v_cndmask_b32_e64 v46, 0, v15, s[14:15]
	v_cndmask_b32_e64 v47, 0, v14, s[14:15]
	v_cndmask_b32_e64 v48, 0, v13, s[14:15]
	v_cndmask_b32_e64 v49, 0, v12, s[14:15]
	v_cndmask_b32_e64 v51, 0, v2, s[14:15]
	v_cndmask_b32_e64 v52, 0, v1, s[14:15]
	v_cndmask_b32_e64 v53, 0, v0, s[14:15]
	global_load_dwordx4 v[0:3], v[36:37], off offset:16
	global_load_dwordx4 v[12:15], v[36:37], off
	v_lshlrev_b32_e32 v54, 16, v49
	v_and_b32_e32 v55, 0xffff0000, v49
	v_lshlrev_b32_e32 v102, 16, v48
	v_and_b32_e32 v103, 0xffff0000, v48
	v_lshlrev_b32_e32 v104, 16, v47
	v_and_b32_e32 v105, 0xffff0000, v47
	v_lshlrev_b32_e32 v106, 16, v46
	v_and_b32_e32 v107, 0xffff0000, v46
	v_lshlrev_b32_e32 v108, 16, v53
	v_and_b32_e32 v109, 0xffff0000, v53
	v_lshlrev_b32_e32 v110, 16, v52
	v_and_b32_e32 v111, 0xffff0000, v52
	v_lshlrev_b32_e32 v112, 16, v51
	v_and_b32_e32 v113, 0xffff0000, v51
	v_lshlrev_b32_e32 v24, 16, v50
	v_and_b32_e32 v25, 0xffff0000, v50
	s_waitcnt vmcnt(1)
	v_cndmask_b32_e64 v122, 0, v3, s[8:9]
	s_waitcnt vmcnt(0)
	v_cndmask_b32_e64 v56, 0, v15, s[8:9]
	v_cndmask_b32_e64 v57, 0, v14, s[8:9]
	v_cndmask_b32_e64 v85, 0, v13, s[8:9]
	v_cndmask_b32_e64 v115, 0, v12, s[8:9]
	v_cndmask_b32_e64 v123, 0, v2, s[8:9]
	v_cndmask_b32_e64 v124, 0, v1, s[8:9]
	v_cndmask_b32_e64 v125, 0, v0, s[8:9]
	v_lshlrev_b32_e32 v12, 16, v32
	v_and_b32_e32 v13, 0xffff0000, v32
	v_lshlrev_b32_e32 v14, 16, v42
	v_and_b32_e32 v15, 0xffff0000, v42
	ds_read_b128 v[32:35], v84 offset:40960
	ds_read_b128 v[38:41], v84 offset:40976
	ds_read_b128 v[42:45], v84 offset:40992
	ds_read_b128 v[0:3], v84 offset:41008
	ds_read_b128 v[46:49], v84 offset:41984
	ds_read_b128 v[50:53], v84 offset:43008
	s_waitcnt lgkmcnt(5)
	v_pk_fma_f32 v[16:17], v[32:33], v[16:17], 0 op_sel_hi:[1,1,0]
	v_lshlrev_b32_e32 v118, 16, v57
	v_and_b32_e32 v119, 0xffff0000, v57
	s_waitcnt lgkmcnt(1)
	v_pk_fma_f32 v[16:17], v[46:47], v[26:27], v[16:17]
	v_lshlrev_b32_e32 v120, 16, v56
	v_and_b32_e32 v121, 0xffff0000, v56
	s_waitcnt lgkmcnt(0)
; DI float sigmoidf_(float x) { return __builtin_amdgcn_rcpf(1.f + __expf(-x)); }
; DI void conv32(const bf16_t* __restrict__ Pcol, int tok, int spos, const float* wl, int wstride, float* acc) {
; #pragma unroll
;   for (int hq = 0; hq < 2; ++hq) {
;     __builtin_amdgcn_sched_barrier(0);
;     uint4 v[4][2];
; #pragma unroll
;     for (int j = 0; j < 4; ++j) {
;       const bool ok = (spos - 3 + j >= 0);
;       const uint4* src = (const uint4*)(Pcol + (size_t)(tok - 3 + (ok ? j : 3)) * 4096) + 2 * hq;
; #pragma unroll
;       for (int q = 0; q < 2; ++q) {
;         v[j][q] = src[q];
;         if (!ok) v[j][q] = make_uint4(0u, 0u, 0u, 0u);
;       }
;     }
; #pragma unroll
;     for (int i = 0; i < 16; ++i) acc[16 * hq + i] = 0.f;
; #pragma unroll
;     for (int j = 0; j < 4; ++j) {
;       const float4* w4 = (const float4*)(wl + j * wstride + 16 * hq);
; #pragma unroll
;       for (int q = 0; q < 2; ++q) {
;         float f[8];
;         unpack8(v[j][q], f);
;         float4 wa = w4[2 * q], wb = w4[2 * q + 1];
;         float* a = acc + 16 * hq + 8 * q;
;         a[0] += wa.x * f[0]; a[1] += wa.y * f[1]; a[2] += wa.z * f[2]; a[3] += wa.w * f[3];
;         a[4] += wb.x * f[4]; a[5] += wb.y * f[5]; a[6] += wb.z * f[6]; a[7] += wb.w * f[7];
;       }
;     }
; #pragma unroll
;     for (int i = 0; i < 16; ++i) acc[16 * hq + i] = acc[16 * hq + i] * sigmoidf_(acc[16 * hq + i]);
;   }
	v_pk_fma_f32 v[16:17], v[50:51], v[54:55], v[16:17]
	ds_read_b128 v[54:57], v84 offset:44032
	v_lshlrev_b32_e32 v114, 16, v115
	v_and_b32_e32 v115, 0xffff0000, v115
	v_pk_fma_f32 v[38:39], v[38:39], v[60:61], 0 op_sel_hi:[1,1,0]
	v_lshlrev_b32_e32 v116, 16, v85
	s_waitcnt lgkmcnt(0)
	v_pk_fma_f32 v[26:27], v[54:55], v[114:115], v[16:17]
	v_pk_fma_f32 v[16:17], v[34:35], v[58:59], 0 op_sel_hi:[1,1,0]
	ds_read_b128 v[32:35], v84 offset:42000
	v_pk_fma_f32 v[16:17], v[48:49], v[90:91], v[16:17]
	ds_read_b128 v[46:49], v84 offset:43024
	v_pk_fma_f32 v[16:17], v[52:53], v[102:103], v[16:17]
	ds_read_b128 v[50:53], v84 offset:44048
	s_waitcnt lgkmcnt(2)
	v_pk_fma_f32 v[32:33], v[32:33], v[92:93], v[38:39]
	v_pk_fma_f32 v[38:39], v[42:43], v[64:65], 0 op_sel_hi:[1,1,0]
	s_waitcnt lgkmcnt(1)
	v_pk_fma_f32 v[32:33], v[46:47], v[104:105], v[32:33]
	v_lshlrev_b32_e32 v54, 16, v125
	s_waitcnt lgkmcnt(0)
	v_pk_fma_f32 v[50:51], v[50:51], v[118:119], v[32:33]
	v_pk_fma_f32 v[32:33], v[40:41], v[62:63], 0 op_sel_hi:[1,1,0]
	v_and_b32_e32 v55, 0xffff0000, v125
	v_pk_fma_f32 v[32:33], v[34:35], v[94:95], v[32:33]
	v_and_b32_e32 v117, 0xffff0000, v85
	v_pk_fma_f32 v[32:33], v[48:49], v[106:107], v[32:33]
	ds_read_b128 v[46:49], v84 offset:44064
	v_pk_fma_f32 v[52:53], v[52:53], v[120:121], v[32:33]
	ds_read_b128 v[32:35], v84 offset:42016
	v_pk_fma_f32 v[16:17], v[56:57], v[116:117], v[16:17]
	v_lshlrev_b32_e32 v56, 16, v124
	v_and_b32_e32 v57, 0xffff0000, v124
	v_pk_fma_f32 v[0:1], v[0:1], v[88:89], 0 op_sel_hi:[1,1,0]
	s_waitcnt lgkmcnt(0)
	v_pk_fma_f32 v[32:33], v[32:33], v[96:97], v[38:39]
	ds_read_b128 v[38:41], v84 offset:43040
	v_lshlrev_b32_e32 v58, 16, v123
	v_and_b32_e32 v59, 0xffff0000, v123
	v_pk_fma_f32 v[2:3], v[2:3], v[12:13], 0 op_sel_hi:[1,1,0]
	v_mul_f32_e32 v12, 0xbfb8aa3b, v26
	s_waitcnt lgkmcnt(0)
	v_pk_fma_f32 v[32:33], v[38:39], v[108:109], v[32:33]
	v_mul_f32_e32 v13, 0xbfb8aa3b, v27
	v_pk_fma_f32 v[54:55], v[46:47], v[54:55], v[32:33]
	v_pk_fma_f32 v[32:33], v[44:45], v[86:87], 0 op_sel_hi:[1,1,0]
	ds_read_b128 v[42:45], v84 offset:43056
	v_pk_fma_f32 v[32:33], v[34:35], v[98:99], v[32:33]
	v_exp_f32_e32 v12, v12
	v_pk_fma_f32 v[32:33], v[40:41], v[110:111], v[32:33]
	ds_read_b128 v[38:41], v84 offset:42032
	v_pk_fma_f32 v[32:33], v[48:49], v[56:57], v[32:33]
	ds_read_b128 v[46:49], v84 offset:44080
	v_mul_f32_e32 v34, 0xbfb8aa3b, v32
	v_mul_f32_e32 v35, 0xbfb8aa3b, v33
	v_exp_f32_e32 v34, v34
	v_exp_f32_e32 v35, v35
	s_waitcnt lgkmcnt(1)
	v_pk_fma_f32 v[0:1], v[38:39], v[100:101], v[0:1]
	v_pk_fma_f32 v[2:3], v[40:41], v[14:15], v[2:3]
	v_add_f32_e32 v34, 1.0, v34
	v_add_f32_e32 v35, 1.0, v35
	v_rcp_f32_e32 v34, v34
	v_rcp_f32_e32 v35, v35
	v_pk_fma_f32 v[0:1], v[42:43], v[112:113], v[0:1]
	v_mul_f32_e32 v14, 0xbfb8aa3b, v16
	s_waitcnt lgkmcnt(0)
	v_pk_fma_f32 v[0:1], v[46:47], v[58:59], v[0:1]
	v_mul_f32_e32 v15, 0xbfb8aa3b, v17
	v_exp_f32_e32 v14, v14
	v_exp_f32_e32 v15, v15
	v_pk_mul_f32 v[32:33], v[32:33], v[34:35]
	v_mul_f32_e32 v34, 0xbfb8aa3b, v0
	v_mul_f32_e32 v35, 0xbfb8aa3b, v1
	v_exp_f32_e32 v13, v13
	v_exp_f32_e32 v34, v34
	v_exp_f32_e32 v35, v35
	v_add_f32_e32 v14, 1.0, v14
	v_add_f32_e32 v15, 1.0, v15
	v_add_f32_e32 v12, 1.0, v12
	v_add_f32_e32 v13, 1.0, v13
	v_rcp_f32_e32 v14, v14
	v_rcp_f32_e32 v15, v15
	v_add_f32_e32 v34, 1.0, v34
	v_add_f32_e32 v35, 1.0, v35
	v_rcp_f32_e32 v12, v12
	v_rcp_f32_e32 v13, v13
	v_rcp_f32_e32 v34, v34
	v_rcp_f32_e32 v35, v35
	v_lshlrev_b32_e32 v60, 16, v122
	v_and_b32_e32 v61, 0xffff0000, v122
	v_pk_fma_f32 v[2:3], v[44:45], v[24:25], v[2:3]
	v_pk_mul_f32 v[14:15], v[16:17], v[14:15]
	v_pk_fma_f32 v[2:3], v[48:49], v[60:61], v[2:3]
	v_mul_f32_e32 v16, 0xbfb8aa3b, v50
	v_mul_f32_e32 v17, 0xbfb8aa3b, v51
	v_mul_f32_e32 v24, 0xbfb8aa3b, v52
	v_mul_f32_e32 v25, 0xbfb8aa3b, v53
	v_pk_mul_f32 v[12:13], v[26:27], v[12:13]
	v_exp_f32_e32 v16, v16
	v_exp_f32_e32 v17, v17
	v_exp_f32_e32 v24, v24
	v_exp_f32_e32 v25, v25
	v_mul_f32_e32 v26, 0xbfb8aa3b, v54
	v_mul_f32_e32 v27, 0xbfb8aa3b, v55
	v_pk_mul_f32 v[34:35], v[0:1], v[34:35]
	v_mul_f32_e32 v0, 0xbfb8aa3b, v2
	v_mul_f32_e32 v1, 0xbfb8aa3b, v3
	v_exp_f32_e32 v26, v26
	v_exp_f32_e32 v27, v27
	v_exp_f32_e32 v0, v0
	v_exp_f32_e32 v1, v1
	v_add_f32_e32 v16, 1.0, v16
	v_add_f32_e32 v17, 1.0, v17
	v_add_f32_e32 v24, 1.0, v24
	v_add_f32_e32 v25, 1.0, v25
	v_rcp_f32_e32 v16, v16
	v_rcp_f32_e32 v17, v17
	v_rcp_f32_e32 v24, v24
	v_rcp_f32_e32 v25, v25
	v_add_f32_e32 v26, 1.0, v26
	v_add_f32_e32 v27, 1.0, v27
	v_add_f32_e32 v0, 1.0, v0
	v_add_f32_e32 v1, 1.0, v1
	v_rcp_f32_e32 v26, v26
	v_rcp_f32_e32 v27, v27
	v_rcp_f32_e32 v0, v0
	v_rcp_f32_e32 v1, v1
	v_pk_mul_f32 v[16:17], v[50:51], v[16:17]
	v_pk_mul_f32 v[24:25], v[52:53], v[24:25]
	v_pk_mul_f32 v[26:27], v[54:55], v[26:27]
	v_pk_mul_f32 v[38:39], v[2:3], v[0:1]
	global_load_dwordx4 v[0:3], v[22:23], off offset:32
	global_load_dwordx4 v[40:43], v[22:23], off offset:48
	global_load_dwordx4 v[44:47], v[20:21], off offset:32
	s_nop 0
	global_load_dwordx4 v[20:23], v[20:21], off offset:48
	s_nop 0
	global_load_dwordx4 v[48:51], v[18:19], off offset:32
	global_load_dwordx4 v[52:55], v[18:19], off offset:48
	global_load_dwordx4 v[56:59], v[36:37], off offset:32
	global_load_dwordx4 v[60:63], v[36:37], off offset:48
	s_waitcnt vmcnt(7)
	v_cndmask_b32_e64 v3, 0, v3, s[10:11]
	v_cndmask_b32_e64 v2, 0, v2, s[10:11]
	v_cndmask_b32_e64 v1, 0, v1, s[10:11]
	v_cndmask_b32_e64 v0, 0, v0, s[10:11]
	s_waitcnt vmcnt(6)
	v_cndmask_b32_e64 v19, 0, v43, s[10:11]
	v_cndmask_b32_e64 v18, 0, v42, s[10:11]
	v_cndmask_b32_e64 v36, 0, v41, s[10:11]
	v_cndmask_b32_e64 v37, 0, v40, s[10:11]
	s_waitcnt vmcnt(5)
; DI float sigmoidf_(float x) { return __builtin_amdgcn_rcpf(1.f + __expf(-x)); }
; DI void conv32(const bf16_t* __restrict__ Pcol, int tok, int spos, const float* wl, int wstride, float* acc) {
; #pragma unroll
;   for (int hq = 0; hq < 2; ++hq) {
;     __builtin_amdgcn_sched_barrier(0);
;     uint4 v[4][2];
; #pragma unroll
;     for (int j = 0; j < 4; ++j) {
;       const bool ok = (spos - 3 + j >= 0);
;       const uint4* src = (const uint4*)(Pcol + (size_t)(tok - 3 + (ok ? j : 3)) * 4096) + 2 * hq;
; #pragma unroll
;       for (int q = 0; q < 2; ++q) {
;         v[j][q] = src[q];
;         if (!ok) v[j][q] = make_uint4(0u, 0u, 0u, 0u);
;       }
;     }
; #pragma unroll
;     for (int i = 0; i < 16; ++i) acc[16 * hq + i] = 0.f;
; #pragma unroll
;     for (int j = 0; j < 4; ++j) {
;       const float4* w4 = (const float4*)(wl + j * wstride + 16 * hq);
; #pragma unroll
;       for (int q = 0; q < 2; ++q) {
;         float f[8];
;         unpack8(v[j][q], f);
;         float4 wa = w4[2 * q], wb = w4[2 * q + 1];
;         float* a = acc + 16 * hq + 8 * q;
;         a[0] += wa.x * f[0]; a[1] += wa.y * f[1]; a[2] += wa.z * f[2]; a[3] += wa.w * f[3];
;         a[4] += wb.x * f[4]; a[5] += wb.y * f[5]; a[6] += wb.z * f[6]; a[7] += wb.w * f[7];
;       }
;     }
; #pragma unroll
;     for (int i = 0; i < 16; ++i) acc[16 * hq + i] = acc[16 * hq + i] * sigmoidf_(acc[16 * hq + i]);
;   }
	v_cndmask_b32_e64 v40, 0, v47, s[12:13]
	v_cndmask_b32_e64 v41, 0, v46, s[12:13]
	v_cndmask_b32_e64 v42, 0, v45, s[12:13]
	v_cndmask_b32_e64 v43, 0, v44, s[12:13]
	s_waitcnt vmcnt(4)
	v_cndmask_b32_e64 v86, 0, v22, s[12:13]
	s_waitcnt vmcnt(3)
	v_cndmask_b32_e64 v87, 0, v51, s[14:15]
	v_cndmask_b32_e64 v88, 0, v50, s[14:15]
	v_cndmask_b32_e64 v89, 0, v49, s[14:15]
	v_cndmask_b32_e64 v90, 0, v48, s[14:15]
	s_waitcnt vmcnt(2)
	v_cndmask_b32_e64 v91, 0, v55, s[14:15]
	v_cndmask_b32_e64 v92, 0, v54, s[14:15]
	s_waitcnt vmcnt(1)
	v_cndmask_b32_e64 v93, 0, v58, s[8:9]
	v_cndmask_b32_e64 v94, 0, v57, s[8:9]
	v_cndmask_b32_e64 v95, 0, v56, s[8:9]
	v_cndmask_b32_e64 v85, 0, v23, s[12:13]
	v_cndmask_b32_e64 v121, 0, v59, s[8:9]
	s_waitcnt vmcnt(0)
	v_cndmask_b32_e64 v64, 0, v63, s[8:9]
	v_cndmask_b32_e64 v65, 0, v62, s[8:9]
	v_cndmask_b32_e64 v122, 0, v61, s[8:9]
	v_cndmask_b32_e64 v123, 0, v60, s[8:9]
	v_lshlrev_b32_e32 v22, 16, v0
	v_and_b32_e32 v23, 0xffff0000, v0
	v_lshlrev_b32_e32 v102, 16, v1
	v_and_b32_e32 v103, 0xffff0000, v1
	v_lshlrev_b32_e32 v106, 16, v2
	v_and_b32_e32 v107, 0xffff0000, v2
	v_lshlrev_b32_e32 v58, 16, v3
	v_and_b32_e32 v59, 0xffff0000, v3
	v_lshlrev_b32_e32 v50, 16, v37
	v_and_b32_e32 v51, 0xffff0000, v37
	v_lshlrev_b32_e32 v46, 16, v36
	v_and_b32_e32 v47, 0xffff0000, v36
	v_lshlrev_b32_e32 v98, 16, v43
	v_and_b32_e32 v99, 0xffff0000, v43
	v_lshlrev_b32_e32 v104, 16, v42
	v_and_b32_e32 v105, 0xffff0000, v42
	v_lshlrev_b32_e32 v108, 16, v41
	v_and_b32_e32 v109, 0xffff0000, v41
	v_lshlrev_b32_e32 v60, 16, v40
	v_and_b32_e32 v61, 0xffff0000, v40
	v_lshlrev_b32_e32 v40, 16, v86
	v_and_b32_e32 v41, 0xffff0000, v86
	v_lshlrev_b32_e32 v100, 16, v90
	v_and_b32_e32 v101, 0xffff0000, v90
	v_lshlrev_b32_e32 v110, 16, v89
	v_and_b32_e32 v111, 0xffff0000, v89
	v_lshlrev_b32_e32 v112, 16, v88
	v_and_b32_e32 v113, 0xffff0000, v88
	v_lshlrev_b32_e32 v62, 16, v87
	v_and_b32_e32 v63, 0xffff0000, v87
	v_lshlrev_b32_e32 v42, 16, v92
	v_and_b32_e32 v43, 0xffff0000, v92
	v_lshlrev_b32_e32 v36, 16, v91
	v_and_b32_e32 v37, 0xffff0000, v91
	v_lshlrev_b32_e32 v114, 16, v95
	v_and_b32_e32 v115, 0xffff0000, v95
	v_lshlrev_b32_e32 v116, 16, v94
	v_and_b32_e32 v117, 0xffff0000, v94
	v_lshlrev_b32_e32 v118, 16, v93
	v_and_b32_e32 v119, 0xffff0000, v93
	ds_read_b128 v[0:3], v84 offset:41024
	ds_read_b128 v[86:89], v84 offset:42048
	ds_read_b128 v[90:93], v84 offset:43072
	ds_read_b128 v[94:97], v84 offset:44096
	v_cndmask_b32_e64 v21, 0, v21, s[12:13]
	s_waitcnt lgkmcnt(3)
	v_pk_fma_f32 v[0:1], v[0:1], v[22:23], 0 op_sel_hi:[1,1,0]
	v_cndmask_b32_e64 v20, 0, v20, s[12:13]
	s_waitcnt lgkmcnt(2)
	v_pk_fma_f32 v[0:1], v[86:87], v[98:99], v[0:1]
	v_cndmask_b32_e64 v55, 0, v53, s[14:15]
	s_waitcnt lgkmcnt(1)
	v_pk_fma_f32 v[0:1], v[90:91], v[100:101], v[0:1]
	ds_read_b128 v[98:101], v84 offset:41040
	s_waitcnt lgkmcnt(1)
	v_pk_fma_f32 v[22:23], v[94:95], v[114:115], v[0:1]
	v_cndmask_b32_e64 v54, 0, v52, s[14:15]
	v_mul_f32_e32 v0, 0xbfb8aa3b, v22
	v_exp_f32_e32 v0, v0
	v_mul_f32_e32 v1, 0xbfb8aa3b, v23
	v_exp_f32_e32 v1, v1
	v_lshlrev_b32_e32 v52, 16, v20
	v_add_f32_e32 v0, 1.0, v0
	v_rcp_f32_e32 v90, v0
	v_add_f32_e32 v0, 1.0, v1
	v_rcp_f32_e32 v91, v0
	v_pk_fma_f32 v[0:1], v[2:3], v[102:103], 0 op_sel_hi:[1,1,0]
	v_and_b32_e32 v53, 0xffff0000, v20
	v_pk_fma_f32 v[0:1], v[88:89], v[104:105], v[0:1]
	v_lshlrev_b32_e32 v48, 16, v21
	v_pk_fma_f32 v[0:1], v[92:93], v[110:111], v[0:1]
	v_and_b32_e32 v49, 0xffff0000, v21
	v_pk_fma_f32 v[110:111], v[96:97], v[116:117], v[0:1]
	v_lshlrev_b32_e32 v20, 16, v85
	v_mul_f32_e32 v0, 0xbfb8aa3b, v110
	v_and_b32_e32 v21, 0xffff0000, v85
	v_exp_f32_e32 v85, v0
	ds_read_b128 v[86:89], v84 offset:41056
	ds_read_b128 v[0:3], v84 offset:41072
	v_pk_mul_f32 v[22:23], v[22:23], v[90:91]
	ds_read_b128 v[90:93], v84 offset:42064
	ds_read_b128 v[94:97], v84 offset:43088
	ds_read_b128 v[102:105], v84 offset:44112
	s_waitcnt lgkmcnt(5)
	v_pk_fma_f32 v[98:99], v[98:99], v[106:107], 0 op_sel_hi:[1,1,0]
	v_pk_fma_f32 v[58:59], v[100:101], v[58:59], 0 op_sel_hi:[1,1,0]
	s_waitcnt lgkmcnt(2)
	v_pk_fma_f32 v[90:91], v[90:91], v[108:109], v[98:99]
	v_add_f32_e32 v85, 1.0, v85
	s_waitcnt lgkmcnt(1)
	v_pk_fma_f32 v[90:91], v[94:95], v[112:113], v[90:91]
	v_pk_fma_f32 v[58:59], v[92:93], v[60:61], v[58:59]
	v_lshlrev_b32_e32 v120, 16, v121
	v_and_b32_e32 v121, 0xffff0000, v121
	v_rcp_f32_e32 v114, v85
	v_mul_f32_e32 v85, 0xbfb8aa3b, v111
	s_waitcnt lgkmcnt(0)
	v_pk_fma_f32 v[98:99], v[102:103], v[118:119], v[90:91]
	v_pk_fma_f32 v[58:59], v[96:97], v[62:63], v[58:59]
	v_exp_f32_e32 v85, v85
	v_mul_f32_e32 v90, 0xbfb8aa3b, v98
	v_pk_fma_f32 v[62:63], v[104:105], v[120:121], v[58:59]
	v_exp_f32_e32 v90, v90
	v_mul_f32_e32 v91, 0xbfb8aa3b, v99
	v_mul_f32_e32 v58, 0xbfb8aa3b, v62
	v_exp_f32_e32 v91, v91
	v_exp_f32_e32 v58, v58
	v_mul_f32_e32 v59, 0xbfb8aa3b, v63
	v_exp_f32_e32 v59, v59
	v_add_f32_e32 v85, 1.0, v85
	v_rcp_f32_e32 v115, v85
	v_add_f32_e32 v85, 1.0, v90
	v_rcp_f32_e32 v102, v85
	v_add_f32_e32 v85, 1.0, v91
	v_add_f32_e32 v58, 1.0, v58
	v_rcp_f32_e32 v103, v85
	v_rcp_f32_e32 v100, v58
	v_add_f32_e32 v85, 1.0, v59
	ds_read_b128 v[58:61], v84 offset:42080
	ds_read_b128 v[90:93], v84 offset:43104
	ds_read_b128 v[94:97], v84 offset:44128
	v_rcp_f32_e32 v101, v85
	v_pk_fma_f32 v[50:51], v[86:87], v[50:51], 0 op_sel_hi:[1,1,0]
	v_lshlrev_b32_e32 v56, 16, v54
	v_and_b32_e32 v57, 0xffff0000, v54
	s_waitcnt lgkmcnt(2)
	v_pk_fma_f32 v[50:51], v[58:59], v[52:53], v[50:51]
	v_pk_fma_f32 v[46:47], v[88:89], v[46:47], 0 op_sel_hi:[1,1,0]
	v_lshlrev_b32_e32 v54, 16, v55
	v_and_b32_e32 v55, 0xffff0000, v55
	s_waitcnt lgkmcnt(1)
; DI int fragoff(int row, int k, int KS) { return (((row >> 4) * KS + (k >> 5)) << 9) + (((((k >> 3) & 3) << 4) + (row & 15)) << 3) + (k & 7); }
; DI void mlstm_pre(const Params& p, int ch, char* smem) {
;     ...
;     conv32(P + 2048 + h * 128 + part * 32, tok0 + t, c * 64 + t, s_w + part * 32, 256, a);
; #pragma unroll
;     for (int q = 0; q < 4; ++q) *(uint4*)(qs + t * 136 + part * 32 + 8 * q) = pack8(a + 8 * q);
;     {
;       const float sct = s_sc[t];
; #pragma unroll
;       for (int i = 0; i < 32; ++i) a[i] *= sct;
; #pragma unroll
;       for (int q = 0; q < 4; ++q) *(uint4*)(o_q + fragoff(t, part * 32 + 8 * q, 4)) = pack8(a + 8 * q);
;     }
;     conv32(P + 2560 + h * 128 + part * 32, tok0 + t, c * 64 + t, s_w + 128 + part * 32, 256, a);
	v_pk_fma_f32 v[50:51], v[90:91], v[56:57], v[50:51]
	v_lshlrev_b32_e32 v52, 16, v123
	v_and_b32_e32 v53, 0xffff0000, v123
	v_pk_fma_f32 v[46:47], v[60:61], v[48:49], v[46:47]
	s_waitcnt lgkmcnt(0)
	v_pk_fma_f32 v[58:59], v[94:95], v[52:53], v[50:51]
	v_pk_fma_f32 v[46:47], v[92:93], v[54:55], v[46:47]
	v_lshlrev_b32_e32 v48, 16, v122
	v_and_b32_e32 v49, 0xffff0000, v122
	v_pk_mul_f32 v[56:57], v[62:63], v[100:101]
	v_mul_f32_e32 v63, 0xbfb8aa3b, v59
	v_pk_fma_f32 v[54:55], v[96:97], v[48:49], v[46:47]
	v_mul_f32_e32 v50, 0xbfb8aa3b, v58
	v_exp_f32_e32 v63, v63
	v_mul_f32_e32 v46, 0xbfb8aa3b, v54
	v_exp_f32_e32 v85, v50
	v_exp_f32_e32 v46, v46
	v_add_f32_e32 v47, 1.0, v63
	v_rcp_f32_e32 v91, v47
	v_add_f32_e32 v62, 1.0, v85
	v_add_f32_e32 v46, 1.0, v46
	v_mul_f32_e32 v47, 0xbfb8aa3b, v55
	v_rcp_f32_e32 v90, v62
	v_exp_f32_e32 v85, v47
	v_rcp_f32_e32 v92, v46
	ds_read_b128 v[46:49], v84 offset:42096
	ds_read_b128 v[60:63], v84 offset:43120
	ds_read_b128 v[86:89], v84 offset:44144
	v_lshlrev_b32_e32 v44, 16, v18
	v_and_b32_e32 v45, 0xffff0000, v18
	v_lshlrev_b32_e32 v18, 16, v19
	v_and_b32_e32 v19, 0xffff0000, v19
	v_pk_fma_f32 v[2:3], v[2:3], v[18:19], 0 op_sel_hi:[1,1,0]
	v_pk_fma_f32 v[0:1], v[0:1], v[44:45], 0 op_sel_hi:[1,1,0]
	s_waitcnt lgkmcnt(2)
	v_pk_fma_f32 v[2:3], v[48:49], v[20:21], v[2:3]
	v_pk_fma_f32 v[0:1], v[46:47], v[40:41], v[0:1]
	s_waitcnt lgkmcnt(1)
	v_pk_fma_f32 v[2:3], v[62:63], v[36:37], v[2:3]
	v_lshlrev_b32_e32 v18, 16, v64
	v_and_b32_e32 v19, 0xffff0000, v64
	v_pk_fma_f32 v[0:1], v[60:61], v[42:43], v[0:1]
	v_lshlrev_b32_e32 v40, 16, v65
	v_and_b32_e32 v41, 0xffff0000, v65
	s_waitcnt lgkmcnt(0)
	v_pk_fma_f32 v[2:3], v[88:89], v[18:19], v[2:3]
	v_pk_fma_f32 v[0:1], v[86:87], v[40:41], v[0:1]
	v_mul_f32_e32 v18, 0xbfb8aa3b, v2
	v_mul_f32_e32 v19, 0xbfb8aa3b, v3
	v_mul_f32_e32 v40, 0xbfb8aa3b, v0
	v_mul_f32_e32 v41, 0xbfb8aa3b, v1
	v_exp_f32_e32 v18, v18
	v_exp_f32_e32 v19, v19
	v_exp_f32_e32 v40, v40
	v_exp_f32_e32 v41, v41
	v_add_f32_e32 v18, 1.0, v18
	v_add_f32_e32 v19, 1.0, v19
	v_add_f32_e32 v85, 1.0, v85
	v_add_f32_e32 v40, 1.0, v40
	v_add_f32_e32 v41, 1.0, v41
	v_rcp_f32_e32 v18, v18
	v_rcp_f32_e32 v19, v19
	v_rcp_f32_e32 v93, v85
	v_rcp_f32_e32 v40, v40
	v_rcp_f32_e32 v41, v41
	v_pk_mul_f32 v[20:21], v[58:59], v[90:91]
	v_pk_mul_f32 v[18:19], v[2:3], v[18:19]
	v_pk_mul_f32 v[50:51], v[110:111], v[114:115]
	v_pk_mul_f32 v[52:53], v[98:99], v[102:103]
	v_pk_mul_f32 v[36:37], v[54:55], v[92:93]
	v_pk_mul_f32 v[40:41], v[0:1], v[40:41]
	v_mul_lo_u32 v42, v79, s75
	v_add_u32_e32 v85, v42, v28
	v_cvt_pk_bf16_f32 v0, v12, v13
	v_cvt_pk_bf16_f32 v1, v14, v15
	v_cvt_pk_bf16_f32 v2, v16, v17
	v_cvt_pk_bf16_f32 v3, v24, v25
	ds_write_b128 v85, v[0:3]
	v_cvt_pk_bf16_f32 v0, v26, v27
	v_cvt_pk_bf16_f32 v1, v32, v33
	v_cvt_pk_bf16_f32 v2, v34, v35
	v_cvt_pk_bf16_f32 v3, v38, v39
	ds_write_b128 v85, v[0:3] offset:16
	v_cvt_pk_bf16_f32 v0, v22, v23
	v_cvt_pk_bf16_f32 v1, v50, v51
	v_cvt_pk_bf16_f32 v2, v52, v53
	v_cvt_pk_bf16_f32 v3, v56, v57
	ds_write_b128 v85, v[0:3] offset:32
	v_cvt_pk_bf16_f32 v0, v20, v21
	v_cvt_pk_bf16_f32 v1, v36, v37
	v_cvt_pk_bf16_f32 v2, v40, v41
	v_cvt_pk_bf16_f32 v3, v18, v19
	s_movk_i32 s45, 0xfef4
	ds_write_b128 v85, v[0:3] offset:48
	v_mad_u64_u32 v[0:1], s[70:71], v79, s45, v[42:43]
	ds_read_b32 v0, v0 offset:37408
	s_add_u32 s70, s5, s34
	s_addc_u32 s71, s20, 0
	s_waitcnt lgkmcnt(0)
	v_pk_mul_f32 v[2:3], v[12:13], v[0:1] op_sel_hi:[1,0]
	v_pk_mul_f32 v[12:13], v[14:15], v[0:1] op_sel_hi:[1,0]
	v_pk_mul_f32 v[14:15], v[16:17], v[0:1] op_sel_hi:[1,0]
	v_pk_mul_f32 v[16:17], v[24:25], v[0:1] op_sel_hi:[1,0]
	v_pk_mul_f32 v[24:25], v[26:27], v[0:1] op_sel_hi:[1,0]
	v_pk_mul_f32 v[26:27], v[32:33], v[0:1] op_sel_hi:[1,0]
	v_pk_mul_f32 v[32:33], v[34:35], v[0:1] op_sel_hi:[1,0]
	v_pk_mul_f32 v[34:35], v[38:39], v[0:1] op_sel_hi:[1,0]
	v_pk_mul_f32 v[22:23], v[22:23], v[0:1] op_sel_hi:[1,0]
	v_pk_mul_f32 v[38:39], v[50:51], v[0:1] op_sel_hi:[1,0]
	v_pk_mul_f32 v[42:43], v[52:53], v[0:1] op_sel_hi:[1,0]
	v_pk_mul_f32 v[44:45], v[56:57], v[0:1] op_sel_hi:[1,0]
	v_pk_mul_f32 v[20:21], v[20:21], v[0:1] op_sel_hi:[1,0]
	v_pk_mul_f32 v[36:37], v[36:37], v[0:1] op_sel_hi:[1,0]
	v_pk_mul_f32 v[40:41], v[40:41], v[0:1] op_sel_hi:[1,0]
	v_pk_mul_f32 v[18:19], v[18:19], v[0:1] op_sel_hi:[1,0]
	v_lshrrev_b32_e32 v0, 2, v79
	v_lshlrev_b32_e32 v1, 3, v79
	v_and_or_b32 v0, v0, s76, v81
	v_and_b32_e32 v1, 0x78, v1
	v_lshl_or_b32 v46, v0, 9, v1
	v_ashrrev_i32_e32 v47, 31, v46
	v_cvt_pk_bf16_f32 v0, v2, v3
	v_cvt_pk_bf16_f32 v1, v12, v13
	v_cvt_pk_bf16_f32 v2, v14, v15
	v_cvt_pk_bf16_f32 v3, v16, v17
	v_lshl_add_u64 v[12:13], v[46:47], 1, s[60:61]
	global_store_dwordx4 v[12:13], v[0:3], off
	v_lshl_add_u64 v[16:17], s[70:71], 0, v[28:29]
	s_nop 0
	v_cvt_pk_bf16_f32 v0, v24, v25
	v_cvt_pk_bf16_f32 v1, v26, v27
	v_cvt_pk_bf16_f32 v2, v32, v33
	v_cvt_pk_bf16_f32 v3, v34, v35
	global_store_dwordx4 v[12:13], v[0:3], off offset:256
	s_nop 1
	v_cvt_pk_bf16_f32 v0, v22, v23
	v_cvt_pk_bf16_f32 v1, v38, v39
	v_cvt_pk_bf16_f32 v2, v42, v43
	v_cvt_pk_bf16_f32 v3, v44, v45
	global_store_dwordx4 v[12:13], v[0:3], off offset:512
	s_nop 1
	v_cvt_pk_bf16_f32 v0, v20, v21
	v_cvt_pk_bf16_f32 v1, v36, v37
	v_cvt_pk_bf16_f32 v2, v40, v41
	v_cvt_pk_bf16_f32 v3, v18, v19
	global_store_dwordx4 v[12:13], v[0:3], off offset:768
	v_lshl_add_u64 v[10:11], v[16:17], 0, v[10:11]
	global_load_dwordx4 v[0:3], v[10:11], off offset:16
	global_load_dwordx4 v[12:15], v[10:11], off
	v_lshl_add_u64 v[6:7], v[16:17], 0, v[6:7]
	v_lshl_add_u64 v[4:5], v[16:17], 0, v[4:5]
	s_waitcnt vmcnt(1)
	v_cndmask_b32_e64 v24, 0, v3, s[10:11]
	s_waitcnt vmcnt(0)
; DI void conv32(const bf16_t* __restrict__ Pcol, int tok, int spos, const float* wl, int wstride, float* acc) {
; #pragma unroll
;   for (int hq = 0; hq < 2; ++hq) {
;     __builtin_amdgcn_sched_barrier(0);
;     uint4 v[4][2];
; #pragma unroll
;     for (int j = 0; j < 4; ++j) {
;       const bool ok = (spos - 3 + j >= 0);
;       const uint4* src = (const uint4*)(Pcol + (size_t)(tok - 3 + (ok ? j : 3)) * 4096) + 2 * hq;
; #pragma unroll
;       for (int q = 0; q < 2; ++q) {
;         v[j][q] = src[q];
;         if (!ok) v[j][q] = make_uint4(0u, 0u, 0u, 0u);
;       }
;     }
; #pragma unroll
;     for (int i = 0; i < 16; ++i) acc[16 * hq + i] = 0.f;
; #pragma unroll
;     for (int j = 0; j < 4; ++j) {
;       const float4* w4 = (const float4*)(wl + j * wstride + 16 * hq);
; #pragma unroll
;       for (int q = 0; q < 2; ++q) {
;         float f[8];
;         unpack8(v[j][q], f);
;         float4 wa = w4[2 * q], wb = w4[2 * q + 1];
;         float* a = acc + 16 * hq + 8 * q;
;         a[0] += wa.x * f[0]; a[1] += wa.y * f[1]; a[2] += wa.z * f[2]; a[3] += wa.w * f[3];
;         a[4] += wb.x * f[4]; a[5] += wb.y * f[5]; a[6] += wb.z * f[6]; a[7] += wb.w * f[7];
;       }
;     }
	v_cndmask_b32_e64 v20, 0, v15, s[10:11]
	v_cndmask_b32_e64 v21, 0, v14, s[10:11]
	v_cndmask_b32_e64 v23, 0, v13, s[10:11]
	v_cndmask_b32_e64 v19, 0, v12, s[10:11]
	v_cndmask_b32_e64 v25, 0, v2, s[10:11]
	v_cndmask_b32_e64 v26, 0, v1, s[10:11]
	v_cndmask_b32_e64 v27, 0, v0, s[10:11]
	global_load_dwordx4 v[0:3], v[6:7], off offset:16
	global_load_dwordx4 v[12:15], v[6:7], off
	v_lshlrev_b32_e32 v56, 16, v27
	v_and_b32_e32 v57, 0xffff0000, v27
	v_lshlrev_b32_e32 v58, 16, v26
	v_and_b32_e32 v59, 0xffff0000, v26
	v_lshlrev_b32_e32 v60, 16, v25
	v_and_b32_e32 v61, 0xffff0000, v25
	v_lshlrev_b32_e32 v18, 16, v19
	v_and_b32_e32 v19, 0xffff0000, v19
	v_lshlrev_b32_e32 v52, 16, v21
	v_and_b32_e32 v53, 0xffff0000, v21
	v_lshlrev_b32_e32 v54, 16, v20
	v_and_b32_e32 v55, 0xffff0000, v20
	v_lshlrev_b32_e32 v22, 16, v23
	v_and_b32_e32 v23, 0xffff0000, v23
	s_waitcnt vmcnt(1)
	v_cndmask_b32_e64 v36, 0, v3, s[12:13]
	s_waitcnt vmcnt(0)
	v_cndmask_b32_e64 v32, 0, v15, s[12:13]
	v_cndmask_b32_e64 v33, 0, v14, s[12:13]
	v_cndmask_b32_e64 v34, 0, v13, s[12:13]
	v_cndmask_b32_e64 v35, 0, v12, s[12:13]
	v_cndmask_b32_e64 v37, 0, v2, s[12:13]
	v_cndmask_b32_e64 v38, 0, v1, s[12:13]
	v_cndmask_b32_e64 v39, 0, v0, s[12:13]
	global_load_dwordx4 v[0:3], v[4:5], off offset:16
	global_load_dwordx4 v[12:15], v[4:5], off
	v_lshlrev_b32_e32 v44, 16, v35
	v_and_b32_e32 v45, 0xffff0000, v35
	v_lshlrev_b32_e32 v62, 16, v34
	v_and_b32_e32 v63, 0xffff0000, v34
	v_lshlrev_b32_e32 v64, 16, v33
	v_and_b32_e32 v65, 0xffff0000, v33
	v_lshlrev_b32_e32 v86, 16, v32
	v_and_b32_e32 v87, 0xffff0000, v32
	v_lshlrev_b32_e32 v88, 16, v39
	v_and_b32_e32 v89, 0xffff0000, v39
	v_lshlrev_b32_e32 v90, 16, v38
	v_and_b32_e32 v91, 0xffff0000, v38
	v_lshlrev_b32_e32 v92, 16, v37
	v_and_b32_e32 v93, 0xffff0000, v37
	s_waitcnt vmcnt(1)
	v_cndmask_b32_e64 v46, 0, v3, s[14:15]
	s_waitcnt vmcnt(0)
	v_cndmask_b32_e64 v42, 0, v13, s[14:15]
	v_cndmask_b32_e64 v43, 0, v12, s[14:15]
	v_lshl_add_u64 v[12:13], v[16:17], 0, v[8:9]
	v_cndmask_b32_e64 v40, 0, v15, s[14:15]
	v_cndmask_b32_e64 v41, 0, v14, s[14:15]
	v_cndmask_b32_e64 v47, 0, v2, s[14:15]
	v_cndmask_b32_e64 v50, 0, v1, s[14:15]
	v_cndmask_b32_e64 v51, 0, v0, s[14:15]
	global_load_dwordx4 v[0:3], v[12:13], off offset:16
	global_load_dwordx4 v[14:17], v[12:13], off
	v_lshlrev_b32_e32 v48, 16, v43
	v_and_b32_e32 v49, 0xffff0000, v43
	v_lshlrev_b32_e32 v94, 16, v42
	v_and_b32_e32 v95, 0xffff0000, v42
	v_lshlrev_b32_e32 v96, 16, v41
	v_and_b32_e32 v97, 0xffff0000, v41
	v_lshlrev_b32_e32 v98, 16, v40
	v_and_b32_e32 v99, 0xffff0000, v40
	v_lshlrev_b32_e32 v104, 16, v47
	v_and_b32_e32 v105, 0xffff0000, v47
	v_lshlrev_b32_e32 v20, 16, v46
	v_and_b32_e32 v21, 0xffff0000, v46
	v_lshlrev_b32_e32 v100, 16, v51
	v_and_b32_e32 v101, 0xffff0000, v51
	v_lshlrev_b32_e32 v102, 16, v50
	v_and_b32_e32 v103, 0xffff0000, v50
	s_waitcnt vmcnt(1)
	v_cndmask_b32_e64 v114, 0, v3, s[8:9]
	s_waitcnt vmcnt(0)
	v_cndmask_b32_e64 v113, 0, v17, s[8:9]
	v_cndmask_b32_e64 v111, 0, v16, s[8:9]
	v_cndmask_b32_e64 v109, 0, v15, s[8:9]
	v_cndmask_b32_e64 v107, 0, v14, s[8:9]
	v_cndmask_b32_e64 v115, 0, v2, s[8:9]
	v_cndmask_b32_e64 v116, 0, v1, s[8:9]
	v_cndmask_b32_e64 v117, 0, v0, s[8:9]
	v_lshlrev_b32_e32 v14, 16, v24
	v_and_b32_e32 v15, 0xffff0000, v24
	v_lshlrev_b32_e32 v16, 16, v36
	v_and_b32_e32 v17, 0xffff0000, v36
	ds_read_b128 v[24:27], v84 offset:41472
	ds_read_b128 v[32:35], v84 offset:41488
	ds_read_b128 v[36:39], v84 offset:41504
	ds_read_b128 v[0:3], v84 offset:41520
	ds_read_b128 v[40:43], v84 offset:42496
	s_waitcnt lgkmcnt(4)
	v_pk_fma_f32 v[18:19], v[24:25], v[18:19], 0 op_sel_hi:[1,1,0]
	v_lshlrev_b32_e32 v106, 16, v107
	v_and_b32_e32 v107, 0xffff0000, v107
	v_lshlrev_b32_e32 v108, 16, v109
	s_waitcnt lgkmcnt(0)
	v_pk_fma_f32 v[18:19], v[40:41], v[44:45], v[18:19]
	ds_read_b128 v[44:47], v84 offset:43520
	v_and_b32_e32 v109, 0xffff0000, v109
	v_lshlrev_b32_e32 v110, 16, v111
	v_and_b32_e32 v111, 0xffff0000, v111
	v_pk_fma_f32 v[36:37], v[36:37], v[56:57], 0 op_sel_hi:[1,1,0]
	s_waitcnt lgkmcnt(0)
	v_pk_fma_f32 v[18:19], v[44:45], v[48:49], v[18:19]
	ds_read_b128 v[48:51], v84 offset:44544
	v_lshlrev_b32_e32 v112, 16, v113
	v_and_b32_e32 v113, 0xffff0000, v113
	v_pk_fma_f32 v[0:1], v[0:1], v[60:61], 0 op_sel_hi:[1,1,0]
	s_waitcnt lgkmcnt(0)
	v_pk_fma_f32 v[24:25], v[48:49], v[106:107], v[18:19]
	v_pk_fma_f32 v[18:19], v[26:27], v[22:23], 0 op_sel_hi:[1,1,0]
	v_pk_fma_f32 v[22:23], v[32:33], v[52:53], 0 op_sel_hi:[1,1,0]
	v_pk_fma_f32 v[18:19], v[42:43], v[62:63], v[18:19]
	ds_read_b128 v[40:43], v84 offset:42512
	v_pk_fma_f32 v[18:19], v[46:47], v[94:95], v[18:19]
	ds_read_b128 v[44:47], v84 offset:43536
	v_pk_fma_f32 v[18:19], v[50:51], v[108:109], v[18:19]
	ds_read_b128 v[48:51], v84 offset:44560
	s_waitcnt lgkmcnt(2)
	v_pk_fma_f32 v[22:23], v[40:41], v[64:65], v[22:23]
	v_lshlrev_b32_e32 v52, 16, v115
	s_waitcnt lgkmcnt(1)
	v_pk_fma_f32 v[22:23], v[44:45], v[96:97], v[22:23]
	v_and_b32_e32 v53, 0xffff0000, v115
	s_waitcnt lgkmcnt(0)
	v_pk_fma_f32 v[26:27], v[48:49], v[110:111], v[22:23]
	v_pk_fma_f32 v[22:23], v[34:35], v[54:55], 0 op_sel_hi:[1,1,0]
	ds_read_b128 v[32:35], v84 offset:42528
	v_pk_fma_f32 v[22:23], v[42:43], v[86:87], v[22:23]
	ds_read_b128 v[40:43], v84 offset:43552
	v_pk_fma_f32 v[22:23], v[46:47], v[98:99], v[22:23]
	ds_read_b128 v[44:47], v84 offset:44576
	s_waitcnt lgkmcnt(2)
	v_pk_fma_f32 v[32:33], v[32:33], v[88:89], v[36:37]
	v_pk_fma_f32 v[48:49], v[50:51], v[112:113], v[22:23]
	v_lshlrev_b32_e32 v22, 16, v117
	v_and_b32_e32 v23, 0xffff0000, v117
	s_waitcnt lgkmcnt(1)
	v_pk_fma_f32 v[32:33], v[40:41], v[100:101], v[32:33]
	v_lshlrev_b32_e32 v54, 16, v114
	s_waitcnt lgkmcnt(0)
; DI float sigmoidf_(float x) { return __builtin_amdgcn_rcpf(1.f + __expf(-x)); }
; DI void conv32(const bf16_t* __restrict__ Pcol, int tok, int spos, const float* wl, int wstride, float* acc) {
; #pragma unroll
;   for (int hq = 0; hq < 2; ++hq) {
;     __builtin_amdgcn_sched_barrier(0);
;     uint4 v[4][2];
; #pragma unroll
;     for (int j = 0; j < 4; ++j) {
;       const bool ok = (spos - 3 + j >= 0);
;       const uint4* src = (const uint4*)(Pcol + (size_t)(tok - 3 + (ok ? j : 3)) * 4096) + 2 * hq;
; #pragma unroll
;       for (int q = 0; q < 2; ++q) {
;         v[j][q] = src[q];
;         if (!ok) v[j][q] = make_uint4(0u, 0u, 0u, 0u);
;       }
;     }
; #pragma unroll
;     for (int i = 0; i < 16; ++i) acc[16 * hq + i] = 0.f;
; #pragma unroll
;     for (int j = 0; j < 4; ++j) {
;       const float4* w4 = (const float4*)(wl + j * wstride + 16 * hq);
; #pragma unroll
;       for (int q = 0; q < 2; ++q) {
;         float f[8];
;         unpack8(v[j][q], f);
;         float4 wa = w4[2 * q], wb = w4[2 * q + 1];
;         float* a = acc + 16 * hq + 8 * q;
;         a[0] += wa.x * f[0]; a[1] += wa.y * f[1]; a[2] += wa.z * f[2]; a[3] += wa.w * f[3];
;         a[4] += wb.x * f[4]; a[5] += wb.y * f[5]; a[6] += wb.z * f[6]; a[7] += wb.w * f[7];
;       }
;     }
; #pragma unroll
;     for (int i = 0; i < 16; ++i) acc[16 * hq + i] = acc[16 * hq + i] * sigmoidf_(acc[16 * hq + i]);
;   }
; DI void mlstm_pre(const Params& p, int ch, char* smem) {
;     ...
;     conv32(P + 2560 + h * 128 + part * 32, tok0 + t, c * 64 + t, s_w + 128 + part * 32, 256, a);
; #pragma unroll
;     for (int i = 0; i < 32; ++i) a[i] *= 0.08838834764831845f;
	v_pk_fma_f32 v[44:45], v[44:45], v[22:23], v[32:33]
	v_pk_fma_f32 v[22:23], v[38:39], v[58:59], 0 op_sel_hi:[1,1,0]
	ds_read_b128 v[36:39], v84 offset:43568
	v_pk_fma_f32 v[22:23], v[34:35], v[90:91], v[22:23]
	ds_read_b128 v[32:35], v84 offset:42544
	v_pk_fma_f32 v[22:23], v[42:43], v[102:103], v[22:23]
	ds_read_b128 v[40:43], v84 offset:44592
	v_and_b32_e32 v55, 0xffff0000, v114
	v_lshlrev_b32_e32 v50, 16, v116
	s_waitcnt lgkmcnt(1)
	v_pk_fma_f32 v[0:1], v[32:33], v[92:93], v[0:1]
	v_and_b32_e32 v51, 0xffff0000, v116
	v_pk_fma_f32 v[0:1], v[36:37], v[104:105], v[0:1]
	v_pk_fma_f32 v[22:23], v[46:47], v[50:51], v[22:23]
	s_waitcnt lgkmcnt(0)
	v_pk_fma_f32 v[32:33], v[40:41], v[52:53], v[0:1]
	v_pk_fma_f32 v[0:1], v[2:3], v[14:15], 0 op_sel_hi:[1,1,0]
	v_mul_f32_e32 v2, 0xbfb8aa3b, v18
	v_pk_fma_f32 v[0:1], v[34:35], v[16:17], v[0:1]
	v_mul_f32_e32 v3, 0xbfb8aa3b, v19
	v_pk_fma_f32 v[0:1], v[38:39], v[20:21], v[0:1]
	v_exp_f32_e32 v2, v2
	v_pk_fma_f32 v[20:21], v[42:43], v[54:55], v[0:1]
	v_mul_f32_e32 v0, 0xbfb8aa3b, v24
	v_mul_f32_e32 v1, 0xbfb8aa3b, v25
	v_exp_f32_e32 v0, v0
	v_exp_f32_e32 v1, v1
	v_exp_f32_e32 v3, v3
	v_add_f32_e32 v2, 1.0, v2
	v_add_f32_e32 v0, 1.0, v0
	v_add_f32_e32 v1, 1.0, v1
	v_rcp_f32_e32 v0, v0
	v_rcp_f32_e32 v1, v1
	v_add_f32_e32 v3, 1.0, v3
	v_rcp_f32_e32 v2, v2
	v_rcp_f32_e32 v3, v3
	v_pk_mul_f32 v[0:1], v[24:25], v[0:1]
	v_mul_f32_e32 v24, 0xbfb8aa3b, v22
	v_mul_f32_e32 v25, 0xbfb8aa3b, v23
	v_exp_f32_e32 v24, v24
	v_exp_f32_e32 v25, v25
	v_pk_mul_f32 v[2:3], v[18:19], v[2:3]
	v_mul_f32_e32 v14, 0xbfb8aa3b, v26
	v_add_f32_e32 v24, 1.0, v24
	v_add_f32_e32 v25, 1.0, v25
	v_rcp_f32_e32 v24, v24
	v_rcp_f32_e32 v25, v25
	v_mul_f32_e32 v15, 0xbfb8aa3b, v27
	v_mul_f32_e32 v16, 0xbfb8aa3b, v48
	v_mul_f32_e32 v17, 0xbfb8aa3b, v49
	v_pk_mul_f32 v[64:65], v[22:23], v[24:25]
	v_mul_f32_e32 v22, 0xbfb8aa3b, v32
	v_mul_f32_e32 v23, 0xbfb8aa3b, v33
	v_exp_f32_e32 v22, v22
	v_exp_f32_e32 v23, v23
	v_mul_f32_e32 v18, 0xbfb8aa3b, v44
	v_mul_f32_e32 v19, 0xbfb8aa3b, v45
	v_add_f32_e32 v22, 1.0, v22
	v_add_f32_e32 v23, 1.0, v23
	v_rcp_f32_e32 v22, v22
	v_rcp_f32_e32 v23, v23
	v_exp_f32_e32 v14, v14
	v_exp_f32_e32 v15, v15
	v_exp_f32_e32 v16, v16
	v_exp_f32_e32 v17, v17
	v_exp_f32_e32 v18, v18
	v_exp_f32_e32 v19, v19
	v_pk_mul_f32 v[88:89], v[32:33], v[22:23]
	v_mul_f32_e32 v22, 0xbfb8aa3b, v20
	v_mul_f32_e32 v23, 0xbfb8aa3b, v21
	v_exp_f32_e32 v22, v22
	v_exp_f32_e32 v23, v23
	v_add_f32_e32 v14, 1.0, v14
	v_add_f32_e32 v15, 1.0, v15
	v_add_f32_e32 v16, 1.0, v16
	v_add_f32_e32 v17, 1.0, v17
	v_add_f32_e32 v18, 1.0, v18
	v_add_f32_e32 v19, 1.0, v19
	v_rcp_f32_e32 v14, v14
	v_rcp_f32_e32 v15, v15
	v_rcp_f32_e32 v16, v16
	v_rcp_f32_e32 v17, v17
	v_rcp_f32_e32 v18, v18
	v_rcp_f32_e32 v19, v19
	v_add_f32_e32 v22, 1.0, v22
	v_add_f32_e32 v23, 1.0, v23
	v_rcp_f32_e32 v22, v22
	v_rcp_f32_e32 v23, v23
	v_pk_mul_f32 v[14:15], v[26:27], v[14:15]
	v_pk_mul_f32 v[16:17], v[48:49], v[16:17]
	v_pk_mul_f32 v[18:19], v[44:45], v[18:19]
	v_pk_mul_f32 v[90:91], v[20:21], v[22:23]
	global_load_dwordx4 v[20:23], v[10:11], off offset:32
	global_load_dwordx4 v[24:27], v[10:11], off offset:48
	global_load_dwordx4 v[32:35], v[6:7], off offset:32
	global_load_dwordx4 v[36:39], v[6:7], off offset:48
	global_load_dwordx4 v[40:43], v[4:5], off offset:32
	s_nop 0
	global_load_dwordx4 v[4:7], v[4:5], off offset:48
	s_nop 0
	global_load_dwordx4 v[44:47], v[12:13], off offset:32
	s_nop 0
	global_load_dwordx4 v[10:13], v[12:13], off offset:48
	v_pk_mul_f32 v[18:19], v[18:19], s[36:37] op_sel_hi:[1,0]
	s_waitcnt vmcnt(7)
	v_cndmask_b32_e64 v20, 0, v20, s[10:11]
	s_waitcnt vmcnt(6)
	v_cndmask_b32_e64 v27, 0, v27, s[10:11]
	v_cndmask_b32_e64 v26, 0, v26, s[10:11]
	v_cndmask_b32_e64 v25, 0, v25, s[10:11]
	v_cndmask_b32_e64 v24, 0, v24, s[10:11]
	s_waitcnt vmcnt(5)
	v_cndmask_b32_e64 v52, 0, v35, s[12:13]
	v_cndmask_b32_e64 v53, 0, v34, s[12:13]
	v_cndmask_b32_e64 v54, 0, v33, s[12:13]
	v_cndmask_b32_e64 v55, 0, v32, s[12:13]
	s_waitcnt vmcnt(4)
	v_cndmask_b32_e64 v56, 0, v39, s[12:13]
	v_cndmask_b32_e64 v57, 0, v38, s[12:13]
	v_cndmask_b32_e64 v37, 0, v37, s[12:13]
	v_cndmask_b32_e64 v36, 0, v36, s[12:13]
	s_waitcnt vmcnt(3)
	v_cndmask_b32_e64 v41, 0, v41, s[14:15]
	v_cndmask_b32_e64 v40, 0, v40, s[14:15]
	s_waitcnt vmcnt(2)
	v_cndmask_b32_e64 v62, 0, v7, s[14:15]
	v_cndmask_b32_e64 v63, 0, v6, s[14:15]
	v_cndmask_b32_e64 v92, 0, v5, s[14:15]
	v_cndmask_b32_e64 v93, 0, v4, s[14:15]
	s_waitcnt vmcnt(1)
	v_cndmask_b32_e64 v94, 0, v47, s[8:9]
	v_cndmask_b32_e64 v95, 0, v46, s[8:9]
	v_cndmask_b32_e64 v96, 0, v45, s[8:9]
	v_cndmask_b32_e64 v97, 0, v44, s[8:9]
	v_cndmask_b32_e64 v61, 0, v43, s[14:15]
	v_cndmask_b32_e64 v60, 0, v42, s[14:15]
	s_waitcnt vmcnt(0)
; DI float sigmoidf_(float x) { return __builtin_amdgcn_rcpf(1.f + __expf(-x)); }
; DI void conv32(const bf16_t* __restrict__ Pcol, int tok, int spos, const float* wl, int wstride, float* acc) {
; #pragma unroll
;   for (int hq = 0; hq < 2; ++hq) {
;     __builtin_amdgcn_sched_barrier(0);
;     uint4 v[4][2];
; #pragma unroll
;     for (int j = 0; j < 4; ++j) {
;       const bool ok = (spos - 3 + j >= 0);
;       const uint4* src = (const uint4*)(Pcol + (size_t)(tok - 3 + (ok ? j : 3)) * 4096) + 2 * hq;
; #pragma unroll
;       for (int q = 0; q < 2; ++q) {
;         v[j][q] = src[q];
;         if (!ok) v[j][q] = make_uint4(0u, 0u, 0u, 0u);
;       }
;     }
; #pragma unroll
;     for (int i = 0; i < 16; ++i) acc[16 * hq + i] = 0.f;
; #pragma unroll
;     for (int j = 0; j < 4; ++j) {
;       const float4* w4 = (const float4*)(wl + j * wstride + 16 * hq);
; #pragma unroll
;       for (int q = 0; q < 2; ++q) {
;         float f[8];
;         unpack8(v[j][q], f);
;         float4 wa = w4[2 * q], wb = w4[2 * q + 1];
;         float* a = acc + 16 * hq + 8 * q;
;         a[0] += wa.x * f[0]; a[1] += wa.y * f[1]; a[2] += wa.z * f[2]; a[3] += wa.w * f[3];
;         a[4] += wb.x * f[4]; a[5] += wb.y * f[5]; a[6] += wb.z * f[6]; a[7] += wb.w * f[7];
;       }
;     }
; #pragma unroll
;     for (int i = 0; i < 16; ++i) acc[16 * hq + i] = acc[16 * hq + i] * sigmoidf_(acc[16 * hq + i]);
;   }
; DI void mlstm_pre(const Params& p, int ch, char* smem) {
;     ...
;     conv32(P + 2560 + h * 128 + part * 32, tok0 + t, c * 64 + t, s_w + 128 + part * 32, 256, a);
; #pragma unroll
;     for (int i = 0; i < 32; ++i) a[i] *= 0.08838834764831845f;
	v_cndmask_b32_e64 v86, 0, v13, s[8:9]
	v_cndmask_b32_e64 v87, 0, v12, s[8:9]
	v_cndmask_b32_e64 v124, 0, v11, s[8:9]
	v_cndmask_b32_e64 v125, 0, v10, s[8:9]
	v_lshlrev_b32_e32 v4, 16, v20
	v_and_b32_e32 v5, 0xffff0000, v20
	v_lshlrev_b32_e32 v38, 16, v24
	v_and_b32_e32 v39, 0xffff0000, v24
	v_lshlrev_b32_e32 v50, 16, v25
	v_and_b32_e32 v51, 0xffff0000, v25
	v_lshlrev_b32_e32 v48, 16, v26
	v_and_b32_e32 v49, 0xffff0000, v26
	v_lshlrev_b32_e32 v32, 16, v27
	v_and_b32_e32 v33, 0xffff0000, v27
	v_lshlrev_b32_e32 v6, 16, v55
	v_and_b32_e32 v7, 0xffff0000, v55
	v_lshlrev_b32_e32 v108, 16, v54
	v_and_b32_e32 v109, 0xffff0000, v54
	v_lshlrev_b32_e32 v110, 16, v53
	v_and_b32_e32 v111, 0xffff0000, v53
	v_lshlrev_b32_e32 v58, 16, v52
	v_and_b32_e32 v59, 0xffff0000, v52
	v_lshlrev_b32_e32 v42, 16, v36
	v_and_b32_e32 v43, 0xffff0000, v36
	v_lshlrev_b32_e32 v52, 16, v37
	v_and_b32_e32 v53, 0xffff0000, v37
	v_lshlrev_b32_e32 v44, 16, v57
	v_and_b32_e32 v45, 0xffff0000, v57
	v_lshlrev_b32_e32 v36, 16, v56
	v_and_b32_e32 v37, 0xffff0000, v56
	v_lshlrev_b32_e32 v112, 16, v40
	v_and_b32_e32 v113, 0xffff0000, v40
	v_lshlrev_b32_e32 v114, 16, v41
	v_and_b32_e32 v115, 0xffff0000, v41
	v_lshlrev_b32_e32 v56, 16, v93
	v_and_b32_e32 v57, 0xffff0000, v93
	v_lshlrev_b32_e32 v54, 16, v92
	v_and_b32_e32 v55, 0xffff0000, v92
	v_lshlrev_b32_e32 v46, 16, v63
	v_and_b32_e32 v47, 0xffff0000, v63
	v_lshlrev_b32_e32 v40, 16, v62
	v_and_b32_e32 v41, 0xffff0000, v62
	v_lshlrev_b32_e32 v118, 16, v97
	v_and_b32_e32 v119, 0xffff0000, v97
	v_lshlrev_b32_e32 v120, 16, v96
	v_and_b32_e32 v121, 0xffff0000, v96
	v_lshlrev_b32_e32 v122, 16, v95
	v_and_b32_e32 v123, 0xffff0000, v95
	v_lshlrev_b32_e32 v62, 16, v94
	v_and_b32_e32 v63, 0xffff0000, v94
	v_pk_mul_f32 v[26:27], v[0:1], s[36:37] op_sel_hi:[1,0]
	v_pk_mul_f32 v[24:25], v[2:3], s[36:37] op_sel_hi:[1,0]
	v_pk_mul_f32 v[12:13], v[88:89], s[36:37] op_sel_hi:[1,0]
	v_pk_mul_f32 v[10:11], v[90:91], s[36:37] op_sel_hi:[1,0]
	ds_read_b128 v[0:3], v84 offset:41536
	ds_read_b128 v[88:91], v84 offset:42560
	ds_read_b128 v[92:95], v84 offset:43584
	ds_read_b128 v[96:99], v84 offset:44608
	ds_read_b128 v[100:103], v84 offset:41552
	s_waitcnt lgkmcnt(4)
	v_pk_fma_f32 v[0:1], v[0:1], v[4:5], 0 op_sel_hi:[1,1,0]
	v_cndmask_b32_e64 v23, 0, v23, s[10:11]
	s_waitcnt lgkmcnt(3)
	v_pk_fma_f32 v[0:1], v[88:89], v[6:7], v[0:1]
	v_cndmask_b32_e64 v22, 0, v22, s[10:11]
	s_waitcnt lgkmcnt(2)
	v_pk_fma_f32 v[0:1], v[92:93], v[112:113], v[0:1]
	v_lshlrev_b32_e32 v106, 16, v22
	v_and_b32_e32 v107, 0xffff0000, v22
	v_lshlrev_b32_e32 v34, 16, v23
	v_and_b32_e32 v35, 0xffff0000, v23
	v_pk_mul_f32 v[22:23], v[14:15], s[36:37] op_sel_hi:[1,0]
	s_waitcnt lgkmcnt(1)
	v_pk_fma_f32 v[14:15], v[96:97], v[118:119], v[0:1]
	v_cndmask_b32_e64 v21, 0, v21, s[10:11]
	v_mul_f32_e32 v0, 0xbfb8aa3b, v14
	v_exp_f32_e32 v0, v0
	v_mul_f32_e32 v1, 0xbfb8aa3b, v15
	v_exp_f32_e32 v1, v1
	v_lshlrev_b32_e32 v104, 16, v21
	v_add_f32_e32 v0, 1.0, v0
	v_and_b32_e32 v105, 0xffff0000, v21
	v_pk_mul_f32 v[20:21], v[16:17], s[36:37] op_sel_hi:[1,0]
	v_pk_mul_f32 v[16:17], v[64:65], s[36:37] op_sel_hi:[1,0]
	v_rcp_f32_e32 v64, v0
	v_add_f32_e32 v0, 1.0, v1
	v_rcp_f32_e32 v65, v0
	v_pk_fma_f32 v[0:1], v[2:3], v[104:105], 0 op_sel_hi:[1,1,0]
	ds_read_b128 v[4:7], v84 offset:41568
	v_pk_fma_f32 v[0:1], v[90:91], v[108:109], v[0:1]
	v_pk_mul_f32 v[14:15], v[14:15], v[64:65]
	v_pk_fma_f32 v[0:1], v[94:95], v[114:115], v[0:1]
	s_waitcnt lgkmcnt(1)
	v_pk_fma_f32 v[100:101], v[100:101], v[106:107], 0 op_sel_hi:[1,1,0]
	v_pk_fma_f32 v[104:105], v[98:99], v[120:121], v[0:1]
	v_lshlrev_b32_e32 v116, 16, v60
	v_mul_f32_e32 v0, 0xbfb8aa3b, v104
	v_exp_f32_e32 v88, v0
	ds_read_b128 v[0:3], v84 offset:41584
	v_and_b32_e32 v117, 0xffff0000, v60
	v_mul_f32_e32 v65, 0xbfb8aa3b, v105
	v_add_f32_e32 v64, 1.0, v88
	ds_read_b128 v[88:91], v84 offset:42576
	ds_read_b128 v[92:95], v84 offset:43600
	ds_read_b128 v[96:99], v84 offset:44624
	v_pk_fma_f32 v[34:35], v[102:103], v[34:35], 0 op_sel_hi:[1,1,0]
	v_lshlrev_b32_e32 v60, 16, v61
	s_waitcnt lgkmcnt(2)
	v_pk_fma_f32 v[88:89], v[88:89], v[110:111], v[100:101]
	v_and_b32_e32 v61, 0xffff0000, v61
	s_waitcnt lgkmcnt(1)
	v_pk_fma_f32 v[88:89], v[92:93], v[116:117], v[88:89]
	v_exp_f32_e32 v65, v65
	s_waitcnt lgkmcnt(0)
	v_pk_fma_f32 v[88:89], v[96:97], v[122:123], v[88:89]
	v_pk_fma_f32 v[34:35], v[90:91], v[58:59], v[34:35]
	v_mul_f32_e32 v92, 0xbfb8aa3b, v88
	v_mul_f32_e32 v93, 0xbfb8aa3b, v89
	v_exp_f32_e32 v92, v92
	v_exp_f32_e32 v93, v93
	v_pk_fma_f32 v[34:35], v[94:95], v[60:61], v[34:35]
	v_add_f32_e32 v65, 1.0, v65
	v_add_f32_e32 v92, 1.0, v92
	v_add_f32_e32 v93, 1.0, v93
	v_rcp_f32_e32 v92, v92
	v_rcp_f32_e32 v93, v93
	v_pk_fma_f32 v[94:95], v[98:99], v[62:63], v[34:35]
	v_rcp_f32_e32 v64, v64
	v_mul_f32_e32 v34, 0xbfb8aa3b, v94
	v_exp_f32_e32 v58, v34
	v_rcp_f32_e32 v65, v65
	v_mul_f32_e32 v59, 0xbfb8aa3b, v95
	v_pk_mul_f32 v[92:93], v[88:89], v[92:93]
	v_exp_f32_e32 v88, v59
	v_add_f32_e32 v58, 1.0, v58
	v_pk_mul_f32 v[34:35], v[104:105], v[64:65]
	v_rcp_f32_e32 v96, v58
	ds_read_b128 v[58:61], v84 offset:42592
	ds_read_b128 v[62:65], v84 offset:43616
	v_add_f32_e32 v97, 1.0, v88
	ds_read_b128 v[88:91], v84 offset:44640
	v_pk_fma_f32 v[4:5], v[4:5], v[38:39], 0 op_sel_hi:[1,1,0]
	v_lshlrev_b32_e32 v38, 16, v125
	s_waitcnt lgkmcnt(2)
	v_pk_fma_f32 v[4:5], v[58:59], v[42:43], v[4:5]
	v_and_b32_e32 v39, 0xffff0000, v125
	s_waitcnt lgkmcnt(1)
	v_pk_fma_f32 v[4:5], v[62:63], v[56:57], v[4:5]
	v_pk_fma_f32 v[6:7], v[6:7], v[50:51], 0 op_sel_hi:[1,1,0]
	s_waitcnt lgkmcnt(0)
; DI bf16_t f2bf(float f) { return (bf16_t)(pk2(f, 0.f) & 0xffffu); }
; DI float bf2f(bf16_t h) { return __uint_as_float(((unsigned)h) << 16); }
; DI int fragoff(int row, int k, int KS) { return (((row >> 4) * KS + (k >> 5)) << 9) + (((((k >> 3) & 3) << 4) + (row & 15)) << 3) + (k & 7); }
; DI void mlstm_pre(const Params& p, int ch, char* smem) {
;     ...
;     for (int i = 0; i < 32; ++i) a[i] *= 0.08838834764831845f;
; #pragma unroll
;     for (int q = 0; q < 4; ++q) *(uint4*)(ks + t * 136 + part * 32 + 8 * q) = pack8(a + 8 * q);
; #pragma unroll
;     for (int i = 0; i < 32; ++i) {
;       bf16_t kb = f2bf(a[i] * wgt);
;       o_kwT[fragoff(part * 32 + i, t, 2)] = kb;
;       atomicAdd(&s_kw[part * 32 + i], bf2f(kb));
;     }
	v_pk_fma_f32 v[4:5], v[88:89], v[38:39], v[4:5]
	v_pk_fma_f32 v[6:7], v[60:61], v[52:53], v[6:7]
	v_mul_f32_e32 v38, 0xbfb8aa3b, v4
	v_exp_f32_e32 v38, v38
	v_mul_f32_e32 v39, 0xbfb8aa3b, v5
	v_exp_f32_e32 v39, v39
	v_pk_fma_f32 v[6:7], v[64:65], v[54:55], v[6:7]
	v_lshlrev_b32_e32 v50, 16, v124
	v_and_b32_e32 v51, 0xffff0000, v124
	v_pk_fma_f32 v[6:7], v[90:91], v[50:51], v[6:7]
	v_add_f32_e32 v38, 1.0, v38
	v_mul_f32_e32 v50, 0xbfb8aa3b, v6
	v_rcp_f32_e32 v56, v38
	v_add_f32_e32 v38, 1.0, v39
	v_exp_f32_e32 v50, v50
	v_mul_f32_e32 v51, 0xbfb8aa3b, v7
	v_rcp_f32_e32 v57, v38
	v_exp_f32_e32 v51, v51
	v_add_f32_e32 v50, 1.0, v50
	v_rcp_f32_e32 v62, v50
	v_pk_mul_f32 v[4:5], v[4:5], v[56:57]
	v_add_f32_e32 v58, 1.0, v51
	ds_read_b128 v[50:53], v84 offset:42608
	ds_read_b128 v[54:57], v84 offset:43632
	v_rcp_f32_e32 v63, v58
	ds_read_b128 v[58:61], v84 offset:44656
	v_pk_fma_f32 v[0:1], v[0:1], v[48:49], 0 op_sel_hi:[1,1,0]
	v_pk_fma_f32 v[2:3], v[2:3], v[32:33], 0 op_sel_hi:[1,1,0]
	s_waitcnt lgkmcnt(2)
	v_pk_fma_f32 v[0:1], v[50:51], v[44:45], v[0:1]
	v_pk_fma_f32 v[2:3], v[52:53], v[36:37], v[2:3]
	s_waitcnt lgkmcnt(1)
	v_pk_fma_f32 v[0:1], v[54:55], v[46:47], v[0:1]
	v_lshlrev_b32_e32 v44, 16, v87
	v_and_b32_e32 v45, 0xffff0000, v87
	v_pk_fma_f32 v[2:3], v[56:57], v[40:41], v[2:3]
	v_lshlrev_b32_e32 v32, 16, v86
	v_and_b32_e32 v33, 0xffff0000, v86
	s_waitcnt lgkmcnt(0)
	v_pk_fma_f32 v[0:1], v[58:59], v[44:45], v[0:1]
	v_pk_fma_f32 v[36:37], v[60:61], v[32:33], v[2:3]
	v_mul_f32_e32 v44, 0xbfb8aa3b, v0
	v_mul_f32_e32 v45, 0xbfb8aa3b, v1
	v_mul_f32_e32 v2, 0xbfb8aa3b, v36
	v_exp_f32_e32 v44, v44
	v_exp_f32_e32 v45, v45
	v_exp_f32_e32 v2, v2
	v_mul_f32_e32 v3, 0xbfb8aa3b, v37
	v_exp_f32_e32 v3, v3
	v_add_f32_e32 v44, 1.0, v44
	v_add_f32_e32 v45, 1.0, v45
	v_add_f32_e32 v2, 1.0, v2
	v_rcp_f32_e32 v44, v44
	v_rcp_f32_e32 v45, v45
	v_rcp_f32_e32 v40, v2
	v_add_f32_e32 v2, 1.0, v3
	v_rcp_f32_e32 v97, v97
	v_rcp_f32_e32 v41, v2
	v_pk_mul_f32 v[0:1], v[0:1], v[44:45]
	v_pk_mul_f32 v[14:15], v[14:15], s[36:37] op_sel_hi:[1,0]
	v_pk_mul_f32 v[38:39], v[94:95], v[96:97]
	v_pk_mul_f32 v[4:5], v[4:5], s[36:37] op_sel_hi:[1,0]
	v_pk_mul_f32 v[6:7], v[6:7], v[62:63]
	v_pk_mul_f32 v[2:3], v[0:1], s[36:37] op_sel_hi:[1,0]
	v_pk_mul_f32 v[0:1], v[36:37], v[40:41]
	v_pk_mul_f32 v[34:35], v[34:35], s[36:37] op_sel_hi:[1,0]
	v_pk_mul_f32 v[42:43], v[92:93], s[36:37] op_sel_hi:[1,0]
	v_pk_mul_f32 v[38:39], v[38:39], s[36:37] op_sel_hi:[1,0]
	v_pk_mul_f32 v[32:33], v[6:7], s[36:37] op_sel_hi:[1,0]
	v_cvt_pk_bf16_f32 v44, v26, v27
	v_cvt_pk_bf16_f32 v45, v24, v25
	v_cvt_pk_bf16_f32 v46, v22, v23
	v_cvt_pk_bf16_f32 v47, v20, v21
	ds_write_b128 v85, v[44:47] offset:17408
	v_cvt_pk_bf16_f32 v44, v18, v19
	v_cvt_pk_bf16_f32 v45, v16, v17
	v_cvt_pk_bf16_f32 v46, v12, v13
	v_cvt_pk_bf16_f32 v47, v10, v11
	v_lshlrev_b32_e32 v6, 4, v79
	v_pk_mul_f32 v[0:1], v[0:1], s[36:37] op_sel_hi:[1,0]
	ds_write_b128 v85, v[44:47] offset:17424
	v_cvt_pk_bf16_f32 v44, v14, v15
	v_cvt_pk_bf16_f32 v45, v34, v35
	v_cvt_pk_bf16_f32 v46, v42, v43
	v_cvt_pk_bf16_f32 v47, v38, v39
	v_and_b32_e32 v57, 0x180, v6
	v_mul_f32_e32 v6, v83, v26
	ds_write_b128 v85, v[44:47] offset:17440
	v_cvt_pk_bf16_f32 v44, v4, v5
	v_cvt_pk_bf16_f32 v45, v32, v33
	v_cvt_pk_bf16_f32 v46, v2, v3
	v_cvt_pk_bf16_f32 v47, v0, v1
	v_lshrrev_b32_e32 v56, 5, v79
	v_cvt_pk_bf16_f32 v26, v6, s0
	v_lshlrev_b32_e32 v6, 11, v81
	ds_write_b128 v85, v[44:47] offset:17456
	v_bfe_u32 v85, v30, 2, 3
	v_lshl_add_u32 v6, v56, 9, v6
	v_or_b32_e32 v58, v6, v85
	v_or_b32_e32 v6, v58, v57
	v_ashrrev_i32_e32 v7, 31, v6
	v_lshlrev_b64 v[6:7], 1, v[6:7]
	v_lshl_add_u64 v[36:37], s[66:67], 0, v[6:7]
	v_mov_b32_e32 v248, v36
	v_mov_b32_e32 v249, v37
	global_store_short v[36:37], v26, off
	v_lshlrev_b32_e32 v26, 16, v26
	s_nop 1
	v_add_f32_dpp v200, v26, v26 row_ror:8 row_mask:0xf bank_mask:0xf
	s_nop 1
	v_add_f32_dpp v200, v200, v200 row_ror:4 row_mask:0xf bank_mask:0xf
	v_mul_f32_e32 v26, v83, v27
	v_cvt_pk_bf16_f32 v40, v26, s0
	global_store_short v[248:249], v40, off offset:16
	v_lshlrev_b32_e32 v36, 16, v40
	s_nop 1
	v_add_f32_dpp v201, v36, v36 row_ror:8 row_mask:0xf bank_mask:0xf
	s_nop 1
	v_add_f32_dpp v201, v201, v201 row_ror:4 row_mask:0xf bank_mask:0xf
	v_mul_f32_e32 v24, v83, v24
	v_cvt_pk_bf16_f32 v24, v24, s0
	global_store_short v[248:249], v24, off offset:32
	v_lshlrev_b32_e32 v24, 16, v24
	s_nop 1
	v_add_f32_dpp v202, v24, v24 row_ror:8 row_mask:0xf bank_mask:0xf
	s_nop 1
	v_add_f32_dpp v202, v202, v202 row_ror:4 row_mask:0xf bank_mask:0xf
	v_mul_f32_e32 v24, v83, v25
	v_cvt_pk_bf16_f32 v44, v24, s0
	global_store_short v[248:249], v44, off offset:48
	v_lshlrev_b32_e32 v40, 16, v44
	s_nop 1
	v_add_f32_dpp v203, v40, v40 row_ror:8 row_mask:0xf bank_mask:0xf
	s_nop 1
	v_add_f32_dpp v203, v203, v203 row_ror:4 row_mask:0xf bank_mask:0xf
	v_mul_f32_e32 v22, v83, v22
	v_cvt_pk_bf16_f32 v22, v22, s0
	global_store_short v[248:249], v22, off offset:64
	v_lshlrev_b32_e32 v22, 16, v22
	s_nop 1
	v_add_f32_dpp v204, v22, v22 row_ror:8 row_mask:0xf bank_mask:0xf
	s_nop 1
	v_add_f32_dpp v204, v204, v204 row_ror:4 row_mask:0xf bank_mask:0xf
	v_mul_f32_e32 v22, v83, v23
	v_cvt_pk_bf16_f32 v46, v22, s0
	global_store_short v[248:249], v46, off offset:80
	v_lshlrev_b32_e32 v44, 16, v46
	s_nop 1
	v_add_f32_dpp v205, v44, v44 row_ror:8 row_mask:0xf bank_mask:0xf
	s_nop 1
	v_add_f32_dpp v205, v205, v205 row_ror:4 row_mask:0xf bank_mask:0xf
	v_mul_f32_e32 v20, v83, v20
	v_cvt_pk_bf16_f32 v20, v20, s0
	global_store_short v[248:249], v20, off offset:96
	v_lshlrev_b32_e32 v20, 16, v20
	s_nop 1
	v_add_f32_dpp v206, v20, v20 row_ror:8 row_mask:0xf bank_mask:0xf
; DI bf16_t f2bf(float f) { return (bf16_t)(pk2(f, 0.f) & 0xffffu); }
; DI float bf2f(bf16_t h) { return __uint_as_float(((unsigned)h) << 16); }
; DI int fragoff(int row, int k, int KS) { return (((row >> 4) * KS + (k >> 5)) << 9) + (((((k >> 3) & 3) << 4) + (row & 15)) << 3) + (k & 7); }
; DI void mlstm_pre(const Params& p, int ch, char* smem) {
;     ...
; #pragma unroll
;     for (int i = 0; i < 32; ++i) {
;       bf16_t kb = f2bf(a[i] * wgt);
;       o_kwT[fragoff(part * 32 + i, t, 2)] = kb;
;       atomicAdd(&s_kw[part * 32 + i], bf2f(kb));
;     }
	s_nop 1
	v_add_f32_dpp v206, v206, v206 row_ror:4 row_mask:0xf bank_mask:0xf
	v_mul_f32_e32 v20, v83, v21
	v_cvt_pk_bf16_f32 v48, v20, s0
	global_store_short v[248:249], v48, off offset:112
	v_lshlrev_b32_e32 v46, 16, v48
	s_nop 1
	v_add_f32_dpp v207, v46, v46 row_ror:8 row_mask:0xf bank_mask:0xf
	s_nop 1
	v_add_f32_dpp v207, v207, v207 row_ror:4 row_mask:0xf bank_mask:0xf
	v_mul_f32_e32 v18, v83, v18
	v_cvt_pk_bf16_f32 v18, v18, s0
	global_store_short v[248:249], v18, off offset:128
	v_lshlrev_b32_e32 v18, 16, v18
	s_nop 1
	v_add_f32_dpp v208, v18, v18 row_ror:8 row_mask:0xf bank_mask:0xf
	s_nop 1
	v_add_f32_dpp v208, v208, v208 row_ror:4 row_mask:0xf bank_mask:0xf
	v_mul_f32_e32 v18, v83, v19
	v_cvt_pk_bf16_f32 v50, v18, s0
	global_store_short v[248:249], v50, off offset:144
	v_lshlrev_b32_e32 v48, 16, v50
	s_nop 1
	v_add_f32_dpp v209, v48, v48 row_ror:8 row_mask:0xf bank_mask:0xf
	s_nop 1
	v_add_f32_dpp v209, v209, v209 row_ror:4 row_mask:0xf bank_mask:0xf
	v_mul_f32_e32 v16, v83, v16
	v_cvt_pk_bf16_f32 v16, v16, s0
	global_store_short v[248:249], v16, off offset:160
	v_lshlrev_b32_e32 v16, 16, v16
	s_nop 1
	v_add_f32_dpp v210, v16, v16 row_ror:8 row_mask:0xf bank_mask:0xf
	s_nop 1
	v_add_f32_dpp v210, v210, v210 row_ror:4 row_mask:0xf bank_mask:0xf
	v_mul_f32_e32 v16, v83, v17
	v_or_b32_e32 v89, 0x58, v57
	v_cvt_pk_bf16_f32 v52, v16, s0
	global_store_short v[248:249], v52, off offset:176
	v_lshlrev_b32_e32 v50, 16, v52
	s_nop 1
	v_add_f32_dpp v211, v50, v50 row_ror:8 row_mask:0xf bank_mask:0xf
	s_nop 1
	v_add_f32_dpp v211, v211, v211 row_ror:4 row_mask:0xf bank_mask:0xf
	v_mul_f32_e32 v12, v83, v12
	v_cvt_pk_bf16_f32 v12, v12, s0
	global_store_short v[248:249], v12, off offset:192
	v_lshlrev_b32_e32 v12, 16, v12
	s_nop 1
	v_add_f32_dpp v212, v12, v12 row_ror:8 row_mask:0xf bank_mask:0xf
	s_nop 1
	v_add_f32_dpp v212, v212, v212 row_ror:4 row_mask:0xf bank_mask:0xf
	v_mul_f32_e32 v12, v83, v13
	v_cvt_pk_bf16_f32 v54, v12, s0
	global_store_short v[248:249], v54, off offset:208
	v_lshlrev_b32_e32 v52, 16, v54
	s_nop 1
	v_add_f32_dpp v213, v52, v52 row_ror:8 row_mask:0xf bank_mask:0xf
	s_nop 1
	v_add_f32_dpp v213, v213, v213 row_ror:4 row_mask:0xf bank_mask:0xf
	v_mul_f32_e32 v10, v83, v10
	v_cvt_pk_bf16_f32 v10, v10, s0
	global_store_short v[248:249], v10, off offset:224
	v_lshlrev_b32_e32 v10, 16, v10
	s_nop 1
	v_add_f32_dpp v214, v10, v10 row_ror:8 row_mask:0xf bank_mask:0xf
	s_nop 1
	v_add_f32_dpp v214, v214, v214 row_ror:4 row_mask:0xf bank_mask:0xf
	v_mul_f32_e32 v10, v83, v11
	v_cvt_pk_bf16_f32 v93, v10, s0
	global_store_short v[248:249], v93, off offset:240
	v_lshlrev_b32_e32 v54, 16, v93
	s_nop 1
	v_add_f32_dpp v215, v54, v54 row_ror:8 row_mask:0xf bank_mask:0xf
	s_nop 1
	v_add_f32_dpp v215, v215, v215 row_ror:4 row_mask:0xf bank_mask:0xf
	v_lshl_add_u32 v54, v81, 2, v56
	v_lshl_add_u32 v81, v54, 9, v78
	v_mul_f32_e32 v14, v83, v14
	v_cvt_pk_bf16_f32 v14, v14, s0
	global_store_short v[248:249], v14, off offset:2048
	v_lshlrev_b32_e32 v14, 16, v14
	s_nop 1
	v_add_f32_dpp v216, v14, v14 row_ror:8 row_mask:0xf bank_mask:0xf
	s_nop 1
	v_add_f32_dpp v216, v216, v216 row_ror:4 row_mask:0xf bank_mask:0xf
	v_mul_f32_e32 v14, v83, v15
	v_cvt_pk_bf16_f32 v58, v14, s0
	global_store_short v[248:249], v58, off offset:2064
	v_lshlrev_b32_e32 v56, 16, v58
	s_nop 1
	v_add_f32_dpp v217, v56, v56 row_ror:8 row_mask:0xf bank_mask:0xf
	s_nop 1
	v_add_f32_dpp v217, v217, v217 row_ror:4 row_mask:0xf bank_mask:0xf
	v_mul_f32_e32 v34, v83, v34
	v_cvt_pk_bf16_f32 v34, v34, s0
	global_store_short v[248:249], v34, off offset:2080
	v_lshlrev_b32_e32 v34, 16, v34
	s_nop 1
	v_add_f32_dpp v218, v34, v34 row_ror:8 row_mask:0xf bank_mask:0xf
	s_nop 1
	v_add_f32_dpp v218, v218, v218 row_ror:4 row_mask:0xf bank_mask:0xf
	v_mul_f32_e32 v34, v83, v35
	v_cvt_pk_bf16_f32 v60, v34, s0
	global_store_short v[248:249], v60, off offset:2096
	v_lshlrev_b32_e32 v58, 16, v60
	s_nop 1
	v_add_f32_dpp v219, v58, v58 row_ror:8 row_mask:0xf bank_mask:0xf
	s_nop 1
	v_add_f32_dpp v219, v219, v219 row_ror:4 row_mask:0xf bank_mask:0xf
	v_mul_f32_e32 v42, v83, v42
	v_cvt_pk_bf16_f32 v42, v42, s0
	global_store_short v[248:249], v42, off offset:2112
	v_lshlrev_b32_e32 v42, 16, v42
	s_nop 1
	v_add_f32_dpp v220, v42, v42 row_ror:8 row_mask:0xf bank_mask:0xf
	s_nop 1
	v_add_f32_dpp v220, v220, v220 row_ror:4 row_mask:0xf bank_mask:0xf
	v_mul_f32_e32 v42, v83, v43
	v_cvt_pk_bf16_f32 v62, v42, s0
	global_store_short v[248:249], v62, off offset:2128
	v_lshlrev_b32_e32 v60, 16, v62
	s_nop 1
	v_add_f32_dpp v221, v60, v60 row_ror:8 row_mask:0xf bank_mask:0xf
	s_nop 1
	v_add_f32_dpp v221, v221, v221 row_ror:4 row_mask:0xf bank_mask:0xf
	v_mul_f32_e32 v38, v83, v38
	v_cvt_pk_bf16_f32 v38, v38, s0
	global_store_short v[248:249], v38, off offset:2144
	v_lshlrev_b32_e32 v38, 16, v38
	s_nop 1
	v_add_f32_dpp v222, v38, v38 row_ror:8 row_mask:0xf bank_mask:0xf
	s_nop 1
	v_add_f32_dpp v222, v222, v222 row_ror:4 row_mask:0xf bank_mask:0xf
	v_mul_f32_e32 v38, v83, v39
	v_cvt_pk_bf16_f32 v64, v38, s0
	global_store_short v[248:249], v64, off offset:2160
	v_lshlrev_b32_e32 v62, 16, v64
	s_nop 1
	v_add_f32_dpp v223, v62, v62 row_ror:8 row_mask:0xf bank_mask:0xf
	s_nop 1
	v_add_f32_dpp v223, v223, v223 row_ror:4 row_mask:0xf bank_mask:0xf
	v_mul_f32_e32 v4, v83, v4
	v_cvt_pk_bf16_f32 v4, v4, s0
	global_store_short v[248:249], v4, off offset:2176
	v_lshlrev_b32_e32 v4, 16, v4
	s_nop 1
	v_add_f32_dpp v224, v4, v4 row_ror:8 row_mask:0xf bank_mask:0xf
	s_nop 1
	v_add_f32_dpp v224, v224, v224 row_ror:4 row_mask:0xf bank_mask:0xf
	v_mul_f32_e32 v4, v83, v5
	v_cvt_pk_bf16_f32 v86, v4, s0
	global_store_short v[248:249], v86, off offset:2192
; DI bf16_t f2bf(float f) { return (bf16_t)(pk2(f, 0.f) & 0xffffu); }
; DI float bf2f(bf16_t h) { return __uint_as_float(((unsigned)h) << 16); }
; DI int fragoff(int row, int k, int KS) { return (((row >> 4) * KS + (k >> 5)) << 9) + (((((k >> 3) & 3) << 4) + (row & 15)) << 3) + (k & 7); }
; DI void mlstm_pre(const Params& p, int ch, char* smem) {
;     ...
;     for (int i = 0; i < 32; ++i) {
;       bf16_t kb = f2bf(a[i] * wgt);
;       o_kwT[fragoff(part * 32 + i, t, 2)] = kb;
;       atomicAdd(&s_kw[part * 32 + i], bf2f(kb));
;     }
;     const uint4* vsrc = (const uint4*)(P + (size_t)(tok0 + t) * 4096 + 3072 + h * 128 + part * 32);
; #pragma unroll
;     for (int q = 0; q < 4; ++q) {
;       uint4 v = vsrc[q];
;       const unsigned uu[4] = {v.x, v.y, v.z, v.w};
; #pragma unroll
;       for (int e = 0; e < 4; ++e) {
;         o_vT[fragoff(part * 32 + 8 * q + 2 * e, t, 2)] = (bf16_t)(uu[e] & 0xffffu);
;         o_vT[fragoff(part * 32 + 8 * q + 2 * e + 1, t, 2)] = (bf16_t)(uu[e] >> 16);
;       }
;     }
	v_lshlrev_b32_e32 v64, 16, v86
	s_nop 1
	v_add_f32_dpp v225, v64, v64 row_ror:8 row_mask:0xf bank_mask:0xf
	s_nop 1
	v_add_f32_dpp v225, v225, v225 row_ror:4 row_mask:0xf bank_mask:0xf
	v_mul_f32_e32 v32, v83, v32
	v_cvt_pk_bf16_f32 v32, v32, s0
	global_store_short v[248:249], v32, off offset:2208
	v_lshlrev_b32_e32 v32, 16, v32
	s_nop 1
	v_add_f32_dpp v226, v32, v32 row_ror:8 row_mask:0xf bank_mask:0xf
	s_nop 1
	v_add_f32_dpp v226, v226, v226 row_ror:4 row_mask:0xf bank_mask:0xf
	v_mul_f32_e32 v32, v83, v33
	v_cvt_pk_bf16_f32 v88, v32, s0
	v_or3_b32 v32, v89, v85, v81
	v_ashrrev_i32_e32 v33, 31, v32
	v_lshlrev_b64 v[32:33], 1, v[32:33]
	global_store_short v[248:249], v88, off offset:2224
	v_lshlrev_b32_e32 v86, 16, v88
	s_nop 1
	v_add_f32_dpp v227, v86, v86 row_ror:8 row_mask:0xf bank_mask:0xf
	s_nop 1
	v_add_f32_dpp v227, v227, v227 row_ror:4 row_mask:0xf bank_mask:0xf
	v_mul_f32_e32 v2, v83, v2
	v_cvt_pk_bf16_f32 v2, v2, s0
	global_store_short v[248:249], v2, off offset:2240
	v_lshlrev_b32_e32 v2, 16, v2
	s_nop 1
	v_add_f32_dpp v228, v2, v2 row_ror:8 row_mask:0xf bank_mask:0xf
	s_nop 1
	v_add_f32_dpp v228, v228, v228 row_ror:4 row_mask:0xf bank_mask:0xf
	v_mul_f32_e32 v2, v83, v3
	v_cvt_pk_bf16_f32 v90, v2, s0
	global_store_short v[248:249], v90, off offset:2256
	v_lshlrev_b32_e32 v2, 16, v90
	s_nop 1
	v_add_f32_dpp v229, v2, v2 row_ror:8 row_mask:0xf bank_mask:0xf
	s_nop 1
	v_add_f32_dpp v229, v229, v229 row_ror:4 row_mask:0xf bank_mask:0xf
	v_mul_f32_e32 v0, v83, v0
	v_cvt_pk_bf16_f32 v0, v0, s0
	global_store_short v[248:249], v0, off offset:2272
	v_lshlrev_b32_e32 v0, 16, v0
	s_nop 1
	v_add_f32_dpp v232, v0, v0 row_ror:8 row_mask:0xf bank_mask:0xf
	s_nop 1
	v_add_f32_dpp v232, v232, v232 row_ror:4 row_mask:0xf bank_mask:0xf
	v_mul_f32_e32 v0, v83, v1
	v_cvt_pk_bf16_f32 v2, v0, s0
	global_store_short v[248:249], v2, off offset:2288
	v_lshlrev_b32_e32 v0, 16, v2
	s_nop 1
	v_add_f32_dpp v233, v0, v0 row_ror:8 row_mask:0xf bank_mask:0xf
	s_nop 1
	v_add_f32_dpp v233, v233, v233 row_ror:4 row_mask:0xf bank_mask:0xf
	s_mov_b64 s[100:101], exec
	s_mov_b32 s98, 0xf000f
	s_mov_b32 s99, 0xf000f
	s_and_b64 exec, s[98:99], s[100:101]
	ds_add_f32 v84, v200 offset:36864
	ds_add_f32 v84, v201 offset:36868
	ds_add_f32 v84, v202 offset:36872
	ds_add_f32 v84, v203 offset:36876
	ds_add_f32 v84, v204 offset:36880
	ds_add_f32 v84, v205 offset:36884
	ds_add_f32 v84, v206 offset:36888
	ds_add_f32 v84, v207 offset:36892
	ds_add_f32 v84, v208 offset:36896
	ds_add_f32 v84, v209 offset:36900
	ds_add_f32 v84, v210 offset:36904
	ds_add_f32 v84, v211 offset:36908
	ds_add_f32 v84, v212 offset:36912
	ds_add_f32 v84, v213 offset:36916
	ds_add_f32 v84, v214 offset:36920
	ds_add_f32 v84, v215 offset:36924
	ds_add_f32 v84, v216 offset:36928
	ds_add_f32 v84, v217 offset:36932
	ds_add_f32 v84, v218 offset:36936
	ds_add_f32 v84, v219 offset:36940
	ds_add_f32 v84, v220 offset:36944
	ds_add_f32 v84, v221 offset:36948
	ds_add_f32 v84, v222 offset:36952
	ds_add_f32 v84, v223 offset:36956
	ds_add_f32 v84, v224 offset:36960
	ds_add_f32 v84, v225 offset:36964
	ds_add_f32 v84, v226 offset:36968
	ds_add_f32 v84, v227 offset:36972
	ds_add_f32 v84, v228 offset:36976
	ds_add_f32 v84, v229 offset:36980
	ds_add_f32 v84, v232 offset:36984
	ds_add_f32 v84, v233 offset:36988
	s_mov_b64 exec, s[100:101]
	v_lshl_add_u64 v[0:1], s[86:87], 0, v[8:9]
	v_lshl_add_u64 v[0:1], v[0:1], 0, s[34:35]
	v_lshl_add_u64 v[8:9], v[0:1], 0, v[28:29]
	s_movk_i32 s8, 0x1000
	v_add_co_u32_e64 v0, s[8:9], s8, v8
	v_lshl_add_u64 v[6:7], s[64:65], 0, v[6:7]
	v_mov_b32_e32 v250, v6
	v_mov_b32_e32 v251, v7
	s_nop 0
	v_addc_co_u32_e64 v1, s[8:9], 0, v9, s[8:9]
	global_load_dwordx4 v[0:3], v[0:1], off offset:2048
	v_lshl_add_u64 v[8:9], v[8:9], 0, s[42:43]
	s_waitcnt vmcnt(0)
	global_store_short v[6:7], v0, off
	global_store_short_d16_hi v[250:251], v0, off offset:16
	global_store_short v[250:251], v1, off offset:32
	global_store_short_d16_hi v[250:251], v1, off offset:48
	global_store_short v[250:251], v2, off offset:64
	global_store_short_d16_hi v[250:251], v2, off offset:80
	global_store_short v[250:251], v3, off offset:96
	global_store_short_d16_hi v[250:251], v3, off offset:112
	global_load_dwordx4 v[0:3], v[8:9], off offset:16
	v_and_b32_e32 v21, 31, v30
	s_waitcnt vmcnt(0)
	global_store_short v[250:251], v0, off offset:128
	global_store_short_d16_hi v[250:251], v0, off offset:144
	global_store_short v[250:251], v1, off offset:160
	global_store_short_d16_hi v[250:251], v1, off offset:176
	global_store_short v[250:251], v2, off offset:192
	global_store_short_d16_hi v[250:251], v2, off offset:208
	global_store_short v[250:251], v3, off offset:224
	global_store_short_d16_hi v[250:251], v3, off offset:240
	global_load_dwordx4 v[0:3], v[8:9], off offset:32
	v_bfe_u32 v16, v30, 6, 1
	v_lshl_or_b32 v17, v16, 5, v21
	s_waitcnt vmcnt(0)
	global_store_short v[250:251], v0, off offset:2048
	global_store_short_d16_hi v[250:251], v0, off offset:2064
	global_store_short v[250:251], v1, off offset:2080
	global_store_short_d16_hi v[250:251], v1, off offset:2096
	global_store_short v[250:251], v2, off offset:2112
	global_store_short_d16_hi v[250:251], v2, off offset:2128
	global_store_short v[250:251], v3, off offset:2144
	global_store_short_d16_hi v[250:251], v3, off offset:2160
	global_load_dwordx4 v[0:3], v[8:9], off offset:48
	s_waitcnt vmcnt(0)
	global_store_short_d16_hi v[250:251], v0, off offset:2192
	global_store_short v[250:251], v1, off offset:2208
	v_lshl_add_u64 v[4:5], s[64:65], 0, v[32:33]
	global_store_short v[250:251], v0, off offset:2176
	global_store_short_d16_hi v[250:251], v1, off offset:2224
	global_store_short v[250:251], v2, off offset:2240
	global_store_short_d16_hi v[250:251], v2, off offset:2256
	global_store_short v[250:251], v3, off offset:2272
	global_store_short_d16_hi v[250:251], v3, off offset:2288
	v_lshrrev_b32_e32 v1, 1, v30
	v_bfi_b32 v0, s79, v79, v30
	v_and_b32_e32 v4, 16, v1
	v_mad_u64_u32 v[18:19], s[8:9], v0, s75, v[4:5]
	s_waitcnt lgkmcnt(0)
	s_barrier
; #define MFMA32(a, b, c) __builtin_amdgcn_mfma_f32_32x32x16_bf16((a), (b), (c), 0, 0, 0)
; DI int crow32(int r, int half) { return (r & 3) + 8 * (r >> 2) + 4 * half; }
; DI void mlstm_pre(const Params& p, int ch, char* smem) {
;     ...
;   __syncthreads();
;   {
;     const int ti = wave >> 1, tj = wave & 1;
;     f32x16 acc;
; #pragma unroll
;     for (int r = 0; r < 16; ++r) acc[r] = 0.f;
; #pragma unroll
;     for (int s = 0; s < 8; ++s) {
;       const int ko = s * 16 + (lane >> 5) * 8;
;       bf16x8 bk = *(const bf16x8*)(ks + (tj * 32 + (lane & 31)) * 136 + ko);
;       bf16x8 aq = *(const bf16x8*)(qs + (ti * 32 + (lane & 31)) * 136 + ko);
;       acc = MFMA32(aq, bk, acc);
;     }
;     const int j = tj * 32 + (lane & 31);
;     const float cj = s_li[j] - s_bc[j];
; #pragma unroll
;     for (int r = 0; r < 16; ++r) {
;       const int i = ti * 32 + crow32(r, lane >> 5);
;       float pv = (i >= j) ? acc[r] * __expf(s_bc[i] + cj - s_mt[i]) : 0.f;
	ds_read_b128 v[0:3], v18
	v_mad_u32_u24 v19, v17, s75, v4
	ds_read_b128 v[4:7], v19 offset:17408
	ds_read_b128 v[22:25], v19 offset:17440
	ds_read_b128 v[32:35], v18 offset:32
	s_waitcnt lgkmcnt(2)
	v_mfma_f32_32x32x16_bf16 v[0:15], v[0:3], v[4:7], 0
	s_waitcnt lgkmcnt(0)
	v_mfma_f32_32x32x16_bf16 v[0:15], v[32:35], v[22:25], v[0:15]
	ds_read_b128 v[22:25], v18 offset:64
	ds_read_b128 v[32:35], v19 offset:17472
	ds_read_b128 v[36:39], v19 offset:17504
	ds_read_b128 v[40:43], v18 offset:96
	s_waitcnt lgkmcnt(2)
	v_mfma_f32_32x32x16_bf16 v[0:15], v[22:25], v[32:35], v[0:15]
	s_waitcnt lgkmcnt(0)
	v_mfma_f32_32x32x16_bf16 v[0:15], v[40:43], v[36:39], v[0:15]
	ds_read_b128 v[22:25], v18 offset:128
	ds_read_b128 v[32:35], v19 offset:17536
	ds_read_b128 v[36:39], v19 offset:17568
	ds_read_b128 v[40:43], v18 offset:160
	s_waitcnt lgkmcnt(2)
	v_mfma_f32_32x32x16_bf16 v[0:15], v[22:25], v[32:35], v[0:15]
	s_waitcnt lgkmcnt(0)
	v_mfma_f32_32x32x16_bf16 v[0:15], v[40:43], v[36:39], v[0:15]
	ds_read_b128 v[22:25], v18 offset:192
	ds_read_b128 v[32:35], v19 offset:17600
	ds_read_b128 v[36:39], v19 offset:17632
	ds_read_b128 v[40:43], v18 offset:224
	v_mul_i32_i24_e32 v18, 0xfffffef4, v17
	v_mad_u32_u24 v18, v17, s75, v18
	ds_read2st64_b32 v[18:19], v18 offset0:136 offset1:138
	s_waitcnt lgkmcnt(0)
	v_sub_f32_e32 v19, v18, v19
	v_mfma_f32_32x32x16_bf16 v[0:15], v[22:25], v[32:35], v[0:15]
	v_lshrrev_b32_e32 v18, 3, v30
	v_and_b32_e32 v22, 0xffffffe0, v79
	v_and_b32_e32 v23, 4, v18
	v_or_b32_e32 v20, v23, v22
	v_cmp_ge_i32_e64 s[8:9], v20, v17
	v_mov_b32_e32 v24, 0
	v_lshlrev_b32_e32 v18, 2, v20
	v_mfma_f32_32x32x16_bf16 v[0:15], v[40:43], v[36:39], v[0:15]
	s_and_saveexec_b64 s[10:11], s[8:9]
	s_cbranch_execz .LBB0_406
	ds_read2st64_b32 v[24:25], v18 offset0:138 offset1:140
	s_waitcnt lgkmcnt(0)
	v_add_f32_e32 v24, v19, v24
	v_sub_f32_e32 v24, v24, v25
	v_mul_f32_e32 v24, 0x3fb8aa3b, v24
	v_exp_f32_e32 v24, v24
	s_nop 3
	v_mul_f32_e32 v24, v0, v24
